# FFN-down layer 0: workgroups 0..431 compute one 128x256 pair-tile over full K (hidden tile read once for two column blocks), chunked K loop
# baseline (speedup 1.0000x reference)
; DI int opaque_tid() { int t = threadIdx.x; asm volatile("" : "+v"(t)); return t; }
; #define G_LOAD(S, kt_) do { G_LD1(S##a0, S##b0, 0, kt_); G_LD1(S##a1, S##b1, 1, kt_); G_LD1(S##a2, S##b2, 2, kt_); G_LD1(S##a3, S##b3, 3, kt_); } while (0)
; #define G_STORE(S, buf_) do { G_ST1(S##a0, S##b0, 0, buf_); G_ST1(S##a1, S##b1, 1, buf_); G_ST1(S##a2, S##b2, 2, buf_); G_ST1(S##a3, S##b3, 3, buf_); } while (0)
; template <class AL, class BL>
; DI void gemm_core(AL al, BL bl, int m0, int n0, int K, char* smem, f32x16 (&acc)[2][2]) {
;   const int tid = opaque_tid(), lane = tid & 63, w = tid >> 6, wm = w >> 1, wn = w & 1;
;   u16* As = (u16*)smem;
;   u16* Bs = As + 2 * 128 * 72;
;   uint4 xa0, xa1, xa2, xa3, xb0, xb1, xb2, xb3, ya0, ya1, ya2, ya3, yb0, yb1, yb2, yb3;
;   const int nk = K / 64;
; #pragma unroll
;   for (int mt = 0; mt < 2; mt++)
; #pragma unroll
;     for (int nt = 0; nt < 2; nt++)
; #pragma unroll
;       for (int i = 0; i < 16; i++) acc[mt][nt][i] = 0.f;
;   const int srow = tid >> 3, sch = tid & 7;
;     ...
;   G_LOAD(x, 0);
;   G_STORE(x, 0);
;   G_LOAD(x, 1);
;   G_LOAD(y, (nk > 2) ? 2 : 1);
;   __syncthreads();
; template <class AL, class BL>
; DI void gemm_phase_n1024(int K, AL al, BL bl, u16* Y, u16* parts, char* smem) {
;   for (int u = blockIdx.x; u < 1024 + 512; u += gridDim.x) {
;     f32x16 acc[2][2];
;     if (u < 1024) {
;       const int tm = u % 144, tn = u / 144;
;       gemm_core(al, bl, tm * 128, tn * 128, K, smem, acc);
;       epi_bf16_tile(acc, tm * 128, tn * 128, Y + (long)tm * 128 * 1024 + tn * 128, 1024, smem, [=](int m, int n, float v) { return v; });
.LBB0_1032:
	s_or_b64 exec, exec, s[0:1]
	s_waitcnt lgkmcnt(0)
	v_cndmask_b32_e64 v0, 0, 1, s[42:43]
	v_cmp_ne_u32_e64 s[8:9], 1, v0
	s_andn2_b64 vcc, exec, s[42:43]
	s_barrier
	s_cbranch_vccnz .LBB0_1069
	s_add_u32 s16, s48, 0x4c00000
	s_addc_u32 s17, s49, 0
	s_add_u32 s18, s48, 0xe400000
	s_addc_u32 s19, s49, 0
	s_add_u32 s33, s48, 0x400000
	s_addc_u32 s42, s49, 0
	s_add_u32 s43, s48, 0xec00000
	s_addc_u32 s44, s49, 0
	s_movk_i32 s45, 0x90
	s_waitcnt vmcnt(1)
	v_mov_b32_e32 v157, 0
	s_mov_b64 s[20:21], 0x700000
	s_mov_b32 s46, 0x700000
	s_mov_b64 s[22:23], 0x40000
	s_mov_b32 s47, 0x40000
	s_mov_b64 s[24:25], 0x740000
	s_mov_b32 s51, 0x740000
	s_mov_b64 s[26:27], 0x80000
	s_mov_b32 s52, 0x80000
	s_mov_b64 s[28:29], 0x780000
	s_mov_b32 s53, 0x780000
	s_mov_b64 s[30:31], 0xc0000
	s_mov_b32 s54, 0xc0000
	s_mov_b64 s[34:35], 0x7c0000
	s_mov_b32 s55, 0x7c0000
	s_mov_b32 s56, 0xfffffc0
	s_movk_i32 s57, 0x110
	s_mov_b64 s[36:37], 0x100
	s_cmpk_ge_u32 s78, 0x1b0
	s_cbranch_scc1 .Lfd0_skip
	v_bfe_u32 v252, v202, 5, 1
	v_and_b32_e32 v253, 31, v202
	v_lshrrev_b32_e32 v156, 7, v202
	v_bfe_u32 v254, v202, 6, 1
	v_lshlrev_b32_e32 v247, 2, v252
	v_lshl_add_u32 v247, v156, 6, v247
	v_mul_u32_u24_e32 v243, 528, v247
	v_lshl_add_u32 v247, v254, 7, v253
	v_lshl_add_u32 v243, v247, 1, v243
	v_mul_u32_u24_e32 v241, 80, v247
	v_lshl_add_u32 v241, v252, 4, v241
	v_add_u32_e32 v241, 10240, v241
	v_lshl_add_u32 v247, v156, 6, v253
	v_mul_u32_u24_e32 v240, 80, v247
	v_lshl_add_u32 v240, v252, 4, v240
	v_lshrrev_b32_e32 v247, 5, v202
	v_mul_u32_u24_e32 v244, 528, v247
	v_lshl_add_u32 v244, v253, 4, v244
	v_mul_u32_u24_e32 v245, 2048, v247
	v_and_b32_e32 v252, 15, v202
	v_lshl_add_u32 v245, v252, 4, v245
	v_and_b32_e32 v252, 16, v202
	v_cmp_ne_u32_e64 s[12:13], 0, v252
	v_lshrrev_b32_e32 v247, 2, v202
	v_and_b32_e32 v254, 3, v202
	v_lshlrev_b32_e32 v254, 4, v254
	v_mov_b32_e32 v255, 0
	v_mul_u32_u24_e32 v242, 80, v247
	v_add_u32_e32 v242, v242, v254
	s_cmpk_lt_u32 s78, 0x90
	s_cbranch_scc0 .Lfd0_c1
	s_mov_b32 s38, s78
	s_mov_b32 s39, 0
	s_mov_b32 s40, 1
	s_branch .Lfd0_cd
.Lfd0_c1:
	s_cmpk_lt_u32 s78, 0x120
	s_cbranch_scc0 .Lfd0_c2
	s_sub_u32 s38, s78, 0x90
	s_mov_b32 s39, 4
	s_mov_b32 s40, 5
	s_branch .Lfd0_cd
.Lfd0_c2:
	s_cmpk_lt_u32 s78, 0x160
	s_cbranch_scc0 .Lfd0_c3
	s_sub_u32 s38, s78, 0xd0
	s_mov_b32 s39, 2
	s_mov_b32 s40, 3
	s_branch .Lfd0_cd
.Lfd0_c3:
	s_sub_u32 s38, s78, 0x160
	s_mov_b32 s39, 2
	s_mov_b32 s40, 6
.Lfd0_cd:
	s_lshl_b32 s0, s38, 7
	v_add_u32_e32 v252, s0, v247
	v_mov_b32_e32 v253, 8192
	v_mad_u64_u32 v[182:183], s[0:1], v252, v253, v[254:255]
	v_lshl_add_u64 v[182:183], v[182:183], 0, s[16:17]
	s_mov_b32 s0, 524288
	s_mov_b32 s1, 0
	v_lshl_add_u64 v[184:185], v[182:183], 0, s[0:1]
	s_lshl_b32 s0, s39, 7
	v_add_u32_e32 v252, s0, v247
	v_mov_b32_e32 v253, 8192
	v_mad_u64_u32 v[186:187], s[0:1], v252, v253, v[254:255]
	v_lshl_add_u64 v[186:187], v[186:187], 0, s[18:19]
	s_mov_b32 s0, 524288
	s_mov_b32 s1, 0
	v_lshl_add_u64 v[188:189], v[186:187], 0, s[0:1]
	s_lshl_b32 s0, s40, 7
	v_add_u32_e32 v252, s0, v247
	v_mov_b32_e32 v253, 8192
	v_mad_u64_u32 v[190:191], s[0:1], v252, v253, v[254:255]
	v_lshl_add_u64 v[190:191], v[190:191], 0, s[18:19]
	s_mov_b32 s0, 524288
	s_mov_b32 s1, 0
	v_lshl_add_u64 v[192:193], v[190:191], 0, s[0:1]
	global_load_dwordx4 v[158:161], v[182:183], off offset:0
	global_load_dwordx4 v[162:165], v[184:185], off offset:0
	global_load_dwordx4 v[166:169], v[186:187], off offset:0
	global_load_dwordx4 v[170:173], v[188:189], off offset:0
	global_load_dwordx4 v[174:177], v[190:191], off offset:0
	global_load_dwordx4 v[178:181], v[192:193], off offset:0
	global_load_dwordx4 v[214:217], v[182:183], off offset:64
	global_load_dwordx4 v[218:221], v[184:185], off offset:64
	global_load_dwordx4 v[222:225], v[186:187], off offset:64
	global_load_dwordx4 v[228:231], v[188:189], off offset:64
	global_load_dwordx4 v[232:235], v[190:191], off offset:64
	global_load_dwordx4 v[236:239], v[192:193], off offset:64
	s_lshl_b32 s0, s38, 7
	s_mul_i32 s1, s0, 2048
	s_mul_hi_u32 s2, s0, 2048
	s_add_u32 s14, s33, s1
	s_addc_u32 s15, s42, s2
	s_lshl_b32 s0, s39, 8
	s_lshl_b32 s1, s40, 8
	v_mov_b32_e32 v252, s0
	v_mov_b32_e32 v253, s1
	v_cndmask_b32_e64 v252, v252, v253, s[12:13]
	v_add_u32_e32 v227, v245, v252
	s_mov_b32 s2, 0x800
	s_mov_b32 s3, 0
	s_waitcnt vmcnt(6)
	ds_write_b128 v242, v[158:161] offset:0
	ds_write_b128 v242, v[162:165] offset:5120
	ds_write_b128 v242, v[166:169] offset:10240
	ds_write_b128 v242, v[170:173] offset:15360
	ds_write_b128 v242, v[174:177] offset:20480
	ds_write_b128 v242, v[178:181] offset:25600
	global_load_dwordx4 v[158:161], v[182:183], off offset:128
	global_load_dwordx4 v[162:165], v[184:185], off offset:128
	global_load_dwordx4 v[166:169], v[186:187], off offset:128
	global_load_dwordx4 v[170:173], v[188:189], off offset:128
	global_load_dwordx4 v[174:177], v[190:191], off offset:128
	global_load_dwordx4 v[178:181], v[192:193], off offset:128
	s_waitcnt lgkmcnt(0)
	s_barrier
; #define G_LOAD(S, kt_) do { G_LD1(S##a0, S##b0, 0, kt_); G_LD1(S##a1, S##b1, 1, kt_); G_LD1(S##a2, S##b2, 2, kt_); G_LD1(S##a3, S##b3, 3, kt_); } while (0)
; #define G_STORE(S, buf_) do { G_ST1(S##a0, S##b0, 0, buf_); G_ST1(S##a1, S##b1, 1, buf_); G_ST1(S##a2, S##b2, 2, buf_); G_ST1(S##a3, S##b3, 3, buf_); } while (0)
; template <class AL, class BL>
; DI void gemm_core(AL al, BL bl, int m0, int n0, int K, char* smem, f32x16 (&acc)[2][2]) {
;     ...
;   G_LOAD(x, 0);
;   G_STORE(x, 0);
;   G_LOAD(x, 1);
;   G_LOAD(y, (nk > 2) ? 2 : 1);
;   __syncthreads();
;   for (int kt = 0; kt < nk; kt += 2) {
;     G_TILE(0, x, true, (kt + 3 < nk), kt + 3);
;     __syncthreads();
;     G_TILE(1, y, (kt + 2 < nk), (kt + 4 < nk), kt + 4);
;     __syncthreads();
	ds_read_b128 v[128:131], v241 offset:0
	ds_read_b128 v[132:135], v241 offset:2560
	ds_read_b128 v[136:139], v241 offset:5120
	ds_read_b128 v[140:143], v241 offset:7680
	ds_read_b128 v[144:147], v240 offset:0
	ds_read_b128 v[148:151], v240 offset:2560
	ds_read_b128 v[152:155], v240 offset:32
	ds_read_b128 v[248:251], v240 offset:2592
	s_waitcnt lgkmcnt(2)
	v_mfma_f32_32x32x16_bf16 v[0:15], v[144:147], v[128:131], 0
	v_mfma_f32_32x32x16_bf16 v[64:79], v[148:151], v[128:131], 0
	ds_read_b128 v[128:131], v241 offset:32
	s_waitcnt vmcnt(6)
	ds_write_b128 v242, v[214:217] offset:30720
	ds_write_b128 v242, v[218:221] offset:35840
	v_mfma_f32_32x32x16_bf16 v[16:31], v[144:147], v[132:135], 0
	v_mfma_f32_32x32x16_bf16 v[80:95], v[148:151], v[132:135], 0
	ds_read_b128 v[132:135], v241 offset:2592
	ds_write_b128 v242, v[222:225] offset:40960
	ds_write_b128 v242, v[228:231] offset:46080
	v_mfma_f32_32x32x16_bf16 v[32:47], v[144:147], v[136:139], 0
	v_mfma_f32_32x32x16_bf16 v[96:111], v[148:151], v[136:139], 0
	ds_read_b128 v[136:139], v241 offset:5152
	ds_write_b128 v242, v[232:235] offset:51200
	ds_write_b128 v242, v[236:239] offset:56320
	v_mfma_f32_32x32x16_bf16 v[48:63], v[144:147], v[140:143], 0
	v_mfma_f32_32x32x16_bf16 v[112:127], v[148:151], v[140:143], 0
	ds_read_b128 v[140:143], v241 offset:7712
	s_waitcnt lgkmcnt(9)
	v_mfma_f32_32x32x16_bf16 v[0:15], v[152:155], v[128:131], v[0:15]
	global_load_dwordx4 v[214:217], v[182:183], off offset:192
	global_load_dwordx4 v[218:221], v[184:185], off offset:192
	v_mfma_f32_32x32x16_bf16 v[64:79], v[248:251], v[128:131], v[64:79]
	s_waitcnt lgkmcnt(6)
	v_mfma_f32_32x32x16_bf16 v[16:31], v[152:155], v[132:135], v[16:31]
	global_load_dwordx4 v[222:225], v[186:187], off offset:192
	global_load_dwordx4 v[228:231], v[188:189], off offset:192
	v_mfma_f32_32x32x16_bf16 v[80:95], v[248:251], v[132:135], v[80:95]
	s_waitcnt lgkmcnt(3)
	v_mfma_f32_32x32x16_bf16 v[32:47], v[152:155], v[136:139], v[32:47]
	global_load_dwordx4 v[232:235], v[190:191], off offset:192
	global_load_dwordx4 v[236:239], v[192:193], off offset:192
	v_mfma_f32_32x32x16_bf16 v[96:111], v[248:251], v[136:139], v[96:111]
	s_waitcnt lgkmcnt(0)
	v_mfma_f32_32x32x16_bf16 v[48:63], v[152:155], v[140:143], v[48:63]
	v_mfma_f32_32x32x16_bf16 v[112:127], v[248:251], v[140:143], v[112:127]
	s_waitcnt lgkmcnt(0)
	s_barrier
	ds_read_b128 v[128:131], v241 offset:30720
	ds_read_b128 v[132:135], v241 offset:33280
	ds_read_b128 v[136:139], v241 offset:35840
	ds_read_b128 v[140:143], v241 offset:38400
	ds_read_b128 v[144:147], v240 offset:30720
	ds_read_b128 v[148:151], v240 offset:33280
	ds_read_b128 v[152:155], v240 offset:30752
	ds_read_b128 v[248:251], v240 offset:33312
	s_waitcnt lgkmcnt(2)
	v_mfma_f32_32x32x16_bf16 v[0:15], v[144:147], v[128:131], v[0:15]
	v_mfma_f32_32x32x16_bf16 v[64:79], v[148:151], v[128:131], v[64:79]
	ds_read_b128 v[128:131], v241 offset:30752
	s_waitcnt vmcnt(6)
	ds_write_b128 v242, v[158:161] offset:0
	ds_write_b128 v242, v[162:165] offset:5120
	v_mfma_f32_32x32x16_bf16 v[16:31], v[144:147], v[132:135], v[16:31]
	v_mfma_f32_32x32x16_bf16 v[80:95], v[148:151], v[132:135], v[80:95]
	ds_read_b128 v[132:135], v241 offset:33312
	ds_write_b128 v242, v[166:169] offset:10240
	ds_write_b128 v242, v[170:173] offset:15360
	v_mfma_f32_32x32x16_bf16 v[32:47], v[144:147], v[136:139], v[32:47]
	v_mfma_f32_32x32x16_bf16 v[96:111], v[148:151], v[136:139], v[96:111]
	ds_read_b128 v[136:139], v241 offset:35872
	ds_write_b128 v242, v[174:177] offset:20480
	ds_write_b128 v242, v[178:181] offset:25600
	v_mfma_f32_32x32x16_bf16 v[48:63], v[144:147], v[140:143], v[48:63]
	v_mfma_f32_32x32x16_bf16 v[112:127], v[148:151], v[140:143], v[112:127]
	ds_read_b128 v[140:143], v241 offset:38432
	s_waitcnt lgkmcnt(9)
	v_mfma_f32_32x32x16_bf16 v[0:15], v[152:155], v[128:131], v[0:15]
	global_load_dwordx4 v[158:161], v[182:183], off offset:256
	global_load_dwordx4 v[162:165], v[184:185], off offset:256
	v_mfma_f32_32x32x16_bf16 v[64:79], v[248:251], v[128:131], v[64:79]
	s_waitcnt lgkmcnt(6)
	v_mfma_f32_32x32x16_bf16 v[16:31], v[152:155], v[132:135], v[16:31]
	global_load_dwordx4 v[166:169], v[186:187], off offset:256
	global_load_dwordx4 v[170:173], v[188:189], off offset:256
	v_mfma_f32_32x32x16_bf16 v[80:95], v[248:251], v[132:135], v[80:95]
	s_waitcnt lgkmcnt(3)
	v_mfma_f32_32x32x16_bf16 v[32:47], v[152:155], v[136:139], v[32:47]
	global_load_dwordx4 v[174:177], v[190:191], off offset:256
	global_load_dwordx4 v[178:181], v[192:193], off offset:256
	v_mfma_f32_32x32x16_bf16 v[96:111], v[248:251], v[136:139], v[96:111]
	s_waitcnt lgkmcnt(0)
	v_mfma_f32_32x32x16_bf16 v[48:63], v[152:155], v[140:143], v[48:63]
	v_mfma_f32_32x32x16_bf16 v[112:127], v[248:251], v[140:143], v[112:127]
	s_waitcnt lgkmcnt(0)
	s_barrier
; #define G_LOAD(S, kt_) do { G_LD1(S##a0, S##b0, 0, kt_); G_LD1(S##a1, S##b1, 1, kt_); G_LD1(S##a2, S##b2, 2, kt_); G_LD1(S##a3, S##b3, 3, kt_); } while (0)
; #define G_STORE(S, buf_) do { G_ST1(S##a0, S##b0, 0, buf_); G_ST1(S##a1, S##b1, 1, buf_); G_ST1(S##a2, S##b2, 2, buf_); G_ST1(S##a3, S##b3, 3, buf_); } while (0)
; template <class AL, class BL>
; DI void gemm_core(AL al, BL bl, int m0, int n0, int K, char* smem, f32x16 (&acc)[2][2]) {
;     ...
;   G_LOAD(x, 0);
;   G_STORE(x, 0);
;   G_LOAD(x, 1);
;   G_LOAD(y, (nk > 2) ? 2 : 1);
;   __syncthreads();
;   for (int kt = 0; kt < nk; kt += 2) {
;     G_TILE(0, x, true, (kt + 3 < nk), kt + 3);
;     __syncthreads();
;     G_TILE(1, y, (kt + 2 < nk), (kt + 4 < nk), kt + 4);
;     __syncthreads();
	ds_read_b128 v[128:131], v241 offset:0
	ds_read_b128 v[132:135], v241 offset:2560
	ds_read_b128 v[136:139], v241 offset:5120
	ds_read_b128 v[140:143], v241 offset:7680
	ds_read_b128 v[144:147], v240 offset:0
	ds_read_b128 v[148:151], v240 offset:2560
	ds_read_b128 v[152:155], v240 offset:32
	ds_read_b128 v[248:251], v240 offset:2592
	s_waitcnt lgkmcnt(2)
	v_mfma_f32_32x32x16_bf16 v[0:15], v[144:147], v[128:131], v[0:15]
	v_mfma_f32_32x32x16_bf16 v[64:79], v[148:151], v[128:131], v[64:79]
	ds_read_b128 v[128:131], v241 offset:32
	s_waitcnt vmcnt(6)
	ds_write_b128 v242, v[214:217] offset:30720
	ds_write_b128 v242, v[218:221] offset:35840
	v_mfma_f32_32x32x16_bf16 v[16:31], v[144:147], v[132:135], v[16:31]
	v_mfma_f32_32x32x16_bf16 v[80:95], v[148:151], v[132:135], v[80:95]
	ds_read_b128 v[132:135], v241 offset:2592
	ds_write_b128 v242, v[222:225] offset:40960
	ds_write_b128 v242, v[228:231] offset:46080
	v_mfma_f32_32x32x16_bf16 v[32:47], v[144:147], v[136:139], v[32:47]
	v_mfma_f32_32x32x16_bf16 v[96:111], v[148:151], v[136:139], v[96:111]
	ds_read_b128 v[136:139], v241 offset:5152
	ds_write_b128 v242, v[232:235] offset:51200
	ds_write_b128 v242, v[236:239] offset:56320
	v_mfma_f32_32x32x16_bf16 v[48:63], v[144:147], v[140:143], v[48:63]
	v_mfma_f32_32x32x16_bf16 v[112:127], v[148:151], v[140:143], v[112:127]
	ds_read_b128 v[140:143], v241 offset:7712
	s_waitcnt lgkmcnt(9)
	v_mfma_f32_32x32x16_bf16 v[0:15], v[152:155], v[128:131], v[0:15]
	global_load_dwordx4 v[214:217], v[182:183], off offset:320
	global_load_dwordx4 v[218:221], v[184:185], off offset:320
	v_mfma_f32_32x32x16_bf16 v[64:79], v[248:251], v[128:131], v[64:79]
	s_waitcnt lgkmcnt(6)
	v_mfma_f32_32x32x16_bf16 v[16:31], v[152:155], v[132:135], v[16:31]
	global_load_dwordx4 v[222:225], v[186:187], off offset:320
	global_load_dwordx4 v[228:231], v[188:189], off offset:320
	v_mfma_f32_32x32x16_bf16 v[80:95], v[248:251], v[132:135], v[80:95]
	s_waitcnt lgkmcnt(3)
	v_mfma_f32_32x32x16_bf16 v[32:47], v[152:155], v[136:139], v[32:47]
	global_load_dwordx4 v[232:235], v[190:191], off offset:320
	global_load_dwordx4 v[236:239], v[192:193], off offset:320
	v_mfma_f32_32x32x16_bf16 v[96:111], v[248:251], v[136:139], v[96:111]
	s_waitcnt lgkmcnt(0)
	v_mfma_f32_32x32x16_bf16 v[48:63], v[152:155], v[140:143], v[48:63]
	v_mfma_f32_32x32x16_bf16 v[112:127], v[248:251], v[140:143], v[112:127]
	s_waitcnt lgkmcnt(0)
	s_barrier
	ds_read_b128 v[128:131], v241 offset:30720
	ds_read_b128 v[132:135], v241 offset:33280
	ds_read_b128 v[136:139], v241 offset:35840
	ds_read_b128 v[140:143], v241 offset:38400
	ds_read_b128 v[144:147], v240 offset:30720
	ds_read_b128 v[148:151], v240 offset:33280
	ds_read_b128 v[152:155], v240 offset:30752
	ds_read_b128 v[248:251], v240 offset:33312
	s_waitcnt lgkmcnt(2)
	v_mfma_f32_32x32x16_bf16 v[0:15], v[144:147], v[128:131], v[0:15]
	v_mfma_f32_32x32x16_bf16 v[64:79], v[148:151], v[128:131], v[64:79]
	ds_read_b128 v[128:131], v241 offset:30752
	s_waitcnt vmcnt(6)
	ds_write_b128 v242, v[158:161] offset:0
	ds_write_b128 v242, v[162:165] offset:5120
	v_mfma_f32_32x32x16_bf16 v[16:31], v[144:147], v[132:135], v[16:31]
	v_mfma_f32_32x32x16_bf16 v[80:95], v[148:151], v[132:135], v[80:95]
	ds_read_b128 v[132:135], v241 offset:33312
	ds_write_b128 v242, v[166:169] offset:10240
	ds_write_b128 v242, v[170:173] offset:15360
	v_mfma_f32_32x32x16_bf16 v[32:47], v[144:147], v[136:139], v[32:47]
	v_mfma_f32_32x32x16_bf16 v[96:111], v[148:151], v[136:139], v[96:111]
	ds_read_b128 v[136:139], v241 offset:35872
	ds_write_b128 v242, v[174:177] offset:20480
	ds_write_b128 v242, v[178:181] offset:25600
	v_mfma_f32_32x32x16_bf16 v[48:63], v[144:147], v[140:143], v[48:63]
	v_mfma_f32_32x32x16_bf16 v[112:127], v[148:151], v[140:143], v[112:127]
	ds_read_b128 v[140:143], v241 offset:38432
	s_waitcnt lgkmcnt(9)
	v_mfma_f32_32x32x16_bf16 v[0:15], v[152:155], v[128:131], v[0:15]
	global_load_dwordx4 v[158:161], v[182:183], off offset:384
	global_load_dwordx4 v[162:165], v[184:185], off offset:384
	v_mfma_f32_32x32x16_bf16 v[64:79], v[248:251], v[128:131], v[64:79]
	s_waitcnt lgkmcnt(6)
	v_mfma_f32_32x32x16_bf16 v[16:31], v[152:155], v[132:135], v[16:31]
	global_load_dwordx4 v[166:169], v[186:187], off offset:384
	global_load_dwordx4 v[170:173], v[188:189], off offset:384
	v_mfma_f32_32x32x16_bf16 v[80:95], v[248:251], v[132:135], v[80:95]
	s_waitcnt lgkmcnt(3)
	v_mfma_f32_32x32x16_bf16 v[32:47], v[152:155], v[136:139], v[32:47]
	global_load_dwordx4 v[174:177], v[190:191], off offset:384
	global_load_dwordx4 v[178:181], v[192:193], off offset:384
	v_mfma_f32_32x32x16_bf16 v[96:111], v[248:251], v[136:139], v[96:111]
	s_waitcnt lgkmcnt(0)
	v_mfma_f32_32x32x16_bf16 v[48:63], v[152:155], v[140:143], v[48:63]
	v_mfma_f32_32x32x16_bf16 v[112:127], v[248:251], v[140:143], v[112:127]
	s_waitcnt lgkmcnt(0)
	s_barrier
; #define G_LOAD(S, kt_) do { G_LD1(S##a0, S##b0, 0, kt_); G_LD1(S##a1, S##b1, 1, kt_); G_LD1(S##a2, S##b2, 2, kt_); G_LD1(S##a3, S##b3, 3, kt_); } while (0)
; #define G_STORE(S, buf_) do { G_ST1(S##a0, S##b0, 0, buf_); G_ST1(S##a1, S##b1, 1, buf_); G_ST1(S##a2, S##b2, 2, buf_); G_ST1(S##a3, S##b3, 3, buf_); } while (0)
; template <class AL, class BL>
; DI void gemm_core(AL al, BL bl, int m0, int n0, int K, char* smem, f32x16 (&acc)[2][2]) {
;     ...
;   G_LOAD(x, 0);
;   G_STORE(x, 0);
;   G_LOAD(x, 1);
;   G_LOAD(y, (nk > 2) ? 2 : 1);
;   __syncthreads();
;   for (int kt = 0; kt < nk; kt += 2) {
;     G_TILE(0, x, true, (kt + 3 < nk), kt + 3);
;     __syncthreads();
;     G_TILE(1, y, (kt + 2 < nk), (kt + 4 < nk), kt + 4);
;     __syncthreads();
	ds_read_b128 v[128:131], v241 offset:0
	ds_read_b128 v[132:135], v241 offset:2560
	ds_read_b128 v[136:139], v241 offset:5120
	ds_read_b128 v[140:143], v241 offset:7680
	ds_read_b128 v[144:147], v240 offset:0
	ds_read_b128 v[148:151], v240 offset:2560
	ds_read_b128 v[152:155], v240 offset:32
	ds_read_b128 v[248:251], v240 offset:2592
	s_waitcnt lgkmcnt(2)
	v_mfma_f32_32x32x16_bf16 v[0:15], v[144:147], v[128:131], v[0:15]
	v_mfma_f32_32x32x16_bf16 v[64:79], v[148:151], v[128:131], v[64:79]
	ds_read_b128 v[128:131], v241 offset:32
	s_waitcnt vmcnt(6)
	ds_write_b128 v242, v[214:217] offset:30720
	ds_write_b128 v242, v[218:221] offset:35840
	v_mfma_f32_32x32x16_bf16 v[16:31], v[144:147], v[132:135], v[16:31]
	v_mfma_f32_32x32x16_bf16 v[80:95], v[148:151], v[132:135], v[80:95]
	ds_read_b128 v[132:135], v241 offset:2592
	ds_write_b128 v242, v[222:225] offset:40960
	ds_write_b128 v242, v[228:231] offset:46080
	v_mfma_f32_32x32x16_bf16 v[32:47], v[144:147], v[136:139], v[32:47]
	v_mfma_f32_32x32x16_bf16 v[96:111], v[148:151], v[136:139], v[96:111]
	ds_read_b128 v[136:139], v241 offset:5152
	ds_write_b128 v242, v[232:235] offset:51200
	ds_write_b128 v242, v[236:239] offset:56320
	v_mfma_f32_32x32x16_bf16 v[48:63], v[144:147], v[140:143], v[48:63]
	v_mfma_f32_32x32x16_bf16 v[112:127], v[148:151], v[140:143], v[112:127]
	ds_read_b128 v[140:143], v241 offset:7712
	s_waitcnt lgkmcnt(9)
	v_mfma_f32_32x32x16_bf16 v[0:15], v[152:155], v[128:131], v[0:15]
	global_load_dwordx4 v[214:217], v[182:183], off offset:448
	global_load_dwordx4 v[218:221], v[184:185], off offset:448
	v_mfma_f32_32x32x16_bf16 v[64:79], v[248:251], v[128:131], v[64:79]
	s_waitcnt lgkmcnt(6)
	v_mfma_f32_32x32x16_bf16 v[16:31], v[152:155], v[132:135], v[16:31]
	global_load_dwordx4 v[222:225], v[186:187], off offset:448
	global_load_dwordx4 v[228:231], v[188:189], off offset:448
	v_mfma_f32_32x32x16_bf16 v[80:95], v[248:251], v[132:135], v[80:95]
	s_waitcnt lgkmcnt(3)
	v_mfma_f32_32x32x16_bf16 v[32:47], v[152:155], v[136:139], v[32:47]
	global_load_dwordx4 v[232:235], v[190:191], off offset:448
	global_load_dwordx4 v[236:239], v[192:193], off offset:448
	v_mfma_f32_32x32x16_bf16 v[96:111], v[248:251], v[136:139], v[96:111]
	s_waitcnt lgkmcnt(0)
	v_mfma_f32_32x32x16_bf16 v[48:63], v[152:155], v[140:143], v[48:63]
	v_mfma_f32_32x32x16_bf16 v[112:127], v[248:251], v[140:143], v[112:127]
	s_waitcnt lgkmcnt(0)
	s_barrier
	ds_read_b128 v[128:131], v241 offset:30720
	ds_read_b128 v[132:135], v241 offset:33280
	ds_read_b128 v[136:139], v241 offset:35840
	ds_read_b128 v[140:143], v241 offset:38400
	ds_read_b128 v[144:147], v240 offset:30720
	ds_read_b128 v[148:151], v240 offset:33280
	ds_read_b128 v[152:155], v240 offset:30752
	ds_read_b128 v[248:251], v240 offset:33312
	s_waitcnt lgkmcnt(2)
	v_mfma_f32_32x32x16_bf16 v[0:15], v[144:147], v[128:131], v[0:15]
	v_mfma_f32_32x32x16_bf16 v[64:79], v[148:151], v[128:131], v[64:79]
	ds_read_b128 v[128:131], v241 offset:30752
	s_waitcnt vmcnt(6)
	ds_write_b128 v242, v[158:161] offset:0
	ds_write_b128 v242, v[162:165] offset:5120
	v_mfma_f32_32x32x16_bf16 v[16:31], v[144:147], v[132:135], v[16:31]
	v_mfma_f32_32x32x16_bf16 v[80:95], v[148:151], v[132:135], v[80:95]
	ds_read_b128 v[132:135], v241 offset:33312
	ds_write_b128 v242, v[166:169] offset:10240
	ds_write_b128 v242, v[170:173] offset:15360
	v_mfma_f32_32x32x16_bf16 v[32:47], v[144:147], v[136:139], v[32:47]
	v_mfma_f32_32x32x16_bf16 v[96:111], v[148:151], v[136:139], v[96:111]
	ds_read_b128 v[136:139], v241 offset:35872
	ds_write_b128 v242, v[174:177] offset:20480
	ds_write_b128 v242, v[178:181] offset:25600
	v_mfma_f32_32x32x16_bf16 v[48:63], v[144:147], v[140:143], v[48:63]
	v_mfma_f32_32x32x16_bf16 v[112:127], v[148:151], v[140:143], v[112:127]
	ds_read_b128 v[140:143], v241 offset:38432
	s_waitcnt lgkmcnt(9)
	v_mfma_f32_32x32x16_bf16 v[0:15], v[152:155], v[128:131], v[0:15]
	global_load_dwordx4 v[158:161], v[182:183], off offset:512
	global_load_dwordx4 v[162:165], v[184:185], off offset:512
	v_mfma_f32_32x32x16_bf16 v[64:79], v[248:251], v[128:131], v[64:79]
	s_waitcnt lgkmcnt(6)
	v_mfma_f32_32x32x16_bf16 v[16:31], v[152:155], v[132:135], v[16:31]
	global_load_dwordx4 v[166:169], v[186:187], off offset:512
	global_load_dwordx4 v[170:173], v[188:189], off offset:512
	v_mfma_f32_32x32x16_bf16 v[80:95], v[248:251], v[132:135], v[80:95]
	s_waitcnt lgkmcnt(3)
	v_mfma_f32_32x32x16_bf16 v[32:47], v[152:155], v[136:139], v[32:47]
	global_load_dwordx4 v[174:177], v[190:191], off offset:512
	global_load_dwordx4 v[178:181], v[192:193], off offset:512
	v_mfma_f32_32x32x16_bf16 v[96:111], v[248:251], v[136:139], v[96:111]
	s_waitcnt lgkmcnt(0)
	v_mfma_f32_32x32x16_bf16 v[48:63], v[152:155], v[140:143], v[48:63]
	v_mfma_f32_32x32x16_bf16 v[112:127], v[248:251], v[140:143], v[112:127]
	s_waitcnt lgkmcnt(0)
	s_barrier
; #define G_LOAD(S, kt_) do { G_LD1(S##a0, S##b0, 0, kt_); G_LD1(S##a1, S##b1, 1, kt_); G_LD1(S##a2, S##b2, 2, kt_); G_LD1(S##a3, S##b3, 3, kt_); } while (0)
; #define G_STORE(S, buf_) do { G_ST1(S##a0, S##b0, 0, buf_); G_ST1(S##a1, S##b1, 1, buf_); G_ST1(S##a2, S##b2, 2, buf_); G_ST1(S##a3, S##b3, 3, buf_); } while (0)
; template <class AL, class BL>
; DI void gemm_core(AL al, BL bl, int m0, int n0, int K, char* smem, f32x16 (&acc)[2][2]) {
;     ...
;   G_LOAD(x, 0);
;   G_STORE(x, 0);
;   G_LOAD(x, 1);
;   G_LOAD(y, (nk > 2) ? 2 : 1);
;   __syncthreads();
;   for (int kt = 0; kt < nk; kt += 2) {
;     G_TILE(0, x, true, (kt + 3 < nk), kt + 3);
;     __syncthreads();
;     G_TILE(1, y, (kt + 2 < nk), (kt + 4 < nk), kt + 4);
;     __syncthreads();
	ds_read_b128 v[128:131], v241 offset:0
	ds_read_b128 v[132:135], v241 offset:2560
	ds_read_b128 v[136:139], v241 offset:5120
	ds_read_b128 v[140:143], v241 offset:7680
	ds_read_b128 v[144:147], v240 offset:0
	ds_read_b128 v[148:151], v240 offset:2560
	ds_read_b128 v[152:155], v240 offset:32
	ds_read_b128 v[248:251], v240 offset:2592
	s_waitcnt lgkmcnt(2)
	v_mfma_f32_32x32x16_bf16 v[0:15], v[144:147], v[128:131], v[0:15]
	v_mfma_f32_32x32x16_bf16 v[64:79], v[148:151], v[128:131], v[64:79]
	ds_read_b128 v[128:131], v241 offset:32
	s_waitcnt vmcnt(6)
	ds_write_b128 v242, v[214:217] offset:30720
	ds_write_b128 v242, v[218:221] offset:35840
	v_mfma_f32_32x32x16_bf16 v[16:31], v[144:147], v[132:135], v[16:31]
	v_mfma_f32_32x32x16_bf16 v[80:95], v[148:151], v[132:135], v[80:95]
	ds_read_b128 v[132:135], v241 offset:2592
	ds_write_b128 v242, v[222:225] offset:40960
	ds_write_b128 v242, v[228:231] offset:46080
	v_mfma_f32_32x32x16_bf16 v[32:47], v[144:147], v[136:139], v[32:47]
	v_mfma_f32_32x32x16_bf16 v[96:111], v[148:151], v[136:139], v[96:111]
	ds_read_b128 v[136:139], v241 offset:5152
	ds_write_b128 v242, v[232:235] offset:51200
	ds_write_b128 v242, v[236:239] offset:56320
	v_mfma_f32_32x32x16_bf16 v[48:63], v[144:147], v[140:143], v[48:63]
	v_mfma_f32_32x32x16_bf16 v[112:127], v[148:151], v[140:143], v[112:127]
	ds_read_b128 v[140:143], v241 offset:7712
	s_waitcnt lgkmcnt(9)
	v_mfma_f32_32x32x16_bf16 v[0:15], v[152:155], v[128:131], v[0:15]
	global_load_dwordx4 v[214:217], v[182:183], off offset:576
	global_load_dwordx4 v[218:221], v[184:185], off offset:576
	v_mfma_f32_32x32x16_bf16 v[64:79], v[248:251], v[128:131], v[64:79]
	s_waitcnt lgkmcnt(6)
	v_mfma_f32_32x32x16_bf16 v[16:31], v[152:155], v[132:135], v[16:31]
	global_load_dwordx4 v[222:225], v[186:187], off offset:576
	global_load_dwordx4 v[228:231], v[188:189], off offset:576
	v_mfma_f32_32x32x16_bf16 v[80:95], v[248:251], v[132:135], v[80:95]
	s_waitcnt lgkmcnt(3)
	v_mfma_f32_32x32x16_bf16 v[32:47], v[152:155], v[136:139], v[32:47]
	global_load_dwordx4 v[232:235], v[190:191], off offset:576
	global_load_dwordx4 v[236:239], v[192:193], off offset:576
	v_mfma_f32_32x32x16_bf16 v[96:111], v[248:251], v[136:139], v[96:111]
	s_waitcnt lgkmcnt(0)
	v_mfma_f32_32x32x16_bf16 v[48:63], v[152:155], v[140:143], v[48:63]
	v_mfma_f32_32x32x16_bf16 v[112:127], v[248:251], v[140:143], v[112:127]
	s_waitcnt lgkmcnt(0)
	s_barrier
	ds_read_b128 v[128:131], v241 offset:30720
	ds_read_b128 v[132:135], v241 offset:33280
	ds_read_b128 v[136:139], v241 offset:35840
	ds_read_b128 v[140:143], v241 offset:38400
	ds_read_b128 v[144:147], v240 offset:30720
	ds_read_b128 v[148:151], v240 offset:33280
	ds_read_b128 v[152:155], v240 offset:30752
	ds_read_b128 v[248:251], v240 offset:33312
	s_waitcnt lgkmcnt(2)
	v_mfma_f32_32x32x16_bf16 v[0:15], v[144:147], v[128:131], v[0:15]
	v_mfma_f32_32x32x16_bf16 v[64:79], v[148:151], v[128:131], v[64:79]
	ds_read_b128 v[128:131], v241 offset:30752
	s_waitcnt vmcnt(6)
	ds_write_b128 v242, v[158:161] offset:0
	ds_write_b128 v242, v[162:165] offset:5120
	v_mfma_f32_32x32x16_bf16 v[16:31], v[144:147], v[132:135], v[16:31]
	v_mfma_f32_32x32x16_bf16 v[80:95], v[148:151], v[132:135], v[80:95]
	ds_read_b128 v[132:135], v241 offset:33312
	ds_write_b128 v242, v[166:169] offset:10240
	ds_write_b128 v242, v[170:173] offset:15360
	v_mfma_f32_32x32x16_bf16 v[32:47], v[144:147], v[136:139], v[32:47]
	v_mfma_f32_32x32x16_bf16 v[96:111], v[148:151], v[136:139], v[96:111]
	ds_read_b128 v[136:139], v241 offset:35872
	ds_write_b128 v242, v[174:177] offset:20480
	ds_write_b128 v242, v[178:181] offset:25600
	v_mfma_f32_32x32x16_bf16 v[48:63], v[144:147], v[140:143], v[48:63]
	v_mfma_f32_32x32x16_bf16 v[112:127], v[148:151], v[140:143], v[112:127]
	ds_read_b128 v[140:143], v241 offset:38432
	s_waitcnt lgkmcnt(9)
	v_mfma_f32_32x32x16_bf16 v[0:15], v[152:155], v[128:131], v[0:15]
	global_load_dwordx4 v[158:161], v[182:183], off offset:640
	global_load_dwordx4 v[162:165], v[184:185], off offset:640
	v_mfma_f32_32x32x16_bf16 v[64:79], v[248:251], v[128:131], v[64:79]
	s_waitcnt lgkmcnt(6)
	v_mfma_f32_32x32x16_bf16 v[16:31], v[152:155], v[132:135], v[16:31]
	global_load_dwordx4 v[166:169], v[186:187], off offset:640
	global_load_dwordx4 v[170:173], v[188:189], off offset:640
	v_mfma_f32_32x32x16_bf16 v[80:95], v[248:251], v[132:135], v[80:95]
	s_waitcnt lgkmcnt(3)
	v_mfma_f32_32x32x16_bf16 v[32:47], v[152:155], v[136:139], v[32:47]
	global_load_dwordx4 v[174:177], v[190:191], off offset:640
	global_load_dwordx4 v[178:181], v[192:193], off offset:640
	v_mfma_f32_32x32x16_bf16 v[96:111], v[248:251], v[136:139], v[96:111]
	s_waitcnt lgkmcnt(0)
	v_mfma_f32_32x32x16_bf16 v[48:63], v[152:155], v[140:143], v[48:63]
	v_mfma_f32_32x32x16_bf16 v[112:127], v[248:251], v[140:143], v[112:127]
	s_waitcnt lgkmcnt(0)
	s_barrier
; #define G_LOAD(S, kt_) do { G_LD1(S##a0, S##b0, 0, kt_); G_LD1(S##a1, S##b1, 1, kt_); G_LD1(S##a2, S##b2, 2, kt_); G_LD1(S##a3, S##b3, 3, kt_); } while (0)
; #define G_STORE(S, buf_) do { G_ST1(S##a0, S##b0, 0, buf_); G_ST1(S##a1, S##b1, 1, buf_); G_ST1(S##a2, S##b2, 2, buf_); G_ST1(S##a3, S##b3, 3, buf_); } while (0)
; template <class AL, class BL>
; DI void gemm_core(AL al, BL bl, int m0, int n0, int K, char* smem, f32x16 (&acc)[2][2]) {
;     ...
;   G_LOAD(x, 0);
;   G_STORE(x, 0);
;   G_LOAD(x, 1);
;   G_LOAD(y, (nk > 2) ? 2 : 1);
;   __syncthreads();
;   for (int kt = 0; kt < nk; kt += 2) {
;     G_TILE(0, x, true, (kt + 3 < nk), kt + 3);
;     __syncthreads();
;     G_TILE(1, y, (kt + 2 < nk), (kt + 4 < nk), kt + 4);
;     __syncthreads();
	ds_read_b128 v[128:131], v241 offset:0
	ds_read_b128 v[132:135], v241 offset:2560
	ds_read_b128 v[136:139], v241 offset:5120
	ds_read_b128 v[140:143], v241 offset:7680
	ds_read_b128 v[144:147], v240 offset:0
	ds_read_b128 v[148:151], v240 offset:2560
	ds_read_b128 v[152:155], v240 offset:32
	ds_read_b128 v[248:251], v240 offset:2592
	s_waitcnt lgkmcnt(2)
	v_mfma_f32_32x32x16_bf16 v[0:15], v[144:147], v[128:131], v[0:15]
	v_mfma_f32_32x32x16_bf16 v[64:79], v[148:151], v[128:131], v[64:79]
	ds_read_b128 v[128:131], v241 offset:32
	s_waitcnt vmcnt(6)
	ds_write_b128 v242, v[214:217] offset:30720
	ds_write_b128 v242, v[218:221] offset:35840
	v_mfma_f32_32x32x16_bf16 v[16:31], v[144:147], v[132:135], v[16:31]
	v_mfma_f32_32x32x16_bf16 v[80:95], v[148:151], v[132:135], v[80:95]
	ds_read_b128 v[132:135], v241 offset:2592
	ds_write_b128 v242, v[222:225] offset:40960
	ds_write_b128 v242, v[228:231] offset:46080
	v_mfma_f32_32x32x16_bf16 v[32:47], v[144:147], v[136:139], v[32:47]
	v_mfma_f32_32x32x16_bf16 v[96:111], v[148:151], v[136:139], v[96:111]
	ds_read_b128 v[136:139], v241 offset:5152
	ds_write_b128 v242, v[232:235] offset:51200
	ds_write_b128 v242, v[236:239] offset:56320
	v_mfma_f32_32x32x16_bf16 v[48:63], v[144:147], v[140:143], v[48:63]
	v_mfma_f32_32x32x16_bf16 v[112:127], v[148:151], v[140:143], v[112:127]
	ds_read_b128 v[140:143], v241 offset:7712
	s_waitcnt lgkmcnt(9)
	v_mfma_f32_32x32x16_bf16 v[0:15], v[152:155], v[128:131], v[0:15]
	global_load_dwordx4 v[214:217], v[182:183], off offset:704
	global_load_dwordx4 v[218:221], v[184:185], off offset:704
	v_mfma_f32_32x32x16_bf16 v[64:79], v[248:251], v[128:131], v[64:79]
	s_waitcnt lgkmcnt(6)
	v_mfma_f32_32x32x16_bf16 v[16:31], v[152:155], v[132:135], v[16:31]
	global_load_dwordx4 v[222:225], v[186:187], off offset:704
	global_load_dwordx4 v[228:231], v[188:189], off offset:704
	v_mfma_f32_32x32x16_bf16 v[80:95], v[248:251], v[132:135], v[80:95]
	s_waitcnt lgkmcnt(3)
	v_mfma_f32_32x32x16_bf16 v[32:47], v[152:155], v[136:139], v[32:47]
	global_load_dwordx4 v[232:235], v[190:191], off offset:704
	global_load_dwordx4 v[236:239], v[192:193], off offset:704
	v_mfma_f32_32x32x16_bf16 v[96:111], v[248:251], v[136:139], v[96:111]
	s_waitcnt lgkmcnt(0)
	v_mfma_f32_32x32x16_bf16 v[48:63], v[152:155], v[140:143], v[48:63]
	v_mfma_f32_32x32x16_bf16 v[112:127], v[248:251], v[140:143], v[112:127]
	s_waitcnt lgkmcnt(0)
	s_barrier
	ds_read_b128 v[128:131], v241 offset:30720
	ds_read_b128 v[132:135], v241 offset:33280
	ds_read_b128 v[136:139], v241 offset:35840
	ds_read_b128 v[140:143], v241 offset:38400
	ds_read_b128 v[144:147], v240 offset:30720
	ds_read_b128 v[148:151], v240 offset:33280
	ds_read_b128 v[152:155], v240 offset:30752
	ds_read_b128 v[248:251], v240 offset:33312
	s_waitcnt lgkmcnt(2)
	v_mfma_f32_32x32x16_bf16 v[0:15], v[144:147], v[128:131], v[0:15]
	v_mfma_f32_32x32x16_bf16 v[64:79], v[148:151], v[128:131], v[64:79]
	ds_read_b128 v[128:131], v241 offset:30752
	s_waitcnt vmcnt(6)
	ds_write_b128 v242, v[158:161] offset:0
	ds_write_b128 v242, v[162:165] offset:5120
	v_mfma_f32_32x32x16_bf16 v[16:31], v[144:147], v[132:135], v[16:31]
	v_mfma_f32_32x32x16_bf16 v[80:95], v[148:151], v[132:135], v[80:95]
	ds_read_b128 v[132:135], v241 offset:33312
	ds_write_b128 v242, v[166:169] offset:10240
	ds_write_b128 v242, v[170:173] offset:15360
	v_mfma_f32_32x32x16_bf16 v[32:47], v[144:147], v[136:139], v[32:47]
	v_mfma_f32_32x32x16_bf16 v[96:111], v[148:151], v[136:139], v[96:111]
	ds_read_b128 v[136:139], v241 offset:35872
	ds_write_b128 v242, v[174:177] offset:20480
	ds_write_b128 v242, v[178:181] offset:25600
	v_mfma_f32_32x32x16_bf16 v[48:63], v[144:147], v[140:143], v[48:63]
	v_mfma_f32_32x32x16_bf16 v[112:127], v[148:151], v[140:143], v[112:127]
	ds_read_b128 v[140:143], v241 offset:38432
	s_waitcnt lgkmcnt(9)
	v_mfma_f32_32x32x16_bf16 v[0:15], v[152:155], v[128:131], v[0:15]
	global_load_dwordx4 v[158:161], v[182:183], off offset:768
	global_load_dwordx4 v[162:165], v[184:185], off offset:768
	v_mfma_f32_32x32x16_bf16 v[64:79], v[248:251], v[128:131], v[64:79]
	s_waitcnt lgkmcnt(6)
	v_mfma_f32_32x32x16_bf16 v[16:31], v[152:155], v[132:135], v[16:31]
	global_load_dwordx4 v[166:169], v[186:187], off offset:768
	global_load_dwordx4 v[170:173], v[188:189], off offset:768
	v_mfma_f32_32x32x16_bf16 v[80:95], v[248:251], v[132:135], v[80:95]
	s_waitcnt lgkmcnt(3)
	v_mfma_f32_32x32x16_bf16 v[32:47], v[152:155], v[136:139], v[32:47]
	global_load_dwordx4 v[174:177], v[190:191], off offset:768
	global_load_dwordx4 v[178:181], v[192:193], off offset:768
	v_mfma_f32_32x32x16_bf16 v[96:111], v[248:251], v[136:139], v[96:111]
	s_waitcnt lgkmcnt(0)
	v_mfma_f32_32x32x16_bf16 v[48:63], v[152:155], v[140:143], v[48:63]
	v_mfma_f32_32x32x16_bf16 v[112:127], v[248:251], v[140:143], v[112:127]
	s_waitcnt lgkmcnt(0)
	s_barrier
; #define G_LOAD(S, kt_) do { G_LD1(S##a0, S##b0, 0, kt_); G_LD1(S##a1, S##b1, 1, kt_); G_LD1(S##a2, S##b2, 2, kt_); G_LD1(S##a3, S##b3, 3, kt_); } while (0)
; #define G_STORE(S, buf_) do { G_ST1(S##a0, S##b0, 0, buf_); G_ST1(S##a1, S##b1, 1, buf_); G_ST1(S##a2, S##b2, 2, buf_); G_ST1(S##a3, S##b3, 3, buf_); } while (0)
; template <class AL, class BL>
; DI void gemm_core(AL al, BL bl, int m0, int n0, int K, char* smem, f32x16 (&acc)[2][2]) {
;     ...
;   G_LOAD(x, 0);
;   G_STORE(x, 0);
;   G_LOAD(x, 1);
;   G_LOAD(y, (nk > 2) ? 2 : 1);
;   __syncthreads();
;   for (int kt = 0; kt < nk; kt += 2) {
;     G_TILE(0, x, true, (kt + 3 < nk), kt + 3);
;     __syncthreads();
;     G_TILE(1, y, (kt + 2 < nk), (kt + 4 < nk), kt + 4);
;     __syncthreads();
	ds_read_b128 v[128:131], v241 offset:0
	ds_read_b128 v[132:135], v241 offset:2560
	ds_read_b128 v[136:139], v241 offset:5120
	ds_read_b128 v[140:143], v241 offset:7680
	ds_read_b128 v[144:147], v240 offset:0
	ds_read_b128 v[148:151], v240 offset:2560
	ds_read_b128 v[152:155], v240 offset:32
	ds_read_b128 v[248:251], v240 offset:2592
	s_waitcnt lgkmcnt(2)
	v_mfma_f32_32x32x16_bf16 v[0:15], v[144:147], v[128:131], v[0:15]
	v_mfma_f32_32x32x16_bf16 v[64:79], v[148:151], v[128:131], v[64:79]
	ds_read_b128 v[128:131], v241 offset:32
	s_waitcnt vmcnt(6)
	ds_write_b128 v242, v[214:217] offset:30720
	ds_write_b128 v242, v[218:221] offset:35840
	v_mfma_f32_32x32x16_bf16 v[16:31], v[144:147], v[132:135], v[16:31]
	v_mfma_f32_32x32x16_bf16 v[80:95], v[148:151], v[132:135], v[80:95]
	ds_read_b128 v[132:135], v241 offset:2592
	ds_write_b128 v242, v[222:225] offset:40960
	ds_write_b128 v242, v[228:231] offset:46080
	v_mfma_f32_32x32x16_bf16 v[32:47], v[144:147], v[136:139], v[32:47]
	v_mfma_f32_32x32x16_bf16 v[96:111], v[148:151], v[136:139], v[96:111]
	ds_read_b128 v[136:139], v241 offset:5152
	ds_write_b128 v242, v[232:235] offset:51200
	ds_write_b128 v242, v[236:239] offset:56320
	v_mfma_f32_32x32x16_bf16 v[48:63], v[144:147], v[140:143], v[48:63]
	v_mfma_f32_32x32x16_bf16 v[112:127], v[148:151], v[140:143], v[112:127]
	ds_read_b128 v[140:143], v241 offset:7712
	s_waitcnt lgkmcnt(9)
	v_mfma_f32_32x32x16_bf16 v[0:15], v[152:155], v[128:131], v[0:15]
	global_load_dwordx4 v[214:217], v[182:183], off offset:832
	global_load_dwordx4 v[218:221], v[184:185], off offset:832
	v_mfma_f32_32x32x16_bf16 v[64:79], v[248:251], v[128:131], v[64:79]
	s_waitcnt lgkmcnt(6)
	v_mfma_f32_32x32x16_bf16 v[16:31], v[152:155], v[132:135], v[16:31]
	global_load_dwordx4 v[222:225], v[186:187], off offset:832
	global_load_dwordx4 v[228:231], v[188:189], off offset:832
	v_mfma_f32_32x32x16_bf16 v[80:95], v[248:251], v[132:135], v[80:95]
	s_waitcnt lgkmcnt(3)
	v_mfma_f32_32x32x16_bf16 v[32:47], v[152:155], v[136:139], v[32:47]
	global_load_dwordx4 v[232:235], v[190:191], off offset:832
	global_load_dwordx4 v[236:239], v[192:193], off offset:832
	v_mfma_f32_32x32x16_bf16 v[96:111], v[248:251], v[136:139], v[96:111]
	s_waitcnt lgkmcnt(0)
	v_mfma_f32_32x32x16_bf16 v[48:63], v[152:155], v[140:143], v[48:63]
	v_mfma_f32_32x32x16_bf16 v[112:127], v[248:251], v[140:143], v[112:127]
	s_waitcnt lgkmcnt(0)
	s_barrier
	ds_read_b128 v[128:131], v241 offset:30720
	ds_read_b128 v[132:135], v241 offset:33280
	ds_read_b128 v[136:139], v241 offset:35840
	ds_read_b128 v[140:143], v241 offset:38400
	ds_read_b128 v[144:147], v240 offset:30720
	ds_read_b128 v[148:151], v240 offset:33280
	ds_read_b128 v[152:155], v240 offset:30752
	ds_read_b128 v[248:251], v240 offset:33312
	s_waitcnt lgkmcnt(2)
	v_mfma_f32_32x32x16_bf16 v[0:15], v[144:147], v[128:131], v[0:15]
	v_mfma_f32_32x32x16_bf16 v[64:79], v[148:151], v[128:131], v[64:79]
	ds_read_b128 v[128:131], v241 offset:30752
	s_waitcnt vmcnt(6)
	ds_write_b128 v242, v[158:161] offset:0
	ds_write_b128 v242, v[162:165] offset:5120
	v_mfma_f32_32x32x16_bf16 v[16:31], v[144:147], v[132:135], v[16:31]
	v_mfma_f32_32x32x16_bf16 v[80:95], v[148:151], v[132:135], v[80:95]
	ds_read_b128 v[132:135], v241 offset:33312
	ds_write_b128 v242, v[166:169] offset:10240
	ds_write_b128 v242, v[170:173] offset:15360
	v_mfma_f32_32x32x16_bf16 v[32:47], v[144:147], v[136:139], v[32:47]
	v_mfma_f32_32x32x16_bf16 v[96:111], v[148:151], v[136:139], v[96:111]
	ds_read_b128 v[136:139], v241 offset:35872
	ds_write_b128 v242, v[174:177] offset:20480
	ds_write_b128 v242, v[178:181] offset:25600
	v_mfma_f32_32x32x16_bf16 v[48:63], v[144:147], v[140:143], v[48:63]
	v_mfma_f32_32x32x16_bf16 v[112:127], v[148:151], v[140:143], v[112:127]
	ds_read_b128 v[140:143], v241 offset:38432
	s_waitcnt lgkmcnt(9)
	v_mfma_f32_32x32x16_bf16 v[0:15], v[152:155], v[128:131], v[0:15]
	global_load_dwordx4 v[158:161], v[182:183], off offset:896
	global_load_dwordx4 v[162:165], v[184:185], off offset:896
	v_mfma_f32_32x32x16_bf16 v[64:79], v[248:251], v[128:131], v[64:79]
	s_waitcnt lgkmcnt(6)
	v_mfma_f32_32x32x16_bf16 v[16:31], v[152:155], v[132:135], v[16:31]
	global_load_dwordx4 v[166:169], v[186:187], off offset:896
	global_load_dwordx4 v[170:173], v[188:189], off offset:896
	v_mfma_f32_32x32x16_bf16 v[80:95], v[248:251], v[132:135], v[80:95]
	s_waitcnt lgkmcnt(3)
	v_mfma_f32_32x32x16_bf16 v[32:47], v[152:155], v[136:139], v[32:47]
	global_load_dwordx4 v[174:177], v[190:191], off offset:896
	global_load_dwordx4 v[178:181], v[192:193], off offset:896
	v_mfma_f32_32x32x16_bf16 v[96:111], v[248:251], v[136:139], v[96:111]
	s_waitcnt lgkmcnt(0)
	v_mfma_f32_32x32x16_bf16 v[48:63], v[152:155], v[140:143], v[48:63]
	v_mfma_f32_32x32x16_bf16 v[112:127], v[248:251], v[140:143], v[112:127]
	s_waitcnt lgkmcnt(0)
	s_barrier
; #define G_LOAD(S, kt_) do { G_LD1(S##a0, S##b0, 0, kt_); G_LD1(S##a1, S##b1, 1, kt_); G_LD1(S##a2, S##b2, 2, kt_); G_LD1(S##a3, S##b3, 3, kt_); } while (0)
; #define G_STORE(S, buf_) do { G_ST1(S##a0, S##b0, 0, buf_); G_ST1(S##a1, S##b1, 1, buf_); G_ST1(S##a2, S##b2, 2, buf_); G_ST1(S##a3, S##b3, 3, buf_); } while (0)
; template <class AL, class BL>
; DI void gemm_core(AL al, BL bl, int m0, int n0, int K, char* smem, f32x16 (&acc)[2][2]) {
;     ...
;   G_LOAD(x, 0);
;   G_STORE(x, 0);
;   G_LOAD(x, 1);
;   G_LOAD(y, (nk > 2) ? 2 : 1);
;   __syncthreads();
;   for (int kt = 0; kt < nk; kt += 2) {
;     G_TILE(0, x, true, (kt + 3 < nk), kt + 3);
;     __syncthreads();
;     G_TILE(1, y, (kt + 2 < nk), (kt + 4 < nk), kt + 4);
;     __syncthreads();
	ds_read_b128 v[128:131], v241 offset:0
	ds_read_b128 v[132:135], v241 offset:2560
	ds_read_b128 v[136:139], v241 offset:5120
	ds_read_b128 v[140:143], v241 offset:7680
	ds_read_b128 v[144:147], v240 offset:0
	ds_read_b128 v[148:151], v240 offset:2560
	ds_read_b128 v[152:155], v240 offset:32
	ds_read_b128 v[248:251], v240 offset:2592
	s_waitcnt lgkmcnt(2)
	v_mfma_f32_32x32x16_bf16 v[0:15], v[144:147], v[128:131], v[0:15]
	v_mfma_f32_32x32x16_bf16 v[64:79], v[148:151], v[128:131], v[64:79]
	ds_read_b128 v[128:131], v241 offset:32
	s_waitcnt vmcnt(6)
	ds_write_b128 v242, v[214:217] offset:30720
	ds_write_b128 v242, v[218:221] offset:35840
	v_mfma_f32_32x32x16_bf16 v[16:31], v[144:147], v[132:135], v[16:31]
	v_mfma_f32_32x32x16_bf16 v[80:95], v[148:151], v[132:135], v[80:95]
	ds_read_b128 v[132:135], v241 offset:2592
	ds_write_b128 v242, v[222:225] offset:40960
	ds_write_b128 v242, v[228:231] offset:46080
	v_mfma_f32_32x32x16_bf16 v[32:47], v[144:147], v[136:139], v[32:47]
	v_mfma_f32_32x32x16_bf16 v[96:111], v[148:151], v[136:139], v[96:111]
	ds_read_b128 v[136:139], v241 offset:5152
	ds_write_b128 v242, v[232:235] offset:51200
	ds_write_b128 v242, v[236:239] offset:56320
	v_mfma_f32_32x32x16_bf16 v[48:63], v[144:147], v[140:143], v[48:63]
	v_mfma_f32_32x32x16_bf16 v[112:127], v[148:151], v[140:143], v[112:127]
	ds_read_b128 v[140:143], v241 offset:7712
	s_waitcnt lgkmcnt(9)
	v_mfma_f32_32x32x16_bf16 v[0:15], v[152:155], v[128:131], v[0:15]
	global_load_dwordx4 v[214:217], v[182:183], off offset:960
	global_load_dwordx4 v[218:221], v[184:185], off offset:960
	v_mfma_f32_32x32x16_bf16 v[64:79], v[248:251], v[128:131], v[64:79]
	s_waitcnt lgkmcnt(6)
	v_mfma_f32_32x32x16_bf16 v[16:31], v[152:155], v[132:135], v[16:31]
	global_load_dwordx4 v[222:225], v[186:187], off offset:960
	global_load_dwordx4 v[228:231], v[188:189], off offset:960
	v_mfma_f32_32x32x16_bf16 v[80:95], v[248:251], v[132:135], v[80:95]
	s_waitcnt lgkmcnt(3)
	v_mfma_f32_32x32x16_bf16 v[32:47], v[152:155], v[136:139], v[32:47]
	global_load_dwordx4 v[232:235], v[190:191], off offset:960
	global_load_dwordx4 v[236:239], v[192:193], off offset:960
	v_mfma_f32_32x32x16_bf16 v[96:111], v[248:251], v[136:139], v[96:111]
	s_waitcnt lgkmcnt(0)
	v_mfma_f32_32x32x16_bf16 v[48:63], v[152:155], v[140:143], v[48:63]
	v_mfma_f32_32x32x16_bf16 v[112:127], v[248:251], v[140:143], v[112:127]
	s_waitcnt lgkmcnt(0)
	s_barrier
	ds_read_b128 v[128:131], v241 offset:30720
	ds_read_b128 v[132:135], v241 offset:33280
	ds_read_b128 v[136:139], v241 offset:35840
	ds_read_b128 v[140:143], v241 offset:38400
	ds_read_b128 v[144:147], v240 offset:30720
	ds_read_b128 v[148:151], v240 offset:33280
	ds_read_b128 v[152:155], v240 offset:30752
	ds_read_b128 v[248:251], v240 offset:33312
	s_waitcnt lgkmcnt(2)
	v_mfma_f32_32x32x16_bf16 v[0:15], v[144:147], v[128:131], v[0:15]
	v_mfma_f32_32x32x16_bf16 v[64:79], v[148:151], v[128:131], v[64:79]
	ds_read_b128 v[128:131], v241 offset:30752
	s_waitcnt vmcnt(6)
	ds_write_b128 v242, v[158:161] offset:0
	ds_write_b128 v242, v[162:165] offset:5120
	v_mfma_f32_32x32x16_bf16 v[16:31], v[144:147], v[132:135], v[16:31]
	v_mfma_f32_32x32x16_bf16 v[80:95], v[148:151], v[132:135], v[80:95]
	ds_read_b128 v[132:135], v241 offset:33312
	ds_write_b128 v242, v[166:169] offset:10240
	ds_write_b128 v242, v[170:173] offset:15360
	v_mfma_f32_32x32x16_bf16 v[32:47], v[144:147], v[136:139], v[32:47]
	v_mfma_f32_32x32x16_bf16 v[96:111], v[148:151], v[136:139], v[96:111]
	ds_read_b128 v[136:139], v241 offset:35872
	ds_write_b128 v242, v[174:177] offset:20480
	ds_write_b128 v242, v[178:181] offset:25600
	v_mfma_f32_32x32x16_bf16 v[48:63], v[144:147], v[140:143], v[48:63]
	v_mfma_f32_32x32x16_bf16 v[112:127], v[148:151], v[140:143], v[112:127]
	ds_read_b128 v[140:143], v241 offset:38432
	s_waitcnt lgkmcnt(9)
	v_mfma_f32_32x32x16_bf16 v[0:15], v[152:155], v[128:131], v[0:15]
	global_load_dwordx4 v[158:161], v[182:183], off offset:1024
	global_load_dwordx4 v[162:165], v[184:185], off offset:1024
	v_mfma_f32_32x32x16_bf16 v[64:79], v[248:251], v[128:131], v[64:79]
	s_waitcnt lgkmcnt(6)
	v_mfma_f32_32x32x16_bf16 v[16:31], v[152:155], v[132:135], v[16:31]
	global_load_dwordx4 v[166:169], v[186:187], off offset:1024
	global_load_dwordx4 v[170:173], v[188:189], off offset:1024
	v_mfma_f32_32x32x16_bf16 v[80:95], v[248:251], v[132:135], v[80:95]
	s_waitcnt lgkmcnt(3)
	v_mfma_f32_32x32x16_bf16 v[32:47], v[152:155], v[136:139], v[32:47]
	global_load_dwordx4 v[174:177], v[190:191], off offset:1024
	global_load_dwordx4 v[178:181], v[192:193], off offset:1024
	v_mfma_f32_32x32x16_bf16 v[96:111], v[248:251], v[136:139], v[96:111]
	s_waitcnt lgkmcnt(0)
	v_mfma_f32_32x32x16_bf16 v[48:63], v[152:155], v[140:143], v[48:63]
	v_mfma_f32_32x32x16_bf16 v[112:127], v[248:251], v[140:143], v[112:127]
	s_waitcnt lgkmcnt(0)
	s_barrier
; #define G_LOAD(S, kt_) do { G_LD1(S##a0, S##b0, 0, kt_); G_LD1(S##a1, S##b1, 1, kt_); G_LD1(S##a2, S##b2, 2, kt_); G_LD1(S##a3, S##b3, 3, kt_); } while (0)
; #define G_STORE(S, buf_) do { G_ST1(S##a0, S##b0, 0, buf_); G_ST1(S##a1, S##b1, 1, buf_); G_ST1(S##a2, S##b2, 2, buf_); G_ST1(S##a3, S##b3, 3, buf_); } while (0)
; template <class AL, class BL>
; DI void gemm_core(AL al, BL bl, int m0, int n0, int K, char* smem, f32x16 (&acc)[2][2]) {
;     ...
;   G_LOAD(x, 0);
;   G_STORE(x, 0);
;   G_LOAD(x, 1);
;   G_LOAD(y, (nk > 2) ? 2 : 1);
;   __syncthreads();
;   for (int kt = 0; kt < nk; kt += 2) {
;     G_TILE(0, x, true, (kt + 3 < nk), kt + 3);
;     __syncthreads();
;     G_TILE(1, y, (kt + 2 < nk), (kt + 4 < nk), kt + 4);
;     __syncthreads();
	ds_read_b128 v[128:131], v241 offset:0
	ds_read_b128 v[132:135], v241 offset:2560
	ds_read_b128 v[136:139], v241 offset:5120
	ds_read_b128 v[140:143], v241 offset:7680
	ds_read_b128 v[144:147], v240 offset:0
	ds_read_b128 v[148:151], v240 offset:2560
	ds_read_b128 v[152:155], v240 offset:32
	ds_read_b128 v[248:251], v240 offset:2592
	s_waitcnt lgkmcnt(2)
	v_mfma_f32_32x32x16_bf16 v[0:15], v[144:147], v[128:131], v[0:15]
	v_mfma_f32_32x32x16_bf16 v[64:79], v[148:151], v[128:131], v[64:79]
	ds_read_b128 v[128:131], v241 offset:32
	s_waitcnt vmcnt(6)
	ds_write_b128 v242, v[214:217] offset:30720
	ds_write_b128 v242, v[218:221] offset:35840
	v_mfma_f32_32x32x16_bf16 v[16:31], v[144:147], v[132:135], v[16:31]
	v_mfma_f32_32x32x16_bf16 v[80:95], v[148:151], v[132:135], v[80:95]
	ds_read_b128 v[132:135], v241 offset:2592
	ds_write_b128 v242, v[222:225] offset:40960
	ds_write_b128 v242, v[228:231] offset:46080
	v_mfma_f32_32x32x16_bf16 v[32:47], v[144:147], v[136:139], v[32:47]
	v_mfma_f32_32x32x16_bf16 v[96:111], v[148:151], v[136:139], v[96:111]
	ds_read_b128 v[136:139], v241 offset:5152
	ds_write_b128 v242, v[232:235] offset:51200
	ds_write_b128 v242, v[236:239] offset:56320
	v_mfma_f32_32x32x16_bf16 v[48:63], v[144:147], v[140:143], v[48:63]
	v_mfma_f32_32x32x16_bf16 v[112:127], v[148:151], v[140:143], v[112:127]
	ds_read_b128 v[140:143], v241 offset:7712
	s_waitcnt lgkmcnt(9)
	v_mfma_f32_32x32x16_bf16 v[0:15], v[152:155], v[128:131], v[0:15]
	global_load_dwordx4 v[214:217], v[182:183], off offset:1088
	global_load_dwordx4 v[218:221], v[184:185], off offset:1088
	v_mfma_f32_32x32x16_bf16 v[64:79], v[248:251], v[128:131], v[64:79]
	s_waitcnt lgkmcnt(6)
	v_mfma_f32_32x32x16_bf16 v[16:31], v[152:155], v[132:135], v[16:31]
	global_load_dwordx4 v[222:225], v[186:187], off offset:1088
	global_load_dwordx4 v[228:231], v[188:189], off offset:1088
	v_mfma_f32_32x32x16_bf16 v[80:95], v[248:251], v[132:135], v[80:95]
	s_waitcnt lgkmcnt(3)
	v_mfma_f32_32x32x16_bf16 v[32:47], v[152:155], v[136:139], v[32:47]
	global_load_dwordx4 v[232:235], v[190:191], off offset:1088
	global_load_dwordx4 v[236:239], v[192:193], off offset:1088
	v_mfma_f32_32x32x16_bf16 v[96:111], v[248:251], v[136:139], v[96:111]
	s_waitcnt lgkmcnt(0)
	v_mfma_f32_32x32x16_bf16 v[48:63], v[152:155], v[140:143], v[48:63]
	v_mfma_f32_32x32x16_bf16 v[112:127], v[248:251], v[140:143], v[112:127]
	s_waitcnt lgkmcnt(0)
	s_barrier
	ds_read_b128 v[128:131], v241 offset:30720
	ds_read_b128 v[132:135], v241 offset:33280
	ds_read_b128 v[136:139], v241 offset:35840
	ds_read_b128 v[140:143], v241 offset:38400
	ds_read_b128 v[144:147], v240 offset:30720
	ds_read_b128 v[148:151], v240 offset:33280
	ds_read_b128 v[152:155], v240 offset:30752
	ds_read_b128 v[248:251], v240 offset:33312
	s_waitcnt lgkmcnt(2)
	v_mfma_f32_32x32x16_bf16 v[0:15], v[144:147], v[128:131], v[0:15]
	v_mfma_f32_32x32x16_bf16 v[64:79], v[148:151], v[128:131], v[64:79]
	ds_read_b128 v[128:131], v241 offset:30752
	s_waitcnt vmcnt(6)
	ds_write_b128 v242, v[158:161] offset:0
	ds_write_b128 v242, v[162:165] offset:5120
	v_mfma_f32_32x32x16_bf16 v[16:31], v[144:147], v[132:135], v[16:31]
	v_mfma_f32_32x32x16_bf16 v[80:95], v[148:151], v[132:135], v[80:95]
	ds_read_b128 v[132:135], v241 offset:33312
	ds_write_b128 v242, v[166:169] offset:10240
	ds_write_b128 v242, v[170:173] offset:15360
	v_mfma_f32_32x32x16_bf16 v[32:47], v[144:147], v[136:139], v[32:47]
	v_mfma_f32_32x32x16_bf16 v[96:111], v[148:151], v[136:139], v[96:111]
	ds_read_b128 v[136:139], v241 offset:35872
	ds_write_b128 v242, v[174:177] offset:20480
	ds_write_b128 v242, v[178:181] offset:25600
	v_mfma_f32_32x32x16_bf16 v[48:63], v[144:147], v[140:143], v[48:63]
	v_mfma_f32_32x32x16_bf16 v[112:127], v[148:151], v[140:143], v[112:127]
	ds_read_b128 v[140:143], v241 offset:38432
	s_waitcnt lgkmcnt(9)
	v_mfma_f32_32x32x16_bf16 v[0:15], v[152:155], v[128:131], v[0:15]
	global_load_dwordx4 v[158:161], v[182:183], off offset:1152
	global_load_dwordx4 v[162:165], v[184:185], off offset:1152
	v_mfma_f32_32x32x16_bf16 v[64:79], v[248:251], v[128:131], v[64:79]
	s_waitcnt lgkmcnt(6)
	v_mfma_f32_32x32x16_bf16 v[16:31], v[152:155], v[132:135], v[16:31]
	global_load_dwordx4 v[166:169], v[186:187], off offset:1152
	global_load_dwordx4 v[170:173], v[188:189], off offset:1152
	v_mfma_f32_32x32x16_bf16 v[80:95], v[248:251], v[132:135], v[80:95]
	s_waitcnt lgkmcnt(3)
	v_mfma_f32_32x32x16_bf16 v[32:47], v[152:155], v[136:139], v[32:47]
	global_load_dwordx4 v[174:177], v[190:191], off offset:1152
	global_load_dwordx4 v[178:181], v[192:193], off offset:1152
	v_mfma_f32_32x32x16_bf16 v[96:111], v[248:251], v[136:139], v[96:111]
	s_waitcnt lgkmcnt(0)
	v_mfma_f32_32x32x16_bf16 v[48:63], v[152:155], v[140:143], v[48:63]
	v_mfma_f32_32x32x16_bf16 v[112:127], v[248:251], v[140:143], v[112:127]
	s_waitcnt lgkmcnt(0)
	s_barrier
; #define G_LOAD(S, kt_) do { G_LD1(S##a0, S##b0, 0, kt_); G_LD1(S##a1, S##b1, 1, kt_); G_LD1(S##a2, S##b2, 2, kt_); G_LD1(S##a3, S##b3, 3, kt_); } while (0)
; #define G_STORE(S, buf_) do { G_ST1(S##a0, S##b0, 0, buf_); G_ST1(S##a1, S##b1, 1, buf_); G_ST1(S##a2, S##b2, 2, buf_); G_ST1(S##a3, S##b3, 3, buf_); } while (0)
; template <class AL, class BL>
; DI void gemm_core(AL al, BL bl, int m0, int n0, int K, char* smem, f32x16 (&acc)[2][2]) {
;     ...
;   G_LOAD(x, 0);
;   G_STORE(x, 0);
;   G_LOAD(x, 1);
;   G_LOAD(y, (nk > 2) ? 2 : 1);
;   __syncthreads();
;   for (int kt = 0; kt < nk; kt += 2) {
;     G_TILE(0, x, true, (kt + 3 < nk), kt + 3);
;     __syncthreads();
;     G_TILE(1, y, (kt + 2 < nk), (kt + 4 < nk), kt + 4);
;     __syncthreads();
;   }
; DI void ffn_down_phase(const u16* hid, const u16* wdownT, u16* Y, u16* parts, char* smem) {
;   gemm_phase_n1024(4096,
;                    [=](int m, int k) { return hid + (long)m * 4096 + k; },
;                    [=](int n, int k) { return wdownT + (long)n * 4096 + k; }, Y, parts, smem);
	ds_read_b128 v[128:131], v241 offset:0
	ds_read_b128 v[132:135], v241 offset:2560
	ds_read_b128 v[136:139], v241 offset:5120
	ds_read_b128 v[140:143], v241 offset:7680
	ds_read_b128 v[144:147], v240 offset:0
	ds_read_b128 v[148:151], v240 offset:2560
	ds_read_b128 v[152:155], v240 offset:32
	ds_read_b128 v[248:251], v240 offset:2592
	s_waitcnt lgkmcnt(2)
	v_mfma_f32_32x32x16_bf16 v[0:15], v[144:147], v[128:131], v[0:15]
	v_mfma_f32_32x32x16_bf16 v[64:79], v[148:151], v[128:131], v[64:79]
	ds_read_b128 v[128:131], v241 offset:32
	s_waitcnt vmcnt(6)
	ds_write_b128 v242, v[214:217] offset:30720
	ds_write_b128 v242, v[218:221] offset:35840
	v_mfma_f32_32x32x16_bf16 v[16:31], v[144:147], v[132:135], v[16:31]
	v_mfma_f32_32x32x16_bf16 v[80:95], v[148:151], v[132:135], v[80:95]
	ds_read_b128 v[132:135], v241 offset:2592
	ds_write_b128 v242, v[222:225] offset:40960
	ds_write_b128 v242, v[228:231] offset:46080
	v_mfma_f32_32x32x16_bf16 v[32:47], v[144:147], v[136:139], v[32:47]
	v_mfma_f32_32x32x16_bf16 v[96:111], v[148:151], v[136:139], v[96:111]
	ds_read_b128 v[136:139], v241 offset:5152
	ds_write_b128 v242, v[232:235] offset:51200
	ds_write_b128 v242, v[236:239] offset:56320
	v_mfma_f32_32x32x16_bf16 v[48:63], v[144:147], v[140:143], v[48:63]
	v_mfma_f32_32x32x16_bf16 v[112:127], v[148:151], v[140:143], v[112:127]
	ds_read_b128 v[140:143], v241 offset:7712
	s_waitcnt lgkmcnt(9)
	v_mfma_f32_32x32x16_bf16 v[0:15], v[152:155], v[128:131], v[0:15]
	global_load_dwordx4 v[214:217], v[182:183], off offset:1216
	global_load_dwordx4 v[218:221], v[184:185], off offset:1216
	v_mfma_f32_32x32x16_bf16 v[64:79], v[248:251], v[128:131], v[64:79]
	s_waitcnt lgkmcnt(6)
	v_mfma_f32_32x32x16_bf16 v[16:31], v[152:155], v[132:135], v[16:31]
	global_load_dwordx4 v[222:225], v[186:187], off offset:1216
	global_load_dwordx4 v[228:231], v[188:189], off offset:1216
	v_mfma_f32_32x32x16_bf16 v[80:95], v[248:251], v[132:135], v[80:95]
	s_waitcnt lgkmcnt(3)
	v_mfma_f32_32x32x16_bf16 v[32:47], v[152:155], v[136:139], v[32:47]
	global_load_dwordx4 v[232:235], v[190:191], off offset:1216
	global_load_dwordx4 v[236:239], v[192:193], off offset:1216
	v_mfma_f32_32x32x16_bf16 v[96:111], v[248:251], v[136:139], v[96:111]
	s_waitcnt lgkmcnt(0)
	v_mfma_f32_32x32x16_bf16 v[48:63], v[152:155], v[140:143], v[48:63]
	v_mfma_f32_32x32x16_bf16 v[112:127], v[248:251], v[140:143], v[112:127]
	s_waitcnt lgkmcnt(0)
	s_barrier
	ds_read_b128 v[128:131], v241 offset:30720
	ds_read_b128 v[132:135], v241 offset:33280
	ds_read_b128 v[136:139], v241 offset:35840
	ds_read_b128 v[140:143], v241 offset:38400
	ds_read_b128 v[144:147], v240 offset:30720
	ds_read_b128 v[148:151], v240 offset:33280
	ds_read_b128 v[152:155], v240 offset:30752
	ds_read_b128 v[248:251], v240 offset:33312
	s_waitcnt lgkmcnt(2)
	v_mfma_f32_32x32x16_bf16 v[0:15], v[144:147], v[128:131], v[0:15]
	v_mfma_f32_32x32x16_bf16 v[64:79], v[148:151], v[128:131], v[64:79]
	ds_read_b128 v[128:131], v241 offset:30752
	s_waitcnt vmcnt(6)
	ds_write_b128 v242, v[158:161] offset:0
	ds_write_b128 v242, v[162:165] offset:5120
	v_mfma_f32_32x32x16_bf16 v[16:31], v[144:147], v[132:135], v[16:31]
	v_mfma_f32_32x32x16_bf16 v[80:95], v[148:151], v[132:135], v[80:95]
	ds_read_b128 v[132:135], v241 offset:33312
	ds_write_b128 v242, v[166:169] offset:10240
	ds_write_b128 v242, v[170:173] offset:15360
	v_mfma_f32_32x32x16_bf16 v[32:47], v[144:147], v[136:139], v[32:47]
	v_mfma_f32_32x32x16_bf16 v[96:111], v[148:151], v[136:139], v[96:111]
	ds_read_b128 v[136:139], v241 offset:35872
	ds_write_b128 v242, v[174:177] offset:20480
	ds_write_b128 v242, v[178:181] offset:25600
	v_mfma_f32_32x32x16_bf16 v[48:63], v[144:147], v[140:143], v[48:63]
	v_mfma_f32_32x32x16_bf16 v[112:127], v[148:151], v[140:143], v[112:127]
	ds_read_b128 v[140:143], v241 offset:38432
	s_waitcnt lgkmcnt(9)
	v_mfma_f32_32x32x16_bf16 v[0:15], v[152:155], v[128:131], v[0:15]
	global_load_dwordx4 v[158:161], v[182:183], off offset:1280
	global_load_dwordx4 v[162:165], v[184:185], off offset:1280
	v_mfma_f32_32x32x16_bf16 v[64:79], v[248:251], v[128:131], v[64:79]
	s_waitcnt lgkmcnt(6)
	v_mfma_f32_32x32x16_bf16 v[16:31], v[152:155], v[132:135], v[16:31]
	global_load_dwordx4 v[166:169], v[186:187], off offset:1280
	global_load_dwordx4 v[170:173], v[188:189], off offset:1280
	v_mfma_f32_32x32x16_bf16 v[80:95], v[248:251], v[132:135], v[80:95]
	s_waitcnt lgkmcnt(3)
	v_mfma_f32_32x32x16_bf16 v[32:47], v[152:155], v[136:139], v[32:47]
	global_load_dwordx4 v[174:177], v[190:191], off offset:1280
	global_load_dwordx4 v[178:181], v[192:193], off offset:1280
	v_mfma_f32_32x32x16_bf16 v[96:111], v[248:251], v[136:139], v[96:111]
	s_waitcnt lgkmcnt(0)
	v_mfma_f32_32x32x16_bf16 v[48:63], v[152:155], v[140:143], v[48:63]
	v_mfma_f32_32x32x16_bf16 v[112:127], v[248:251], v[140:143], v[112:127]
	s_waitcnt lgkmcnt(0)
	s_barrier
; #define G_LOAD(S, kt_) do { G_LD1(S##a0, S##b0, 0, kt_); G_LD1(S##a1, S##b1, 1, kt_); G_LD1(S##a2, S##b2, 2, kt_); G_LD1(S##a3, S##b3, 3, kt_); } while (0)
; #define G_STORE(S, buf_) do { G_ST1(S##a0, S##b0, 0, buf_); G_ST1(S##a1, S##b1, 1, buf_); G_ST1(S##a2, S##b2, 2, buf_); G_ST1(S##a3, S##b3, 3, buf_); } while (0)
; template <class AL, class BL>
; DI void gemm_core(AL al, BL bl, int m0, int n0, int K, char* smem, f32x16 (&acc)[2][2]) {
;     ...
;   G_LOAD(x, 0);
;   G_STORE(x, 0);
;   G_LOAD(x, 1);
;   G_LOAD(y, (nk > 2) ? 2 : 1);
;   __syncthreads();
;   for (int kt = 0; kt < nk; kt += 2) {
;     G_TILE(0, x, true, (kt + 3 < nk), kt + 3);
;     __syncthreads();
;     G_TILE(1, y, (kt + 2 < nk), (kt + 4 < nk), kt + 4);
;     __syncthreads();
;   }
	ds_read_b128 v[128:131], v241 offset:0
	ds_read_b128 v[132:135], v241 offset:2560
	ds_read_b128 v[136:139], v241 offset:5120
	ds_read_b128 v[140:143], v241 offset:7680
	ds_read_b128 v[144:147], v240 offset:0
	ds_read_b128 v[148:151], v240 offset:2560
	ds_read_b128 v[152:155], v240 offset:32
	ds_read_b128 v[248:251], v240 offset:2592
	s_waitcnt lgkmcnt(2)
	v_mfma_f32_32x32x16_bf16 v[0:15], v[144:147], v[128:131], v[0:15]
	v_mfma_f32_32x32x16_bf16 v[64:79], v[148:151], v[128:131], v[64:79]
	ds_read_b128 v[128:131], v241 offset:32
	s_waitcnt vmcnt(6)
	ds_write_b128 v242, v[214:217] offset:30720
	ds_write_b128 v242, v[218:221] offset:35840
	v_mfma_f32_32x32x16_bf16 v[16:31], v[144:147], v[132:135], v[16:31]
	v_mfma_f32_32x32x16_bf16 v[80:95], v[148:151], v[132:135], v[80:95]
	ds_read_b128 v[132:135], v241 offset:2592
	ds_write_b128 v242, v[222:225] offset:40960
	ds_write_b128 v242, v[228:231] offset:46080
	v_mfma_f32_32x32x16_bf16 v[32:47], v[144:147], v[136:139], v[32:47]
	v_mfma_f32_32x32x16_bf16 v[96:111], v[148:151], v[136:139], v[96:111]
	ds_read_b128 v[136:139], v241 offset:5152
	ds_write_b128 v242, v[232:235] offset:51200
	ds_write_b128 v242, v[236:239] offset:56320
	v_mfma_f32_32x32x16_bf16 v[48:63], v[144:147], v[140:143], v[48:63]
	v_mfma_f32_32x32x16_bf16 v[112:127], v[148:151], v[140:143], v[112:127]
	ds_read_b128 v[140:143], v241 offset:7712
	s_waitcnt lgkmcnt(9)
	v_mfma_f32_32x32x16_bf16 v[0:15], v[152:155], v[128:131], v[0:15]
	global_load_dwordx4 v[214:217], v[182:183], off offset:1344
	global_load_dwordx4 v[218:221], v[184:185], off offset:1344
	v_mfma_f32_32x32x16_bf16 v[64:79], v[248:251], v[128:131], v[64:79]
	s_waitcnt lgkmcnt(6)
	v_mfma_f32_32x32x16_bf16 v[16:31], v[152:155], v[132:135], v[16:31]
	global_load_dwordx4 v[222:225], v[186:187], off offset:1344
	global_load_dwordx4 v[228:231], v[188:189], off offset:1344
	v_mfma_f32_32x32x16_bf16 v[80:95], v[248:251], v[132:135], v[80:95]
	s_waitcnt lgkmcnt(3)
	v_mfma_f32_32x32x16_bf16 v[32:47], v[152:155], v[136:139], v[32:47]
	global_load_dwordx4 v[232:235], v[190:191], off offset:1344
	global_load_dwordx4 v[236:239], v[192:193], off offset:1344
	v_mfma_f32_32x32x16_bf16 v[96:111], v[248:251], v[136:139], v[96:111]
	s_waitcnt lgkmcnt(0)
	v_mfma_f32_32x32x16_bf16 v[48:63], v[152:155], v[140:143], v[48:63]
	v_mfma_f32_32x32x16_bf16 v[112:127], v[248:251], v[140:143], v[112:127]
	s_waitcnt lgkmcnt(0)
	s_barrier
	ds_read_b128 v[128:131], v241 offset:30720
	ds_read_b128 v[132:135], v241 offset:33280
	ds_read_b128 v[136:139], v241 offset:35840
	ds_read_b128 v[140:143], v241 offset:38400
	ds_read_b128 v[144:147], v240 offset:30720
	ds_read_b128 v[148:151], v240 offset:33280
	ds_read_b128 v[152:155], v240 offset:30752
	ds_read_b128 v[248:251], v240 offset:33312
	s_waitcnt lgkmcnt(2)
	v_mfma_f32_32x32x16_bf16 v[0:15], v[144:147], v[128:131], v[0:15]
	v_mfma_f32_32x32x16_bf16 v[64:79], v[148:151], v[128:131], v[64:79]
	ds_read_b128 v[128:131], v241 offset:30752
	s_waitcnt vmcnt(6)
	ds_write_b128 v242, v[158:161] offset:0
	ds_write_b128 v242, v[162:165] offset:5120
	v_mfma_f32_32x32x16_bf16 v[16:31], v[144:147], v[132:135], v[16:31]
	v_mfma_f32_32x32x16_bf16 v[80:95], v[148:151], v[132:135], v[80:95]
	ds_read_b128 v[132:135], v241 offset:33312
	ds_write_b128 v242, v[166:169] offset:10240
	ds_write_b128 v242, v[170:173] offset:15360
	v_mfma_f32_32x32x16_bf16 v[32:47], v[144:147], v[136:139], v[32:47]
	v_mfma_f32_32x32x16_bf16 v[96:111], v[148:151], v[136:139], v[96:111]
	ds_read_b128 v[136:139], v241 offset:35872
	ds_write_b128 v242, v[174:177] offset:20480
	ds_write_b128 v242, v[178:181] offset:25600
	v_mfma_f32_32x32x16_bf16 v[48:63], v[144:147], v[140:143], v[48:63]
	v_mfma_f32_32x32x16_bf16 v[112:127], v[148:151], v[140:143], v[112:127]
	ds_read_b128 v[140:143], v241 offset:38432
	s_waitcnt lgkmcnt(9)
	v_mfma_f32_32x32x16_bf16 v[0:15], v[152:155], v[128:131], v[0:15]
	global_load_dwordx4 v[158:161], v[182:183], off offset:1408
	global_load_dwordx4 v[162:165], v[184:185], off offset:1408
	v_mfma_f32_32x32x16_bf16 v[64:79], v[248:251], v[128:131], v[64:79]
	s_waitcnt lgkmcnt(6)
	v_mfma_f32_32x32x16_bf16 v[16:31], v[152:155], v[132:135], v[16:31]
	global_load_dwordx4 v[166:169], v[186:187], off offset:1408
	global_load_dwordx4 v[170:173], v[188:189], off offset:1408
	v_mfma_f32_32x32x16_bf16 v[80:95], v[248:251], v[132:135], v[80:95]
	s_waitcnt lgkmcnt(3)
	v_mfma_f32_32x32x16_bf16 v[32:47], v[152:155], v[136:139], v[32:47]
	global_load_dwordx4 v[174:177], v[190:191], off offset:1408
	global_load_dwordx4 v[178:181], v[192:193], off offset:1408
	v_mfma_f32_32x32x16_bf16 v[96:111], v[248:251], v[136:139], v[96:111]
	s_waitcnt lgkmcnt(0)
	v_mfma_f32_32x32x16_bf16 v[48:63], v[152:155], v[140:143], v[48:63]
	v_mfma_f32_32x32x16_bf16 v[112:127], v[248:251], v[140:143], v[112:127]
	s_waitcnt lgkmcnt(0)
	s_barrier
; #define G_LOAD(S, kt_) do { G_LD1(S##a0, S##b0, 0, kt_); G_LD1(S##a1, S##b1, 1, kt_); G_LD1(S##a2, S##b2, 2, kt_); G_LD1(S##a3, S##b3, 3, kt_); } while (0)
; #define G_STORE(S, buf_) do { G_ST1(S##a0, S##b0, 0, buf_); G_ST1(S##a1, S##b1, 1, buf_); G_ST1(S##a2, S##b2, 2, buf_); G_ST1(S##a3, S##b3, 3, buf_); } while (0)
; template <class AL, class BL>
; DI void gemm_core(AL al, BL bl, int m0, int n0, int K, char* smem, f32x16 (&acc)[2][2]) {
;     ...
;   G_LOAD(x, 0);
;   G_STORE(x, 0);
;   G_LOAD(x, 1);
;   G_LOAD(y, (nk > 2) ? 2 : 1);
;   __syncthreads();
;   for (int kt = 0; kt < nk; kt += 2) {
;     G_TILE(0, x, true, (kt + 3 < nk), kt + 3);
;     __syncthreads();
;     G_TILE(1, y, (kt + 2 < nk), (kt + 4 < nk), kt + 4);
;     __syncthreads();
;   }
	ds_read_b128 v[128:131], v241 offset:0
	ds_read_b128 v[132:135], v241 offset:2560
	ds_read_b128 v[136:139], v241 offset:5120
	ds_read_b128 v[140:143], v241 offset:7680
	ds_read_b128 v[144:147], v240 offset:0
	ds_read_b128 v[148:151], v240 offset:2560
	ds_read_b128 v[152:155], v240 offset:32
	ds_read_b128 v[248:251], v240 offset:2592
	s_waitcnt lgkmcnt(2)
	v_mfma_f32_32x32x16_bf16 v[0:15], v[144:147], v[128:131], v[0:15]
	v_mfma_f32_32x32x16_bf16 v[64:79], v[148:151], v[128:131], v[64:79]
	ds_read_b128 v[128:131], v241 offset:32
	s_waitcnt vmcnt(6)
	ds_write_b128 v242, v[214:217] offset:30720
	ds_write_b128 v242, v[218:221] offset:35840
	v_mfma_f32_32x32x16_bf16 v[16:31], v[144:147], v[132:135], v[16:31]
	v_mfma_f32_32x32x16_bf16 v[80:95], v[148:151], v[132:135], v[80:95]
	ds_read_b128 v[132:135], v241 offset:2592
	ds_write_b128 v242, v[222:225] offset:40960
	ds_write_b128 v242, v[228:231] offset:46080
	v_mfma_f32_32x32x16_bf16 v[32:47], v[144:147], v[136:139], v[32:47]
	v_mfma_f32_32x32x16_bf16 v[96:111], v[148:151], v[136:139], v[96:111]
	ds_read_b128 v[136:139], v241 offset:5152
	ds_write_b128 v242, v[232:235] offset:51200
	ds_write_b128 v242, v[236:239] offset:56320
	v_mfma_f32_32x32x16_bf16 v[48:63], v[144:147], v[140:143], v[48:63]
	v_mfma_f32_32x32x16_bf16 v[112:127], v[148:151], v[140:143], v[112:127]
	ds_read_b128 v[140:143], v241 offset:7712
	s_waitcnt lgkmcnt(9)
	v_mfma_f32_32x32x16_bf16 v[0:15], v[152:155], v[128:131], v[0:15]
	global_load_dwordx4 v[214:217], v[182:183], off offset:1472
	global_load_dwordx4 v[218:221], v[184:185], off offset:1472
	v_mfma_f32_32x32x16_bf16 v[64:79], v[248:251], v[128:131], v[64:79]
	s_waitcnt lgkmcnt(6)
	v_mfma_f32_32x32x16_bf16 v[16:31], v[152:155], v[132:135], v[16:31]
	global_load_dwordx4 v[222:225], v[186:187], off offset:1472
	global_load_dwordx4 v[228:231], v[188:189], off offset:1472
	v_mfma_f32_32x32x16_bf16 v[80:95], v[248:251], v[132:135], v[80:95]
	s_waitcnt lgkmcnt(3)
	v_mfma_f32_32x32x16_bf16 v[32:47], v[152:155], v[136:139], v[32:47]
	global_load_dwordx4 v[232:235], v[190:191], off offset:1472
	global_load_dwordx4 v[236:239], v[192:193], off offset:1472
	v_mfma_f32_32x32x16_bf16 v[96:111], v[248:251], v[136:139], v[96:111]
	s_waitcnt lgkmcnt(0)
	v_mfma_f32_32x32x16_bf16 v[48:63], v[152:155], v[140:143], v[48:63]
	v_mfma_f32_32x32x16_bf16 v[112:127], v[248:251], v[140:143], v[112:127]
	s_waitcnt lgkmcnt(0)
	s_barrier
	ds_read_b128 v[128:131], v241 offset:30720
	ds_read_b128 v[132:135], v241 offset:33280
	ds_read_b128 v[136:139], v241 offset:35840
	ds_read_b128 v[140:143], v241 offset:38400
	ds_read_b128 v[144:147], v240 offset:30720
	ds_read_b128 v[148:151], v240 offset:33280
	ds_read_b128 v[152:155], v240 offset:30752
	ds_read_b128 v[248:251], v240 offset:33312
	s_waitcnt lgkmcnt(2)
	v_mfma_f32_32x32x16_bf16 v[0:15], v[144:147], v[128:131], v[0:15]
	v_mfma_f32_32x32x16_bf16 v[64:79], v[148:151], v[128:131], v[64:79]
	ds_read_b128 v[128:131], v241 offset:30752
	s_waitcnt vmcnt(6)
	ds_write_b128 v242, v[158:161] offset:0
	ds_write_b128 v242, v[162:165] offset:5120
	v_mfma_f32_32x32x16_bf16 v[16:31], v[144:147], v[132:135], v[16:31]
	v_mfma_f32_32x32x16_bf16 v[80:95], v[148:151], v[132:135], v[80:95]
	ds_read_b128 v[132:135], v241 offset:33312
	ds_write_b128 v242, v[166:169] offset:10240
	ds_write_b128 v242, v[170:173] offset:15360
	v_mfma_f32_32x32x16_bf16 v[32:47], v[144:147], v[136:139], v[32:47]
	v_mfma_f32_32x32x16_bf16 v[96:111], v[148:151], v[136:139], v[96:111]
	ds_read_b128 v[136:139], v241 offset:35872
	ds_write_b128 v242, v[174:177] offset:20480
	ds_write_b128 v242, v[178:181] offset:25600
	v_mfma_f32_32x32x16_bf16 v[48:63], v[144:147], v[140:143], v[48:63]
	v_mfma_f32_32x32x16_bf16 v[112:127], v[148:151], v[140:143], v[112:127]
	ds_read_b128 v[140:143], v241 offset:38432
	s_waitcnt lgkmcnt(9)
	v_mfma_f32_32x32x16_bf16 v[0:15], v[152:155], v[128:131], v[0:15]
	global_load_dwordx4 v[158:161], v[182:183], off offset:1536
	global_load_dwordx4 v[162:165], v[184:185], off offset:1536
	v_mfma_f32_32x32x16_bf16 v[64:79], v[248:251], v[128:131], v[64:79]
	s_waitcnt lgkmcnt(6)
	v_mfma_f32_32x32x16_bf16 v[16:31], v[152:155], v[132:135], v[16:31]
	global_load_dwordx4 v[166:169], v[186:187], off offset:1536
	global_load_dwordx4 v[170:173], v[188:189], off offset:1536
	v_mfma_f32_32x32x16_bf16 v[80:95], v[248:251], v[132:135], v[80:95]
	s_waitcnt lgkmcnt(3)
	v_mfma_f32_32x32x16_bf16 v[32:47], v[152:155], v[136:139], v[32:47]
	global_load_dwordx4 v[174:177], v[190:191], off offset:1536
	global_load_dwordx4 v[178:181], v[192:193], off offset:1536
	v_mfma_f32_32x32x16_bf16 v[96:111], v[248:251], v[136:139], v[96:111]
	s_waitcnt lgkmcnt(0)
	v_mfma_f32_32x32x16_bf16 v[48:63], v[152:155], v[140:143], v[48:63]
	v_mfma_f32_32x32x16_bf16 v[112:127], v[248:251], v[140:143], v[112:127]
	s_waitcnt lgkmcnt(0)
	s_barrier
; template <class AL, class BL>
; DI void gemm_core(AL al, BL bl, int m0, int n0, int K, char* smem, f32x16 (&acc)[2][2]) {
;     ...
;   for (int kt = 0; kt < nk; kt += 2) {
;     G_TILE(0, x, true, (kt + 3 < nk), kt + 3);
;     __syncthreads();
;     G_TILE(1, y, (kt + 2 < nk), (kt + 4 < nk), kt + 4);
;     __syncthreads();
;   }
	ds_read_b128 v[128:131], v241 offset:0
	ds_read_b128 v[132:135], v241 offset:2560
	ds_read_b128 v[136:139], v241 offset:5120
	ds_read_b128 v[140:143], v241 offset:7680
	ds_read_b128 v[144:147], v240 offset:0
	ds_read_b128 v[148:151], v240 offset:2560
	ds_read_b128 v[152:155], v240 offset:32
	ds_read_b128 v[248:251], v240 offset:2592
	s_waitcnt lgkmcnt(2)
	v_mfma_f32_32x32x16_bf16 v[0:15], v[144:147], v[128:131], v[0:15]
	v_mfma_f32_32x32x16_bf16 v[64:79], v[148:151], v[128:131], v[64:79]
	ds_read_b128 v[128:131], v241 offset:32
	s_waitcnt vmcnt(6)
	ds_write_b128 v242, v[214:217] offset:30720
	ds_write_b128 v242, v[218:221] offset:35840
	v_mfma_f32_32x32x16_bf16 v[16:31], v[144:147], v[132:135], v[16:31]
	v_mfma_f32_32x32x16_bf16 v[80:95], v[148:151], v[132:135], v[80:95]
	ds_read_b128 v[132:135], v241 offset:2592
	ds_write_b128 v242, v[222:225] offset:40960
	ds_write_b128 v242, v[228:231] offset:46080
	v_mfma_f32_32x32x16_bf16 v[32:47], v[144:147], v[136:139], v[32:47]
	v_mfma_f32_32x32x16_bf16 v[96:111], v[148:151], v[136:139], v[96:111]
	ds_read_b128 v[136:139], v241 offset:5152
	ds_write_b128 v242, v[232:235] offset:51200
	ds_write_b128 v242, v[236:239] offset:56320
	v_mfma_f32_32x32x16_bf16 v[48:63], v[144:147], v[140:143], v[48:63]
	v_mfma_f32_32x32x16_bf16 v[112:127], v[148:151], v[140:143], v[112:127]
	ds_read_b128 v[140:143], v241 offset:7712
	s_waitcnt lgkmcnt(9)
	v_mfma_f32_32x32x16_bf16 v[0:15], v[152:155], v[128:131], v[0:15]
	global_load_dwordx4 v[214:217], v[182:183], off offset:1600
	global_load_dwordx4 v[218:221], v[184:185], off offset:1600
	v_mfma_f32_32x32x16_bf16 v[64:79], v[248:251], v[128:131], v[64:79]
	s_waitcnt lgkmcnt(6)
	v_mfma_f32_32x32x16_bf16 v[16:31], v[152:155], v[132:135], v[16:31]
	global_load_dwordx4 v[222:225], v[186:187], off offset:1600
	global_load_dwordx4 v[228:231], v[188:189], off offset:1600
	v_mfma_f32_32x32x16_bf16 v[80:95], v[248:251], v[132:135], v[80:95]
	s_waitcnt lgkmcnt(3)
	v_mfma_f32_32x32x16_bf16 v[32:47], v[152:155], v[136:139], v[32:47]
	global_load_dwordx4 v[232:235], v[190:191], off offset:1600
	global_load_dwordx4 v[236:239], v[192:193], off offset:1600
	v_mfma_f32_32x32x16_bf16 v[96:111], v[248:251], v[136:139], v[96:111]
	s_waitcnt lgkmcnt(0)
	v_mfma_f32_32x32x16_bf16 v[48:63], v[152:155], v[140:143], v[48:63]
	v_mfma_f32_32x32x16_bf16 v[112:127], v[248:251], v[140:143], v[112:127]
	s_waitcnt lgkmcnt(0)
	s_barrier
	ds_read_b128 v[128:131], v241 offset:30720
	ds_read_b128 v[132:135], v241 offset:33280
	ds_read_b128 v[136:139], v241 offset:35840
	ds_read_b128 v[140:143], v241 offset:38400
	ds_read_b128 v[144:147], v240 offset:30720
	ds_read_b128 v[148:151], v240 offset:33280
	ds_read_b128 v[152:155], v240 offset:30752
	ds_read_b128 v[248:251], v240 offset:33312
	s_waitcnt lgkmcnt(2)
	v_mfma_f32_32x32x16_bf16 v[0:15], v[144:147], v[128:131], v[0:15]
	v_mfma_f32_32x32x16_bf16 v[64:79], v[148:151], v[128:131], v[64:79]
	ds_read_b128 v[128:131], v241 offset:30752
	s_waitcnt vmcnt(6)
	ds_write_b128 v242, v[158:161] offset:0
	ds_write_b128 v242, v[162:165] offset:5120
	v_mfma_f32_32x32x16_bf16 v[16:31], v[144:147], v[132:135], v[16:31]
	v_mfma_f32_32x32x16_bf16 v[80:95], v[148:151], v[132:135], v[80:95]
	ds_read_b128 v[132:135], v241 offset:33312
	ds_write_b128 v242, v[166:169] offset:10240
	ds_write_b128 v242, v[170:173] offset:15360
	v_mfma_f32_32x32x16_bf16 v[32:47], v[144:147], v[136:139], v[32:47]
	v_mfma_f32_32x32x16_bf16 v[96:111], v[148:151], v[136:139], v[96:111]
	ds_read_b128 v[136:139], v241 offset:35872
	ds_write_b128 v242, v[174:177] offset:20480
	ds_write_b128 v242, v[178:181] offset:25600
	v_mfma_f32_32x32x16_bf16 v[48:63], v[144:147], v[140:143], v[48:63]
	v_mfma_f32_32x32x16_bf16 v[112:127], v[148:151], v[140:143], v[112:127]
	ds_read_b128 v[140:143], v241 offset:38432
	s_waitcnt lgkmcnt(9)
	v_mfma_f32_32x32x16_bf16 v[0:15], v[152:155], v[128:131], v[0:15]
	global_load_dwordx4 v[158:161], v[182:183], off offset:1664
	global_load_dwordx4 v[162:165], v[184:185], off offset:1664
	v_mfma_f32_32x32x16_bf16 v[64:79], v[248:251], v[128:131], v[64:79]
	s_waitcnt lgkmcnt(6)
	v_mfma_f32_32x32x16_bf16 v[16:31], v[152:155], v[132:135], v[16:31]
	global_load_dwordx4 v[166:169], v[186:187], off offset:1664
	global_load_dwordx4 v[170:173], v[188:189], off offset:1664
	v_mfma_f32_32x32x16_bf16 v[80:95], v[248:251], v[132:135], v[80:95]
	s_waitcnt lgkmcnt(3)
	v_mfma_f32_32x32x16_bf16 v[32:47], v[152:155], v[136:139], v[32:47]
	global_load_dwordx4 v[174:177], v[190:191], off offset:1664
	global_load_dwordx4 v[178:181], v[192:193], off offset:1664
	v_mfma_f32_32x32x16_bf16 v[96:111], v[248:251], v[136:139], v[96:111]
	s_waitcnt lgkmcnt(0)
	v_mfma_f32_32x32x16_bf16 v[48:63], v[152:155], v[140:143], v[48:63]
	v_mfma_f32_32x32x16_bf16 v[112:127], v[248:251], v[140:143], v[112:127]
	s_waitcnt lgkmcnt(0)
	s_barrier
	ds_read_b128 v[128:131], v241 offset:0
	ds_read_b128 v[132:135], v241 offset:2560
	ds_read_b128 v[136:139], v241 offset:5120
	ds_read_b128 v[140:143], v241 offset:7680
	ds_read_b128 v[144:147], v240 offset:0
	ds_read_b128 v[148:151], v240 offset:2560
	ds_read_b128 v[152:155], v240 offset:32
	ds_read_b128 v[248:251], v240 offset:2592
	s_waitcnt lgkmcnt(2)
	v_mfma_f32_32x32x16_bf16 v[0:15], v[144:147], v[128:131], v[0:15]
	v_mfma_f32_32x32x16_bf16 v[64:79], v[148:151], v[128:131], v[64:79]
	ds_read_b128 v[128:131], v241 offset:32
	s_waitcnt vmcnt(6)
	ds_write_b128 v242, v[214:217] offset:30720
	ds_write_b128 v242, v[218:221] offset:35840
	v_mfma_f32_32x32x16_bf16 v[16:31], v[144:147], v[132:135], v[16:31]
	v_mfma_f32_32x32x16_bf16 v[80:95], v[148:151], v[132:135], v[80:95]
	ds_read_b128 v[132:135], v241 offset:2592
	ds_write_b128 v242, v[222:225] offset:40960
	ds_write_b128 v242, v[228:231] offset:46080
	v_mfma_f32_32x32x16_bf16 v[32:47], v[144:147], v[136:139], v[32:47]
	v_mfma_f32_32x32x16_bf16 v[96:111], v[148:151], v[136:139], v[96:111]
	ds_read_b128 v[136:139], v241 offset:5152
	ds_write_b128 v242, v[232:235] offset:51200
	ds_write_b128 v242, v[236:239] offset:56320
	v_mfma_f32_32x32x16_bf16 v[48:63], v[144:147], v[140:143], v[48:63]
	v_mfma_f32_32x32x16_bf16 v[112:127], v[148:151], v[140:143], v[112:127]
	ds_read_b128 v[140:143], v241 offset:7712
	s_waitcnt lgkmcnt(9)
	v_mfma_f32_32x32x16_bf16 v[0:15], v[152:155], v[128:131], v[0:15]
	global_load_dwordx4 v[214:217], v[182:183], off offset:1728
	global_load_dwordx4 v[218:221], v[184:185], off offset:1728
	v_mfma_f32_32x32x16_bf16 v[64:79], v[248:251], v[128:131], v[64:79]
	s_waitcnt lgkmcnt(6)
	v_mfma_f32_32x32x16_bf16 v[16:31], v[152:155], v[132:135], v[16:31]
	global_load_dwordx4 v[222:225], v[186:187], off offset:1728
	global_load_dwordx4 v[228:231], v[188:189], off offset:1728
	v_mfma_f32_32x32x16_bf16 v[80:95], v[248:251], v[132:135], v[80:95]
	s_waitcnt lgkmcnt(3)
	v_mfma_f32_32x32x16_bf16 v[32:47], v[152:155], v[136:139], v[32:47]
	global_load_dwordx4 v[232:235], v[190:191], off offset:1728
	global_load_dwordx4 v[236:239], v[192:193], off offset:1728
	v_mfma_f32_32x32x16_bf16 v[96:111], v[248:251], v[136:139], v[96:111]
	s_waitcnt lgkmcnt(0)
	v_mfma_f32_32x32x16_bf16 v[48:63], v[152:155], v[140:143], v[48:63]
	v_mfma_f32_32x32x16_bf16 v[112:127], v[248:251], v[140:143], v[112:127]
	s_waitcnt lgkmcnt(0)
	s_barrier
	ds_read_b128 v[128:131], v241 offset:30720
	ds_read_b128 v[132:135], v241 offset:33280
	ds_read_b128 v[136:139], v241 offset:35840
	ds_read_b128 v[140:143], v241 offset:38400
	ds_read_b128 v[144:147], v240 offset:30720
	ds_read_b128 v[148:151], v240 offset:33280
	ds_read_b128 v[152:155], v240 offset:30752
	ds_read_b128 v[248:251], v240 offset:33312
	s_waitcnt lgkmcnt(2)
	v_mfma_f32_32x32x16_bf16 v[0:15], v[144:147], v[128:131], v[0:15]
	v_mfma_f32_32x32x16_bf16 v[64:79], v[148:151], v[128:131], v[64:79]
	ds_read_b128 v[128:131], v241 offset:30752
	s_waitcnt vmcnt(6)
	ds_write_b128 v242, v[158:161] offset:0
	ds_write_b128 v242, v[162:165] offset:5120
	v_mfma_f32_32x32x16_bf16 v[16:31], v[144:147], v[132:135], v[16:31]
	v_mfma_f32_32x32x16_bf16 v[80:95], v[148:151], v[132:135], v[80:95]
	ds_read_b128 v[132:135], v241 offset:33312
	ds_write_b128 v242, v[166:169] offset:10240
	ds_write_b128 v242, v[170:173] offset:15360
	v_mfma_f32_32x32x16_bf16 v[32:47], v[144:147], v[136:139], v[32:47]
	v_mfma_f32_32x32x16_bf16 v[96:111], v[148:151], v[136:139], v[96:111]
	ds_read_b128 v[136:139], v241 offset:35872
	ds_write_b128 v242, v[174:177] offset:20480
	ds_write_b128 v242, v[178:181] offset:25600
	v_mfma_f32_32x32x16_bf16 v[48:63], v[144:147], v[140:143], v[48:63]
	v_mfma_f32_32x32x16_bf16 v[112:127], v[148:151], v[140:143], v[112:127]
	ds_read_b128 v[140:143], v241 offset:38432
	s_waitcnt lgkmcnt(9)
	v_mfma_f32_32x32x16_bf16 v[0:15], v[152:155], v[128:131], v[0:15]
	global_load_dwordx4 v[158:161], v[182:183], off offset:1792
	global_load_dwordx4 v[162:165], v[184:185], off offset:1792
	v_mfma_f32_32x32x16_bf16 v[64:79], v[248:251], v[128:131], v[64:79]
	s_waitcnt lgkmcnt(6)
	v_mfma_f32_32x32x16_bf16 v[16:31], v[152:155], v[132:135], v[16:31]
	global_load_dwordx4 v[166:169], v[186:187], off offset:1792
	global_load_dwordx4 v[170:173], v[188:189], off offset:1792
	v_mfma_f32_32x32x16_bf16 v[80:95], v[248:251], v[132:135], v[80:95]
	s_waitcnt lgkmcnt(3)
	v_mfma_f32_32x32x16_bf16 v[32:47], v[152:155], v[136:139], v[32:47]
	global_load_dwordx4 v[174:177], v[190:191], off offset:1792
	global_load_dwordx4 v[178:181], v[192:193], off offset:1792
	v_mfma_f32_32x32x16_bf16 v[96:111], v[248:251], v[136:139], v[96:111]
	s_waitcnt lgkmcnt(0)
	v_mfma_f32_32x32x16_bf16 v[48:63], v[152:155], v[140:143], v[48:63]
	v_mfma_f32_32x32x16_bf16 v[112:127], v[248:251], v[140:143], v[112:127]
	s_waitcnt lgkmcnt(0)
	s_barrier
	ds_read_b128 v[128:131], v241 offset:0
	ds_read_b128 v[132:135], v241 offset:2560
	ds_read_b128 v[136:139], v241 offset:5120
	ds_read_b128 v[140:143], v241 offset:7680
	ds_read_b128 v[144:147], v240 offset:0
	ds_read_b128 v[148:151], v240 offset:2560
	ds_read_b128 v[152:155], v240 offset:32
	ds_read_b128 v[248:251], v240 offset:2592
	s_waitcnt lgkmcnt(2)
	v_mfma_f32_32x32x16_bf16 v[0:15], v[144:147], v[128:131], v[0:15]
	v_mfma_f32_32x32x16_bf16 v[64:79], v[148:151], v[128:131], v[64:79]
	ds_read_b128 v[128:131], v241 offset:32
	s_waitcnt vmcnt(6)
	ds_write_b128 v242, v[214:217] offset:30720
	ds_write_b128 v242, v[218:221] offset:35840
	v_mfma_f32_32x32x16_bf16 v[16:31], v[144:147], v[132:135], v[16:31]
	v_mfma_f32_32x32x16_bf16 v[80:95], v[148:151], v[132:135], v[80:95]
	ds_read_b128 v[132:135], v241 offset:2592
	ds_write_b128 v242, v[222:225] offset:40960
	ds_write_b128 v242, v[228:231] offset:46080
	v_mfma_f32_32x32x16_bf16 v[32:47], v[144:147], v[136:139], v[32:47]
	v_mfma_f32_32x32x16_bf16 v[96:111], v[148:151], v[136:139], v[96:111]
	ds_read_b128 v[136:139], v241 offset:5152
	ds_write_b128 v242, v[232:235] offset:51200
	ds_write_b128 v242, v[236:239] offset:56320
	v_mfma_f32_32x32x16_bf16 v[48:63], v[144:147], v[140:143], v[48:63]
	v_mfma_f32_32x32x16_bf16 v[112:127], v[148:151], v[140:143], v[112:127]
	ds_read_b128 v[140:143], v241 offset:7712
	s_waitcnt lgkmcnt(9)
	v_mfma_f32_32x32x16_bf16 v[0:15], v[152:155], v[128:131], v[0:15]
	global_load_dwordx4 v[214:217], v[182:183], off offset:1856
	global_load_dwordx4 v[218:221], v[184:185], off offset:1856
	v_mfma_f32_32x32x16_bf16 v[64:79], v[248:251], v[128:131], v[64:79]
	s_waitcnt lgkmcnt(6)
	v_mfma_f32_32x32x16_bf16 v[16:31], v[152:155], v[132:135], v[16:31]
	global_load_dwordx4 v[222:225], v[186:187], off offset:1856
	global_load_dwordx4 v[228:231], v[188:189], off offset:1856
	v_mfma_f32_32x32x16_bf16 v[80:95], v[248:251], v[132:135], v[80:95]
	s_waitcnt lgkmcnt(3)
	v_mfma_f32_32x32x16_bf16 v[32:47], v[152:155], v[136:139], v[32:47]
	global_load_dwordx4 v[232:235], v[190:191], off offset:1856
	global_load_dwordx4 v[236:239], v[192:193], off offset:1856
	v_mfma_f32_32x32x16_bf16 v[96:111], v[248:251], v[136:139], v[96:111]
	s_waitcnt lgkmcnt(0)
	v_mfma_f32_32x32x16_bf16 v[48:63], v[152:155], v[140:143], v[48:63]
	v_mfma_f32_32x32x16_bf16 v[112:127], v[248:251], v[140:143], v[112:127]
	s_waitcnt lgkmcnt(0)
	s_barrier
	ds_read_b128 v[128:131], v241 offset:30720
	ds_read_b128 v[132:135], v241 offset:33280
	ds_read_b128 v[136:139], v241 offset:35840
	ds_read_b128 v[140:143], v241 offset:38400
	ds_read_b128 v[144:147], v240 offset:30720
	ds_read_b128 v[148:151], v240 offset:33280
	ds_read_b128 v[152:155], v240 offset:30752
	ds_read_b128 v[248:251], v240 offset:33312
	s_waitcnt lgkmcnt(2)
	v_mfma_f32_32x32x16_bf16 v[0:15], v[144:147], v[128:131], v[0:15]
	v_mfma_f32_32x32x16_bf16 v[64:79], v[148:151], v[128:131], v[64:79]
	ds_read_b128 v[128:131], v241 offset:30752
	s_waitcnt vmcnt(6)
	ds_write_b128 v242, v[158:161] offset:0
	ds_write_b128 v242, v[162:165] offset:5120
	v_mfma_f32_32x32x16_bf16 v[16:31], v[144:147], v[132:135], v[16:31]
	v_mfma_f32_32x32x16_bf16 v[80:95], v[148:151], v[132:135], v[80:95]
	ds_read_b128 v[132:135], v241 offset:33312
	ds_write_b128 v242, v[166:169] offset:10240
	ds_write_b128 v242, v[170:173] offset:15360
	v_mfma_f32_32x32x16_bf16 v[32:47], v[144:147], v[136:139], v[32:47]
	v_mfma_f32_32x32x16_bf16 v[96:111], v[148:151], v[136:139], v[96:111]
	ds_read_b128 v[136:139], v241 offset:35872
	ds_write_b128 v242, v[174:177] offset:20480
	ds_write_b128 v242, v[178:181] offset:25600
	v_mfma_f32_32x32x16_bf16 v[48:63], v[144:147], v[140:143], v[48:63]
	v_mfma_f32_32x32x16_bf16 v[112:127], v[148:151], v[140:143], v[112:127]
	ds_read_b128 v[140:143], v241 offset:38432
	s_waitcnt lgkmcnt(9)
	v_mfma_f32_32x32x16_bf16 v[0:15], v[152:155], v[128:131], v[0:15]
	global_load_dwordx4 v[158:161], v[182:183], off offset:1920
	global_load_dwordx4 v[162:165], v[184:185], off offset:1920
	v_mfma_f32_32x32x16_bf16 v[64:79], v[248:251], v[128:131], v[64:79]
	s_waitcnt lgkmcnt(6)
	v_mfma_f32_32x32x16_bf16 v[16:31], v[152:155], v[132:135], v[16:31]
	global_load_dwordx4 v[166:169], v[186:187], off offset:1920
	global_load_dwordx4 v[170:173], v[188:189], off offset:1920
	v_mfma_f32_32x32x16_bf16 v[80:95], v[248:251], v[132:135], v[80:95]
	s_waitcnt lgkmcnt(3)
	v_mfma_f32_32x32x16_bf16 v[32:47], v[152:155], v[136:139], v[32:47]
	global_load_dwordx4 v[174:177], v[190:191], off offset:1920
	global_load_dwordx4 v[178:181], v[192:193], off offset:1920
	v_mfma_f32_32x32x16_bf16 v[96:111], v[248:251], v[136:139], v[96:111]
	s_waitcnt lgkmcnt(0)
	v_mfma_f32_32x32x16_bf16 v[48:63], v[152:155], v[140:143], v[48:63]
	v_mfma_f32_32x32x16_bf16 v[112:127], v[248:251], v[140:143], v[112:127]
	s_waitcnt lgkmcnt(0)
	s_barrier
; #define G_LOAD(S, kt_) do { G_LD1(S##a0, S##b0, 0, kt_); G_LD1(S##a1, S##b1, 1, kt_); G_LD1(S##a2, S##b2, 2, kt_); G_LD1(S##a3, S##b3, 3, kt_); } while (0)
; #define G_STORE(S, buf_) do { G_ST1(S##a0, S##b0, 0, buf_); G_ST1(S##a1, S##b1, 1, buf_); G_ST1(S##a2, S##b2, 2, buf_); G_ST1(S##a3, S##b3, 3, buf_); } while (0)
; template <class AL, class BL>
; DI void gemm_core(AL al, BL bl, int m0, int n0, int K, char* smem, f32x16 (&acc)[2][2]) {
;     ...
;   G_LOAD(x, 0);
;   G_STORE(x, 0);
;   G_LOAD(x, 1);
;   G_LOAD(y, (nk > 2) ? 2 : 1);
;   __syncthreads();
;   for (int kt = 0; kt < nk; kt += 2) {
;     G_TILE(0, x, true, (kt + 3 < nk), kt + 3);
;     __syncthreads();
;     G_TILE(1, y, (kt + 2 < nk), (kt + 4 < nk), kt + 4);
;     __syncthreads();
;   }
	ds_read_b128 v[128:131], v241 offset:0
	ds_read_b128 v[132:135], v241 offset:2560
	ds_read_b128 v[136:139], v241 offset:5120
	ds_read_b128 v[140:143], v241 offset:7680
	ds_read_b128 v[144:147], v240 offset:0
	ds_read_b128 v[148:151], v240 offset:2560
	ds_read_b128 v[152:155], v240 offset:32
	ds_read_b128 v[248:251], v240 offset:2592
	s_waitcnt lgkmcnt(2)
	v_mfma_f32_32x32x16_bf16 v[0:15], v[144:147], v[128:131], v[0:15]
	v_mfma_f32_32x32x16_bf16 v[64:79], v[148:151], v[128:131], v[64:79]
	ds_read_b128 v[128:131], v241 offset:32
	s_waitcnt vmcnt(6)
	ds_write_b128 v242, v[214:217] offset:30720
	ds_write_b128 v242, v[218:221] offset:35840
	v_mfma_f32_32x32x16_bf16 v[16:31], v[144:147], v[132:135], v[16:31]
	v_mfma_f32_32x32x16_bf16 v[80:95], v[148:151], v[132:135], v[80:95]
	ds_read_b128 v[132:135], v241 offset:2592
	ds_write_b128 v242, v[222:225] offset:40960
	ds_write_b128 v242, v[228:231] offset:46080
	v_mfma_f32_32x32x16_bf16 v[32:47], v[144:147], v[136:139], v[32:47]
	v_mfma_f32_32x32x16_bf16 v[96:111], v[148:151], v[136:139], v[96:111]
	ds_read_b128 v[136:139], v241 offset:5152
	ds_write_b128 v242, v[232:235] offset:51200
	ds_write_b128 v242, v[236:239] offset:56320
	v_mfma_f32_32x32x16_bf16 v[48:63], v[144:147], v[140:143], v[48:63]
	v_mfma_f32_32x32x16_bf16 v[112:127], v[148:151], v[140:143], v[112:127]
	ds_read_b128 v[140:143], v241 offset:7712
	s_waitcnt lgkmcnt(9)
	v_mfma_f32_32x32x16_bf16 v[0:15], v[152:155], v[128:131], v[0:15]
	global_load_dwordx4 v[214:217], v[182:183], off offset:1984
	global_load_dwordx4 v[218:221], v[184:185], off offset:1984
	v_mfma_f32_32x32x16_bf16 v[64:79], v[248:251], v[128:131], v[64:79]
	s_waitcnt lgkmcnt(6)
	v_mfma_f32_32x32x16_bf16 v[16:31], v[152:155], v[132:135], v[16:31]
	global_load_dwordx4 v[222:225], v[186:187], off offset:1984
	global_load_dwordx4 v[228:231], v[188:189], off offset:1984
	v_mfma_f32_32x32x16_bf16 v[80:95], v[248:251], v[132:135], v[80:95]
	s_waitcnt lgkmcnt(3)
	v_mfma_f32_32x32x16_bf16 v[32:47], v[152:155], v[136:139], v[32:47]
	global_load_dwordx4 v[232:235], v[190:191], off offset:1984
	global_load_dwordx4 v[236:239], v[192:193], off offset:1984
	v_mfma_f32_32x32x16_bf16 v[96:111], v[248:251], v[136:139], v[96:111]
	s_waitcnt lgkmcnt(0)
	v_mfma_f32_32x32x16_bf16 v[48:63], v[152:155], v[140:143], v[48:63]
	v_mfma_f32_32x32x16_bf16 v[112:127], v[248:251], v[140:143], v[112:127]
	s_waitcnt lgkmcnt(0)
	s_barrier
	ds_read_b128 v[128:131], v241 offset:30720
	ds_read_b128 v[132:135], v241 offset:33280
	ds_read_b128 v[136:139], v241 offset:35840
	ds_read_b128 v[140:143], v241 offset:38400
	ds_read_b128 v[144:147], v240 offset:30720
	ds_read_b128 v[148:151], v240 offset:33280
	ds_read_b128 v[152:155], v240 offset:30752
	ds_read_b128 v[248:251], v240 offset:33312
	s_waitcnt lgkmcnt(2)
	v_mfma_f32_32x32x16_bf16 v[0:15], v[144:147], v[128:131], v[0:15]
	v_mfma_f32_32x32x16_bf16 v[64:79], v[148:151], v[128:131], v[64:79]
	ds_read_b128 v[128:131], v241 offset:30752
	s_waitcnt vmcnt(6)
	ds_write_b128 v242, v[158:161] offset:0
	ds_write_b128 v242, v[162:165] offset:5120
	v_mfma_f32_32x32x16_bf16 v[16:31], v[144:147], v[132:135], v[16:31]
	v_mfma_f32_32x32x16_bf16 v[80:95], v[148:151], v[132:135], v[80:95]
	ds_read_b128 v[132:135], v241 offset:33312
	ds_write_b128 v242, v[166:169] offset:10240
	ds_write_b128 v242, v[170:173] offset:15360
	v_mfma_f32_32x32x16_bf16 v[32:47], v[144:147], v[136:139], v[32:47]
	v_mfma_f32_32x32x16_bf16 v[96:111], v[148:151], v[136:139], v[96:111]
	ds_read_b128 v[136:139], v241 offset:35872
	ds_write_b128 v242, v[174:177] offset:20480
	ds_write_b128 v242, v[178:181] offset:25600
	v_mfma_f32_32x32x16_bf16 v[48:63], v[144:147], v[140:143], v[48:63]
	v_mfma_f32_32x32x16_bf16 v[112:127], v[148:151], v[140:143], v[112:127]
	ds_read_b128 v[140:143], v241 offset:38432
	s_waitcnt lgkmcnt(9)
	v_mfma_f32_32x32x16_bf16 v[0:15], v[152:155], v[128:131], v[0:15]
	global_load_dwordx4 v[158:161], v[182:183], off offset:2048
	global_load_dwordx4 v[162:165], v[184:185], off offset:2048
	v_mfma_f32_32x32x16_bf16 v[64:79], v[248:251], v[128:131], v[64:79]
	s_waitcnt lgkmcnt(6)
	v_mfma_f32_32x32x16_bf16 v[16:31], v[152:155], v[132:135], v[16:31]
	global_load_dwordx4 v[166:169], v[186:187], off offset:2048
	global_load_dwordx4 v[170:173], v[188:189], off offset:2048
	v_mfma_f32_32x32x16_bf16 v[80:95], v[248:251], v[132:135], v[80:95]
	s_waitcnt lgkmcnt(3)
	v_mfma_f32_32x32x16_bf16 v[32:47], v[152:155], v[136:139], v[32:47]
	global_load_dwordx4 v[174:177], v[190:191], off offset:2048
	global_load_dwordx4 v[178:181], v[192:193], off offset:2048
	v_mfma_f32_32x32x16_bf16 v[96:111], v[248:251], v[136:139], v[96:111]
	s_waitcnt lgkmcnt(0)
	v_mfma_f32_32x32x16_bf16 v[48:63], v[152:155], v[140:143], v[48:63]
	v_mfma_f32_32x32x16_bf16 v[112:127], v[248:251], v[140:143], v[112:127]
	s_waitcnt lgkmcnt(0)
	s_barrier
; template <class AL, class BL>
; DI void gemm_core(AL al, BL bl, int m0, int n0, int K, char* smem, f32x16 (&acc)[2][2]) {
;     ...
;   for (int kt = 0; kt < nk; kt += 2) {
;     G_TILE(0, x, true, (kt + 3 < nk), kt + 3);
;     __syncthreads();
;     G_TILE(1, y, (kt + 2 < nk), (kt + 4 < nk), kt + 4);
;     __syncthreads();
;   }
	ds_read_b128 v[128:131], v241 offset:0
	ds_read_b128 v[132:135], v241 offset:2560
	ds_read_b128 v[136:139], v241 offset:5120
	ds_read_b128 v[140:143], v241 offset:7680
	ds_read_b128 v[144:147], v240 offset:0
	ds_read_b128 v[148:151], v240 offset:2560
	ds_read_b128 v[152:155], v240 offset:32
	ds_read_b128 v[248:251], v240 offset:2592
	s_waitcnt lgkmcnt(2)
	v_mfma_f32_32x32x16_bf16 v[0:15], v[144:147], v[128:131], v[0:15]
	v_mfma_f32_32x32x16_bf16 v[64:79], v[148:151], v[128:131], v[64:79]
	ds_read_b128 v[128:131], v241 offset:32
	s_waitcnt vmcnt(6)
	ds_write_b128 v242, v[214:217] offset:30720
	ds_write_b128 v242, v[218:221] offset:35840
	v_mfma_f32_32x32x16_bf16 v[16:31], v[144:147], v[132:135], v[16:31]
	v_mfma_f32_32x32x16_bf16 v[80:95], v[148:151], v[132:135], v[80:95]
	ds_read_b128 v[132:135], v241 offset:2592
	ds_write_b128 v242, v[222:225] offset:40960
	ds_write_b128 v242, v[228:231] offset:46080
	v_mfma_f32_32x32x16_bf16 v[32:47], v[144:147], v[136:139], v[32:47]
	v_mfma_f32_32x32x16_bf16 v[96:111], v[148:151], v[136:139], v[96:111]
	ds_read_b128 v[136:139], v241 offset:5152
	ds_write_b128 v242, v[232:235] offset:51200
	ds_write_b128 v242, v[236:239] offset:56320
	v_mfma_f32_32x32x16_bf16 v[48:63], v[144:147], v[140:143], v[48:63]
	v_mfma_f32_32x32x16_bf16 v[112:127], v[148:151], v[140:143], v[112:127]
	ds_read_b128 v[140:143], v241 offset:7712
	s_waitcnt lgkmcnt(9)
	v_mfma_f32_32x32x16_bf16 v[0:15], v[152:155], v[128:131], v[0:15]
	global_load_dwordx4 v[214:217], v[182:183], off offset:2112
	global_load_dwordx4 v[218:221], v[184:185], off offset:2112
	v_mfma_f32_32x32x16_bf16 v[64:79], v[248:251], v[128:131], v[64:79]
	s_waitcnt lgkmcnt(6)
	v_mfma_f32_32x32x16_bf16 v[16:31], v[152:155], v[132:135], v[16:31]
	global_load_dwordx4 v[222:225], v[186:187], off offset:2112
	global_load_dwordx4 v[228:231], v[188:189], off offset:2112
	v_mfma_f32_32x32x16_bf16 v[80:95], v[248:251], v[132:135], v[80:95]
	s_waitcnt lgkmcnt(3)
	v_mfma_f32_32x32x16_bf16 v[32:47], v[152:155], v[136:139], v[32:47]
	global_load_dwordx4 v[232:235], v[190:191], off offset:2112
	global_load_dwordx4 v[236:239], v[192:193], off offset:2112
	v_mfma_f32_32x32x16_bf16 v[96:111], v[248:251], v[136:139], v[96:111]
	s_waitcnt lgkmcnt(0)
	v_mfma_f32_32x32x16_bf16 v[48:63], v[152:155], v[140:143], v[48:63]
	v_mfma_f32_32x32x16_bf16 v[112:127], v[248:251], v[140:143], v[112:127]
	s_waitcnt lgkmcnt(0)
	s_barrier
	ds_read_b128 v[128:131], v241 offset:30720
	ds_read_b128 v[132:135], v241 offset:33280
	ds_read_b128 v[136:139], v241 offset:35840
	ds_read_b128 v[140:143], v241 offset:38400
	ds_read_b128 v[144:147], v240 offset:30720
	ds_read_b128 v[148:151], v240 offset:33280
	ds_read_b128 v[152:155], v240 offset:30752
	ds_read_b128 v[248:251], v240 offset:33312
	s_waitcnt lgkmcnt(2)
	v_mfma_f32_32x32x16_bf16 v[0:15], v[144:147], v[128:131], v[0:15]
	v_mfma_f32_32x32x16_bf16 v[64:79], v[148:151], v[128:131], v[64:79]
	ds_read_b128 v[128:131], v241 offset:30752
	s_waitcnt vmcnt(6)
	ds_write_b128 v242, v[158:161] offset:0
	ds_write_b128 v242, v[162:165] offset:5120
	v_mfma_f32_32x32x16_bf16 v[16:31], v[144:147], v[132:135], v[16:31]
	v_mfma_f32_32x32x16_bf16 v[80:95], v[148:151], v[132:135], v[80:95]
	ds_read_b128 v[132:135], v241 offset:33312
	ds_write_b128 v242, v[166:169] offset:10240
	ds_write_b128 v242, v[170:173] offset:15360
	v_mfma_f32_32x32x16_bf16 v[32:47], v[144:147], v[136:139], v[32:47]
	v_mfma_f32_32x32x16_bf16 v[96:111], v[148:151], v[136:139], v[96:111]
	ds_read_b128 v[136:139], v241 offset:35872
	ds_write_b128 v242, v[174:177] offset:20480
	ds_write_b128 v242, v[178:181] offset:25600
	v_mfma_f32_32x32x16_bf16 v[48:63], v[144:147], v[140:143], v[48:63]
	v_mfma_f32_32x32x16_bf16 v[112:127], v[148:151], v[140:143], v[112:127]
	ds_read_b128 v[140:143], v241 offset:38432
	s_waitcnt lgkmcnt(9)
	v_mfma_f32_32x32x16_bf16 v[0:15], v[152:155], v[128:131], v[0:15]
	global_load_dwordx4 v[158:161], v[182:183], off offset:2176
	global_load_dwordx4 v[162:165], v[184:185], off offset:2176
	v_mfma_f32_32x32x16_bf16 v[64:79], v[248:251], v[128:131], v[64:79]
	s_waitcnt lgkmcnt(6)
	v_mfma_f32_32x32x16_bf16 v[16:31], v[152:155], v[132:135], v[16:31]
	global_load_dwordx4 v[166:169], v[186:187], off offset:2176
	global_load_dwordx4 v[170:173], v[188:189], off offset:2176
	v_mfma_f32_32x32x16_bf16 v[80:95], v[248:251], v[132:135], v[80:95]
	s_waitcnt lgkmcnt(3)
	v_mfma_f32_32x32x16_bf16 v[32:47], v[152:155], v[136:139], v[32:47]
	global_load_dwordx4 v[174:177], v[190:191], off offset:2176
	global_load_dwordx4 v[178:181], v[192:193], off offset:2176
	v_mfma_f32_32x32x16_bf16 v[96:111], v[248:251], v[136:139], v[96:111]
	s_waitcnt lgkmcnt(0)
	v_mfma_f32_32x32x16_bf16 v[48:63], v[152:155], v[140:143], v[48:63]
	v_mfma_f32_32x32x16_bf16 v[112:127], v[248:251], v[140:143], v[112:127]
	s_waitcnt lgkmcnt(0)
	s_barrier
	s_mov_b32 s41, 2
; #define G_LOAD(S, kt_) do { G_LD1(S##a0, S##b0, 0, kt_); G_LD1(S##a1, S##b1, 1, kt_); G_LD1(S##a2, S##b2, 2, kt_); G_LD1(S##a3, S##b3, 3, kt_); } while (0)
; #define G_STORE(S, buf_) do { G_ST1(S##a0, S##b0, 0, buf_); G_ST1(S##a1, S##b1, 1, buf_); G_ST1(S##a2, S##b2, 2, buf_); G_ST1(S##a3, S##b3, 3, buf_); } while (0)
; template <class AL, class BL>
; DI void gemm_core(AL al, BL bl, int m0, int n0, int K, char* smem, f32x16 (&acc)[2][2]) {
;     ...
;   G_LOAD(x, 0);
;   G_STORE(x, 0);
;   G_LOAD(x, 1);
;   G_LOAD(y, (nk > 2) ? 2 : 1);
;   __syncthreads();
;   for (int kt = 0; kt < nk; kt += 2) {
;     G_TILE(0, x, true, (kt + 3 < nk), kt + 3);
;     __syncthreads();
;     G_TILE(1, y, (kt + 2 < nk), (kt + 4 < nk), kt + 4);
;     __syncthreads();
;   }
.Lfd0_kloop:
	v_lshl_add_u64 v[182:183], v[182:183], 0, s[2:3]
	v_lshl_add_u64 v[184:185], v[184:185], 0, s[2:3]
	v_lshl_add_u64 v[186:187], v[186:187], 0, s[2:3]
	v_lshl_add_u64 v[188:189], v[188:189], 0, s[2:3]
	v_lshl_add_u64 v[190:191], v[190:191], 0, s[2:3]
	v_lshl_add_u64 v[192:193], v[192:193], 0, s[2:3]
	ds_read_b128 v[128:131], v241 offset:0
	ds_read_b128 v[132:135], v241 offset:2560
	ds_read_b128 v[136:139], v241 offset:5120
	ds_read_b128 v[140:143], v241 offset:7680
	ds_read_b128 v[144:147], v240 offset:0
	ds_read_b128 v[148:151], v240 offset:2560
	ds_read_b128 v[152:155], v240 offset:32
	ds_read_b128 v[248:251], v240 offset:2592
	s_waitcnt lgkmcnt(2)
	v_mfma_f32_32x32x16_bf16 v[0:15], v[144:147], v[128:131], v[0:15]
	v_mfma_f32_32x32x16_bf16 v[64:79], v[148:151], v[128:131], v[64:79]
	ds_read_b128 v[128:131], v241 offset:32
	s_waitcnt vmcnt(6)
	ds_write_b128 v242, v[214:217] offset:30720
	ds_write_b128 v242, v[218:221] offset:35840
	v_mfma_f32_32x32x16_bf16 v[16:31], v[144:147], v[132:135], v[16:31]
	v_mfma_f32_32x32x16_bf16 v[80:95], v[148:151], v[132:135], v[80:95]
	ds_read_b128 v[132:135], v241 offset:2592
	ds_write_b128 v242, v[222:225] offset:40960
	ds_write_b128 v242, v[228:231] offset:46080
	v_mfma_f32_32x32x16_bf16 v[32:47], v[144:147], v[136:139], v[32:47]
	v_mfma_f32_32x32x16_bf16 v[96:111], v[148:151], v[136:139], v[96:111]
	ds_read_b128 v[136:139], v241 offset:5152
	ds_write_b128 v242, v[232:235] offset:51200
	ds_write_b128 v242, v[236:239] offset:56320
	v_mfma_f32_32x32x16_bf16 v[48:63], v[144:147], v[140:143], v[48:63]
	v_mfma_f32_32x32x16_bf16 v[112:127], v[148:151], v[140:143], v[112:127]
	ds_read_b128 v[140:143], v241 offset:7712
	s_waitcnt lgkmcnt(9)
	v_mfma_f32_32x32x16_bf16 v[0:15], v[152:155], v[128:131], v[0:15]
	global_load_dwordx4 v[214:217], v[182:183], off offset:192
	global_load_dwordx4 v[218:221], v[184:185], off offset:192
	v_mfma_f32_32x32x16_bf16 v[64:79], v[248:251], v[128:131], v[64:79]
	s_waitcnt lgkmcnt(6)
	v_mfma_f32_32x32x16_bf16 v[16:31], v[152:155], v[132:135], v[16:31]
	global_load_dwordx4 v[222:225], v[186:187], off offset:192
	global_load_dwordx4 v[228:231], v[188:189], off offset:192
	v_mfma_f32_32x32x16_bf16 v[80:95], v[248:251], v[132:135], v[80:95]
	s_waitcnt lgkmcnt(3)
	v_mfma_f32_32x32x16_bf16 v[32:47], v[152:155], v[136:139], v[32:47]
	global_load_dwordx4 v[232:235], v[190:191], off offset:192
	global_load_dwordx4 v[236:239], v[192:193], off offset:192
	v_mfma_f32_32x32x16_bf16 v[96:111], v[248:251], v[136:139], v[96:111]
	s_waitcnt lgkmcnt(0)
	v_mfma_f32_32x32x16_bf16 v[48:63], v[152:155], v[140:143], v[48:63]
	v_mfma_f32_32x32x16_bf16 v[112:127], v[248:251], v[140:143], v[112:127]
	s_waitcnt lgkmcnt(0)
	s_barrier
	ds_read_b128 v[128:131], v241 offset:30720
	ds_read_b128 v[132:135], v241 offset:33280
	ds_read_b128 v[136:139], v241 offset:35840
	ds_read_b128 v[140:143], v241 offset:38400
	ds_read_b128 v[144:147], v240 offset:30720
	ds_read_b128 v[148:151], v240 offset:33280
	ds_read_b128 v[152:155], v240 offset:30752
	ds_read_b128 v[248:251], v240 offset:33312
	s_waitcnt lgkmcnt(2)
	v_mfma_f32_32x32x16_bf16 v[0:15], v[144:147], v[128:131], v[0:15]
	v_mfma_f32_32x32x16_bf16 v[64:79], v[148:151], v[128:131], v[64:79]
	ds_read_b128 v[128:131], v241 offset:30752
	s_waitcnt vmcnt(6)
	ds_write_b128 v242, v[158:161] offset:0
	ds_write_b128 v242, v[162:165] offset:5120
	v_mfma_f32_32x32x16_bf16 v[16:31], v[144:147], v[132:135], v[16:31]
	v_mfma_f32_32x32x16_bf16 v[80:95], v[148:151], v[132:135], v[80:95]
	ds_read_b128 v[132:135], v241 offset:33312
	ds_write_b128 v242, v[166:169] offset:10240
	ds_write_b128 v242, v[170:173] offset:15360
	v_mfma_f32_32x32x16_bf16 v[32:47], v[144:147], v[136:139], v[32:47]
	v_mfma_f32_32x32x16_bf16 v[96:111], v[148:151], v[136:139], v[96:111]
	ds_read_b128 v[136:139], v241 offset:35872
	ds_write_b128 v242, v[174:177] offset:20480
	ds_write_b128 v242, v[178:181] offset:25600
	v_mfma_f32_32x32x16_bf16 v[48:63], v[144:147], v[140:143], v[48:63]
	v_mfma_f32_32x32x16_bf16 v[112:127], v[148:151], v[140:143], v[112:127]
	ds_read_b128 v[140:143], v241 offset:38432
	s_waitcnt lgkmcnt(9)
	v_mfma_f32_32x32x16_bf16 v[0:15], v[152:155], v[128:131], v[0:15]
	global_load_dwordx4 v[158:161], v[182:183], off offset:256
	global_load_dwordx4 v[162:165], v[184:185], off offset:256
	v_mfma_f32_32x32x16_bf16 v[64:79], v[248:251], v[128:131], v[64:79]
	s_waitcnt lgkmcnt(6)
	v_mfma_f32_32x32x16_bf16 v[16:31], v[152:155], v[132:135], v[16:31]
	global_load_dwordx4 v[166:169], v[186:187], off offset:256
	global_load_dwordx4 v[170:173], v[188:189], off offset:256
	v_mfma_f32_32x32x16_bf16 v[80:95], v[248:251], v[132:135], v[80:95]
	s_waitcnt lgkmcnt(3)
	v_mfma_f32_32x32x16_bf16 v[32:47], v[152:155], v[136:139], v[32:47]
	global_load_dwordx4 v[174:177], v[190:191], off offset:256
	global_load_dwordx4 v[178:181], v[192:193], off offset:256
	v_mfma_f32_32x32x16_bf16 v[96:111], v[248:251], v[136:139], v[96:111]
	s_waitcnt lgkmcnt(0)
	v_mfma_f32_32x32x16_bf16 v[48:63], v[152:155], v[140:143], v[48:63]
	v_mfma_f32_32x32x16_bf16 v[112:127], v[248:251], v[140:143], v[112:127]
	s_waitcnt lgkmcnt(0)
	s_barrier
; #define G_LOAD(S, kt_) do { G_LD1(S##a0, S##b0, 0, kt_); G_LD1(S##a1, S##b1, 1, kt_); G_LD1(S##a2, S##b2, 2, kt_); G_LD1(S##a3, S##b3, 3, kt_); } while (0)
; #define G_STORE(S, buf_) do { G_ST1(S##a0, S##b0, 0, buf_); G_ST1(S##a1, S##b1, 1, buf_); G_ST1(S##a2, S##b2, 2, buf_); G_ST1(S##a3, S##b3, 3, buf_); } while (0)
; template <class AL, class BL>
; DI void gemm_core(AL al, BL bl, int m0, int n0, int K, char* smem, f32x16 (&acc)[2][2]) {
;     ...
;   G_LOAD(x, 0);
;   G_STORE(x, 0);
;   G_LOAD(x, 1);
;   G_LOAD(y, (nk > 2) ? 2 : 1);
;   __syncthreads();
;   for (int kt = 0; kt < nk; kt += 2) {
;     G_TILE(0, x, true, (kt + 3 < nk), kt + 3);
;     __syncthreads();
;     G_TILE(1, y, (kt + 2 < nk), (kt + 4 < nk), kt + 4);
;     __syncthreads();
;   }
	ds_read_b128 v[128:131], v241 offset:0
	ds_read_b128 v[132:135], v241 offset:2560
	ds_read_b128 v[136:139], v241 offset:5120
	ds_read_b128 v[140:143], v241 offset:7680
	ds_read_b128 v[144:147], v240 offset:0
	ds_read_b128 v[148:151], v240 offset:2560
	ds_read_b128 v[152:155], v240 offset:32
	ds_read_b128 v[248:251], v240 offset:2592
	s_waitcnt lgkmcnt(2)
	v_mfma_f32_32x32x16_bf16 v[0:15], v[144:147], v[128:131], v[0:15]
	v_mfma_f32_32x32x16_bf16 v[64:79], v[148:151], v[128:131], v[64:79]
	ds_read_b128 v[128:131], v241 offset:32
	s_waitcnt vmcnt(6)
	ds_write_b128 v242, v[214:217] offset:30720
	ds_write_b128 v242, v[218:221] offset:35840
	v_mfma_f32_32x32x16_bf16 v[16:31], v[144:147], v[132:135], v[16:31]
	v_mfma_f32_32x32x16_bf16 v[80:95], v[148:151], v[132:135], v[80:95]
	ds_read_b128 v[132:135], v241 offset:2592
	ds_write_b128 v242, v[222:225] offset:40960
	ds_write_b128 v242, v[228:231] offset:46080
	v_mfma_f32_32x32x16_bf16 v[32:47], v[144:147], v[136:139], v[32:47]
	v_mfma_f32_32x32x16_bf16 v[96:111], v[148:151], v[136:139], v[96:111]
	ds_read_b128 v[136:139], v241 offset:5152
	ds_write_b128 v242, v[232:235] offset:51200
	ds_write_b128 v242, v[236:239] offset:56320
	v_mfma_f32_32x32x16_bf16 v[48:63], v[144:147], v[140:143], v[48:63]
	v_mfma_f32_32x32x16_bf16 v[112:127], v[148:151], v[140:143], v[112:127]
	ds_read_b128 v[140:143], v241 offset:7712
	s_waitcnt lgkmcnt(9)
	v_mfma_f32_32x32x16_bf16 v[0:15], v[152:155], v[128:131], v[0:15]
	global_load_dwordx4 v[214:217], v[182:183], off offset:320
	global_load_dwordx4 v[218:221], v[184:185], off offset:320
	v_mfma_f32_32x32x16_bf16 v[64:79], v[248:251], v[128:131], v[64:79]
	s_waitcnt lgkmcnt(6)
	v_mfma_f32_32x32x16_bf16 v[16:31], v[152:155], v[132:135], v[16:31]
	global_load_dwordx4 v[222:225], v[186:187], off offset:320
	global_load_dwordx4 v[228:231], v[188:189], off offset:320
	v_mfma_f32_32x32x16_bf16 v[80:95], v[248:251], v[132:135], v[80:95]
	s_waitcnt lgkmcnt(3)
	v_mfma_f32_32x32x16_bf16 v[32:47], v[152:155], v[136:139], v[32:47]
	global_load_dwordx4 v[232:235], v[190:191], off offset:320
	global_load_dwordx4 v[236:239], v[192:193], off offset:320
	v_mfma_f32_32x32x16_bf16 v[96:111], v[248:251], v[136:139], v[96:111]
	s_waitcnt lgkmcnt(0)
	v_mfma_f32_32x32x16_bf16 v[48:63], v[152:155], v[140:143], v[48:63]
	v_mfma_f32_32x32x16_bf16 v[112:127], v[248:251], v[140:143], v[112:127]
	s_waitcnt lgkmcnt(0)
	s_barrier
	ds_read_b128 v[128:131], v241 offset:30720
	ds_read_b128 v[132:135], v241 offset:33280
	ds_read_b128 v[136:139], v241 offset:35840
	ds_read_b128 v[140:143], v241 offset:38400
	ds_read_b128 v[144:147], v240 offset:30720
	ds_read_b128 v[148:151], v240 offset:33280
	ds_read_b128 v[152:155], v240 offset:30752
	ds_read_b128 v[248:251], v240 offset:33312
	s_waitcnt lgkmcnt(2)
	v_mfma_f32_32x32x16_bf16 v[0:15], v[144:147], v[128:131], v[0:15]
	v_mfma_f32_32x32x16_bf16 v[64:79], v[148:151], v[128:131], v[64:79]
	ds_read_b128 v[128:131], v241 offset:30752
	s_waitcnt vmcnt(6)
	ds_write_b128 v242, v[158:161] offset:0
	ds_write_b128 v242, v[162:165] offset:5120
	v_mfma_f32_32x32x16_bf16 v[16:31], v[144:147], v[132:135], v[16:31]
	v_mfma_f32_32x32x16_bf16 v[80:95], v[148:151], v[132:135], v[80:95]
	ds_read_b128 v[132:135], v241 offset:33312
	ds_write_b128 v242, v[166:169] offset:10240
	ds_write_b128 v242, v[170:173] offset:15360
	v_mfma_f32_32x32x16_bf16 v[32:47], v[144:147], v[136:139], v[32:47]
	v_mfma_f32_32x32x16_bf16 v[96:111], v[148:151], v[136:139], v[96:111]
	ds_read_b128 v[136:139], v241 offset:35872
	ds_write_b128 v242, v[174:177] offset:20480
	ds_write_b128 v242, v[178:181] offset:25600
	v_mfma_f32_32x32x16_bf16 v[48:63], v[144:147], v[140:143], v[48:63]
	v_mfma_f32_32x32x16_bf16 v[112:127], v[148:151], v[140:143], v[112:127]
	ds_read_b128 v[140:143], v241 offset:38432
	s_waitcnt lgkmcnt(9)
	v_mfma_f32_32x32x16_bf16 v[0:15], v[152:155], v[128:131], v[0:15]
	global_load_dwordx4 v[158:161], v[182:183], off offset:384
	global_load_dwordx4 v[162:165], v[184:185], off offset:384
	v_mfma_f32_32x32x16_bf16 v[64:79], v[248:251], v[128:131], v[64:79]
	s_waitcnt lgkmcnt(6)
	v_mfma_f32_32x32x16_bf16 v[16:31], v[152:155], v[132:135], v[16:31]
	global_load_dwordx4 v[166:169], v[186:187], off offset:384
	global_load_dwordx4 v[170:173], v[188:189], off offset:384
	v_mfma_f32_32x32x16_bf16 v[80:95], v[248:251], v[132:135], v[80:95]
	s_waitcnt lgkmcnt(3)
	v_mfma_f32_32x32x16_bf16 v[32:47], v[152:155], v[136:139], v[32:47]
	global_load_dwordx4 v[174:177], v[190:191], off offset:384
	global_load_dwordx4 v[178:181], v[192:193], off offset:384
	v_mfma_f32_32x32x16_bf16 v[96:111], v[248:251], v[136:139], v[96:111]
	s_waitcnt lgkmcnt(0)
	v_mfma_f32_32x32x16_bf16 v[48:63], v[152:155], v[140:143], v[48:63]
	v_mfma_f32_32x32x16_bf16 v[112:127], v[248:251], v[140:143], v[112:127]
	s_waitcnt lgkmcnt(0)
	s_barrier
; #define G_LOAD(S, kt_) do { G_LD1(S##a0, S##b0, 0, kt_); G_LD1(S##a1, S##b1, 1, kt_); G_LD1(S##a2, S##b2, 2, kt_); G_LD1(S##a3, S##b3, 3, kt_); } while (0)
; #define G_STORE(S, buf_) do { G_ST1(S##a0, S##b0, 0, buf_); G_ST1(S##a1, S##b1, 1, buf_); G_ST1(S##a2, S##b2, 2, buf_); G_ST1(S##a3, S##b3, 3, buf_); } while (0)
; template <class AL, class BL>
; DI void gemm_core(AL al, BL bl, int m0, int n0, int K, char* smem, f32x16 (&acc)[2][2]) {
;     ...
;   G_LOAD(x, 0);
;   G_STORE(x, 0);
;   G_LOAD(x, 1);
;   G_LOAD(y, (nk > 2) ? 2 : 1);
;   __syncthreads();
;   for (int kt = 0; kt < nk; kt += 2) {
;     G_TILE(0, x, true, (kt + 3 < nk), kt + 3);
;     __syncthreads();
;     G_TILE(1, y, (kt + 2 < nk), (kt + 4 < nk), kt + 4);
;     __syncthreads();
;   }
	ds_read_b128 v[128:131], v241 offset:0
	ds_read_b128 v[132:135], v241 offset:2560
	ds_read_b128 v[136:139], v241 offset:5120
	ds_read_b128 v[140:143], v241 offset:7680
	ds_read_b128 v[144:147], v240 offset:0
	ds_read_b128 v[148:151], v240 offset:2560
	ds_read_b128 v[152:155], v240 offset:32
	ds_read_b128 v[248:251], v240 offset:2592
	s_waitcnt lgkmcnt(2)
	v_mfma_f32_32x32x16_bf16 v[0:15], v[144:147], v[128:131], v[0:15]
	v_mfma_f32_32x32x16_bf16 v[64:79], v[148:151], v[128:131], v[64:79]
	ds_read_b128 v[128:131], v241 offset:32
	s_waitcnt vmcnt(6)
	ds_write_b128 v242, v[214:217] offset:30720
	ds_write_b128 v242, v[218:221] offset:35840
	v_mfma_f32_32x32x16_bf16 v[16:31], v[144:147], v[132:135], v[16:31]
	v_mfma_f32_32x32x16_bf16 v[80:95], v[148:151], v[132:135], v[80:95]
	ds_read_b128 v[132:135], v241 offset:2592
	ds_write_b128 v242, v[222:225] offset:40960
	ds_write_b128 v242, v[228:231] offset:46080
	v_mfma_f32_32x32x16_bf16 v[32:47], v[144:147], v[136:139], v[32:47]
	v_mfma_f32_32x32x16_bf16 v[96:111], v[148:151], v[136:139], v[96:111]
	ds_read_b128 v[136:139], v241 offset:5152
	ds_write_b128 v242, v[232:235] offset:51200
	ds_write_b128 v242, v[236:239] offset:56320
	v_mfma_f32_32x32x16_bf16 v[48:63], v[144:147], v[140:143], v[48:63]
	v_mfma_f32_32x32x16_bf16 v[112:127], v[148:151], v[140:143], v[112:127]
	ds_read_b128 v[140:143], v241 offset:7712
	s_waitcnt lgkmcnt(9)
	v_mfma_f32_32x32x16_bf16 v[0:15], v[152:155], v[128:131], v[0:15]
	global_load_dwordx4 v[214:217], v[182:183], off offset:448
	global_load_dwordx4 v[218:221], v[184:185], off offset:448
	v_mfma_f32_32x32x16_bf16 v[64:79], v[248:251], v[128:131], v[64:79]
	s_waitcnt lgkmcnt(6)
	v_mfma_f32_32x32x16_bf16 v[16:31], v[152:155], v[132:135], v[16:31]
	global_load_dwordx4 v[222:225], v[186:187], off offset:448
	global_load_dwordx4 v[228:231], v[188:189], off offset:448
	v_mfma_f32_32x32x16_bf16 v[80:95], v[248:251], v[132:135], v[80:95]
	s_waitcnt lgkmcnt(3)
	v_mfma_f32_32x32x16_bf16 v[32:47], v[152:155], v[136:139], v[32:47]
	global_load_dwordx4 v[232:235], v[190:191], off offset:448
	global_load_dwordx4 v[236:239], v[192:193], off offset:448
	v_mfma_f32_32x32x16_bf16 v[96:111], v[248:251], v[136:139], v[96:111]
	s_waitcnt lgkmcnt(0)
	v_mfma_f32_32x32x16_bf16 v[48:63], v[152:155], v[140:143], v[48:63]
	v_mfma_f32_32x32x16_bf16 v[112:127], v[248:251], v[140:143], v[112:127]
	s_waitcnt lgkmcnt(0)
	s_barrier
	ds_read_b128 v[128:131], v241 offset:30720
	ds_read_b128 v[132:135], v241 offset:33280
	ds_read_b128 v[136:139], v241 offset:35840
	ds_read_b128 v[140:143], v241 offset:38400
	ds_read_b128 v[144:147], v240 offset:30720
	ds_read_b128 v[148:151], v240 offset:33280
	ds_read_b128 v[152:155], v240 offset:30752
	ds_read_b128 v[248:251], v240 offset:33312
	s_waitcnt lgkmcnt(2)
	v_mfma_f32_32x32x16_bf16 v[0:15], v[144:147], v[128:131], v[0:15]
	v_mfma_f32_32x32x16_bf16 v[64:79], v[148:151], v[128:131], v[64:79]
	ds_read_b128 v[128:131], v241 offset:30752
	s_waitcnt vmcnt(6)
	ds_write_b128 v242, v[158:161] offset:0
	ds_write_b128 v242, v[162:165] offset:5120
	v_mfma_f32_32x32x16_bf16 v[16:31], v[144:147], v[132:135], v[16:31]
	v_mfma_f32_32x32x16_bf16 v[80:95], v[148:151], v[132:135], v[80:95]
	ds_read_b128 v[132:135], v241 offset:33312
	ds_write_b128 v242, v[166:169] offset:10240
	ds_write_b128 v242, v[170:173] offset:15360
	v_mfma_f32_32x32x16_bf16 v[32:47], v[144:147], v[136:139], v[32:47]
	v_mfma_f32_32x32x16_bf16 v[96:111], v[148:151], v[136:139], v[96:111]
	ds_read_b128 v[136:139], v241 offset:35872
	ds_write_b128 v242, v[174:177] offset:20480
	ds_write_b128 v242, v[178:181] offset:25600
	v_mfma_f32_32x32x16_bf16 v[48:63], v[144:147], v[140:143], v[48:63]
	v_mfma_f32_32x32x16_bf16 v[112:127], v[148:151], v[140:143], v[112:127]
	ds_read_b128 v[140:143], v241 offset:38432
	s_waitcnt lgkmcnt(9)
	v_mfma_f32_32x32x16_bf16 v[0:15], v[152:155], v[128:131], v[0:15]
	global_load_dwordx4 v[158:161], v[182:183], off offset:512
	global_load_dwordx4 v[162:165], v[184:185], off offset:512
	v_mfma_f32_32x32x16_bf16 v[64:79], v[248:251], v[128:131], v[64:79]
	s_waitcnt lgkmcnt(6)
	v_mfma_f32_32x32x16_bf16 v[16:31], v[152:155], v[132:135], v[16:31]
	global_load_dwordx4 v[166:169], v[186:187], off offset:512
	global_load_dwordx4 v[170:173], v[188:189], off offset:512
	v_mfma_f32_32x32x16_bf16 v[80:95], v[248:251], v[132:135], v[80:95]
	s_waitcnt lgkmcnt(3)
	v_mfma_f32_32x32x16_bf16 v[32:47], v[152:155], v[136:139], v[32:47]
	global_load_dwordx4 v[174:177], v[190:191], off offset:512
	global_load_dwordx4 v[178:181], v[192:193], off offset:512
	v_mfma_f32_32x32x16_bf16 v[96:111], v[248:251], v[136:139], v[96:111]
	s_waitcnt lgkmcnt(0)
	v_mfma_f32_32x32x16_bf16 v[48:63], v[152:155], v[140:143], v[48:63]
	v_mfma_f32_32x32x16_bf16 v[112:127], v[248:251], v[140:143], v[112:127]
	s_waitcnt lgkmcnt(0)
	s_barrier
; #define G_LOAD(S, kt_) do { G_LD1(S##a0, S##b0, 0, kt_); G_LD1(S##a1, S##b1, 1, kt_); G_LD1(S##a2, S##b2, 2, kt_); G_LD1(S##a3, S##b3, 3, kt_); } while (0)
; #define G_STORE(S, buf_) do { G_ST1(S##a0, S##b0, 0, buf_); G_ST1(S##a1, S##b1, 1, buf_); G_ST1(S##a2, S##b2, 2, buf_); G_ST1(S##a3, S##b3, 3, buf_); } while (0)
; template <class AL, class BL>
; DI void gemm_core(AL al, BL bl, int m0, int n0, int K, char* smem, f32x16 (&acc)[2][2]) {
;     ...
;   G_LOAD(x, 0);
;   G_STORE(x, 0);
;   G_LOAD(x, 1);
;   G_LOAD(y, (nk > 2) ? 2 : 1);
;   __syncthreads();
;   for (int kt = 0; kt < nk; kt += 2) {
;     G_TILE(0, x, true, (kt + 3 < nk), kt + 3);
;     __syncthreads();
;     G_TILE(1, y, (kt + 2 < nk), (kt + 4 < nk), kt + 4);
;     __syncthreads();
;   }
	ds_read_b128 v[128:131], v241 offset:0
	ds_read_b128 v[132:135], v241 offset:2560
	ds_read_b128 v[136:139], v241 offset:5120
	ds_read_b128 v[140:143], v241 offset:7680
	ds_read_b128 v[144:147], v240 offset:0
	ds_read_b128 v[148:151], v240 offset:2560
	ds_read_b128 v[152:155], v240 offset:32
	ds_read_b128 v[248:251], v240 offset:2592
	s_waitcnt lgkmcnt(2)
	v_mfma_f32_32x32x16_bf16 v[0:15], v[144:147], v[128:131], v[0:15]
	v_mfma_f32_32x32x16_bf16 v[64:79], v[148:151], v[128:131], v[64:79]
	ds_read_b128 v[128:131], v241 offset:32
	s_waitcnt vmcnt(6)
	ds_write_b128 v242, v[214:217] offset:30720
	ds_write_b128 v242, v[218:221] offset:35840
	v_mfma_f32_32x32x16_bf16 v[16:31], v[144:147], v[132:135], v[16:31]
	v_mfma_f32_32x32x16_bf16 v[80:95], v[148:151], v[132:135], v[80:95]
	ds_read_b128 v[132:135], v241 offset:2592
	ds_write_b128 v242, v[222:225] offset:40960
	ds_write_b128 v242, v[228:231] offset:46080
	v_mfma_f32_32x32x16_bf16 v[32:47], v[144:147], v[136:139], v[32:47]
	v_mfma_f32_32x32x16_bf16 v[96:111], v[148:151], v[136:139], v[96:111]
	ds_read_b128 v[136:139], v241 offset:5152
	ds_write_b128 v242, v[232:235] offset:51200
	ds_write_b128 v242, v[236:239] offset:56320
	v_mfma_f32_32x32x16_bf16 v[48:63], v[144:147], v[140:143], v[48:63]
	v_mfma_f32_32x32x16_bf16 v[112:127], v[148:151], v[140:143], v[112:127]
	ds_read_b128 v[140:143], v241 offset:7712
	s_waitcnt lgkmcnt(9)
	v_mfma_f32_32x32x16_bf16 v[0:15], v[152:155], v[128:131], v[0:15]
	global_load_dwordx4 v[214:217], v[182:183], off offset:576
	global_load_dwordx4 v[218:221], v[184:185], off offset:576
	v_mfma_f32_32x32x16_bf16 v[64:79], v[248:251], v[128:131], v[64:79]
	s_waitcnt lgkmcnt(6)
	v_mfma_f32_32x32x16_bf16 v[16:31], v[152:155], v[132:135], v[16:31]
	global_load_dwordx4 v[222:225], v[186:187], off offset:576
	global_load_dwordx4 v[228:231], v[188:189], off offset:576
	v_mfma_f32_32x32x16_bf16 v[80:95], v[248:251], v[132:135], v[80:95]
	s_waitcnt lgkmcnt(3)
	v_mfma_f32_32x32x16_bf16 v[32:47], v[152:155], v[136:139], v[32:47]
	global_load_dwordx4 v[232:235], v[190:191], off offset:576
	global_load_dwordx4 v[236:239], v[192:193], off offset:576
	v_mfma_f32_32x32x16_bf16 v[96:111], v[248:251], v[136:139], v[96:111]
	s_waitcnt lgkmcnt(0)
	v_mfma_f32_32x32x16_bf16 v[48:63], v[152:155], v[140:143], v[48:63]
	v_mfma_f32_32x32x16_bf16 v[112:127], v[248:251], v[140:143], v[112:127]
	s_waitcnt lgkmcnt(0)
	s_barrier
	ds_read_b128 v[128:131], v241 offset:30720
	ds_read_b128 v[132:135], v241 offset:33280
	ds_read_b128 v[136:139], v241 offset:35840
	ds_read_b128 v[140:143], v241 offset:38400
	ds_read_b128 v[144:147], v240 offset:30720
	ds_read_b128 v[148:151], v240 offset:33280
	ds_read_b128 v[152:155], v240 offset:30752
	ds_read_b128 v[248:251], v240 offset:33312
	s_waitcnt lgkmcnt(2)
	v_mfma_f32_32x32x16_bf16 v[0:15], v[144:147], v[128:131], v[0:15]
	v_mfma_f32_32x32x16_bf16 v[64:79], v[148:151], v[128:131], v[64:79]
	ds_read_b128 v[128:131], v241 offset:30752
	s_waitcnt vmcnt(6)
	ds_write_b128 v242, v[158:161] offset:0
	ds_write_b128 v242, v[162:165] offset:5120
	v_mfma_f32_32x32x16_bf16 v[16:31], v[144:147], v[132:135], v[16:31]
	v_mfma_f32_32x32x16_bf16 v[80:95], v[148:151], v[132:135], v[80:95]
	ds_read_b128 v[132:135], v241 offset:33312
	ds_write_b128 v242, v[166:169] offset:10240
	ds_write_b128 v242, v[170:173] offset:15360
	v_mfma_f32_32x32x16_bf16 v[32:47], v[144:147], v[136:139], v[32:47]
	v_mfma_f32_32x32x16_bf16 v[96:111], v[148:151], v[136:139], v[96:111]
	ds_read_b128 v[136:139], v241 offset:35872
	ds_write_b128 v242, v[174:177] offset:20480
	ds_write_b128 v242, v[178:181] offset:25600
	v_mfma_f32_32x32x16_bf16 v[48:63], v[144:147], v[140:143], v[48:63]
	v_mfma_f32_32x32x16_bf16 v[112:127], v[148:151], v[140:143], v[112:127]
	ds_read_b128 v[140:143], v241 offset:38432
	s_waitcnt lgkmcnt(9)
	v_mfma_f32_32x32x16_bf16 v[0:15], v[152:155], v[128:131], v[0:15]
	global_load_dwordx4 v[158:161], v[182:183], off offset:640
	global_load_dwordx4 v[162:165], v[184:185], off offset:640
	v_mfma_f32_32x32x16_bf16 v[64:79], v[248:251], v[128:131], v[64:79]
	s_waitcnt lgkmcnt(6)
	v_mfma_f32_32x32x16_bf16 v[16:31], v[152:155], v[132:135], v[16:31]
	global_load_dwordx4 v[166:169], v[186:187], off offset:640
	global_load_dwordx4 v[170:173], v[188:189], off offset:640
	v_mfma_f32_32x32x16_bf16 v[80:95], v[248:251], v[132:135], v[80:95]
	s_waitcnt lgkmcnt(3)
	v_mfma_f32_32x32x16_bf16 v[32:47], v[152:155], v[136:139], v[32:47]
	global_load_dwordx4 v[174:177], v[190:191], off offset:640
	global_load_dwordx4 v[178:181], v[192:193], off offset:640
	v_mfma_f32_32x32x16_bf16 v[96:111], v[248:251], v[136:139], v[96:111]
	s_waitcnt lgkmcnt(0)
	v_mfma_f32_32x32x16_bf16 v[48:63], v[152:155], v[140:143], v[48:63]
	v_mfma_f32_32x32x16_bf16 v[112:127], v[248:251], v[140:143], v[112:127]
	s_waitcnt lgkmcnt(0)
	s_barrier
; #define G_LOAD(S, kt_) do { G_LD1(S##a0, S##b0, 0, kt_); G_LD1(S##a1, S##b1, 1, kt_); G_LD1(S##a2, S##b2, 2, kt_); G_LD1(S##a3, S##b3, 3, kt_); } while (0)
; #define G_STORE(S, buf_) do { G_ST1(S##a0, S##b0, 0, buf_); G_ST1(S##a1, S##b1, 1, buf_); G_ST1(S##a2, S##b2, 2, buf_); G_ST1(S##a3, S##b3, 3, buf_); } while (0)
; template <class AL, class BL>
; DI void gemm_core(AL al, BL bl, int m0, int n0, int K, char* smem, f32x16 (&acc)[2][2]) {
;     ...
;   G_LOAD(x, 0);
;   G_STORE(x, 0);
;   G_LOAD(x, 1);
;   G_LOAD(y, (nk > 2) ? 2 : 1);
;   __syncthreads();
;   for (int kt = 0; kt < nk; kt += 2) {
;     G_TILE(0, x, true, (kt + 3 < nk), kt + 3);
;     __syncthreads();
;     G_TILE(1, y, (kt + 2 < nk), (kt + 4 < nk), kt + 4);
;     __syncthreads();
;   }
	ds_read_b128 v[128:131], v241 offset:0
	ds_read_b128 v[132:135], v241 offset:2560
	ds_read_b128 v[136:139], v241 offset:5120
	ds_read_b128 v[140:143], v241 offset:7680
	ds_read_b128 v[144:147], v240 offset:0
	ds_read_b128 v[148:151], v240 offset:2560
	ds_read_b128 v[152:155], v240 offset:32
	ds_read_b128 v[248:251], v240 offset:2592
	s_waitcnt lgkmcnt(2)
	v_mfma_f32_32x32x16_bf16 v[0:15], v[144:147], v[128:131], v[0:15]
	v_mfma_f32_32x32x16_bf16 v[64:79], v[148:151], v[128:131], v[64:79]
	ds_read_b128 v[128:131], v241 offset:32
	s_waitcnt vmcnt(6)
	ds_write_b128 v242, v[214:217] offset:30720
	ds_write_b128 v242, v[218:221] offset:35840
	v_mfma_f32_32x32x16_bf16 v[16:31], v[144:147], v[132:135], v[16:31]
	v_mfma_f32_32x32x16_bf16 v[80:95], v[148:151], v[132:135], v[80:95]
	ds_read_b128 v[132:135], v241 offset:2592
	ds_write_b128 v242, v[222:225] offset:40960
	ds_write_b128 v242, v[228:231] offset:46080
	v_mfma_f32_32x32x16_bf16 v[32:47], v[144:147], v[136:139], v[32:47]
	v_mfma_f32_32x32x16_bf16 v[96:111], v[148:151], v[136:139], v[96:111]
	ds_read_b128 v[136:139], v241 offset:5152
	ds_write_b128 v242, v[232:235] offset:51200
	ds_write_b128 v242, v[236:239] offset:56320
	v_mfma_f32_32x32x16_bf16 v[48:63], v[144:147], v[140:143], v[48:63]
	v_mfma_f32_32x32x16_bf16 v[112:127], v[148:151], v[140:143], v[112:127]
	ds_read_b128 v[140:143], v241 offset:7712
	s_waitcnt lgkmcnt(9)
	v_mfma_f32_32x32x16_bf16 v[0:15], v[152:155], v[128:131], v[0:15]
	global_load_dwordx4 v[214:217], v[182:183], off offset:704
	global_load_dwordx4 v[218:221], v[184:185], off offset:704
	v_mfma_f32_32x32x16_bf16 v[64:79], v[248:251], v[128:131], v[64:79]
	s_waitcnt lgkmcnt(6)
	v_mfma_f32_32x32x16_bf16 v[16:31], v[152:155], v[132:135], v[16:31]
	global_load_dwordx4 v[222:225], v[186:187], off offset:704
	global_load_dwordx4 v[228:231], v[188:189], off offset:704
	v_mfma_f32_32x32x16_bf16 v[80:95], v[248:251], v[132:135], v[80:95]
	s_waitcnt lgkmcnt(3)
	v_mfma_f32_32x32x16_bf16 v[32:47], v[152:155], v[136:139], v[32:47]
	global_load_dwordx4 v[232:235], v[190:191], off offset:704
	global_load_dwordx4 v[236:239], v[192:193], off offset:704
	v_mfma_f32_32x32x16_bf16 v[96:111], v[248:251], v[136:139], v[96:111]
	s_waitcnt lgkmcnt(0)
	v_mfma_f32_32x32x16_bf16 v[48:63], v[152:155], v[140:143], v[48:63]
	v_mfma_f32_32x32x16_bf16 v[112:127], v[248:251], v[140:143], v[112:127]
	s_waitcnt lgkmcnt(0)
	s_barrier
	ds_read_b128 v[128:131], v241 offset:30720
	ds_read_b128 v[132:135], v241 offset:33280
	ds_read_b128 v[136:139], v241 offset:35840
	ds_read_b128 v[140:143], v241 offset:38400
	ds_read_b128 v[144:147], v240 offset:30720
	ds_read_b128 v[148:151], v240 offset:33280
	ds_read_b128 v[152:155], v240 offset:30752
	ds_read_b128 v[248:251], v240 offset:33312
	s_waitcnt lgkmcnt(2)
	v_mfma_f32_32x32x16_bf16 v[0:15], v[144:147], v[128:131], v[0:15]
	v_mfma_f32_32x32x16_bf16 v[64:79], v[148:151], v[128:131], v[64:79]
	ds_read_b128 v[128:131], v241 offset:30752
	s_waitcnt vmcnt(6)
	ds_write_b128 v242, v[158:161] offset:0
	ds_write_b128 v242, v[162:165] offset:5120
	v_mfma_f32_32x32x16_bf16 v[16:31], v[144:147], v[132:135], v[16:31]
	v_mfma_f32_32x32x16_bf16 v[80:95], v[148:151], v[132:135], v[80:95]
	ds_read_b128 v[132:135], v241 offset:33312
	ds_write_b128 v242, v[166:169] offset:10240
	ds_write_b128 v242, v[170:173] offset:15360
	v_mfma_f32_32x32x16_bf16 v[32:47], v[144:147], v[136:139], v[32:47]
	v_mfma_f32_32x32x16_bf16 v[96:111], v[148:151], v[136:139], v[96:111]
	ds_read_b128 v[136:139], v241 offset:35872
	ds_write_b128 v242, v[174:177] offset:20480
	ds_write_b128 v242, v[178:181] offset:25600
	v_mfma_f32_32x32x16_bf16 v[48:63], v[144:147], v[140:143], v[48:63]
	v_mfma_f32_32x32x16_bf16 v[112:127], v[148:151], v[140:143], v[112:127]
	ds_read_b128 v[140:143], v241 offset:38432
	s_waitcnt lgkmcnt(9)
	v_mfma_f32_32x32x16_bf16 v[0:15], v[152:155], v[128:131], v[0:15]
	global_load_dwordx4 v[158:161], v[182:183], off offset:768
	global_load_dwordx4 v[162:165], v[184:185], off offset:768
	v_mfma_f32_32x32x16_bf16 v[64:79], v[248:251], v[128:131], v[64:79]
	s_waitcnt lgkmcnt(6)
	v_mfma_f32_32x32x16_bf16 v[16:31], v[152:155], v[132:135], v[16:31]
	global_load_dwordx4 v[166:169], v[186:187], off offset:768
	global_load_dwordx4 v[170:173], v[188:189], off offset:768
	v_mfma_f32_32x32x16_bf16 v[80:95], v[248:251], v[132:135], v[80:95]
	s_waitcnt lgkmcnt(3)
	v_mfma_f32_32x32x16_bf16 v[32:47], v[152:155], v[136:139], v[32:47]
	global_load_dwordx4 v[174:177], v[190:191], off offset:768
	global_load_dwordx4 v[178:181], v[192:193], off offset:768
	v_mfma_f32_32x32x16_bf16 v[96:111], v[248:251], v[136:139], v[96:111]
	s_waitcnt lgkmcnt(0)
	v_mfma_f32_32x32x16_bf16 v[48:63], v[152:155], v[140:143], v[48:63]
	v_mfma_f32_32x32x16_bf16 v[112:127], v[248:251], v[140:143], v[112:127]
	s_waitcnt lgkmcnt(0)
	s_barrier
; #define G_LOAD(S, kt_) do { G_LD1(S##a0, S##b0, 0, kt_); G_LD1(S##a1, S##b1, 1, kt_); G_LD1(S##a2, S##b2, 2, kt_); G_LD1(S##a3, S##b3, 3, kt_); } while (0)
; #define G_STORE(S, buf_) do { G_ST1(S##a0, S##b0, 0, buf_); G_ST1(S##a1, S##b1, 1, buf_); G_ST1(S##a2, S##b2, 2, buf_); G_ST1(S##a3, S##b3, 3, buf_); } while (0)
; template <class AL, class BL>
; DI void gemm_core(AL al, BL bl, int m0, int n0, int K, char* smem, f32x16 (&acc)[2][2]) {
;     ...
;   G_LOAD(x, 0);
;   G_STORE(x, 0);
;   G_LOAD(x, 1);
;   G_LOAD(y, (nk > 2) ? 2 : 1);
;   __syncthreads();
;   for (int kt = 0; kt < nk; kt += 2) {
;     G_TILE(0, x, true, (kt + 3 < nk), kt + 3);
;     __syncthreads();
;     G_TILE(1, y, (kt + 2 < nk), (kt + 4 < nk), kt + 4);
;     __syncthreads();
;   }
	ds_read_b128 v[128:131], v241 offset:0
	ds_read_b128 v[132:135], v241 offset:2560
	ds_read_b128 v[136:139], v241 offset:5120
	ds_read_b128 v[140:143], v241 offset:7680
	ds_read_b128 v[144:147], v240 offset:0
	ds_read_b128 v[148:151], v240 offset:2560
	ds_read_b128 v[152:155], v240 offset:32
	ds_read_b128 v[248:251], v240 offset:2592
	s_waitcnt lgkmcnt(2)
	v_mfma_f32_32x32x16_bf16 v[0:15], v[144:147], v[128:131], v[0:15]
	v_mfma_f32_32x32x16_bf16 v[64:79], v[148:151], v[128:131], v[64:79]
	ds_read_b128 v[128:131], v241 offset:32
	s_waitcnt vmcnt(6)
	ds_write_b128 v242, v[214:217] offset:30720
	ds_write_b128 v242, v[218:221] offset:35840
	v_mfma_f32_32x32x16_bf16 v[16:31], v[144:147], v[132:135], v[16:31]
	v_mfma_f32_32x32x16_bf16 v[80:95], v[148:151], v[132:135], v[80:95]
	ds_read_b128 v[132:135], v241 offset:2592
	ds_write_b128 v242, v[222:225] offset:40960
	ds_write_b128 v242, v[228:231] offset:46080
	v_mfma_f32_32x32x16_bf16 v[32:47], v[144:147], v[136:139], v[32:47]
	v_mfma_f32_32x32x16_bf16 v[96:111], v[148:151], v[136:139], v[96:111]
	ds_read_b128 v[136:139], v241 offset:5152
	ds_write_b128 v242, v[232:235] offset:51200
	ds_write_b128 v242, v[236:239] offset:56320
	v_mfma_f32_32x32x16_bf16 v[48:63], v[144:147], v[140:143], v[48:63]
	v_mfma_f32_32x32x16_bf16 v[112:127], v[148:151], v[140:143], v[112:127]
	ds_read_b128 v[140:143], v241 offset:7712
	s_waitcnt lgkmcnt(9)
	v_mfma_f32_32x32x16_bf16 v[0:15], v[152:155], v[128:131], v[0:15]
	global_load_dwordx4 v[214:217], v[182:183], off offset:832
	global_load_dwordx4 v[218:221], v[184:185], off offset:832
	v_mfma_f32_32x32x16_bf16 v[64:79], v[248:251], v[128:131], v[64:79]
	s_waitcnt lgkmcnt(6)
	v_mfma_f32_32x32x16_bf16 v[16:31], v[152:155], v[132:135], v[16:31]
	global_load_dwordx4 v[222:225], v[186:187], off offset:832
	global_load_dwordx4 v[228:231], v[188:189], off offset:832
	v_mfma_f32_32x32x16_bf16 v[80:95], v[248:251], v[132:135], v[80:95]
	s_waitcnt lgkmcnt(3)
	v_mfma_f32_32x32x16_bf16 v[32:47], v[152:155], v[136:139], v[32:47]
	global_load_dwordx4 v[232:235], v[190:191], off offset:832
	global_load_dwordx4 v[236:239], v[192:193], off offset:832
	v_mfma_f32_32x32x16_bf16 v[96:111], v[248:251], v[136:139], v[96:111]
	s_waitcnt lgkmcnt(0)
	v_mfma_f32_32x32x16_bf16 v[48:63], v[152:155], v[140:143], v[48:63]
	v_mfma_f32_32x32x16_bf16 v[112:127], v[248:251], v[140:143], v[112:127]
	s_waitcnt lgkmcnt(0)
	s_barrier
	ds_read_b128 v[128:131], v241 offset:30720
	ds_read_b128 v[132:135], v241 offset:33280
	ds_read_b128 v[136:139], v241 offset:35840
	ds_read_b128 v[140:143], v241 offset:38400
	ds_read_b128 v[144:147], v240 offset:30720
	ds_read_b128 v[148:151], v240 offset:33280
	ds_read_b128 v[152:155], v240 offset:30752
	ds_read_b128 v[248:251], v240 offset:33312
	s_waitcnt lgkmcnt(2)
	v_mfma_f32_32x32x16_bf16 v[0:15], v[144:147], v[128:131], v[0:15]
	v_mfma_f32_32x32x16_bf16 v[64:79], v[148:151], v[128:131], v[64:79]
	ds_read_b128 v[128:131], v241 offset:30752
	s_waitcnt vmcnt(6)
	ds_write_b128 v242, v[158:161] offset:0
	ds_write_b128 v242, v[162:165] offset:5120
	v_mfma_f32_32x32x16_bf16 v[16:31], v[144:147], v[132:135], v[16:31]
	v_mfma_f32_32x32x16_bf16 v[80:95], v[148:151], v[132:135], v[80:95]
	ds_read_b128 v[132:135], v241 offset:33312
	ds_write_b128 v242, v[166:169] offset:10240
	ds_write_b128 v242, v[170:173] offset:15360
	v_mfma_f32_32x32x16_bf16 v[32:47], v[144:147], v[136:139], v[32:47]
	v_mfma_f32_32x32x16_bf16 v[96:111], v[148:151], v[136:139], v[96:111]
	ds_read_b128 v[136:139], v241 offset:35872
	ds_write_b128 v242, v[174:177] offset:20480
	ds_write_b128 v242, v[178:181] offset:25600
	v_mfma_f32_32x32x16_bf16 v[48:63], v[144:147], v[140:143], v[48:63]
	v_mfma_f32_32x32x16_bf16 v[112:127], v[148:151], v[140:143], v[112:127]
	ds_read_b128 v[140:143], v241 offset:38432
	s_waitcnt lgkmcnt(9)
	v_mfma_f32_32x32x16_bf16 v[0:15], v[152:155], v[128:131], v[0:15]
	global_load_dwordx4 v[158:161], v[182:183], off offset:896
	global_load_dwordx4 v[162:165], v[184:185], off offset:896
	v_mfma_f32_32x32x16_bf16 v[64:79], v[248:251], v[128:131], v[64:79]
	s_waitcnt lgkmcnt(6)
	v_mfma_f32_32x32x16_bf16 v[16:31], v[152:155], v[132:135], v[16:31]
	global_load_dwordx4 v[166:169], v[186:187], off offset:896
	global_load_dwordx4 v[170:173], v[188:189], off offset:896
	v_mfma_f32_32x32x16_bf16 v[80:95], v[248:251], v[132:135], v[80:95]
	s_waitcnt lgkmcnt(3)
	v_mfma_f32_32x32x16_bf16 v[32:47], v[152:155], v[136:139], v[32:47]
	global_load_dwordx4 v[174:177], v[190:191], off offset:896
	global_load_dwordx4 v[178:181], v[192:193], off offset:896
	v_mfma_f32_32x32x16_bf16 v[96:111], v[248:251], v[136:139], v[96:111]
	s_waitcnt lgkmcnt(0)
	v_mfma_f32_32x32x16_bf16 v[48:63], v[152:155], v[140:143], v[48:63]
	v_mfma_f32_32x32x16_bf16 v[112:127], v[248:251], v[140:143], v[112:127]
	s_waitcnt lgkmcnt(0)
	s_barrier
; #define G_LOAD(S, kt_) do { G_LD1(S##a0, S##b0, 0, kt_); G_LD1(S##a1, S##b1, 1, kt_); G_LD1(S##a2, S##b2, 2, kt_); G_LD1(S##a3, S##b3, 3, kt_); } while (0)
; #define G_STORE(S, buf_) do { G_ST1(S##a0, S##b0, 0, buf_); G_ST1(S##a1, S##b1, 1, buf_); G_ST1(S##a2, S##b2, 2, buf_); G_ST1(S##a3, S##b3, 3, buf_); } while (0)
; template <class AL, class BL>
; DI void gemm_core(AL al, BL bl, int m0, int n0, int K, char* smem, f32x16 (&acc)[2][2]) {
;     ...
;   G_LOAD(x, 0);
;   G_STORE(x, 0);
;   G_LOAD(x, 1);
;   G_LOAD(y, (nk > 2) ? 2 : 1);
;   __syncthreads();
;   for (int kt = 0; kt < nk; kt += 2) {
;     G_TILE(0, x, true, (kt + 3 < nk), kt + 3);
;     __syncthreads();
;     G_TILE(1, y, (kt + 2 < nk), (kt + 4 < nk), kt + 4);
;     __syncthreads();
;   }
	ds_read_b128 v[128:131], v241 offset:0
	ds_read_b128 v[132:135], v241 offset:2560
	ds_read_b128 v[136:139], v241 offset:5120
	ds_read_b128 v[140:143], v241 offset:7680
	ds_read_b128 v[144:147], v240 offset:0
	ds_read_b128 v[148:151], v240 offset:2560
	ds_read_b128 v[152:155], v240 offset:32
	ds_read_b128 v[248:251], v240 offset:2592
	s_waitcnt lgkmcnt(2)
	v_mfma_f32_32x32x16_bf16 v[0:15], v[144:147], v[128:131], v[0:15]
	v_mfma_f32_32x32x16_bf16 v[64:79], v[148:151], v[128:131], v[64:79]
	ds_read_b128 v[128:131], v241 offset:32
	s_waitcnt vmcnt(6)
	ds_write_b128 v242, v[214:217] offset:30720
	ds_write_b128 v242, v[218:221] offset:35840
	v_mfma_f32_32x32x16_bf16 v[16:31], v[144:147], v[132:135], v[16:31]
	v_mfma_f32_32x32x16_bf16 v[80:95], v[148:151], v[132:135], v[80:95]
	ds_read_b128 v[132:135], v241 offset:2592
	ds_write_b128 v242, v[222:225] offset:40960
	ds_write_b128 v242, v[228:231] offset:46080
	v_mfma_f32_32x32x16_bf16 v[32:47], v[144:147], v[136:139], v[32:47]
	v_mfma_f32_32x32x16_bf16 v[96:111], v[148:151], v[136:139], v[96:111]
	ds_read_b128 v[136:139], v241 offset:5152
	ds_write_b128 v242, v[232:235] offset:51200
	ds_write_b128 v242, v[236:239] offset:56320
	v_mfma_f32_32x32x16_bf16 v[48:63], v[144:147], v[140:143], v[48:63]
	v_mfma_f32_32x32x16_bf16 v[112:127], v[148:151], v[140:143], v[112:127]
	ds_read_b128 v[140:143], v241 offset:7712
	s_waitcnt lgkmcnt(9)
	v_mfma_f32_32x32x16_bf16 v[0:15], v[152:155], v[128:131], v[0:15]
	global_load_dwordx4 v[214:217], v[182:183], off offset:960
	global_load_dwordx4 v[218:221], v[184:185], off offset:960
	v_mfma_f32_32x32x16_bf16 v[64:79], v[248:251], v[128:131], v[64:79]
	s_waitcnt lgkmcnt(6)
	v_mfma_f32_32x32x16_bf16 v[16:31], v[152:155], v[132:135], v[16:31]
	global_load_dwordx4 v[222:225], v[186:187], off offset:960
	global_load_dwordx4 v[228:231], v[188:189], off offset:960
	v_mfma_f32_32x32x16_bf16 v[80:95], v[248:251], v[132:135], v[80:95]
	s_waitcnt lgkmcnt(3)
	v_mfma_f32_32x32x16_bf16 v[32:47], v[152:155], v[136:139], v[32:47]
	global_load_dwordx4 v[232:235], v[190:191], off offset:960
	global_load_dwordx4 v[236:239], v[192:193], off offset:960
	v_mfma_f32_32x32x16_bf16 v[96:111], v[248:251], v[136:139], v[96:111]
	s_waitcnt lgkmcnt(0)
	v_mfma_f32_32x32x16_bf16 v[48:63], v[152:155], v[140:143], v[48:63]
	v_mfma_f32_32x32x16_bf16 v[112:127], v[248:251], v[140:143], v[112:127]
	s_waitcnt lgkmcnt(0)
	s_barrier
	ds_read_b128 v[128:131], v241 offset:30720
	ds_read_b128 v[132:135], v241 offset:33280
	ds_read_b128 v[136:139], v241 offset:35840
	ds_read_b128 v[140:143], v241 offset:38400
	ds_read_b128 v[144:147], v240 offset:30720
	ds_read_b128 v[148:151], v240 offset:33280
	ds_read_b128 v[152:155], v240 offset:30752
	ds_read_b128 v[248:251], v240 offset:33312
	s_waitcnt lgkmcnt(2)
	v_mfma_f32_32x32x16_bf16 v[0:15], v[144:147], v[128:131], v[0:15]
	v_mfma_f32_32x32x16_bf16 v[64:79], v[148:151], v[128:131], v[64:79]
	ds_read_b128 v[128:131], v241 offset:30752
	s_waitcnt vmcnt(6)
	ds_write_b128 v242, v[158:161] offset:0
	ds_write_b128 v242, v[162:165] offset:5120
	v_mfma_f32_32x32x16_bf16 v[16:31], v[144:147], v[132:135], v[16:31]
	v_mfma_f32_32x32x16_bf16 v[80:95], v[148:151], v[132:135], v[80:95]
	ds_read_b128 v[132:135], v241 offset:33312
	ds_write_b128 v242, v[166:169] offset:10240
	ds_write_b128 v242, v[170:173] offset:15360
	v_mfma_f32_32x32x16_bf16 v[32:47], v[144:147], v[136:139], v[32:47]
	v_mfma_f32_32x32x16_bf16 v[96:111], v[148:151], v[136:139], v[96:111]
	ds_read_b128 v[136:139], v241 offset:35872
	ds_write_b128 v242, v[174:177] offset:20480
	ds_write_b128 v242, v[178:181] offset:25600
	v_mfma_f32_32x32x16_bf16 v[48:63], v[144:147], v[140:143], v[48:63]
	v_mfma_f32_32x32x16_bf16 v[112:127], v[148:151], v[140:143], v[112:127]
	ds_read_b128 v[140:143], v241 offset:38432
	s_waitcnt lgkmcnt(9)
	v_mfma_f32_32x32x16_bf16 v[0:15], v[152:155], v[128:131], v[0:15]
	global_load_dwordx4 v[158:161], v[182:183], off offset:1024
	global_load_dwordx4 v[162:165], v[184:185], off offset:1024
	v_mfma_f32_32x32x16_bf16 v[64:79], v[248:251], v[128:131], v[64:79]
	s_waitcnt lgkmcnt(6)
	v_mfma_f32_32x32x16_bf16 v[16:31], v[152:155], v[132:135], v[16:31]
	global_load_dwordx4 v[166:169], v[186:187], off offset:1024
	global_load_dwordx4 v[170:173], v[188:189], off offset:1024
	v_mfma_f32_32x32x16_bf16 v[80:95], v[248:251], v[132:135], v[80:95]
	s_waitcnt lgkmcnt(3)
	v_mfma_f32_32x32x16_bf16 v[32:47], v[152:155], v[136:139], v[32:47]
	global_load_dwordx4 v[174:177], v[190:191], off offset:1024
	global_load_dwordx4 v[178:181], v[192:193], off offset:1024
	v_mfma_f32_32x32x16_bf16 v[96:111], v[248:251], v[136:139], v[96:111]
	s_waitcnt lgkmcnt(0)
	v_mfma_f32_32x32x16_bf16 v[48:63], v[152:155], v[140:143], v[48:63]
	v_mfma_f32_32x32x16_bf16 v[112:127], v[248:251], v[140:143], v[112:127]
	s_waitcnt lgkmcnt(0)
	s_barrier
; #define G_LOAD(S, kt_) do { G_LD1(S##a0, S##b0, 0, kt_); G_LD1(S##a1, S##b1, 1, kt_); G_LD1(S##a2, S##b2, 2, kt_); G_LD1(S##a3, S##b3, 3, kt_); } while (0)
; #define G_STORE(S, buf_) do { G_ST1(S##a0, S##b0, 0, buf_); G_ST1(S##a1, S##b1, 1, buf_); G_ST1(S##a2, S##b2, 2, buf_); G_ST1(S##a3, S##b3, 3, buf_); } while (0)
; template <class AL, class BL>
; DI void gemm_core(AL al, BL bl, int m0, int n0, int K, char* smem, f32x16 (&acc)[2][2]) {
;     ...
;   G_LOAD(x, 0);
;   G_STORE(x, 0);
;   G_LOAD(x, 1);
;   G_LOAD(y, (nk > 2) ? 2 : 1);
;   __syncthreads();
;   for (int kt = 0; kt < nk; kt += 2) {
;     G_TILE(0, x, true, (kt + 3 < nk), kt + 3);
;     __syncthreads();
;     G_TILE(1, y, (kt + 2 < nk), (kt + 4 < nk), kt + 4);
;     __syncthreads();
;   }
	ds_read_b128 v[128:131], v241 offset:0
	ds_read_b128 v[132:135], v241 offset:2560
	ds_read_b128 v[136:139], v241 offset:5120
	ds_read_b128 v[140:143], v241 offset:7680
	ds_read_b128 v[144:147], v240 offset:0
	ds_read_b128 v[148:151], v240 offset:2560
	ds_read_b128 v[152:155], v240 offset:32
	ds_read_b128 v[248:251], v240 offset:2592
	s_waitcnt lgkmcnt(2)
	v_mfma_f32_32x32x16_bf16 v[0:15], v[144:147], v[128:131], v[0:15]
	v_mfma_f32_32x32x16_bf16 v[64:79], v[148:151], v[128:131], v[64:79]
	ds_read_b128 v[128:131], v241 offset:32
	s_waitcnt vmcnt(6)
	ds_write_b128 v242, v[214:217] offset:30720
	ds_write_b128 v242, v[218:221] offset:35840
	v_mfma_f32_32x32x16_bf16 v[16:31], v[144:147], v[132:135], v[16:31]
	v_mfma_f32_32x32x16_bf16 v[80:95], v[148:151], v[132:135], v[80:95]
	ds_read_b128 v[132:135], v241 offset:2592
	ds_write_b128 v242, v[222:225] offset:40960
	ds_write_b128 v242, v[228:231] offset:46080
	v_mfma_f32_32x32x16_bf16 v[32:47], v[144:147], v[136:139], v[32:47]
	v_mfma_f32_32x32x16_bf16 v[96:111], v[148:151], v[136:139], v[96:111]
	ds_read_b128 v[136:139], v241 offset:5152
	ds_write_b128 v242, v[232:235] offset:51200
	ds_write_b128 v242, v[236:239] offset:56320
	v_mfma_f32_32x32x16_bf16 v[48:63], v[144:147], v[140:143], v[48:63]
	v_mfma_f32_32x32x16_bf16 v[112:127], v[148:151], v[140:143], v[112:127]
	ds_read_b128 v[140:143], v241 offset:7712
	s_waitcnt lgkmcnt(9)
	v_mfma_f32_32x32x16_bf16 v[0:15], v[152:155], v[128:131], v[0:15]
	global_load_dwordx4 v[214:217], v[182:183], off offset:1088
	global_load_dwordx4 v[218:221], v[184:185], off offset:1088
	v_mfma_f32_32x32x16_bf16 v[64:79], v[248:251], v[128:131], v[64:79]
	s_waitcnt lgkmcnt(6)
	v_mfma_f32_32x32x16_bf16 v[16:31], v[152:155], v[132:135], v[16:31]
	global_load_dwordx4 v[222:225], v[186:187], off offset:1088
	global_load_dwordx4 v[228:231], v[188:189], off offset:1088
	v_mfma_f32_32x32x16_bf16 v[80:95], v[248:251], v[132:135], v[80:95]
	s_waitcnt lgkmcnt(3)
	v_mfma_f32_32x32x16_bf16 v[32:47], v[152:155], v[136:139], v[32:47]
	global_load_dwordx4 v[232:235], v[190:191], off offset:1088
	global_load_dwordx4 v[236:239], v[192:193], off offset:1088
	v_mfma_f32_32x32x16_bf16 v[96:111], v[248:251], v[136:139], v[96:111]
	s_waitcnt lgkmcnt(0)
	v_mfma_f32_32x32x16_bf16 v[48:63], v[152:155], v[140:143], v[48:63]
	v_mfma_f32_32x32x16_bf16 v[112:127], v[248:251], v[140:143], v[112:127]
	s_waitcnt lgkmcnt(0)
	s_barrier
	ds_read_b128 v[128:131], v241 offset:30720
	ds_read_b128 v[132:135], v241 offset:33280
	ds_read_b128 v[136:139], v241 offset:35840
	ds_read_b128 v[140:143], v241 offset:38400
	ds_read_b128 v[144:147], v240 offset:30720
	ds_read_b128 v[148:151], v240 offset:33280
	ds_read_b128 v[152:155], v240 offset:30752
	ds_read_b128 v[248:251], v240 offset:33312
	s_waitcnt lgkmcnt(2)
	v_mfma_f32_32x32x16_bf16 v[0:15], v[144:147], v[128:131], v[0:15]
	v_mfma_f32_32x32x16_bf16 v[64:79], v[148:151], v[128:131], v[64:79]
	ds_read_b128 v[128:131], v241 offset:30752
	s_waitcnt vmcnt(6)
	ds_write_b128 v242, v[158:161] offset:0
	ds_write_b128 v242, v[162:165] offset:5120
	v_mfma_f32_32x32x16_bf16 v[16:31], v[144:147], v[132:135], v[16:31]
	v_mfma_f32_32x32x16_bf16 v[80:95], v[148:151], v[132:135], v[80:95]
	ds_read_b128 v[132:135], v241 offset:33312
	ds_write_b128 v242, v[166:169] offset:10240
	ds_write_b128 v242, v[170:173] offset:15360
	v_mfma_f32_32x32x16_bf16 v[32:47], v[144:147], v[136:139], v[32:47]
	v_mfma_f32_32x32x16_bf16 v[96:111], v[148:151], v[136:139], v[96:111]
	ds_read_b128 v[136:139], v241 offset:35872
	ds_write_b128 v242, v[174:177] offset:20480
	ds_write_b128 v242, v[178:181] offset:25600
	v_mfma_f32_32x32x16_bf16 v[48:63], v[144:147], v[140:143], v[48:63]
	v_mfma_f32_32x32x16_bf16 v[112:127], v[148:151], v[140:143], v[112:127]
	ds_read_b128 v[140:143], v241 offset:38432
	s_waitcnt lgkmcnt(9)
	v_mfma_f32_32x32x16_bf16 v[0:15], v[152:155], v[128:131], v[0:15]
	global_load_dwordx4 v[158:161], v[182:183], off offset:1152
	global_load_dwordx4 v[162:165], v[184:185], off offset:1152
	v_mfma_f32_32x32x16_bf16 v[64:79], v[248:251], v[128:131], v[64:79]
	s_waitcnt lgkmcnt(6)
	v_mfma_f32_32x32x16_bf16 v[16:31], v[152:155], v[132:135], v[16:31]
	global_load_dwordx4 v[166:169], v[186:187], off offset:1152
	global_load_dwordx4 v[170:173], v[188:189], off offset:1152
	v_mfma_f32_32x32x16_bf16 v[80:95], v[248:251], v[132:135], v[80:95]
	s_waitcnt lgkmcnt(3)
	v_mfma_f32_32x32x16_bf16 v[32:47], v[152:155], v[136:139], v[32:47]
	global_load_dwordx4 v[174:177], v[190:191], off offset:1152
	global_load_dwordx4 v[178:181], v[192:193], off offset:1152
	v_mfma_f32_32x32x16_bf16 v[96:111], v[248:251], v[136:139], v[96:111]
	s_waitcnt lgkmcnt(0)
	v_mfma_f32_32x32x16_bf16 v[48:63], v[152:155], v[140:143], v[48:63]
	v_mfma_f32_32x32x16_bf16 v[112:127], v[248:251], v[140:143], v[112:127]
	s_waitcnt lgkmcnt(0)
	s_barrier
; #define G_LOAD(S, kt_) do { G_LD1(S##a0, S##b0, 0, kt_); G_LD1(S##a1, S##b1, 1, kt_); G_LD1(S##a2, S##b2, 2, kt_); G_LD1(S##a3, S##b3, 3, kt_); } while (0)
; #define G_STORE(S, buf_) do { G_ST1(S##a0, S##b0, 0, buf_); G_ST1(S##a1, S##b1, 1, buf_); G_ST1(S##a2, S##b2, 2, buf_); G_ST1(S##a3, S##b3, 3, buf_); } while (0)
; template <class AL, class BL>
; DI void gemm_core(AL al, BL bl, int m0, int n0, int K, char* smem, f32x16 (&acc)[2][2]) {
;     ...
;   G_LOAD(x, 0);
;   G_STORE(x, 0);
;   G_LOAD(x, 1);
;   G_LOAD(y, (nk > 2) ? 2 : 1);
;   __syncthreads();
;   for (int kt = 0; kt < nk; kt += 2) {
;     G_TILE(0, x, true, (kt + 3 < nk), kt + 3);
;     __syncthreads();
;     G_TILE(1, y, (kt + 2 < nk), (kt + 4 < nk), kt + 4);
;     __syncthreads();
;   }
	ds_read_b128 v[128:131], v241 offset:0
	ds_read_b128 v[132:135], v241 offset:2560
	ds_read_b128 v[136:139], v241 offset:5120
	ds_read_b128 v[140:143], v241 offset:7680
	ds_read_b128 v[144:147], v240 offset:0
	ds_read_b128 v[148:151], v240 offset:2560
	ds_read_b128 v[152:155], v240 offset:32
	ds_read_b128 v[248:251], v240 offset:2592
	s_waitcnt lgkmcnt(2)
	v_mfma_f32_32x32x16_bf16 v[0:15], v[144:147], v[128:131], v[0:15]
	v_mfma_f32_32x32x16_bf16 v[64:79], v[148:151], v[128:131], v[64:79]
	ds_read_b128 v[128:131], v241 offset:32
	s_waitcnt vmcnt(6)
	ds_write_b128 v242, v[214:217] offset:30720
	ds_write_b128 v242, v[218:221] offset:35840
	v_mfma_f32_32x32x16_bf16 v[16:31], v[144:147], v[132:135], v[16:31]
	v_mfma_f32_32x32x16_bf16 v[80:95], v[148:151], v[132:135], v[80:95]
	ds_read_b128 v[132:135], v241 offset:2592
	ds_write_b128 v242, v[222:225] offset:40960
	ds_write_b128 v242, v[228:231] offset:46080
	v_mfma_f32_32x32x16_bf16 v[32:47], v[144:147], v[136:139], v[32:47]
	v_mfma_f32_32x32x16_bf16 v[96:111], v[148:151], v[136:139], v[96:111]
	ds_read_b128 v[136:139], v241 offset:5152
	ds_write_b128 v242, v[232:235] offset:51200
	ds_write_b128 v242, v[236:239] offset:56320
	v_mfma_f32_32x32x16_bf16 v[48:63], v[144:147], v[140:143], v[48:63]
	v_mfma_f32_32x32x16_bf16 v[112:127], v[148:151], v[140:143], v[112:127]
	ds_read_b128 v[140:143], v241 offset:7712
	s_waitcnt lgkmcnt(9)
	v_mfma_f32_32x32x16_bf16 v[0:15], v[152:155], v[128:131], v[0:15]
	global_load_dwordx4 v[214:217], v[182:183], off offset:1216
	global_load_dwordx4 v[218:221], v[184:185], off offset:1216
	v_mfma_f32_32x32x16_bf16 v[64:79], v[248:251], v[128:131], v[64:79]
	s_waitcnt lgkmcnt(6)
	v_mfma_f32_32x32x16_bf16 v[16:31], v[152:155], v[132:135], v[16:31]
	global_load_dwordx4 v[222:225], v[186:187], off offset:1216
	global_load_dwordx4 v[228:231], v[188:189], off offset:1216
	v_mfma_f32_32x32x16_bf16 v[80:95], v[248:251], v[132:135], v[80:95]
	s_waitcnt lgkmcnt(3)
	v_mfma_f32_32x32x16_bf16 v[32:47], v[152:155], v[136:139], v[32:47]
	global_load_dwordx4 v[232:235], v[190:191], off offset:1216
	global_load_dwordx4 v[236:239], v[192:193], off offset:1216
	v_mfma_f32_32x32x16_bf16 v[96:111], v[248:251], v[136:139], v[96:111]
	s_waitcnt lgkmcnt(0)
	v_mfma_f32_32x32x16_bf16 v[48:63], v[152:155], v[140:143], v[48:63]
	v_mfma_f32_32x32x16_bf16 v[112:127], v[248:251], v[140:143], v[112:127]
	s_waitcnt lgkmcnt(0)
	s_barrier
	ds_read_b128 v[128:131], v241 offset:30720
	ds_read_b128 v[132:135], v241 offset:33280
	ds_read_b128 v[136:139], v241 offset:35840
	ds_read_b128 v[140:143], v241 offset:38400
	ds_read_b128 v[144:147], v240 offset:30720
	ds_read_b128 v[148:151], v240 offset:33280
	ds_read_b128 v[152:155], v240 offset:30752
	ds_read_b128 v[248:251], v240 offset:33312
	s_waitcnt lgkmcnt(2)
	v_mfma_f32_32x32x16_bf16 v[0:15], v[144:147], v[128:131], v[0:15]
	v_mfma_f32_32x32x16_bf16 v[64:79], v[148:151], v[128:131], v[64:79]
	ds_read_b128 v[128:131], v241 offset:30752
	s_waitcnt vmcnt(6)
	ds_write_b128 v242, v[158:161] offset:0
	ds_write_b128 v242, v[162:165] offset:5120
	v_mfma_f32_32x32x16_bf16 v[16:31], v[144:147], v[132:135], v[16:31]
	v_mfma_f32_32x32x16_bf16 v[80:95], v[148:151], v[132:135], v[80:95]
	ds_read_b128 v[132:135], v241 offset:33312
	ds_write_b128 v242, v[166:169] offset:10240
	ds_write_b128 v242, v[170:173] offset:15360
	v_mfma_f32_32x32x16_bf16 v[32:47], v[144:147], v[136:139], v[32:47]
	v_mfma_f32_32x32x16_bf16 v[96:111], v[148:151], v[136:139], v[96:111]
	ds_read_b128 v[136:139], v241 offset:35872
	ds_write_b128 v242, v[174:177] offset:20480
	ds_write_b128 v242, v[178:181] offset:25600
	v_mfma_f32_32x32x16_bf16 v[48:63], v[144:147], v[140:143], v[48:63]
	v_mfma_f32_32x32x16_bf16 v[112:127], v[148:151], v[140:143], v[112:127]
	ds_read_b128 v[140:143], v241 offset:38432
	s_waitcnt lgkmcnt(9)
	v_mfma_f32_32x32x16_bf16 v[0:15], v[152:155], v[128:131], v[0:15]
	global_load_dwordx4 v[158:161], v[182:183], off offset:1280
	global_load_dwordx4 v[162:165], v[184:185], off offset:1280
	v_mfma_f32_32x32x16_bf16 v[64:79], v[248:251], v[128:131], v[64:79]
	s_waitcnt lgkmcnt(6)
	v_mfma_f32_32x32x16_bf16 v[16:31], v[152:155], v[132:135], v[16:31]
	global_load_dwordx4 v[166:169], v[186:187], off offset:1280
	global_load_dwordx4 v[170:173], v[188:189], off offset:1280
	v_mfma_f32_32x32x16_bf16 v[80:95], v[248:251], v[132:135], v[80:95]
	s_waitcnt lgkmcnt(3)
	v_mfma_f32_32x32x16_bf16 v[32:47], v[152:155], v[136:139], v[32:47]
	global_load_dwordx4 v[174:177], v[190:191], off offset:1280
	global_load_dwordx4 v[178:181], v[192:193], off offset:1280
	v_mfma_f32_32x32x16_bf16 v[96:111], v[248:251], v[136:139], v[96:111]
	s_waitcnt lgkmcnt(0)
	v_mfma_f32_32x32x16_bf16 v[48:63], v[152:155], v[140:143], v[48:63]
	v_mfma_f32_32x32x16_bf16 v[112:127], v[248:251], v[140:143], v[112:127]
	s_waitcnt lgkmcnt(0)
	s_barrier
; #define G_LOAD(S, kt_) do { G_LD1(S##a0, S##b0, 0, kt_); G_LD1(S##a1, S##b1, 1, kt_); G_LD1(S##a2, S##b2, 2, kt_); G_LD1(S##a3, S##b3, 3, kt_); } while (0)
; #define G_STORE(S, buf_) do { G_ST1(S##a0, S##b0, 0, buf_); G_ST1(S##a1, S##b1, 1, buf_); G_ST1(S##a2, S##b2, 2, buf_); G_ST1(S##a3, S##b3, 3, buf_); } while (0)
; template <class AL, class BL>
; DI void gemm_core(AL al, BL bl, int m0, int n0, int K, char* smem, f32x16 (&acc)[2][2]) {
;     ...
;   G_LOAD(x, 0);
;   G_STORE(x, 0);
;   G_LOAD(x, 1);
;   G_LOAD(y, (nk > 2) ? 2 : 1);
;   __syncthreads();
;   for (int kt = 0; kt < nk; kt += 2) {
;     G_TILE(0, x, true, (kt + 3 < nk), kt + 3);
;     __syncthreads();
;     G_TILE(1, y, (kt + 2 < nk), (kt + 4 < nk), kt + 4);
;     __syncthreads();
;   }
	ds_read_b128 v[128:131], v241 offset:0
	ds_read_b128 v[132:135], v241 offset:2560
	ds_read_b128 v[136:139], v241 offset:5120
	ds_read_b128 v[140:143], v241 offset:7680
	ds_read_b128 v[144:147], v240 offset:0
	ds_read_b128 v[148:151], v240 offset:2560
	ds_read_b128 v[152:155], v240 offset:32
	ds_read_b128 v[248:251], v240 offset:2592
	s_waitcnt lgkmcnt(2)
	v_mfma_f32_32x32x16_bf16 v[0:15], v[144:147], v[128:131], v[0:15]
	v_mfma_f32_32x32x16_bf16 v[64:79], v[148:151], v[128:131], v[64:79]
	ds_read_b128 v[128:131], v241 offset:32
	s_waitcnt vmcnt(6)
	ds_write_b128 v242, v[214:217] offset:30720
	ds_write_b128 v242, v[218:221] offset:35840
	v_mfma_f32_32x32x16_bf16 v[16:31], v[144:147], v[132:135], v[16:31]
	v_mfma_f32_32x32x16_bf16 v[80:95], v[148:151], v[132:135], v[80:95]
	ds_read_b128 v[132:135], v241 offset:2592
	ds_write_b128 v242, v[222:225] offset:40960
	ds_write_b128 v242, v[228:231] offset:46080
	v_mfma_f32_32x32x16_bf16 v[32:47], v[144:147], v[136:139], v[32:47]
	v_mfma_f32_32x32x16_bf16 v[96:111], v[148:151], v[136:139], v[96:111]
	ds_read_b128 v[136:139], v241 offset:5152
	ds_write_b128 v242, v[232:235] offset:51200
	ds_write_b128 v242, v[236:239] offset:56320
	v_mfma_f32_32x32x16_bf16 v[48:63], v[144:147], v[140:143], v[48:63]
	v_mfma_f32_32x32x16_bf16 v[112:127], v[148:151], v[140:143], v[112:127]
	ds_read_b128 v[140:143], v241 offset:7712
	s_waitcnt lgkmcnt(9)
	v_mfma_f32_32x32x16_bf16 v[0:15], v[152:155], v[128:131], v[0:15]
	global_load_dwordx4 v[214:217], v[182:183], off offset:1344
	global_load_dwordx4 v[218:221], v[184:185], off offset:1344
	v_mfma_f32_32x32x16_bf16 v[64:79], v[248:251], v[128:131], v[64:79]
	s_waitcnt lgkmcnt(6)
	v_mfma_f32_32x32x16_bf16 v[16:31], v[152:155], v[132:135], v[16:31]
	global_load_dwordx4 v[222:225], v[186:187], off offset:1344
	global_load_dwordx4 v[228:231], v[188:189], off offset:1344
	v_mfma_f32_32x32x16_bf16 v[80:95], v[248:251], v[132:135], v[80:95]
	s_waitcnt lgkmcnt(3)
	v_mfma_f32_32x32x16_bf16 v[32:47], v[152:155], v[136:139], v[32:47]
	global_load_dwordx4 v[232:235], v[190:191], off offset:1344
	global_load_dwordx4 v[236:239], v[192:193], off offset:1344
	v_mfma_f32_32x32x16_bf16 v[96:111], v[248:251], v[136:139], v[96:111]
	s_waitcnt lgkmcnt(0)
	v_mfma_f32_32x32x16_bf16 v[48:63], v[152:155], v[140:143], v[48:63]
	v_mfma_f32_32x32x16_bf16 v[112:127], v[248:251], v[140:143], v[112:127]
	s_waitcnt lgkmcnt(0)
	s_barrier
	ds_read_b128 v[128:131], v241 offset:30720
	ds_read_b128 v[132:135], v241 offset:33280
	ds_read_b128 v[136:139], v241 offset:35840
	ds_read_b128 v[140:143], v241 offset:38400
	ds_read_b128 v[144:147], v240 offset:30720
	ds_read_b128 v[148:151], v240 offset:33280
	ds_read_b128 v[152:155], v240 offset:30752
	ds_read_b128 v[248:251], v240 offset:33312
	s_waitcnt lgkmcnt(2)
	v_mfma_f32_32x32x16_bf16 v[0:15], v[144:147], v[128:131], v[0:15]
	v_mfma_f32_32x32x16_bf16 v[64:79], v[148:151], v[128:131], v[64:79]
	ds_read_b128 v[128:131], v241 offset:30752
	s_waitcnt vmcnt(6)
	ds_write_b128 v242, v[158:161] offset:0
	ds_write_b128 v242, v[162:165] offset:5120
	v_mfma_f32_32x32x16_bf16 v[16:31], v[144:147], v[132:135], v[16:31]
	v_mfma_f32_32x32x16_bf16 v[80:95], v[148:151], v[132:135], v[80:95]
	ds_read_b128 v[132:135], v241 offset:33312
	ds_write_b128 v242, v[166:169] offset:10240
	ds_write_b128 v242, v[170:173] offset:15360
	v_mfma_f32_32x32x16_bf16 v[32:47], v[144:147], v[136:139], v[32:47]
	v_mfma_f32_32x32x16_bf16 v[96:111], v[148:151], v[136:139], v[96:111]
	ds_read_b128 v[136:139], v241 offset:35872
	ds_write_b128 v242, v[174:177] offset:20480
	ds_write_b128 v242, v[178:181] offset:25600
	v_mfma_f32_32x32x16_bf16 v[48:63], v[144:147], v[140:143], v[48:63]
	v_mfma_f32_32x32x16_bf16 v[112:127], v[148:151], v[140:143], v[112:127]
	ds_read_b128 v[140:143], v241 offset:38432
	s_waitcnt lgkmcnt(9)
	v_mfma_f32_32x32x16_bf16 v[0:15], v[152:155], v[128:131], v[0:15]
	global_load_dwordx4 v[158:161], v[182:183], off offset:1408
	global_load_dwordx4 v[162:165], v[184:185], off offset:1408
	v_mfma_f32_32x32x16_bf16 v[64:79], v[248:251], v[128:131], v[64:79]
	s_waitcnt lgkmcnt(6)
	v_mfma_f32_32x32x16_bf16 v[16:31], v[152:155], v[132:135], v[16:31]
	global_load_dwordx4 v[166:169], v[186:187], off offset:1408
	global_load_dwordx4 v[170:173], v[188:189], off offset:1408
	v_mfma_f32_32x32x16_bf16 v[80:95], v[248:251], v[132:135], v[80:95]
	s_waitcnt lgkmcnt(3)
	v_mfma_f32_32x32x16_bf16 v[32:47], v[152:155], v[136:139], v[32:47]
	global_load_dwordx4 v[174:177], v[190:191], off offset:1408
	global_load_dwordx4 v[178:181], v[192:193], off offset:1408
	v_mfma_f32_32x32x16_bf16 v[96:111], v[248:251], v[136:139], v[96:111]
	s_waitcnt lgkmcnt(0)
	v_mfma_f32_32x32x16_bf16 v[48:63], v[152:155], v[140:143], v[48:63]
	v_mfma_f32_32x32x16_bf16 v[112:127], v[248:251], v[140:143], v[112:127]
	s_waitcnt lgkmcnt(0)
	s_barrier
; #define G_LOAD(S, kt_) do { G_LD1(S##a0, S##b0, 0, kt_); G_LD1(S##a1, S##b1, 1, kt_); G_LD1(S##a2, S##b2, 2, kt_); G_LD1(S##a3, S##b3, 3, kt_); } while (0)
; #define G_STORE(S, buf_) do { G_ST1(S##a0, S##b0, 0, buf_); G_ST1(S##a1, S##b1, 1, buf_); G_ST1(S##a2, S##b2, 2, buf_); G_ST1(S##a3, S##b3, 3, buf_); } while (0)
; template <class AL, class BL>
; DI void gemm_core(AL al, BL bl, int m0, int n0, int K, char* smem, f32x16 (&acc)[2][2]) {
;     ...
;   G_LOAD(x, 0);
;   G_STORE(x, 0);
;   G_LOAD(x, 1);
;   G_LOAD(y, (nk > 2) ? 2 : 1);
;   __syncthreads();
;   for (int kt = 0; kt < nk; kt += 2) {
;     G_TILE(0, x, true, (kt + 3 < nk), kt + 3);
;     __syncthreads();
;     G_TILE(1, y, (kt + 2 < nk), (kt + 4 < nk), kt + 4);
;     __syncthreads();
;   }
	ds_read_b128 v[128:131], v241 offset:0
	ds_read_b128 v[132:135], v241 offset:2560
	ds_read_b128 v[136:139], v241 offset:5120
	ds_read_b128 v[140:143], v241 offset:7680
	ds_read_b128 v[144:147], v240 offset:0
	ds_read_b128 v[148:151], v240 offset:2560
	ds_read_b128 v[152:155], v240 offset:32
	ds_read_b128 v[248:251], v240 offset:2592
	s_waitcnt lgkmcnt(2)
	v_mfma_f32_32x32x16_bf16 v[0:15], v[144:147], v[128:131], v[0:15]
	v_mfma_f32_32x32x16_bf16 v[64:79], v[148:151], v[128:131], v[64:79]
	ds_read_b128 v[128:131], v241 offset:32
	s_waitcnt vmcnt(6)
	ds_write_b128 v242, v[214:217] offset:30720
	ds_write_b128 v242, v[218:221] offset:35840
	v_mfma_f32_32x32x16_bf16 v[16:31], v[144:147], v[132:135], v[16:31]
	v_mfma_f32_32x32x16_bf16 v[80:95], v[148:151], v[132:135], v[80:95]
	ds_read_b128 v[132:135], v241 offset:2592
	ds_write_b128 v242, v[222:225] offset:40960
	ds_write_b128 v242, v[228:231] offset:46080
	v_mfma_f32_32x32x16_bf16 v[32:47], v[144:147], v[136:139], v[32:47]
	v_mfma_f32_32x32x16_bf16 v[96:111], v[148:151], v[136:139], v[96:111]
	ds_read_b128 v[136:139], v241 offset:5152
	ds_write_b128 v242, v[232:235] offset:51200
	ds_write_b128 v242, v[236:239] offset:56320
	v_mfma_f32_32x32x16_bf16 v[48:63], v[144:147], v[140:143], v[48:63]
	v_mfma_f32_32x32x16_bf16 v[112:127], v[148:151], v[140:143], v[112:127]
	ds_read_b128 v[140:143], v241 offset:7712
	s_waitcnt lgkmcnt(9)
	v_mfma_f32_32x32x16_bf16 v[0:15], v[152:155], v[128:131], v[0:15]
	global_load_dwordx4 v[214:217], v[182:183], off offset:1472
	global_load_dwordx4 v[218:221], v[184:185], off offset:1472
	v_mfma_f32_32x32x16_bf16 v[64:79], v[248:251], v[128:131], v[64:79]
	s_waitcnt lgkmcnt(6)
	v_mfma_f32_32x32x16_bf16 v[16:31], v[152:155], v[132:135], v[16:31]
	global_load_dwordx4 v[222:225], v[186:187], off offset:1472
	global_load_dwordx4 v[228:231], v[188:189], off offset:1472
	v_mfma_f32_32x32x16_bf16 v[80:95], v[248:251], v[132:135], v[80:95]
	s_waitcnt lgkmcnt(3)
	v_mfma_f32_32x32x16_bf16 v[32:47], v[152:155], v[136:139], v[32:47]
	global_load_dwordx4 v[232:235], v[190:191], off offset:1472
	global_load_dwordx4 v[236:239], v[192:193], off offset:1472
	v_mfma_f32_32x32x16_bf16 v[96:111], v[248:251], v[136:139], v[96:111]
	s_waitcnt lgkmcnt(0)
	v_mfma_f32_32x32x16_bf16 v[48:63], v[152:155], v[140:143], v[48:63]
	v_mfma_f32_32x32x16_bf16 v[112:127], v[248:251], v[140:143], v[112:127]
	s_waitcnt lgkmcnt(0)
	s_barrier
	ds_read_b128 v[128:131], v241 offset:30720
	ds_read_b128 v[132:135], v241 offset:33280
	ds_read_b128 v[136:139], v241 offset:35840
	ds_read_b128 v[140:143], v241 offset:38400
	ds_read_b128 v[144:147], v240 offset:30720
	ds_read_b128 v[148:151], v240 offset:33280
	ds_read_b128 v[152:155], v240 offset:30752
	ds_read_b128 v[248:251], v240 offset:33312
	s_waitcnt lgkmcnt(2)
	v_mfma_f32_32x32x16_bf16 v[0:15], v[144:147], v[128:131], v[0:15]
	v_mfma_f32_32x32x16_bf16 v[64:79], v[148:151], v[128:131], v[64:79]
	ds_read_b128 v[128:131], v241 offset:30752
	s_waitcnt vmcnt(6)
	ds_write_b128 v242, v[158:161] offset:0
	ds_write_b128 v242, v[162:165] offset:5120
	v_mfma_f32_32x32x16_bf16 v[16:31], v[144:147], v[132:135], v[16:31]
	v_mfma_f32_32x32x16_bf16 v[80:95], v[148:151], v[132:135], v[80:95]
	ds_read_b128 v[132:135], v241 offset:33312
	ds_write_b128 v242, v[166:169] offset:10240
	ds_write_b128 v242, v[170:173] offset:15360
	v_mfma_f32_32x32x16_bf16 v[32:47], v[144:147], v[136:139], v[32:47]
	v_mfma_f32_32x32x16_bf16 v[96:111], v[148:151], v[136:139], v[96:111]
	ds_read_b128 v[136:139], v241 offset:35872
	ds_write_b128 v242, v[174:177] offset:20480
	ds_write_b128 v242, v[178:181] offset:25600
	v_mfma_f32_32x32x16_bf16 v[48:63], v[144:147], v[140:143], v[48:63]
	v_mfma_f32_32x32x16_bf16 v[112:127], v[148:151], v[140:143], v[112:127]
	ds_read_b128 v[140:143], v241 offset:38432
	s_waitcnt lgkmcnt(9)
	v_mfma_f32_32x32x16_bf16 v[0:15], v[152:155], v[128:131], v[0:15]
	global_load_dwordx4 v[158:161], v[182:183], off offset:1536
	global_load_dwordx4 v[162:165], v[184:185], off offset:1536
	v_mfma_f32_32x32x16_bf16 v[64:79], v[248:251], v[128:131], v[64:79]
	s_waitcnt lgkmcnt(6)
	v_mfma_f32_32x32x16_bf16 v[16:31], v[152:155], v[132:135], v[16:31]
	global_load_dwordx4 v[166:169], v[186:187], off offset:1536
	global_load_dwordx4 v[170:173], v[188:189], off offset:1536
	v_mfma_f32_32x32x16_bf16 v[80:95], v[248:251], v[132:135], v[80:95]
	s_waitcnt lgkmcnt(3)
	v_mfma_f32_32x32x16_bf16 v[32:47], v[152:155], v[136:139], v[32:47]
	global_load_dwordx4 v[174:177], v[190:191], off offset:1536
	global_load_dwordx4 v[178:181], v[192:193], off offset:1536
	v_mfma_f32_32x32x16_bf16 v[96:111], v[248:251], v[136:139], v[96:111]
	s_waitcnt lgkmcnt(0)
	v_mfma_f32_32x32x16_bf16 v[48:63], v[152:155], v[140:143], v[48:63]
	v_mfma_f32_32x32x16_bf16 v[112:127], v[248:251], v[140:143], v[112:127]
	s_waitcnt lgkmcnt(0)
	s_barrier
; #define G_LOAD(S, kt_) do { G_LD1(S##a0, S##b0, 0, kt_); G_LD1(S##a1, S##b1, 1, kt_); G_LD1(S##a2, S##b2, 2, kt_); G_LD1(S##a3, S##b3, 3, kt_); } while (0)
; #define G_STORE(S, buf_) do { G_ST1(S##a0, S##b0, 0, buf_); G_ST1(S##a1, S##b1, 1, buf_); G_ST1(S##a2, S##b2, 2, buf_); G_ST1(S##a3, S##b3, 3, buf_); } while (0)
; template <class AL, class BL>
; DI void gemm_core(AL al, BL bl, int m0, int n0, int K, char* smem, f32x16 (&acc)[2][2]) {
;     ...
;   G_LOAD(x, 0);
;   G_STORE(x, 0);
;   G_LOAD(x, 1);
;   G_LOAD(y, (nk > 2) ? 2 : 1);
;   __syncthreads();
;   for (int kt = 0; kt < nk; kt += 2) {
;     G_TILE(0, x, true, (kt + 3 < nk), kt + 3);
;     __syncthreads();
;     G_TILE(1, y, (kt + 2 < nk), (kt + 4 < nk), kt + 4);
;     __syncthreads();
;   }
	ds_read_b128 v[128:131], v241 offset:0
	ds_read_b128 v[132:135], v241 offset:2560
	ds_read_b128 v[136:139], v241 offset:5120
	ds_read_b128 v[140:143], v241 offset:7680
	ds_read_b128 v[144:147], v240 offset:0
	ds_read_b128 v[148:151], v240 offset:2560
	ds_read_b128 v[152:155], v240 offset:32
	ds_read_b128 v[248:251], v240 offset:2592
	s_waitcnt lgkmcnt(2)
	v_mfma_f32_32x32x16_bf16 v[0:15], v[144:147], v[128:131], v[0:15]
	v_mfma_f32_32x32x16_bf16 v[64:79], v[148:151], v[128:131], v[64:79]
	ds_read_b128 v[128:131], v241 offset:32
	s_waitcnt vmcnt(6)
	ds_write_b128 v242, v[214:217] offset:30720
	ds_write_b128 v242, v[218:221] offset:35840
	v_mfma_f32_32x32x16_bf16 v[16:31], v[144:147], v[132:135], v[16:31]
	v_mfma_f32_32x32x16_bf16 v[80:95], v[148:151], v[132:135], v[80:95]
	ds_read_b128 v[132:135], v241 offset:2592
	ds_write_b128 v242, v[222:225] offset:40960
	ds_write_b128 v242, v[228:231] offset:46080
	v_mfma_f32_32x32x16_bf16 v[32:47], v[144:147], v[136:139], v[32:47]
	v_mfma_f32_32x32x16_bf16 v[96:111], v[148:151], v[136:139], v[96:111]
	ds_read_b128 v[136:139], v241 offset:5152
	ds_write_b128 v242, v[232:235] offset:51200
	ds_write_b128 v242, v[236:239] offset:56320
	v_mfma_f32_32x32x16_bf16 v[48:63], v[144:147], v[140:143], v[48:63]
	v_mfma_f32_32x32x16_bf16 v[112:127], v[148:151], v[140:143], v[112:127]
	ds_read_b128 v[140:143], v241 offset:7712
	s_waitcnt lgkmcnt(9)
	v_mfma_f32_32x32x16_bf16 v[0:15], v[152:155], v[128:131], v[0:15]
	global_load_dwordx4 v[214:217], v[182:183], off offset:1600
	global_load_dwordx4 v[218:221], v[184:185], off offset:1600
	v_mfma_f32_32x32x16_bf16 v[64:79], v[248:251], v[128:131], v[64:79]
	s_waitcnt lgkmcnt(6)
	v_mfma_f32_32x32x16_bf16 v[16:31], v[152:155], v[132:135], v[16:31]
	global_load_dwordx4 v[222:225], v[186:187], off offset:1600
	global_load_dwordx4 v[228:231], v[188:189], off offset:1600
	v_mfma_f32_32x32x16_bf16 v[80:95], v[248:251], v[132:135], v[80:95]
	s_waitcnt lgkmcnt(3)
	v_mfma_f32_32x32x16_bf16 v[32:47], v[152:155], v[136:139], v[32:47]
	global_load_dwordx4 v[232:235], v[190:191], off offset:1600
	global_load_dwordx4 v[236:239], v[192:193], off offset:1600
	v_mfma_f32_32x32x16_bf16 v[96:111], v[248:251], v[136:139], v[96:111]
	s_waitcnt lgkmcnt(0)
	v_mfma_f32_32x32x16_bf16 v[48:63], v[152:155], v[140:143], v[48:63]
	v_mfma_f32_32x32x16_bf16 v[112:127], v[248:251], v[140:143], v[112:127]
	s_waitcnt lgkmcnt(0)
	s_barrier
	ds_read_b128 v[128:131], v241 offset:30720
	ds_read_b128 v[132:135], v241 offset:33280
	ds_read_b128 v[136:139], v241 offset:35840
	ds_read_b128 v[140:143], v241 offset:38400
	ds_read_b128 v[144:147], v240 offset:30720
	ds_read_b128 v[148:151], v240 offset:33280
	ds_read_b128 v[152:155], v240 offset:30752
	ds_read_b128 v[248:251], v240 offset:33312
	s_waitcnt lgkmcnt(2)
	v_mfma_f32_32x32x16_bf16 v[0:15], v[144:147], v[128:131], v[0:15]
	v_mfma_f32_32x32x16_bf16 v[64:79], v[148:151], v[128:131], v[64:79]
	ds_read_b128 v[128:131], v241 offset:30752
	s_waitcnt vmcnt(6)
	ds_write_b128 v242, v[158:161] offset:0
	ds_write_b128 v242, v[162:165] offset:5120
	v_mfma_f32_32x32x16_bf16 v[16:31], v[144:147], v[132:135], v[16:31]
	v_mfma_f32_32x32x16_bf16 v[80:95], v[148:151], v[132:135], v[80:95]
	ds_read_b128 v[132:135], v241 offset:33312
	ds_write_b128 v242, v[166:169] offset:10240
	ds_write_b128 v242, v[170:173] offset:15360
	v_mfma_f32_32x32x16_bf16 v[32:47], v[144:147], v[136:139], v[32:47]
	v_mfma_f32_32x32x16_bf16 v[96:111], v[148:151], v[136:139], v[96:111]
	ds_read_b128 v[136:139], v241 offset:35872
	ds_write_b128 v242, v[174:177] offset:20480
	ds_write_b128 v242, v[178:181] offset:25600
	v_mfma_f32_32x32x16_bf16 v[48:63], v[144:147], v[140:143], v[48:63]
	v_mfma_f32_32x32x16_bf16 v[112:127], v[148:151], v[140:143], v[112:127]
	ds_read_b128 v[140:143], v241 offset:38432
	s_waitcnt lgkmcnt(9)
	v_mfma_f32_32x32x16_bf16 v[0:15], v[152:155], v[128:131], v[0:15]
	global_load_dwordx4 v[158:161], v[182:183], off offset:1664
	global_load_dwordx4 v[162:165], v[184:185], off offset:1664
	v_mfma_f32_32x32x16_bf16 v[64:79], v[248:251], v[128:131], v[64:79]
	s_waitcnt lgkmcnt(6)
	v_mfma_f32_32x32x16_bf16 v[16:31], v[152:155], v[132:135], v[16:31]
	global_load_dwordx4 v[166:169], v[186:187], off offset:1664
	global_load_dwordx4 v[170:173], v[188:189], off offset:1664
	v_mfma_f32_32x32x16_bf16 v[80:95], v[248:251], v[132:135], v[80:95]
	s_waitcnt lgkmcnt(3)
	v_mfma_f32_32x32x16_bf16 v[32:47], v[152:155], v[136:139], v[32:47]
	global_load_dwordx4 v[174:177], v[190:191], off offset:1664
	global_load_dwordx4 v[178:181], v[192:193], off offset:1664
	v_mfma_f32_32x32x16_bf16 v[96:111], v[248:251], v[136:139], v[96:111]
	s_waitcnt lgkmcnt(0)
	v_mfma_f32_32x32x16_bf16 v[48:63], v[152:155], v[140:143], v[48:63]
	v_mfma_f32_32x32x16_bf16 v[112:127], v[248:251], v[140:143], v[112:127]
	s_waitcnt lgkmcnt(0)
	s_barrier
; #define G_LOAD(S, kt_) do { G_LD1(S##a0, S##b0, 0, kt_); G_LD1(S##a1, S##b1, 1, kt_); G_LD1(S##a2, S##b2, 2, kt_); G_LD1(S##a3, S##b3, 3, kt_); } while (0)
; #define G_STORE(S, buf_) do { G_ST1(S##a0, S##b0, 0, buf_); G_ST1(S##a1, S##b1, 1, buf_); G_ST1(S##a2, S##b2, 2, buf_); G_ST1(S##a3, S##b3, 3, buf_); } while (0)
; template <class AL, class BL>
; DI void gemm_core(AL al, BL bl, int m0, int n0, int K, char* smem, f32x16 (&acc)[2][2]) {
;     ...
;   G_LOAD(x, 0);
;   G_STORE(x, 0);
;   G_LOAD(x, 1);
;   G_LOAD(y, (nk > 2) ? 2 : 1);
;   __syncthreads();
;   for (int kt = 0; kt < nk; kt += 2) {
;     G_TILE(0, x, true, (kt + 3 < nk), kt + 3);
;     __syncthreads();
;     G_TILE(1, y, (kt + 2 < nk), (kt + 4 < nk), kt + 4);
;     __syncthreads();
;   }
	ds_read_b128 v[128:131], v241 offset:0
	ds_read_b128 v[132:135], v241 offset:2560
	ds_read_b128 v[136:139], v241 offset:5120
	ds_read_b128 v[140:143], v241 offset:7680
	ds_read_b128 v[144:147], v240 offset:0
	ds_read_b128 v[148:151], v240 offset:2560
	ds_read_b128 v[152:155], v240 offset:32
	ds_read_b128 v[248:251], v240 offset:2592
	s_waitcnt lgkmcnt(2)
	v_mfma_f32_32x32x16_bf16 v[0:15], v[144:147], v[128:131], v[0:15]
	v_mfma_f32_32x32x16_bf16 v[64:79], v[148:151], v[128:131], v[64:79]
	ds_read_b128 v[128:131], v241 offset:32
	s_waitcnt vmcnt(6)
	ds_write_b128 v242, v[214:217] offset:30720
	ds_write_b128 v242, v[218:221] offset:35840
	v_mfma_f32_32x32x16_bf16 v[16:31], v[144:147], v[132:135], v[16:31]
	v_mfma_f32_32x32x16_bf16 v[80:95], v[148:151], v[132:135], v[80:95]
	ds_read_b128 v[132:135], v241 offset:2592
	ds_write_b128 v242, v[222:225] offset:40960
	ds_write_b128 v242, v[228:231] offset:46080
	v_mfma_f32_32x32x16_bf16 v[32:47], v[144:147], v[136:139], v[32:47]
	v_mfma_f32_32x32x16_bf16 v[96:111], v[148:151], v[136:139], v[96:111]
	ds_read_b128 v[136:139], v241 offset:5152
	ds_write_b128 v242, v[232:235] offset:51200
	ds_write_b128 v242, v[236:239] offset:56320
	v_mfma_f32_32x32x16_bf16 v[48:63], v[144:147], v[140:143], v[48:63]
	v_mfma_f32_32x32x16_bf16 v[112:127], v[148:151], v[140:143], v[112:127]
	ds_read_b128 v[140:143], v241 offset:7712
	s_waitcnt lgkmcnt(9)
	v_mfma_f32_32x32x16_bf16 v[0:15], v[152:155], v[128:131], v[0:15]
	global_load_dwordx4 v[214:217], v[182:183], off offset:1728
	global_load_dwordx4 v[218:221], v[184:185], off offset:1728
	v_mfma_f32_32x32x16_bf16 v[64:79], v[248:251], v[128:131], v[64:79]
	s_waitcnt lgkmcnt(6)
	v_mfma_f32_32x32x16_bf16 v[16:31], v[152:155], v[132:135], v[16:31]
	global_load_dwordx4 v[222:225], v[186:187], off offset:1728
	global_load_dwordx4 v[228:231], v[188:189], off offset:1728
	v_mfma_f32_32x32x16_bf16 v[80:95], v[248:251], v[132:135], v[80:95]
	s_waitcnt lgkmcnt(3)
	v_mfma_f32_32x32x16_bf16 v[32:47], v[152:155], v[136:139], v[32:47]
	global_load_dwordx4 v[232:235], v[190:191], off offset:1728
	global_load_dwordx4 v[236:239], v[192:193], off offset:1728
	v_mfma_f32_32x32x16_bf16 v[96:111], v[248:251], v[136:139], v[96:111]
	s_waitcnt lgkmcnt(0)
	v_mfma_f32_32x32x16_bf16 v[48:63], v[152:155], v[140:143], v[48:63]
	v_mfma_f32_32x32x16_bf16 v[112:127], v[248:251], v[140:143], v[112:127]
	s_waitcnt lgkmcnt(0)
	s_barrier
	ds_read_b128 v[128:131], v241 offset:30720
	ds_read_b128 v[132:135], v241 offset:33280
	ds_read_b128 v[136:139], v241 offset:35840
	ds_read_b128 v[140:143], v241 offset:38400
	ds_read_b128 v[144:147], v240 offset:30720
	ds_read_b128 v[148:151], v240 offset:33280
	ds_read_b128 v[152:155], v240 offset:30752
	ds_read_b128 v[248:251], v240 offset:33312
	s_waitcnt lgkmcnt(2)
	v_mfma_f32_32x32x16_bf16 v[0:15], v[144:147], v[128:131], v[0:15]
	v_mfma_f32_32x32x16_bf16 v[64:79], v[148:151], v[128:131], v[64:79]
	ds_read_b128 v[128:131], v241 offset:30752
	s_waitcnt vmcnt(6)
	ds_write_b128 v242, v[158:161] offset:0
	ds_write_b128 v242, v[162:165] offset:5120
	v_mfma_f32_32x32x16_bf16 v[16:31], v[144:147], v[132:135], v[16:31]
	v_mfma_f32_32x32x16_bf16 v[80:95], v[148:151], v[132:135], v[80:95]
	ds_read_b128 v[132:135], v241 offset:33312
	ds_write_b128 v242, v[166:169] offset:10240
	ds_write_b128 v242, v[170:173] offset:15360
	v_mfma_f32_32x32x16_bf16 v[32:47], v[144:147], v[136:139], v[32:47]
	v_mfma_f32_32x32x16_bf16 v[96:111], v[148:151], v[136:139], v[96:111]
	ds_read_b128 v[136:139], v241 offset:35872
	ds_write_b128 v242, v[174:177] offset:20480
	ds_write_b128 v242, v[178:181] offset:25600
	v_mfma_f32_32x32x16_bf16 v[48:63], v[144:147], v[140:143], v[48:63]
	v_mfma_f32_32x32x16_bf16 v[112:127], v[148:151], v[140:143], v[112:127]
	ds_read_b128 v[140:143], v241 offset:38432
	s_waitcnt lgkmcnt(9)
	v_mfma_f32_32x32x16_bf16 v[0:15], v[152:155], v[128:131], v[0:15]
	global_load_dwordx4 v[158:161], v[182:183], off offset:1792
	global_load_dwordx4 v[162:165], v[184:185], off offset:1792
	v_mfma_f32_32x32x16_bf16 v[64:79], v[248:251], v[128:131], v[64:79]
	s_waitcnt lgkmcnt(6)
	v_mfma_f32_32x32x16_bf16 v[16:31], v[152:155], v[132:135], v[16:31]
	global_load_dwordx4 v[166:169], v[186:187], off offset:1792
	global_load_dwordx4 v[170:173], v[188:189], off offset:1792
	v_mfma_f32_32x32x16_bf16 v[80:95], v[248:251], v[132:135], v[80:95]
	s_waitcnt lgkmcnt(3)
	v_mfma_f32_32x32x16_bf16 v[32:47], v[152:155], v[136:139], v[32:47]
	global_load_dwordx4 v[174:177], v[190:191], off offset:1792
	global_load_dwordx4 v[178:181], v[192:193], off offset:1792
	v_mfma_f32_32x32x16_bf16 v[96:111], v[248:251], v[136:139], v[96:111]
	s_waitcnt lgkmcnt(0)
	v_mfma_f32_32x32x16_bf16 v[48:63], v[152:155], v[140:143], v[48:63]
	v_mfma_f32_32x32x16_bf16 v[112:127], v[248:251], v[140:143], v[112:127]
	s_waitcnt lgkmcnt(0)
	s_barrier
; #define G_LOAD(S, kt_) do { G_LD1(S##a0, S##b0, 0, kt_); G_LD1(S##a1, S##b1, 1, kt_); G_LD1(S##a2, S##b2, 2, kt_); G_LD1(S##a3, S##b3, 3, kt_); } while (0)
; #define G_STORE(S, buf_) do { G_ST1(S##a0, S##b0, 0, buf_); G_ST1(S##a1, S##b1, 1, buf_); G_ST1(S##a2, S##b2, 2, buf_); G_ST1(S##a3, S##b3, 3, buf_); } while (0)
; template <class AL, class BL>
; DI void gemm_core(AL al, BL bl, int m0, int n0, int K, char* smem, f32x16 (&acc)[2][2]) {
;     ...
;   G_LOAD(x, 0);
;   G_STORE(x, 0);
;   G_LOAD(x, 1);
;   G_LOAD(y, (nk > 2) ? 2 : 1);
;   __syncthreads();
;   for (int kt = 0; kt < nk; kt += 2) {
;     G_TILE(0, x, true, (kt + 3 < nk), kt + 3);
;     __syncthreads();
;     G_TILE(1, y, (kt + 2 < nk), (kt + 4 < nk), kt + 4);
;     __syncthreads();
;   }
	ds_read_b128 v[128:131], v241 offset:0
	ds_read_b128 v[132:135], v241 offset:2560
	ds_read_b128 v[136:139], v241 offset:5120
	ds_read_b128 v[140:143], v241 offset:7680
	ds_read_b128 v[144:147], v240 offset:0
	ds_read_b128 v[148:151], v240 offset:2560
	ds_read_b128 v[152:155], v240 offset:32
	ds_read_b128 v[248:251], v240 offset:2592
	s_waitcnt lgkmcnt(2)
	v_mfma_f32_32x32x16_bf16 v[0:15], v[144:147], v[128:131], v[0:15]
	v_mfma_f32_32x32x16_bf16 v[64:79], v[148:151], v[128:131], v[64:79]
	ds_read_b128 v[128:131], v241 offset:32
	s_waitcnt vmcnt(6)
	ds_write_b128 v242, v[214:217] offset:30720
	ds_write_b128 v242, v[218:221] offset:35840
	v_mfma_f32_32x32x16_bf16 v[16:31], v[144:147], v[132:135], v[16:31]
	v_mfma_f32_32x32x16_bf16 v[80:95], v[148:151], v[132:135], v[80:95]
	ds_read_b128 v[132:135], v241 offset:2592
	ds_write_b128 v242, v[222:225] offset:40960
	ds_write_b128 v242, v[228:231] offset:46080
	v_mfma_f32_32x32x16_bf16 v[32:47], v[144:147], v[136:139], v[32:47]
	v_mfma_f32_32x32x16_bf16 v[96:111], v[148:151], v[136:139], v[96:111]
	ds_read_b128 v[136:139], v241 offset:5152
	ds_write_b128 v242, v[232:235] offset:51200
	ds_write_b128 v242, v[236:239] offset:56320
	v_mfma_f32_32x32x16_bf16 v[48:63], v[144:147], v[140:143], v[48:63]
	v_mfma_f32_32x32x16_bf16 v[112:127], v[148:151], v[140:143], v[112:127]
	ds_read_b128 v[140:143], v241 offset:7712
	s_waitcnt lgkmcnt(9)
	v_mfma_f32_32x32x16_bf16 v[0:15], v[152:155], v[128:131], v[0:15]
	global_load_dwordx4 v[214:217], v[182:183], off offset:1856
	global_load_dwordx4 v[218:221], v[184:185], off offset:1856
	v_mfma_f32_32x32x16_bf16 v[64:79], v[248:251], v[128:131], v[64:79]
	s_waitcnt lgkmcnt(6)
	v_mfma_f32_32x32x16_bf16 v[16:31], v[152:155], v[132:135], v[16:31]
	global_load_dwordx4 v[222:225], v[186:187], off offset:1856
	global_load_dwordx4 v[228:231], v[188:189], off offset:1856
	v_mfma_f32_32x32x16_bf16 v[80:95], v[248:251], v[132:135], v[80:95]
	s_waitcnt lgkmcnt(3)
	v_mfma_f32_32x32x16_bf16 v[32:47], v[152:155], v[136:139], v[32:47]
	global_load_dwordx4 v[232:235], v[190:191], off offset:1856
	global_load_dwordx4 v[236:239], v[192:193], off offset:1856
	v_mfma_f32_32x32x16_bf16 v[96:111], v[248:251], v[136:139], v[96:111]
	s_waitcnt lgkmcnt(0)
	v_mfma_f32_32x32x16_bf16 v[48:63], v[152:155], v[140:143], v[48:63]
	v_mfma_f32_32x32x16_bf16 v[112:127], v[248:251], v[140:143], v[112:127]
	s_waitcnt lgkmcnt(0)
	s_barrier
	ds_read_b128 v[128:131], v241 offset:30720
	ds_read_b128 v[132:135], v241 offset:33280
	ds_read_b128 v[136:139], v241 offset:35840
	ds_read_b128 v[140:143], v241 offset:38400
	ds_read_b128 v[144:147], v240 offset:30720
	ds_read_b128 v[148:151], v240 offset:33280
	ds_read_b128 v[152:155], v240 offset:30752
	ds_read_b128 v[248:251], v240 offset:33312
	s_waitcnt lgkmcnt(2)
	v_mfma_f32_32x32x16_bf16 v[0:15], v[144:147], v[128:131], v[0:15]
	v_mfma_f32_32x32x16_bf16 v[64:79], v[148:151], v[128:131], v[64:79]
	ds_read_b128 v[128:131], v241 offset:30752
	s_waitcnt vmcnt(6)
	ds_write_b128 v242, v[158:161] offset:0
	ds_write_b128 v242, v[162:165] offset:5120
	v_mfma_f32_32x32x16_bf16 v[16:31], v[144:147], v[132:135], v[16:31]
	v_mfma_f32_32x32x16_bf16 v[80:95], v[148:151], v[132:135], v[80:95]
	ds_read_b128 v[132:135], v241 offset:33312
	ds_write_b128 v242, v[166:169] offset:10240
	ds_write_b128 v242, v[170:173] offset:15360
	v_mfma_f32_32x32x16_bf16 v[32:47], v[144:147], v[136:139], v[32:47]
	v_mfma_f32_32x32x16_bf16 v[96:111], v[148:151], v[136:139], v[96:111]
	ds_read_b128 v[136:139], v241 offset:35872
	ds_write_b128 v242, v[174:177] offset:20480
	ds_write_b128 v242, v[178:181] offset:25600
	v_mfma_f32_32x32x16_bf16 v[48:63], v[144:147], v[140:143], v[48:63]
	v_mfma_f32_32x32x16_bf16 v[112:127], v[148:151], v[140:143], v[112:127]
	ds_read_b128 v[140:143], v241 offset:38432
	s_waitcnt lgkmcnt(9)
	v_mfma_f32_32x32x16_bf16 v[0:15], v[152:155], v[128:131], v[0:15]
	global_load_dwordx4 v[158:161], v[182:183], off offset:1920
	global_load_dwordx4 v[162:165], v[184:185], off offset:1920
	v_mfma_f32_32x32x16_bf16 v[64:79], v[248:251], v[128:131], v[64:79]
	s_waitcnt lgkmcnt(6)
	v_mfma_f32_32x32x16_bf16 v[16:31], v[152:155], v[132:135], v[16:31]
	global_load_dwordx4 v[166:169], v[186:187], off offset:1920
	global_load_dwordx4 v[170:173], v[188:189], off offset:1920
	v_mfma_f32_32x32x16_bf16 v[80:95], v[248:251], v[132:135], v[80:95]
	s_waitcnt lgkmcnt(3)
	v_mfma_f32_32x32x16_bf16 v[32:47], v[152:155], v[136:139], v[32:47]
	global_load_dwordx4 v[174:177], v[190:191], off offset:1920
	global_load_dwordx4 v[178:181], v[192:193], off offset:1920
	v_mfma_f32_32x32x16_bf16 v[96:111], v[248:251], v[136:139], v[96:111]
	s_waitcnt lgkmcnt(0)
	v_mfma_f32_32x32x16_bf16 v[48:63], v[152:155], v[140:143], v[48:63]
	v_mfma_f32_32x32x16_bf16 v[112:127], v[248:251], v[140:143], v[112:127]
	s_waitcnt lgkmcnt(0)
	s_barrier
; #define G_LOAD(S, kt_) do { G_LD1(S##a0, S##b0, 0, kt_); G_LD1(S##a1, S##b1, 1, kt_); G_LD1(S##a2, S##b2, 2, kt_); G_LD1(S##a3, S##b3, 3, kt_); } while (0)
; #define G_STORE(S, buf_) do { G_ST1(S##a0, S##b0, 0, buf_); G_ST1(S##a1, S##b1, 1, buf_); G_ST1(S##a2, S##b2, 2, buf_); G_ST1(S##a3, S##b3, 3, buf_); } while (0)
; template <class AL, class BL>
; DI void gemm_core(AL al, BL bl, int m0, int n0, int K, char* smem, f32x16 (&acc)[2][2]) {
;     ...
;   G_LOAD(x, 0);
;   G_STORE(x, 0);
;   G_LOAD(x, 1);
;   G_LOAD(y, (nk > 2) ? 2 : 1);
;   __syncthreads();
;   for (int kt = 0; kt < nk; kt += 2) {
;     G_TILE(0, x, true, (kt + 3 < nk), kt + 3);
;     __syncthreads();
;     G_TILE(1, y, (kt + 2 < nk), (kt + 4 < nk), kt + 4);
;     __syncthreads();
;   }
	ds_read_b128 v[128:131], v241 offset:0
	ds_read_b128 v[132:135], v241 offset:2560
	ds_read_b128 v[136:139], v241 offset:5120
	ds_read_b128 v[140:143], v241 offset:7680
	ds_read_b128 v[144:147], v240 offset:0
	ds_read_b128 v[148:151], v240 offset:2560
	ds_read_b128 v[152:155], v240 offset:32
	ds_read_b128 v[248:251], v240 offset:2592
	s_waitcnt lgkmcnt(2)
	v_mfma_f32_32x32x16_bf16 v[0:15], v[144:147], v[128:131], v[0:15]
	v_mfma_f32_32x32x16_bf16 v[64:79], v[148:151], v[128:131], v[64:79]
	ds_read_b128 v[128:131], v241 offset:32
	s_waitcnt vmcnt(6)
	ds_write_b128 v242, v[214:217] offset:30720
	ds_write_b128 v242, v[218:221] offset:35840
	v_mfma_f32_32x32x16_bf16 v[16:31], v[144:147], v[132:135], v[16:31]
	v_mfma_f32_32x32x16_bf16 v[80:95], v[148:151], v[132:135], v[80:95]
	ds_read_b128 v[132:135], v241 offset:2592
	ds_write_b128 v242, v[222:225] offset:40960
	ds_write_b128 v242, v[228:231] offset:46080
	v_mfma_f32_32x32x16_bf16 v[32:47], v[144:147], v[136:139], v[32:47]
	v_mfma_f32_32x32x16_bf16 v[96:111], v[148:151], v[136:139], v[96:111]
	ds_read_b128 v[136:139], v241 offset:5152
	ds_write_b128 v242, v[232:235] offset:51200
	ds_write_b128 v242, v[236:239] offset:56320
	v_mfma_f32_32x32x16_bf16 v[48:63], v[144:147], v[140:143], v[48:63]
	v_mfma_f32_32x32x16_bf16 v[112:127], v[148:151], v[140:143], v[112:127]
	ds_read_b128 v[140:143], v241 offset:7712
	s_waitcnt lgkmcnt(9)
	v_mfma_f32_32x32x16_bf16 v[0:15], v[152:155], v[128:131], v[0:15]
	global_load_dwordx4 v[214:217], v[182:183], off offset:1984
	global_load_dwordx4 v[218:221], v[184:185], off offset:1984
	v_mfma_f32_32x32x16_bf16 v[64:79], v[248:251], v[128:131], v[64:79]
	s_waitcnt lgkmcnt(6)
	v_mfma_f32_32x32x16_bf16 v[16:31], v[152:155], v[132:135], v[16:31]
	global_load_dwordx4 v[222:225], v[186:187], off offset:1984
	global_load_dwordx4 v[228:231], v[188:189], off offset:1984
	v_mfma_f32_32x32x16_bf16 v[80:95], v[248:251], v[132:135], v[80:95]
	s_waitcnt lgkmcnt(3)
	v_mfma_f32_32x32x16_bf16 v[32:47], v[152:155], v[136:139], v[32:47]
	global_load_dwordx4 v[232:235], v[190:191], off offset:1984
	global_load_dwordx4 v[236:239], v[192:193], off offset:1984
	v_mfma_f32_32x32x16_bf16 v[96:111], v[248:251], v[136:139], v[96:111]
	s_waitcnt lgkmcnt(0)
	v_mfma_f32_32x32x16_bf16 v[48:63], v[152:155], v[140:143], v[48:63]
	v_mfma_f32_32x32x16_bf16 v[112:127], v[248:251], v[140:143], v[112:127]
	s_waitcnt lgkmcnt(0)
	s_barrier
	ds_read_b128 v[128:131], v241 offset:30720
	ds_read_b128 v[132:135], v241 offset:33280
	ds_read_b128 v[136:139], v241 offset:35840
	ds_read_b128 v[140:143], v241 offset:38400
	ds_read_b128 v[144:147], v240 offset:30720
	ds_read_b128 v[148:151], v240 offset:33280
	ds_read_b128 v[152:155], v240 offset:30752
	ds_read_b128 v[248:251], v240 offset:33312
	s_waitcnt lgkmcnt(2)
	v_mfma_f32_32x32x16_bf16 v[0:15], v[144:147], v[128:131], v[0:15]
	v_mfma_f32_32x32x16_bf16 v[64:79], v[148:151], v[128:131], v[64:79]
	ds_read_b128 v[128:131], v241 offset:30752
	s_waitcnt vmcnt(6)
	ds_write_b128 v242, v[158:161] offset:0
	ds_write_b128 v242, v[162:165] offset:5120
	v_mfma_f32_32x32x16_bf16 v[16:31], v[144:147], v[132:135], v[16:31]
	v_mfma_f32_32x32x16_bf16 v[80:95], v[148:151], v[132:135], v[80:95]
	ds_read_b128 v[132:135], v241 offset:33312
	ds_write_b128 v242, v[166:169] offset:10240
	ds_write_b128 v242, v[170:173] offset:15360
	v_mfma_f32_32x32x16_bf16 v[32:47], v[144:147], v[136:139], v[32:47]
	v_mfma_f32_32x32x16_bf16 v[96:111], v[148:151], v[136:139], v[96:111]
	ds_read_b128 v[136:139], v241 offset:35872
	ds_write_b128 v242, v[174:177] offset:20480
	ds_write_b128 v242, v[178:181] offset:25600
	v_mfma_f32_32x32x16_bf16 v[48:63], v[144:147], v[140:143], v[48:63]
	v_mfma_f32_32x32x16_bf16 v[112:127], v[148:151], v[140:143], v[112:127]
	ds_read_b128 v[140:143], v241 offset:38432
	s_waitcnt lgkmcnt(9)
	v_mfma_f32_32x32x16_bf16 v[0:15], v[152:155], v[128:131], v[0:15]
	global_load_dwordx4 v[158:161], v[182:183], off offset:2048
	global_load_dwordx4 v[162:165], v[184:185], off offset:2048
	v_mfma_f32_32x32x16_bf16 v[64:79], v[248:251], v[128:131], v[64:79]
	s_waitcnt lgkmcnt(6)
	v_mfma_f32_32x32x16_bf16 v[16:31], v[152:155], v[132:135], v[16:31]
	global_load_dwordx4 v[166:169], v[186:187], off offset:2048
	global_load_dwordx4 v[170:173], v[188:189], off offset:2048
	v_mfma_f32_32x32x16_bf16 v[80:95], v[248:251], v[132:135], v[80:95]
	s_waitcnt lgkmcnt(3)
	v_mfma_f32_32x32x16_bf16 v[32:47], v[152:155], v[136:139], v[32:47]
	global_load_dwordx4 v[174:177], v[190:191], off offset:2048
	global_load_dwordx4 v[178:181], v[192:193], off offset:2048
	v_mfma_f32_32x32x16_bf16 v[96:111], v[248:251], v[136:139], v[96:111]
	s_waitcnt lgkmcnt(0)
	v_mfma_f32_32x32x16_bf16 v[48:63], v[152:155], v[140:143], v[48:63]
	v_mfma_f32_32x32x16_bf16 v[112:127], v[248:251], v[140:143], v[112:127]
	s_waitcnt lgkmcnt(0)
	s_barrier
; template <class AL, class BL>
; DI void gemm_core(AL al, BL bl, int m0, int n0, int K, char* smem, f32x16 (&acc)[2][2]) {
;     ...
;   for (int kt = 0; kt < nk; kt += 2) {
;     G_TILE(0, x, true, (kt + 3 < nk), kt + 3);
;     __syncthreads();
;     G_TILE(1, y, (kt + 2 < nk), (kt + 4 < nk), kt + 4);
;     __syncthreads();
;   }
	ds_read_b128 v[128:131], v241 offset:0
	ds_read_b128 v[132:135], v241 offset:2560
	ds_read_b128 v[136:139], v241 offset:5120
	ds_read_b128 v[140:143], v241 offset:7680
	ds_read_b128 v[144:147], v240 offset:0
	ds_read_b128 v[148:151], v240 offset:2560
	ds_read_b128 v[152:155], v240 offset:32
	ds_read_b128 v[248:251], v240 offset:2592
	s_waitcnt lgkmcnt(2)
	v_mfma_f32_32x32x16_bf16 v[0:15], v[144:147], v[128:131], v[0:15]
	v_mfma_f32_32x32x16_bf16 v[64:79], v[148:151], v[128:131], v[64:79]
	ds_read_b128 v[128:131], v241 offset:32
	s_waitcnt vmcnt(6)
	ds_write_b128 v242, v[214:217] offset:30720
	ds_write_b128 v242, v[218:221] offset:35840
	v_mfma_f32_32x32x16_bf16 v[16:31], v[144:147], v[132:135], v[16:31]
	v_mfma_f32_32x32x16_bf16 v[80:95], v[148:151], v[132:135], v[80:95]
	ds_read_b128 v[132:135], v241 offset:2592
	ds_write_b128 v242, v[222:225] offset:40960
	ds_write_b128 v242, v[228:231] offset:46080
	v_mfma_f32_32x32x16_bf16 v[32:47], v[144:147], v[136:139], v[32:47]
	v_mfma_f32_32x32x16_bf16 v[96:111], v[148:151], v[136:139], v[96:111]
	ds_read_b128 v[136:139], v241 offset:5152
	ds_write_b128 v242, v[232:235] offset:51200
	ds_write_b128 v242, v[236:239] offset:56320
	v_mfma_f32_32x32x16_bf16 v[48:63], v[144:147], v[140:143], v[48:63]
	v_mfma_f32_32x32x16_bf16 v[112:127], v[148:151], v[140:143], v[112:127]
	ds_read_b128 v[140:143], v241 offset:7712
	s_waitcnt lgkmcnt(9)
	v_mfma_f32_32x32x16_bf16 v[0:15], v[152:155], v[128:131], v[0:15]
	global_load_dwordx4 v[214:217], v[182:183], off offset:2112
	global_load_dwordx4 v[218:221], v[184:185], off offset:2112
	v_mfma_f32_32x32x16_bf16 v[64:79], v[248:251], v[128:131], v[64:79]
	s_waitcnt lgkmcnt(6)
	v_mfma_f32_32x32x16_bf16 v[16:31], v[152:155], v[132:135], v[16:31]
	global_load_dwordx4 v[222:225], v[186:187], off offset:2112
	global_load_dwordx4 v[228:231], v[188:189], off offset:2112
	v_mfma_f32_32x32x16_bf16 v[80:95], v[248:251], v[132:135], v[80:95]
	s_waitcnt lgkmcnt(3)
	v_mfma_f32_32x32x16_bf16 v[32:47], v[152:155], v[136:139], v[32:47]
	global_load_dwordx4 v[232:235], v[190:191], off offset:2112
	global_load_dwordx4 v[236:239], v[192:193], off offset:2112
	v_mfma_f32_32x32x16_bf16 v[96:111], v[248:251], v[136:139], v[96:111]
	s_waitcnt lgkmcnt(0)
	v_mfma_f32_32x32x16_bf16 v[48:63], v[152:155], v[140:143], v[48:63]
	v_mfma_f32_32x32x16_bf16 v[112:127], v[248:251], v[140:143], v[112:127]
	s_waitcnt lgkmcnt(0)
	s_barrier
	ds_read_b128 v[128:131], v241 offset:30720
	ds_read_b128 v[132:135], v241 offset:33280
	ds_read_b128 v[136:139], v241 offset:35840
	ds_read_b128 v[140:143], v241 offset:38400
	ds_read_b128 v[144:147], v240 offset:30720
	ds_read_b128 v[148:151], v240 offset:33280
	ds_read_b128 v[152:155], v240 offset:30752
	ds_read_b128 v[248:251], v240 offset:33312
	s_waitcnt lgkmcnt(2)
	v_mfma_f32_32x32x16_bf16 v[0:15], v[144:147], v[128:131], v[0:15]
	v_mfma_f32_32x32x16_bf16 v[64:79], v[148:151], v[128:131], v[64:79]
	ds_read_b128 v[128:131], v241 offset:30752
	s_waitcnt vmcnt(6)
	ds_write_b128 v242, v[158:161] offset:0
	ds_write_b128 v242, v[162:165] offset:5120
	v_mfma_f32_32x32x16_bf16 v[16:31], v[144:147], v[132:135], v[16:31]
	v_mfma_f32_32x32x16_bf16 v[80:95], v[148:151], v[132:135], v[80:95]
	ds_read_b128 v[132:135], v241 offset:33312
	ds_write_b128 v242, v[166:169] offset:10240
	ds_write_b128 v242, v[170:173] offset:15360
	v_mfma_f32_32x32x16_bf16 v[32:47], v[144:147], v[136:139], v[32:47]
	v_mfma_f32_32x32x16_bf16 v[96:111], v[148:151], v[136:139], v[96:111]
	ds_read_b128 v[136:139], v241 offset:35872
	ds_write_b128 v242, v[174:177] offset:20480
	ds_write_b128 v242, v[178:181] offset:25600
	v_mfma_f32_32x32x16_bf16 v[48:63], v[144:147], v[140:143], v[48:63]
	v_mfma_f32_32x32x16_bf16 v[112:127], v[148:151], v[140:143], v[112:127]
	ds_read_b128 v[140:143], v241 offset:38432
	s_waitcnt lgkmcnt(9)
	v_mfma_f32_32x32x16_bf16 v[0:15], v[152:155], v[128:131], v[0:15]
	global_load_dwordx4 v[158:161], v[182:183], off offset:2176
	global_load_dwordx4 v[162:165], v[184:185], off offset:2176
	v_mfma_f32_32x32x16_bf16 v[64:79], v[248:251], v[128:131], v[64:79]
	s_waitcnt lgkmcnt(6)
	v_mfma_f32_32x32x16_bf16 v[16:31], v[152:155], v[132:135], v[16:31]
	global_load_dwordx4 v[166:169], v[186:187], off offset:2176
	global_load_dwordx4 v[170:173], v[188:189], off offset:2176
	v_mfma_f32_32x32x16_bf16 v[80:95], v[248:251], v[132:135], v[80:95]
	s_waitcnt lgkmcnt(3)
	v_mfma_f32_32x32x16_bf16 v[32:47], v[152:155], v[136:139], v[32:47]
	global_load_dwordx4 v[174:177], v[190:191], off offset:2176
	global_load_dwordx4 v[178:181], v[192:193], off offset:2176
	v_mfma_f32_32x32x16_bf16 v[96:111], v[248:251], v[136:139], v[96:111]
	s_waitcnt lgkmcnt(0)
	v_mfma_f32_32x32x16_bf16 v[48:63], v[152:155], v[140:143], v[48:63]
	v_mfma_f32_32x32x16_bf16 v[112:127], v[248:251], v[140:143], v[112:127]
	s_waitcnt lgkmcnt(0)
	s_barrier
	s_sub_u32 s41, s41, 1
	s_cmp_lg_u32 s41, 0
	s_cbranch_scc1 .Lfd0_kloop
; #define G_LOAD(S, kt_) do { G_LD1(S##a0, S##b0, 0, kt_); G_LD1(S##a1, S##b1, 1, kt_); G_LD1(S##a2, S##b2, 2, kt_); G_LD1(S##a3, S##b3, 3, kt_); } while (0)
; #define G_STORE(S, buf_) do { G_ST1(S##a0, S##b0, 0, buf_); G_ST1(S##a1, S##b1, 1, buf_); G_ST1(S##a2, S##b2, 2, buf_); G_ST1(S##a3, S##b3, 3, buf_); } while (0)
; template <class AL, class BL>
; DI void gemm_core(AL al, BL bl, int m0, int n0, int K, char* smem, f32x16 (&acc)[2][2]) {
;     ...
;   G_LOAD(x, 0);
;   G_STORE(x, 0);
;   G_LOAD(x, 1);
;   G_LOAD(y, (nk > 2) ? 2 : 1);
;   __syncthreads();
;   for (int kt = 0; kt < nk; kt += 2) {
;     G_TILE(0, x, true, (kt + 3 < nk), kt + 3);
;     __syncthreads();
;     G_TILE(1, y, (kt + 2 < nk), (kt + 4 < nk), kt + 4);
;     __syncthreads();
;   }
	v_lshl_add_u64 v[182:183], v[182:183], 0, s[2:3]
	v_lshl_add_u64 v[184:185], v[184:185], 0, s[2:3]
	v_lshl_add_u64 v[186:187], v[186:187], 0, s[2:3]
	v_lshl_add_u64 v[188:189], v[188:189], 0, s[2:3]
	v_lshl_add_u64 v[190:191], v[190:191], 0, s[2:3]
	v_lshl_add_u64 v[192:193], v[192:193], 0, s[2:3]
	ds_read_b128 v[128:131], v241 offset:0
	ds_read_b128 v[132:135], v241 offset:2560
	ds_read_b128 v[136:139], v241 offset:5120
	ds_read_b128 v[140:143], v241 offset:7680
	ds_read_b128 v[144:147], v240 offset:0
	ds_read_b128 v[148:151], v240 offset:2560
	ds_read_b128 v[152:155], v240 offset:32
	ds_read_b128 v[248:251], v240 offset:2592
	s_waitcnt lgkmcnt(2)
	v_mfma_f32_32x32x16_bf16 v[0:15], v[144:147], v[128:131], v[0:15]
	v_mfma_f32_32x32x16_bf16 v[64:79], v[148:151], v[128:131], v[64:79]
	ds_read_b128 v[128:131], v241 offset:32
	s_waitcnt vmcnt(6)
	ds_write_b128 v242, v[214:217] offset:30720
	ds_write_b128 v242, v[218:221] offset:35840
	v_mfma_f32_32x32x16_bf16 v[16:31], v[144:147], v[132:135], v[16:31]
	v_mfma_f32_32x32x16_bf16 v[80:95], v[148:151], v[132:135], v[80:95]
	ds_read_b128 v[132:135], v241 offset:2592
	ds_write_b128 v242, v[222:225] offset:40960
	ds_write_b128 v242, v[228:231] offset:46080
	v_mfma_f32_32x32x16_bf16 v[32:47], v[144:147], v[136:139], v[32:47]
	v_mfma_f32_32x32x16_bf16 v[96:111], v[148:151], v[136:139], v[96:111]
	ds_read_b128 v[136:139], v241 offset:5152
	ds_write_b128 v242, v[232:235] offset:51200
	ds_write_b128 v242, v[236:239] offset:56320
	v_mfma_f32_32x32x16_bf16 v[48:63], v[144:147], v[140:143], v[48:63]
	v_mfma_f32_32x32x16_bf16 v[112:127], v[148:151], v[140:143], v[112:127]
	ds_read_b128 v[140:143], v241 offset:7712
	s_waitcnt lgkmcnt(9)
	v_mfma_f32_32x32x16_bf16 v[0:15], v[152:155], v[128:131], v[0:15]
	global_load_dwordx4 v[214:217], v[182:183], off offset:192
	global_load_dwordx4 v[218:221], v[184:185], off offset:192
	v_mfma_f32_32x32x16_bf16 v[64:79], v[248:251], v[128:131], v[64:79]
	s_waitcnt lgkmcnt(6)
	v_mfma_f32_32x32x16_bf16 v[16:31], v[152:155], v[132:135], v[16:31]
	global_load_dwordx4 v[222:225], v[186:187], off offset:192
	global_load_dwordx4 v[228:231], v[188:189], off offset:192
	v_mfma_f32_32x32x16_bf16 v[80:95], v[248:251], v[132:135], v[80:95]
	s_waitcnt lgkmcnt(3)
	v_mfma_f32_32x32x16_bf16 v[32:47], v[152:155], v[136:139], v[32:47]
	global_load_dwordx4 v[232:235], v[190:191], off offset:192
	global_load_dwordx4 v[236:239], v[192:193], off offset:192
	v_mfma_f32_32x32x16_bf16 v[96:111], v[248:251], v[136:139], v[96:111]
	s_waitcnt lgkmcnt(0)
	v_mfma_f32_32x32x16_bf16 v[48:63], v[152:155], v[140:143], v[48:63]
	v_mfma_f32_32x32x16_bf16 v[112:127], v[248:251], v[140:143], v[112:127]
	s_waitcnt lgkmcnt(0)
	s_barrier
	ds_read_b128 v[128:131], v241 offset:30720
	ds_read_b128 v[132:135], v241 offset:33280
	ds_read_b128 v[136:139], v241 offset:35840
	ds_read_b128 v[140:143], v241 offset:38400
	ds_read_b128 v[144:147], v240 offset:30720
	ds_read_b128 v[148:151], v240 offset:33280
	ds_read_b128 v[152:155], v240 offset:30752
	ds_read_b128 v[248:251], v240 offset:33312
	s_waitcnt lgkmcnt(2)
	v_mfma_f32_32x32x16_bf16 v[0:15], v[144:147], v[128:131], v[0:15]
	v_mfma_f32_32x32x16_bf16 v[64:79], v[148:151], v[128:131], v[64:79]
	ds_read_b128 v[128:131], v241 offset:30752
	s_waitcnt vmcnt(6)
	ds_write_b128 v242, v[158:161] offset:0
	ds_write_b128 v242, v[162:165] offset:5120
	v_mfma_f32_32x32x16_bf16 v[16:31], v[144:147], v[132:135], v[16:31]
	v_mfma_f32_32x32x16_bf16 v[80:95], v[148:151], v[132:135], v[80:95]
	ds_read_b128 v[132:135], v241 offset:33312
	ds_write_b128 v242, v[166:169] offset:10240
	ds_write_b128 v242, v[170:173] offset:15360
	v_mfma_f32_32x32x16_bf16 v[32:47], v[144:147], v[136:139], v[32:47]
	v_mfma_f32_32x32x16_bf16 v[96:111], v[148:151], v[136:139], v[96:111]
	ds_read_b128 v[136:139], v241 offset:35872
	ds_write_b128 v242, v[174:177] offset:20480
	ds_write_b128 v242, v[178:181] offset:25600
	v_mfma_f32_32x32x16_bf16 v[48:63], v[144:147], v[140:143], v[48:63]
	v_mfma_f32_32x32x16_bf16 v[112:127], v[148:151], v[140:143], v[112:127]
	ds_read_b128 v[140:143], v241 offset:38432
	s_waitcnt lgkmcnt(9)
	v_mfma_f32_32x32x16_bf16 v[0:15], v[152:155], v[128:131], v[0:15]
	global_load_dwordx4 v[158:161], v[182:183], off offset:256
	global_load_dwordx4 v[162:165], v[184:185], off offset:256
	v_mfma_f32_32x32x16_bf16 v[64:79], v[248:251], v[128:131], v[64:79]
	s_waitcnt lgkmcnt(6)
	v_mfma_f32_32x32x16_bf16 v[16:31], v[152:155], v[132:135], v[16:31]
	global_load_dwordx4 v[166:169], v[186:187], off offset:256
	global_load_dwordx4 v[170:173], v[188:189], off offset:256
	v_mfma_f32_32x32x16_bf16 v[80:95], v[248:251], v[132:135], v[80:95]
	s_waitcnt lgkmcnt(3)
	v_mfma_f32_32x32x16_bf16 v[32:47], v[152:155], v[136:139], v[32:47]
	global_load_dwordx4 v[174:177], v[190:191], off offset:256
	global_load_dwordx4 v[178:181], v[192:193], off offset:256
	v_mfma_f32_32x32x16_bf16 v[96:111], v[248:251], v[136:139], v[96:111]
	s_waitcnt lgkmcnt(0)
	v_mfma_f32_32x32x16_bf16 v[48:63], v[152:155], v[140:143], v[48:63]
	v_mfma_f32_32x32x16_bf16 v[112:127], v[248:251], v[140:143], v[112:127]
	s_waitcnt lgkmcnt(0)
	s_barrier
; #define G_LOAD(S, kt_) do { G_LD1(S##a0, S##b0, 0, kt_); G_LD1(S##a1, S##b1, 1, kt_); G_LD1(S##a2, S##b2, 2, kt_); G_LD1(S##a3, S##b3, 3, kt_); } while (0)
; #define G_STORE(S, buf_) do { G_ST1(S##a0, S##b0, 0, buf_); G_ST1(S##a1, S##b1, 1, buf_); G_ST1(S##a2, S##b2, 2, buf_); G_ST1(S##a3, S##b3, 3, buf_); } while (0)
; template <class AL, class BL>
; DI void gemm_core(AL al, BL bl, int m0, int n0, int K, char* smem, f32x16 (&acc)[2][2]) {
;     ...
;   G_LOAD(x, 0);
;   G_STORE(x, 0);
;   G_LOAD(x, 1);
;   G_LOAD(y, (nk > 2) ? 2 : 1);
;   __syncthreads();
;   for (int kt = 0; kt < nk; kt += 2) {
;     G_TILE(0, x, true, (kt + 3 < nk), kt + 3);
;     __syncthreads();
;     G_TILE(1, y, (kt + 2 < nk), (kt + 4 < nk), kt + 4);
;     __syncthreads();
;   }
	ds_read_b128 v[128:131], v241 offset:0
	ds_read_b128 v[132:135], v241 offset:2560
	ds_read_b128 v[136:139], v241 offset:5120
	ds_read_b128 v[140:143], v241 offset:7680
	ds_read_b128 v[144:147], v240 offset:0
	ds_read_b128 v[148:151], v240 offset:2560
	ds_read_b128 v[152:155], v240 offset:32
	ds_read_b128 v[248:251], v240 offset:2592
	s_waitcnt lgkmcnt(2)
	v_mfma_f32_32x32x16_bf16 v[0:15], v[144:147], v[128:131], v[0:15]
	v_mfma_f32_32x32x16_bf16 v[64:79], v[148:151], v[128:131], v[64:79]
	ds_read_b128 v[128:131], v241 offset:32
	s_waitcnt vmcnt(6)
	ds_write_b128 v242, v[214:217] offset:30720
	ds_write_b128 v242, v[218:221] offset:35840
	v_mfma_f32_32x32x16_bf16 v[16:31], v[144:147], v[132:135], v[16:31]
	v_mfma_f32_32x32x16_bf16 v[80:95], v[148:151], v[132:135], v[80:95]
	ds_read_b128 v[132:135], v241 offset:2592
	ds_write_b128 v242, v[222:225] offset:40960
	ds_write_b128 v242, v[228:231] offset:46080
	v_mfma_f32_32x32x16_bf16 v[32:47], v[144:147], v[136:139], v[32:47]
	v_mfma_f32_32x32x16_bf16 v[96:111], v[148:151], v[136:139], v[96:111]
	ds_read_b128 v[136:139], v241 offset:5152
	ds_write_b128 v242, v[232:235] offset:51200
	ds_write_b128 v242, v[236:239] offset:56320
	v_mfma_f32_32x32x16_bf16 v[48:63], v[144:147], v[140:143], v[48:63]
	v_mfma_f32_32x32x16_bf16 v[112:127], v[148:151], v[140:143], v[112:127]
	ds_read_b128 v[140:143], v241 offset:7712
	s_waitcnt lgkmcnt(9)
	v_mfma_f32_32x32x16_bf16 v[0:15], v[152:155], v[128:131], v[0:15]
	global_load_dwordx4 v[214:217], v[182:183], off offset:320
	global_load_dwordx4 v[218:221], v[184:185], off offset:320
	v_mfma_f32_32x32x16_bf16 v[64:79], v[248:251], v[128:131], v[64:79]
	s_waitcnt lgkmcnt(6)
	v_mfma_f32_32x32x16_bf16 v[16:31], v[152:155], v[132:135], v[16:31]
	global_load_dwordx4 v[222:225], v[186:187], off offset:320
	global_load_dwordx4 v[228:231], v[188:189], off offset:320
	v_mfma_f32_32x32x16_bf16 v[80:95], v[248:251], v[132:135], v[80:95]
	s_waitcnt lgkmcnt(3)
	v_mfma_f32_32x32x16_bf16 v[32:47], v[152:155], v[136:139], v[32:47]
	global_load_dwordx4 v[232:235], v[190:191], off offset:320
	global_load_dwordx4 v[236:239], v[192:193], off offset:320
	v_mfma_f32_32x32x16_bf16 v[96:111], v[248:251], v[136:139], v[96:111]
	s_waitcnt lgkmcnt(0)
	v_mfma_f32_32x32x16_bf16 v[48:63], v[152:155], v[140:143], v[48:63]
	v_mfma_f32_32x32x16_bf16 v[112:127], v[248:251], v[140:143], v[112:127]
	s_waitcnt lgkmcnt(0)
	s_barrier
	ds_read_b128 v[128:131], v241 offset:30720
	ds_read_b128 v[132:135], v241 offset:33280
	ds_read_b128 v[136:139], v241 offset:35840
	ds_read_b128 v[140:143], v241 offset:38400
	ds_read_b128 v[144:147], v240 offset:30720
	ds_read_b128 v[148:151], v240 offset:33280
	ds_read_b128 v[152:155], v240 offset:30752
	ds_read_b128 v[248:251], v240 offset:33312
	s_waitcnt lgkmcnt(2)
	v_mfma_f32_32x32x16_bf16 v[0:15], v[144:147], v[128:131], v[0:15]
	v_mfma_f32_32x32x16_bf16 v[64:79], v[148:151], v[128:131], v[64:79]
	ds_read_b128 v[128:131], v241 offset:30752
	s_waitcnt vmcnt(6)
	ds_write_b128 v242, v[158:161] offset:0
	ds_write_b128 v242, v[162:165] offset:5120
	v_mfma_f32_32x32x16_bf16 v[16:31], v[144:147], v[132:135], v[16:31]
	v_mfma_f32_32x32x16_bf16 v[80:95], v[148:151], v[132:135], v[80:95]
	ds_read_b128 v[132:135], v241 offset:33312
	ds_write_b128 v242, v[166:169] offset:10240
	ds_write_b128 v242, v[170:173] offset:15360
	v_mfma_f32_32x32x16_bf16 v[32:47], v[144:147], v[136:139], v[32:47]
	v_mfma_f32_32x32x16_bf16 v[96:111], v[148:151], v[136:139], v[96:111]
	ds_read_b128 v[136:139], v241 offset:35872
	ds_write_b128 v242, v[174:177] offset:20480
	ds_write_b128 v242, v[178:181] offset:25600
	v_mfma_f32_32x32x16_bf16 v[48:63], v[144:147], v[140:143], v[48:63]
	v_mfma_f32_32x32x16_bf16 v[112:127], v[148:151], v[140:143], v[112:127]
	ds_read_b128 v[140:143], v241 offset:38432
	s_waitcnt lgkmcnt(9)
	v_mfma_f32_32x32x16_bf16 v[0:15], v[152:155], v[128:131], v[0:15]
	global_load_dwordx4 v[158:161], v[182:183], off offset:384
	global_load_dwordx4 v[162:165], v[184:185], off offset:384
	v_mfma_f32_32x32x16_bf16 v[64:79], v[248:251], v[128:131], v[64:79]
	s_waitcnt lgkmcnt(6)
	v_mfma_f32_32x32x16_bf16 v[16:31], v[152:155], v[132:135], v[16:31]
	global_load_dwordx4 v[166:169], v[186:187], off offset:384
	global_load_dwordx4 v[170:173], v[188:189], off offset:384
	v_mfma_f32_32x32x16_bf16 v[80:95], v[248:251], v[132:135], v[80:95]
	s_waitcnt lgkmcnt(3)
	v_mfma_f32_32x32x16_bf16 v[32:47], v[152:155], v[136:139], v[32:47]
	global_load_dwordx4 v[174:177], v[190:191], off offset:384
	global_load_dwordx4 v[178:181], v[192:193], off offset:384
	v_mfma_f32_32x32x16_bf16 v[96:111], v[248:251], v[136:139], v[96:111]
	s_waitcnt lgkmcnt(0)
	v_mfma_f32_32x32x16_bf16 v[48:63], v[152:155], v[140:143], v[48:63]
	v_mfma_f32_32x32x16_bf16 v[112:127], v[248:251], v[140:143], v[112:127]
	s_waitcnt lgkmcnt(0)
	s_barrier
; #define G_LOAD(S, kt_) do { G_LD1(S##a0, S##b0, 0, kt_); G_LD1(S##a1, S##b1, 1, kt_); G_LD1(S##a2, S##b2, 2, kt_); G_LD1(S##a3, S##b3, 3, kt_); } while (0)
; #define G_STORE(S, buf_) do { G_ST1(S##a0, S##b0, 0, buf_); G_ST1(S##a1, S##b1, 1, buf_); G_ST1(S##a2, S##b2, 2, buf_); G_ST1(S##a3, S##b3, 3, buf_); } while (0)
; template <class AL, class BL>
; DI void gemm_core(AL al, BL bl, int m0, int n0, int K, char* smem, f32x16 (&acc)[2][2]) {
;     ...
;   G_LOAD(x, 0);
;   G_STORE(x, 0);
;   G_LOAD(x, 1);
;   G_LOAD(y, (nk > 2) ? 2 : 1);
;   __syncthreads();
;   for (int kt = 0; kt < nk; kt += 2) {
;     G_TILE(0, x, true, (kt + 3 < nk), kt + 3);
;     __syncthreads();
;     G_TILE(1, y, (kt + 2 < nk), (kt + 4 < nk), kt + 4);
;     __syncthreads();
;   }
	ds_read_b128 v[128:131], v241 offset:0
	ds_read_b128 v[132:135], v241 offset:2560
	ds_read_b128 v[136:139], v241 offset:5120
	ds_read_b128 v[140:143], v241 offset:7680
	ds_read_b128 v[144:147], v240 offset:0
	ds_read_b128 v[148:151], v240 offset:2560
	ds_read_b128 v[152:155], v240 offset:32
	ds_read_b128 v[248:251], v240 offset:2592
	s_waitcnt lgkmcnt(2)
	v_mfma_f32_32x32x16_bf16 v[0:15], v[144:147], v[128:131], v[0:15]
	v_mfma_f32_32x32x16_bf16 v[64:79], v[148:151], v[128:131], v[64:79]
	ds_read_b128 v[128:131], v241 offset:32
	s_waitcnt vmcnt(6)
	ds_write_b128 v242, v[214:217] offset:30720
	ds_write_b128 v242, v[218:221] offset:35840
	v_mfma_f32_32x32x16_bf16 v[16:31], v[144:147], v[132:135], v[16:31]
	v_mfma_f32_32x32x16_bf16 v[80:95], v[148:151], v[132:135], v[80:95]
	ds_read_b128 v[132:135], v241 offset:2592
	ds_write_b128 v242, v[222:225] offset:40960
	ds_write_b128 v242, v[228:231] offset:46080
	v_mfma_f32_32x32x16_bf16 v[32:47], v[144:147], v[136:139], v[32:47]
	v_mfma_f32_32x32x16_bf16 v[96:111], v[148:151], v[136:139], v[96:111]
	ds_read_b128 v[136:139], v241 offset:5152
	ds_write_b128 v242, v[232:235] offset:51200
	ds_write_b128 v242, v[236:239] offset:56320
	v_mfma_f32_32x32x16_bf16 v[48:63], v[144:147], v[140:143], v[48:63]
	v_mfma_f32_32x32x16_bf16 v[112:127], v[148:151], v[140:143], v[112:127]
	ds_read_b128 v[140:143], v241 offset:7712
	s_waitcnt lgkmcnt(9)
	v_mfma_f32_32x32x16_bf16 v[0:15], v[152:155], v[128:131], v[0:15]
	global_load_dwordx4 v[214:217], v[182:183], off offset:448
	global_load_dwordx4 v[218:221], v[184:185], off offset:448
	v_mfma_f32_32x32x16_bf16 v[64:79], v[248:251], v[128:131], v[64:79]
	s_waitcnt lgkmcnt(6)
	v_mfma_f32_32x32x16_bf16 v[16:31], v[152:155], v[132:135], v[16:31]
	global_load_dwordx4 v[222:225], v[186:187], off offset:448
	global_load_dwordx4 v[228:231], v[188:189], off offset:448
	v_mfma_f32_32x32x16_bf16 v[80:95], v[248:251], v[132:135], v[80:95]
	s_waitcnt lgkmcnt(3)
	v_mfma_f32_32x32x16_bf16 v[32:47], v[152:155], v[136:139], v[32:47]
	global_load_dwordx4 v[232:235], v[190:191], off offset:448
	global_load_dwordx4 v[236:239], v[192:193], off offset:448
	v_mfma_f32_32x32x16_bf16 v[96:111], v[248:251], v[136:139], v[96:111]
	s_waitcnt lgkmcnt(0)
	v_mfma_f32_32x32x16_bf16 v[48:63], v[152:155], v[140:143], v[48:63]
	v_mfma_f32_32x32x16_bf16 v[112:127], v[248:251], v[140:143], v[112:127]
	s_waitcnt lgkmcnt(0)
	s_barrier
	ds_read_b128 v[128:131], v241 offset:30720
	ds_read_b128 v[132:135], v241 offset:33280
	ds_read_b128 v[136:139], v241 offset:35840
	ds_read_b128 v[140:143], v241 offset:38400
	ds_read_b128 v[144:147], v240 offset:30720
	ds_read_b128 v[148:151], v240 offset:33280
	ds_read_b128 v[152:155], v240 offset:30752
	ds_read_b128 v[248:251], v240 offset:33312
	s_waitcnt lgkmcnt(2)
	v_mfma_f32_32x32x16_bf16 v[0:15], v[144:147], v[128:131], v[0:15]
	v_mfma_f32_32x32x16_bf16 v[64:79], v[148:151], v[128:131], v[64:79]
	ds_read_b128 v[128:131], v241 offset:30752
	s_waitcnt vmcnt(6)
	ds_write_b128 v242, v[158:161] offset:0
	ds_write_b128 v242, v[162:165] offset:5120
	v_mfma_f32_32x32x16_bf16 v[16:31], v[144:147], v[132:135], v[16:31]
	v_mfma_f32_32x32x16_bf16 v[80:95], v[148:151], v[132:135], v[80:95]
	ds_read_b128 v[132:135], v241 offset:33312
	ds_write_b128 v242, v[166:169] offset:10240
	ds_write_b128 v242, v[170:173] offset:15360
	v_mfma_f32_32x32x16_bf16 v[32:47], v[144:147], v[136:139], v[32:47]
	v_mfma_f32_32x32x16_bf16 v[96:111], v[148:151], v[136:139], v[96:111]
	ds_read_b128 v[136:139], v241 offset:35872
	ds_write_b128 v242, v[174:177] offset:20480
	ds_write_b128 v242, v[178:181] offset:25600
	v_mfma_f32_32x32x16_bf16 v[48:63], v[144:147], v[140:143], v[48:63]
	v_mfma_f32_32x32x16_bf16 v[112:127], v[148:151], v[140:143], v[112:127]
	ds_read_b128 v[140:143], v241 offset:38432
	s_waitcnt lgkmcnt(9)
	v_mfma_f32_32x32x16_bf16 v[0:15], v[152:155], v[128:131], v[0:15]
	global_load_dwordx4 v[158:161], v[182:183], off offset:512
	global_load_dwordx4 v[162:165], v[184:185], off offset:512
	v_mfma_f32_32x32x16_bf16 v[64:79], v[248:251], v[128:131], v[64:79]
	s_waitcnt lgkmcnt(6)
	v_mfma_f32_32x32x16_bf16 v[16:31], v[152:155], v[132:135], v[16:31]
	global_load_dwordx4 v[166:169], v[186:187], off offset:512
	global_load_dwordx4 v[170:173], v[188:189], off offset:512
	v_mfma_f32_32x32x16_bf16 v[80:95], v[248:251], v[132:135], v[80:95]
	s_waitcnt lgkmcnt(3)
	v_mfma_f32_32x32x16_bf16 v[32:47], v[152:155], v[136:139], v[32:47]
	global_load_dwordx4 v[174:177], v[190:191], off offset:512
	global_load_dwordx4 v[178:181], v[192:193], off offset:512
	v_mfma_f32_32x32x16_bf16 v[96:111], v[248:251], v[136:139], v[96:111]
	s_waitcnt lgkmcnt(0)
	v_mfma_f32_32x32x16_bf16 v[48:63], v[152:155], v[140:143], v[48:63]
	v_mfma_f32_32x32x16_bf16 v[112:127], v[248:251], v[140:143], v[112:127]
	s_waitcnt lgkmcnt(0)
	s_barrier
; #define G_LOAD(S, kt_) do { G_LD1(S##a0, S##b0, 0, kt_); G_LD1(S##a1, S##b1, 1, kt_); G_LD1(S##a2, S##b2, 2, kt_); G_LD1(S##a3, S##b3, 3, kt_); } while (0)
; #define G_STORE(S, buf_) do { G_ST1(S##a0, S##b0, 0, buf_); G_ST1(S##a1, S##b1, 1, buf_); G_ST1(S##a2, S##b2, 2, buf_); G_ST1(S##a3, S##b3, 3, buf_); } while (0)
; template <class AL, class BL>
; DI void gemm_core(AL al, BL bl, int m0, int n0, int K, char* smem, f32x16 (&acc)[2][2]) {
;     ...
;   G_LOAD(x, 0);
;   G_STORE(x, 0);
;   G_LOAD(x, 1);
;   G_LOAD(y, (nk > 2) ? 2 : 1);
;   __syncthreads();
;   for (int kt = 0; kt < nk; kt += 2) {
;     G_TILE(0, x, true, (kt + 3 < nk), kt + 3);
;     __syncthreads();
;     G_TILE(1, y, (kt + 2 < nk), (kt + 4 < nk), kt + 4);
;     __syncthreads();
;   }
	ds_read_b128 v[128:131], v241 offset:0
	ds_read_b128 v[132:135], v241 offset:2560
	ds_read_b128 v[136:139], v241 offset:5120
	ds_read_b128 v[140:143], v241 offset:7680
	ds_read_b128 v[144:147], v240 offset:0
	ds_read_b128 v[148:151], v240 offset:2560
	ds_read_b128 v[152:155], v240 offset:32
	ds_read_b128 v[248:251], v240 offset:2592
	s_waitcnt lgkmcnt(2)
	v_mfma_f32_32x32x16_bf16 v[0:15], v[144:147], v[128:131], v[0:15]
	v_mfma_f32_32x32x16_bf16 v[64:79], v[148:151], v[128:131], v[64:79]
	ds_read_b128 v[128:131], v241 offset:32
	s_waitcnt vmcnt(6)
	ds_write_b128 v242, v[214:217] offset:30720
	ds_write_b128 v242, v[218:221] offset:35840
	v_mfma_f32_32x32x16_bf16 v[16:31], v[144:147], v[132:135], v[16:31]
	v_mfma_f32_32x32x16_bf16 v[80:95], v[148:151], v[132:135], v[80:95]
	ds_read_b128 v[132:135], v241 offset:2592
	ds_write_b128 v242, v[222:225] offset:40960
	ds_write_b128 v242, v[228:231] offset:46080
	v_mfma_f32_32x32x16_bf16 v[32:47], v[144:147], v[136:139], v[32:47]
	v_mfma_f32_32x32x16_bf16 v[96:111], v[148:151], v[136:139], v[96:111]
	ds_read_b128 v[136:139], v241 offset:5152
	ds_write_b128 v242, v[232:235] offset:51200
	ds_write_b128 v242, v[236:239] offset:56320
	v_mfma_f32_32x32x16_bf16 v[48:63], v[144:147], v[140:143], v[48:63]
	v_mfma_f32_32x32x16_bf16 v[112:127], v[148:151], v[140:143], v[112:127]
	ds_read_b128 v[140:143], v241 offset:7712
	s_waitcnt lgkmcnt(9)
	v_mfma_f32_32x32x16_bf16 v[0:15], v[152:155], v[128:131], v[0:15]
	global_load_dwordx4 v[214:217], v[182:183], off offset:576
	global_load_dwordx4 v[218:221], v[184:185], off offset:576
	v_mfma_f32_32x32x16_bf16 v[64:79], v[248:251], v[128:131], v[64:79]
	s_waitcnt lgkmcnt(6)
	v_mfma_f32_32x32x16_bf16 v[16:31], v[152:155], v[132:135], v[16:31]
	global_load_dwordx4 v[222:225], v[186:187], off offset:576
	global_load_dwordx4 v[228:231], v[188:189], off offset:576
	v_mfma_f32_32x32x16_bf16 v[80:95], v[248:251], v[132:135], v[80:95]
	s_waitcnt lgkmcnt(3)
	v_mfma_f32_32x32x16_bf16 v[32:47], v[152:155], v[136:139], v[32:47]
	global_load_dwordx4 v[232:235], v[190:191], off offset:576
	global_load_dwordx4 v[236:239], v[192:193], off offset:576
	v_mfma_f32_32x32x16_bf16 v[96:111], v[248:251], v[136:139], v[96:111]
	s_waitcnt lgkmcnt(0)
	v_mfma_f32_32x32x16_bf16 v[48:63], v[152:155], v[140:143], v[48:63]
	v_mfma_f32_32x32x16_bf16 v[112:127], v[248:251], v[140:143], v[112:127]
	s_waitcnt lgkmcnt(0)
	s_barrier
	ds_read_b128 v[128:131], v241 offset:30720
	ds_read_b128 v[132:135], v241 offset:33280
	ds_read_b128 v[136:139], v241 offset:35840
	ds_read_b128 v[140:143], v241 offset:38400
	ds_read_b128 v[144:147], v240 offset:30720
	ds_read_b128 v[148:151], v240 offset:33280
	ds_read_b128 v[152:155], v240 offset:30752
	ds_read_b128 v[248:251], v240 offset:33312
	s_waitcnt lgkmcnt(2)
	v_mfma_f32_32x32x16_bf16 v[0:15], v[144:147], v[128:131], v[0:15]
	v_mfma_f32_32x32x16_bf16 v[64:79], v[148:151], v[128:131], v[64:79]
	ds_read_b128 v[128:131], v241 offset:30752
	s_waitcnt vmcnt(6)
	ds_write_b128 v242, v[158:161] offset:0
	ds_write_b128 v242, v[162:165] offset:5120
	v_mfma_f32_32x32x16_bf16 v[16:31], v[144:147], v[132:135], v[16:31]
	v_mfma_f32_32x32x16_bf16 v[80:95], v[148:151], v[132:135], v[80:95]
	ds_read_b128 v[132:135], v241 offset:33312
	ds_write_b128 v242, v[166:169] offset:10240
	ds_write_b128 v242, v[170:173] offset:15360
	v_mfma_f32_32x32x16_bf16 v[32:47], v[144:147], v[136:139], v[32:47]
	v_mfma_f32_32x32x16_bf16 v[96:111], v[148:151], v[136:139], v[96:111]
	ds_read_b128 v[136:139], v241 offset:35872
	ds_write_b128 v242, v[174:177] offset:20480
	ds_write_b128 v242, v[178:181] offset:25600
	v_mfma_f32_32x32x16_bf16 v[48:63], v[144:147], v[140:143], v[48:63]
	v_mfma_f32_32x32x16_bf16 v[112:127], v[148:151], v[140:143], v[112:127]
	ds_read_b128 v[140:143], v241 offset:38432
	s_waitcnt lgkmcnt(9)
	v_mfma_f32_32x32x16_bf16 v[0:15], v[152:155], v[128:131], v[0:15]
	global_load_dwordx4 v[158:161], v[182:183], off offset:640
	global_load_dwordx4 v[162:165], v[184:185], off offset:640
	v_mfma_f32_32x32x16_bf16 v[64:79], v[248:251], v[128:131], v[64:79]
	s_waitcnt lgkmcnt(6)
	v_mfma_f32_32x32x16_bf16 v[16:31], v[152:155], v[132:135], v[16:31]
	global_load_dwordx4 v[166:169], v[186:187], off offset:640
	global_load_dwordx4 v[170:173], v[188:189], off offset:640
	v_mfma_f32_32x32x16_bf16 v[80:95], v[248:251], v[132:135], v[80:95]
	s_waitcnt lgkmcnt(3)
	v_mfma_f32_32x32x16_bf16 v[32:47], v[152:155], v[136:139], v[32:47]
	global_load_dwordx4 v[174:177], v[190:191], off offset:640
	global_load_dwordx4 v[178:181], v[192:193], off offset:640
	v_mfma_f32_32x32x16_bf16 v[96:111], v[248:251], v[136:139], v[96:111]
	s_waitcnt lgkmcnt(0)
	v_mfma_f32_32x32x16_bf16 v[48:63], v[152:155], v[140:143], v[48:63]
	v_mfma_f32_32x32x16_bf16 v[112:127], v[248:251], v[140:143], v[112:127]
	s_waitcnt lgkmcnt(0)
	s_barrier
; #define G_LOAD(S, kt_) do { G_LD1(S##a0, S##b0, 0, kt_); G_LD1(S##a1, S##b1, 1, kt_); G_LD1(S##a2, S##b2, 2, kt_); G_LD1(S##a3, S##b3, 3, kt_); } while (0)
; #define G_STORE(S, buf_) do { G_ST1(S##a0, S##b0, 0, buf_); G_ST1(S##a1, S##b1, 1, buf_); G_ST1(S##a2, S##b2, 2, buf_); G_ST1(S##a3, S##b3, 3, buf_); } while (0)
; template <class AL, class BL>
; DI void gemm_core(AL al, BL bl, int m0, int n0, int K, char* smem, f32x16 (&acc)[2][2]) {
;     ...
;   G_LOAD(x, 0);
;   G_STORE(x, 0);
;   G_LOAD(x, 1);
;   G_LOAD(y, (nk > 2) ? 2 : 1);
;   __syncthreads();
;   for (int kt = 0; kt < nk; kt += 2) {
;     G_TILE(0, x, true, (kt + 3 < nk), kt + 3);
;     __syncthreads();
;     G_TILE(1, y, (kt + 2 < nk), (kt + 4 < nk), kt + 4);
;     __syncthreads();
;   }
	ds_read_b128 v[128:131], v241 offset:0
	ds_read_b128 v[132:135], v241 offset:2560
	ds_read_b128 v[136:139], v241 offset:5120
	ds_read_b128 v[140:143], v241 offset:7680
	ds_read_b128 v[144:147], v240 offset:0
	ds_read_b128 v[148:151], v240 offset:2560
	ds_read_b128 v[152:155], v240 offset:32
	ds_read_b128 v[248:251], v240 offset:2592
	s_waitcnt lgkmcnt(2)
	v_mfma_f32_32x32x16_bf16 v[0:15], v[144:147], v[128:131], v[0:15]
	v_mfma_f32_32x32x16_bf16 v[64:79], v[148:151], v[128:131], v[64:79]
	ds_read_b128 v[128:131], v241 offset:32
	s_waitcnt vmcnt(6)
	ds_write_b128 v242, v[214:217] offset:30720
	ds_write_b128 v242, v[218:221] offset:35840
	v_mfma_f32_32x32x16_bf16 v[16:31], v[144:147], v[132:135], v[16:31]
	v_mfma_f32_32x32x16_bf16 v[80:95], v[148:151], v[132:135], v[80:95]
	ds_read_b128 v[132:135], v241 offset:2592
	ds_write_b128 v242, v[222:225] offset:40960
	ds_write_b128 v242, v[228:231] offset:46080
	v_mfma_f32_32x32x16_bf16 v[32:47], v[144:147], v[136:139], v[32:47]
	v_mfma_f32_32x32x16_bf16 v[96:111], v[148:151], v[136:139], v[96:111]
	ds_read_b128 v[136:139], v241 offset:5152
	ds_write_b128 v242, v[232:235] offset:51200
	ds_write_b128 v242, v[236:239] offset:56320
	v_mfma_f32_32x32x16_bf16 v[48:63], v[144:147], v[140:143], v[48:63]
	v_mfma_f32_32x32x16_bf16 v[112:127], v[148:151], v[140:143], v[112:127]
	ds_read_b128 v[140:143], v241 offset:7712
	s_waitcnt lgkmcnt(9)
	v_mfma_f32_32x32x16_bf16 v[0:15], v[152:155], v[128:131], v[0:15]
	global_load_dwordx4 v[214:217], v[182:183], off offset:704
	global_load_dwordx4 v[218:221], v[184:185], off offset:704
	v_mfma_f32_32x32x16_bf16 v[64:79], v[248:251], v[128:131], v[64:79]
	s_waitcnt lgkmcnt(6)
	v_mfma_f32_32x32x16_bf16 v[16:31], v[152:155], v[132:135], v[16:31]
	global_load_dwordx4 v[222:225], v[186:187], off offset:704
	global_load_dwordx4 v[228:231], v[188:189], off offset:704
	v_mfma_f32_32x32x16_bf16 v[80:95], v[248:251], v[132:135], v[80:95]
	s_waitcnt lgkmcnt(3)
	v_mfma_f32_32x32x16_bf16 v[32:47], v[152:155], v[136:139], v[32:47]
	global_load_dwordx4 v[232:235], v[190:191], off offset:704
	global_load_dwordx4 v[236:239], v[192:193], off offset:704
	v_mfma_f32_32x32x16_bf16 v[96:111], v[248:251], v[136:139], v[96:111]
	s_waitcnt lgkmcnt(0)
	v_mfma_f32_32x32x16_bf16 v[48:63], v[152:155], v[140:143], v[48:63]
	v_mfma_f32_32x32x16_bf16 v[112:127], v[248:251], v[140:143], v[112:127]
	s_waitcnt lgkmcnt(0)
	s_barrier
	ds_read_b128 v[128:131], v241 offset:30720
	ds_read_b128 v[132:135], v241 offset:33280
	ds_read_b128 v[136:139], v241 offset:35840
	ds_read_b128 v[140:143], v241 offset:38400
	ds_read_b128 v[144:147], v240 offset:30720
	ds_read_b128 v[148:151], v240 offset:33280
	ds_read_b128 v[152:155], v240 offset:30752
	ds_read_b128 v[248:251], v240 offset:33312
	s_waitcnt lgkmcnt(2)
	v_mfma_f32_32x32x16_bf16 v[0:15], v[144:147], v[128:131], v[0:15]
	v_mfma_f32_32x32x16_bf16 v[64:79], v[148:151], v[128:131], v[64:79]
	ds_read_b128 v[128:131], v241 offset:30752
	s_waitcnt vmcnt(6)
	ds_write_b128 v242, v[158:161] offset:0
	ds_write_b128 v242, v[162:165] offset:5120
	v_mfma_f32_32x32x16_bf16 v[16:31], v[144:147], v[132:135], v[16:31]
	v_mfma_f32_32x32x16_bf16 v[80:95], v[148:151], v[132:135], v[80:95]
	ds_read_b128 v[132:135], v241 offset:33312
	ds_write_b128 v242, v[166:169] offset:10240
	ds_write_b128 v242, v[170:173] offset:15360
	v_mfma_f32_32x32x16_bf16 v[32:47], v[144:147], v[136:139], v[32:47]
	v_mfma_f32_32x32x16_bf16 v[96:111], v[148:151], v[136:139], v[96:111]
	ds_read_b128 v[136:139], v241 offset:35872
	ds_write_b128 v242, v[174:177] offset:20480
	ds_write_b128 v242, v[178:181] offset:25600
	v_mfma_f32_32x32x16_bf16 v[48:63], v[144:147], v[140:143], v[48:63]
	v_mfma_f32_32x32x16_bf16 v[112:127], v[148:151], v[140:143], v[112:127]
	ds_read_b128 v[140:143], v241 offset:38432
	s_waitcnt lgkmcnt(9)
	v_mfma_f32_32x32x16_bf16 v[0:15], v[152:155], v[128:131], v[0:15]
	global_load_dwordx4 v[158:161], v[182:183], off offset:768
	global_load_dwordx4 v[162:165], v[184:185], off offset:768
	v_mfma_f32_32x32x16_bf16 v[64:79], v[248:251], v[128:131], v[64:79]
	s_waitcnt lgkmcnt(6)
	v_mfma_f32_32x32x16_bf16 v[16:31], v[152:155], v[132:135], v[16:31]
	global_load_dwordx4 v[166:169], v[186:187], off offset:768
	global_load_dwordx4 v[170:173], v[188:189], off offset:768
	v_mfma_f32_32x32x16_bf16 v[80:95], v[248:251], v[132:135], v[80:95]
	s_waitcnt lgkmcnt(3)
	v_mfma_f32_32x32x16_bf16 v[32:47], v[152:155], v[136:139], v[32:47]
	global_load_dwordx4 v[174:177], v[190:191], off offset:768
	global_load_dwordx4 v[178:181], v[192:193], off offset:768
	v_mfma_f32_32x32x16_bf16 v[96:111], v[248:251], v[136:139], v[96:111]
	s_waitcnt lgkmcnt(0)
	v_mfma_f32_32x32x16_bf16 v[48:63], v[152:155], v[140:143], v[48:63]
	v_mfma_f32_32x32x16_bf16 v[112:127], v[248:251], v[140:143], v[112:127]
	s_waitcnt lgkmcnt(0)
	s_barrier
; #define G_LOAD(S, kt_) do { G_LD1(S##a0, S##b0, 0, kt_); G_LD1(S##a1, S##b1, 1, kt_); G_LD1(S##a2, S##b2, 2, kt_); G_LD1(S##a3, S##b3, 3, kt_); } while (0)
; #define G_STORE(S, buf_) do { G_ST1(S##a0, S##b0, 0, buf_); G_ST1(S##a1, S##b1, 1, buf_); G_ST1(S##a2, S##b2, 2, buf_); G_ST1(S##a3, S##b3, 3, buf_); } while (0)
; template <class AL, class BL>
; DI void gemm_core(AL al, BL bl, int m0, int n0, int K, char* smem, f32x16 (&acc)[2][2]) {
;     ...
;   G_LOAD(x, 0);
;   G_STORE(x, 0);
;   G_LOAD(x, 1);
;   G_LOAD(y, (nk > 2) ? 2 : 1);
;   __syncthreads();
;   for (int kt = 0; kt < nk; kt += 2) {
;     G_TILE(0, x, true, (kt + 3 < nk), kt + 3);
;     __syncthreads();
;     G_TILE(1, y, (kt + 2 < nk), (kt + 4 < nk), kt + 4);
;     __syncthreads();
;   }
	ds_read_b128 v[128:131], v241 offset:0
	ds_read_b128 v[132:135], v241 offset:2560
	ds_read_b128 v[136:139], v241 offset:5120
	ds_read_b128 v[140:143], v241 offset:7680
	ds_read_b128 v[144:147], v240 offset:0
	ds_read_b128 v[148:151], v240 offset:2560
	ds_read_b128 v[152:155], v240 offset:32
	ds_read_b128 v[248:251], v240 offset:2592
	s_waitcnt lgkmcnt(2)
	v_mfma_f32_32x32x16_bf16 v[0:15], v[144:147], v[128:131], v[0:15]
	v_mfma_f32_32x32x16_bf16 v[64:79], v[148:151], v[128:131], v[64:79]
	ds_read_b128 v[128:131], v241 offset:32
	s_waitcnt vmcnt(6)
	ds_write_b128 v242, v[214:217] offset:30720
	ds_write_b128 v242, v[218:221] offset:35840
	v_mfma_f32_32x32x16_bf16 v[16:31], v[144:147], v[132:135], v[16:31]
	v_mfma_f32_32x32x16_bf16 v[80:95], v[148:151], v[132:135], v[80:95]
	ds_read_b128 v[132:135], v241 offset:2592
	ds_write_b128 v242, v[222:225] offset:40960
	ds_write_b128 v242, v[228:231] offset:46080
	v_mfma_f32_32x32x16_bf16 v[32:47], v[144:147], v[136:139], v[32:47]
	v_mfma_f32_32x32x16_bf16 v[96:111], v[148:151], v[136:139], v[96:111]
	ds_read_b128 v[136:139], v241 offset:5152
	ds_write_b128 v242, v[232:235] offset:51200
	ds_write_b128 v242, v[236:239] offset:56320
	v_mfma_f32_32x32x16_bf16 v[48:63], v[144:147], v[140:143], v[48:63]
	v_mfma_f32_32x32x16_bf16 v[112:127], v[148:151], v[140:143], v[112:127]
	ds_read_b128 v[140:143], v241 offset:7712
	s_waitcnt lgkmcnt(9)
	v_mfma_f32_32x32x16_bf16 v[0:15], v[152:155], v[128:131], v[0:15]
	global_load_dwordx4 v[214:217], v[182:183], off offset:832
	global_load_dwordx4 v[218:221], v[184:185], off offset:832
	v_mfma_f32_32x32x16_bf16 v[64:79], v[248:251], v[128:131], v[64:79]
	s_waitcnt lgkmcnt(6)
	v_mfma_f32_32x32x16_bf16 v[16:31], v[152:155], v[132:135], v[16:31]
	global_load_dwordx4 v[222:225], v[186:187], off offset:832
	global_load_dwordx4 v[228:231], v[188:189], off offset:832
	v_mfma_f32_32x32x16_bf16 v[80:95], v[248:251], v[132:135], v[80:95]
	s_waitcnt lgkmcnt(3)
	v_mfma_f32_32x32x16_bf16 v[32:47], v[152:155], v[136:139], v[32:47]
	global_load_dwordx4 v[232:235], v[190:191], off offset:832
	global_load_dwordx4 v[236:239], v[192:193], off offset:832
	v_mfma_f32_32x32x16_bf16 v[96:111], v[248:251], v[136:139], v[96:111]
	s_waitcnt lgkmcnt(0)
	v_mfma_f32_32x32x16_bf16 v[48:63], v[152:155], v[140:143], v[48:63]
	v_mfma_f32_32x32x16_bf16 v[112:127], v[248:251], v[140:143], v[112:127]
	s_waitcnt lgkmcnt(0)
	s_barrier
	ds_read_b128 v[128:131], v241 offset:30720
	ds_read_b128 v[132:135], v241 offset:33280
	ds_read_b128 v[136:139], v241 offset:35840
	ds_read_b128 v[140:143], v241 offset:38400
	ds_read_b128 v[144:147], v240 offset:30720
	ds_read_b128 v[148:151], v240 offset:33280
	ds_read_b128 v[152:155], v240 offset:30752
	ds_read_b128 v[248:251], v240 offset:33312
	s_waitcnt lgkmcnt(2)
	v_mfma_f32_32x32x16_bf16 v[0:15], v[144:147], v[128:131], v[0:15]
	v_mfma_f32_32x32x16_bf16 v[64:79], v[148:151], v[128:131], v[64:79]
	ds_read_b128 v[128:131], v241 offset:30752
	s_waitcnt vmcnt(6)
	ds_write_b128 v242, v[158:161] offset:0
	ds_write_b128 v242, v[162:165] offset:5120
	v_mfma_f32_32x32x16_bf16 v[16:31], v[144:147], v[132:135], v[16:31]
	v_mfma_f32_32x32x16_bf16 v[80:95], v[148:151], v[132:135], v[80:95]
	ds_read_b128 v[132:135], v241 offset:33312
	ds_write_b128 v242, v[166:169] offset:10240
	ds_write_b128 v242, v[170:173] offset:15360
	v_mfma_f32_32x32x16_bf16 v[32:47], v[144:147], v[136:139], v[32:47]
	v_mfma_f32_32x32x16_bf16 v[96:111], v[148:151], v[136:139], v[96:111]
	ds_read_b128 v[136:139], v241 offset:35872
	ds_write_b128 v242, v[174:177] offset:20480
	ds_write_b128 v242, v[178:181] offset:25600
	v_mfma_f32_32x32x16_bf16 v[48:63], v[144:147], v[140:143], v[48:63]
	v_mfma_f32_32x32x16_bf16 v[112:127], v[148:151], v[140:143], v[112:127]
	ds_read_b128 v[140:143], v241 offset:38432
	s_waitcnt lgkmcnt(9)
	v_mfma_f32_32x32x16_bf16 v[0:15], v[152:155], v[128:131], v[0:15]
	global_load_dwordx4 v[158:161], v[182:183], off offset:896
	global_load_dwordx4 v[162:165], v[184:185], off offset:896
	v_mfma_f32_32x32x16_bf16 v[64:79], v[248:251], v[128:131], v[64:79]
	s_waitcnt lgkmcnt(6)
	v_mfma_f32_32x32x16_bf16 v[16:31], v[152:155], v[132:135], v[16:31]
	global_load_dwordx4 v[166:169], v[186:187], off offset:896
	global_load_dwordx4 v[170:173], v[188:189], off offset:896
	v_mfma_f32_32x32x16_bf16 v[80:95], v[248:251], v[132:135], v[80:95]
	s_waitcnt lgkmcnt(3)
	v_mfma_f32_32x32x16_bf16 v[32:47], v[152:155], v[136:139], v[32:47]
	global_load_dwordx4 v[174:177], v[190:191], off offset:896
	global_load_dwordx4 v[178:181], v[192:193], off offset:896
	v_mfma_f32_32x32x16_bf16 v[96:111], v[248:251], v[136:139], v[96:111]
	s_waitcnt lgkmcnt(0)
	v_mfma_f32_32x32x16_bf16 v[48:63], v[152:155], v[140:143], v[48:63]
	v_mfma_f32_32x32x16_bf16 v[112:127], v[248:251], v[140:143], v[112:127]
	s_waitcnt lgkmcnt(0)
	s_barrier
; #define G_LOAD(S, kt_) do { G_LD1(S##a0, S##b0, 0, kt_); G_LD1(S##a1, S##b1, 1, kt_); G_LD1(S##a2, S##b2, 2, kt_); G_LD1(S##a3, S##b3, 3, kt_); } while (0)
; #define G_STORE(S, buf_) do { G_ST1(S##a0, S##b0, 0, buf_); G_ST1(S##a1, S##b1, 1, buf_); G_ST1(S##a2, S##b2, 2, buf_); G_ST1(S##a3, S##b3, 3, buf_); } while (0)
; template <class AL, class BL>
; DI void gemm_core(AL al, BL bl, int m0, int n0, int K, char* smem, f32x16 (&acc)[2][2]) {
;     ...
;   G_LOAD(x, 0);
;   G_STORE(x, 0);
;   G_LOAD(x, 1);
;   G_LOAD(y, (nk > 2) ? 2 : 1);
;   __syncthreads();
;   for (int kt = 0; kt < nk; kt += 2) {
;     G_TILE(0, x, true, (kt + 3 < nk), kt + 3);
;     __syncthreads();
;     G_TILE(1, y, (kt + 2 < nk), (kt + 4 < nk), kt + 4);
;     __syncthreads();
;   }
	ds_read_b128 v[128:131], v241 offset:0
	ds_read_b128 v[132:135], v241 offset:2560
	ds_read_b128 v[136:139], v241 offset:5120
	ds_read_b128 v[140:143], v241 offset:7680
	ds_read_b128 v[144:147], v240 offset:0
	ds_read_b128 v[148:151], v240 offset:2560
	ds_read_b128 v[152:155], v240 offset:32
	ds_read_b128 v[248:251], v240 offset:2592
	s_waitcnt lgkmcnt(2)
	v_mfma_f32_32x32x16_bf16 v[0:15], v[144:147], v[128:131], v[0:15]
	v_mfma_f32_32x32x16_bf16 v[64:79], v[148:151], v[128:131], v[64:79]
	ds_read_b128 v[128:131], v241 offset:32
	s_waitcnt vmcnt(6)
	ds_write_b128 v242, v[214:217] offset:30720
	ds_write_b128 v242, v[218:221] offset:35840
	v_mfma_f32_32x32x16_bf16 v[16:31], v[144:147], v[132:135], v[16:31]
	v_mfma_f32_32x32x16_bf16 v[80:95], v[148:151], v[132:135], v[80:95]
	ds_read_b128 v[132:135], v241 offset:2592
	ds_write_b128 v242, v[222:225] offset:40960
	ds_write_b128 v242, v[228:231] offset:46080
	v_mfma_f32_32x32x16_bf16 v[32:47], v[144:147], v[136:139], v[32:47]
	v_mfma_f32_32x32x16_bf16 v[96:111], v[148:151], v[136:139], v[96:111]
	ds_read_b128 v[136:139], v241 offset:5152
	ds_write_b128 v242, v[232:235] offset:51200
	ds_write_b128 v242, v[236:239] offset:56320
	v_mfma_f32_32x32x16_bf16 v[48:63], v[144:147], v[140:143], v[48:63]
	v_mfma_f32_32x32x16_bf16 v[112:127], v[148:151], v[140:143], v[112:127]
	ds_read_b128 v[140:143], v241 offset:7712
	s_waitcnt lgkmcnt(9)
	v_mfma_f32_32x32x16_bf16 v[0:15], v[152:155], v[128:131], v[0:15]
	global_load_dwordx4 v[214:217], v[182:183], off offset:960
	global_load_dwordx4 v[218:221], v[184:185], off offset:960
	v_mfma_f32_32x32x16_bf16 v[64:79], v[248:251], v[128:131], v[64:79]
	s_waitcnt lgkmcnt(6)
	v_mfma_f32_32x32x16_bf16 v[16:31], v[152:155], v[132:135], v[16:31]
	global_load_dwordx4 v[222:225], v[186:187], off offset:960
	global_load_dwordx4 v[228:231], v[188:189], off offset:960
	v_mfma_f32_32x32x16_bf16 v[80:95], v[248:251], v[132:135], v[80:95]
	s_waitcnt lgkmcnt(3)
	v_mfma_f32_32x32x16_bf16 v[32:47], v[152:155], v[136:139], v[32:47]
	global_load_dwordx4 v[232:235], v[190:191], off offset:960
	global_load_dwordx4 v[236:239], v[192:193], off offset:960
	v_mfma_f32_32x32x16_bf16 v[96:111], v[248:251], v[136:139], v[96:111]
	s_waitcnt lgkmcnt(0)
	v_mfma_f32_32x32x16_bf16 v[48:63], v[152:155], v[140:143], v[48:63]
	v_mfma_f32_32x32x16_bf16 v[112:127], v[248:251], v[140:143], v[112:127]
	s_waitcnt lgkmcnt(0)
	s_barrier
	ds_read_b128 v[128:131], v241 offset:30720
	ds_read_b128 v[132:135], v241 offset:33280
	ds_read_b128 v[136:139], v241 offset:35840
	ds_read_b128 v[140:143], v241 offset:38400
	ds_read_b128 v[144:147], v240 offset:30720
	ds_read_b128 v[148:151], v240 offset:33280
	ds_read_b128 v[152:155], v240 offset:30752
	ds_read_b128 v[248:251], v240 offset:33312
	s_waitcnt lgkmcnt(2)
	v_mfma_f32_32x32x16_bf16 v[0:15], v[144:147], v[128:131], v[0:15]
	v_mfma_f32_32x32x16_bf16 v[64:79], v[148:151], v[128:131], v[64:79]
	ds_read_b128 v[128:131], v241 offset:30752
	s_waitcnt vmcnt(6)
	ds_write_b128 v242, v[158:161] offset:0
	ds_write_b128 v242, v[162:165] offset:5120
	v_mfma_f32_32x32x16_bf16 v[16:31], v[144:147], v[132:135], v[16:31]
	v_mfma_f32_32x32x16_bf16 v[80:95], v[148:151], v[132:135], v[80:95]
	ds_read_b128 v[132:135], v241 offset:33312
	ds_write_b128 v242, v[166:169] offset:10240
	ds_write_b128 v242, v[170:173] offset:15360
	v_mfma_f32_32x32x16_bf16 v[32:47], v[144:147], v[136:139], v[32:47]
	v_mfma_f32_32x32x16_bf16 v[96:111], v[148:151], v[136:139], v[96:111]
	ds_read_b128 v[136:139], v241 offset:35872
	ds_write_b128 v242, v[174:177] offset:20480
	ds_write_b128 v242, v[178:181] offset:25600
	v_mfma_f32_32x32x16_bf16 v[48:63], v[144:147], v[140:143], v[48:63]
	v_mfma_f32_32x32x16_bf16 v[112:127], v[148:151], v[140:143], v[112:127]
	ds_read_b128 v[140:143], v241 offset:38432
	s_waitcnt lgkmcnt(9)
	v_mfma_f32_32x32x16_bf16 v[0:15], v[152:155], v[128:131], v[0:15]
	global_load_dwordx4 v[158:161], v[182:183], off offset:1024
	global_load_dwordx4 v[162:165], v[184:185], off offset:1024
	v_mfma_f32_32x32x16_bf16 v[64:79], v[248:251], v[128:131], v[64:79]
	s_waitcnt lgkmcnt(6)
	v_mfma_f32_32x32x16_bf16 v[16:31], v[152:155], v[132:135], v[16:31]
	global_load_dwordx4 v[166:169], v[186:187], off offset:1024
	global_load_dwordx4 v[170:173], v[188:189], off offset:1024
	v_mfma_f32_32x32x16_bf16 v[80:95], v[248:251], v[132:135], v[80:95]
	s_waitcnt lgkmcnt(3)
	v_mfma_f32_32x32x16_bf16 v[32:47], v[152:155], v[136:139], v[32:47]
	global_load_dwordx4 v[174:177], v[190:191], off offset:1024
	global_load_dwordx4 v[178:181], v[192:193], off offset:1024
	v_mfma_f32_32x32x16_bf16 v[96:111], v[248:251], v[136:139], v[96:111]
	s_waitcnt lgkmcnt(0)
	v_mfma_f32_32x32x16_bf16 v[48:63], v[152:155], v[140:143], v[48:63]
	v_mfma_f32_32x32x16_bf16 v[112:127], v[248:251], v[140:143], v[112:127]
	s_waitcnt lgkmcnt(0)
	s_barrier
; #define G_LOAD(S, kt_) do { G_LD1(S##a0, S##b0, 0, kt_); G_LD1(S##a1, S##b1, 1, kt_); G_LD1(S##a2, S##b2, 2, kt_); G_LD1(S##a3, S##b3, 3, kt_); } while (0)
; #define G_STORE(S, buf_) do { G_ST1(S##a0, S##b0, 0, buf_); G_ST1(S##a1, S##b1, 1, buf_); G_ST1(S##a2, S##b2, 2, buf_); G_ST1(S##a3, S##b3, 3, buf_); } while (0)
; template <class AL, class BL>
; DI void gemm_core(AL al, BL bl, int m0, int n0, int K, char* smem, f32x16 (&acc)[2][2]) {
;     ...
;   G_LOAD(x, 0);
;   G_STORE(x, 0);
;   G_LOAD(x, 1);
;   G_LOAD(y, (nk > 2) ? 2 : 1);
;   __syncthreads();
;   for (int kt = 0; kt < nk; kt += 2) {
;     G_TILE(0, x, true, (kt + 3 < nk), kt + 3);
;     __syncthreads();
;     G_TILE(1, y, (kt + 2 < nk), (kt + 4 < nk), kt + 4);
;     __syncthreads();
;   }
	ds_read_b128 v[128:131], v241 offset:0
	ds_read_b128 v[132:135], v241 offset:2560
	ds_read_b128 v[136:139], v241 offset:5120
	ds_read_b128 v[140:143], v241 offset:7680
	ds_read_b128 v[144:147], v240 offset:0
	ds_read_b128 v[148:151], v240 offset:2560
	ds_read_b128 v[152:155], v240 offset:32
	ds_read_b128 v[248:251], v240 offset:2592
	s_waitcnt lgkmcnt(2)
	v_mfma_f32_32x32x16_bf16 v[0:15], v[144:147], v[128:131], v[0:15]
	v_mfma_f32_32x32x16_bf16 v[64:79], v[148:151], v[128:131], v[64:79]
	ds_read_b128 v[128:131], v241 offset:32
	s_waitcnt vmcnt(6)
	ds_write_b128 v242, v[214:217] offset:30720
	ds_write_b128 v242, v[218:221] offset:35840
	v_mfma_f32_32x32x16_bf16 v[16:31], v[144:147], v[132:135], v[16:31]
	v_mfma_f32_32x32x16_bf16 v[80:95], v[148:151], v[132:135], v[80:95]
	ds_read_b128 v[132:135], v241 offset:2592
	ds_write_b128 v242, v[222:225] offset:40960
	ds_write_b128 v242, v[228:231] offset:46080
	v_mfma_f32_32x32x16_bf16 v[32:47], v[144:147], v[136:139], v[32:47]
	v_mfma_f32_32x32x16_bf16 v[96:111], v[148:151], v[136:139], v[96:111]
	ds_read_b128 v[136:139], v241 offset:5152
	ds_write_b128 v242, v[232:235] offset:51200
	ds_write_b128 v242, v[236:239] offset:56320
	v_mfma_f32_32x32x16_bf16 v[48:63], v[144:147], v[140:143], v[48:63]
	v_mfma_f32_32x32x16_bf16 v[112:127], v[148:151], v[140:143], v[112:127]
	ds_read_b128 v[140:143], v241 offset:7712
	s_waitcnt lgkmcnt(9)
	v_mfma_f32_32x32x16_bf16 v[0:15], v[152:155], v[128:131], v[0:15]
	global_load_dwordx4 v[214:217], v[182:183], off offset:1088
	global_load_dwordx4 v[218:221], v[184:185], off offset:1088
	v_mfma_f32_32x32x16_bf16 v[64:79], v[248:251], v[128:131], v[64:79]
	s_waitcnt lgkmcnt(6)
	v_mfma_f32_32x32x16_bf16 v[16:31], v[152:155], v[132:135], v[16:31]
	global_load_dwordx4 v[222:225], v[186:187], off offset:1088
	global_load_dwordx4 v[228:231], v[188:189], off offset:1088
	v_mfma_f32_32x32x16_bf16 v[80:95], v[248:251], v[132:135], v[80:95]
	s_waitcnt lgkmcnt(3)
	v_mfma_f32_32x32x16_bf16 v[32:47], v[152:155], v[136:139], v[32:47]
	global_load_dwordx4 v[232:235], v[190:191], off offset:1088
	global_load_dwordx4 v[236:239], v[192:193], off offset:1088
	v_mfma_f32_32x32x16_bf16 v[96:111], v[248:251], v[136:139], v[96:111]
	s_waitcnt lgkmcnt(0)
	v_mfma_f32_32x32x16_bf16 v[48:63], v[152:155], v[140:143], v[48:63]
	v_mfma_f32_32x32x16_bf16 v[112:127], v[248:251], v[140:143], v[112:127]
	s_waitcnt lgkmcnt(0)
	s_barrier
	ds_read_b128 v[128:131], v241 offset:30720
	ds_read_b128 v[132:135], v241 offset:33280
	ds_read_b128 v[136:139], v241 offset:35840
	ds_read_b128 v[140:143], v241 offset:38400
	ds_read_b128 v[144:147], v240 offset:30720
	ds_read_b128 v[148:151], v240 offset:33280
	ds_read_b128 v[152:155], v240 offset:30752
	ds_read_b128 v[248:251], v240 offset:33312
	s_waitcnt lgkmcnt(2)
	v_mfma_f32_32x32x16_bf16 v[0:15], v[144:147], v[128:131], v[0:15]
	v_mfma_f32_32x32x16_bf16 v[64:79], v[148:151], v[128:131], v[64:79]
	ds_read_b128 v[128:131], v241 offset:30752
	s_waitcnt vmcnt(6)
	ds_write_b128 v242, v[158:161] offset:0
	ds_write_b128 v242, v[162:165] offset:5120
	v_mfma_f32_32x32x16_bf16 v[16:31], v[144:147], v[132:135], v[16:31]
	v_mfma_f32_32x32x16_bf16 v[80:95], v[148:151], v[132:135], v[80:95]
	ds_read_b128 v[132:135], v241 offset:33312
	ds_write_b128 v242, v[166:169] offset:10240
	ds_write_b128 v242, v[170:173] offset:15360
	v_mfma_f32_32x32x16_bf16 v[32:47], v[144:147], v[136:139], v[32:47]
	v_mfma_f32_32x32x16_bf16 v[96:111], v[148:151], v[136:139], v[96:111]
	ds_read_b128 v[136:139], v241 offset:35872
	ds_write_b128 v242, v[174:177] offset:20480
	ds_write_b128 v242, v[178:181] offset:25600
	v_mfma_f32_32x32x16_bf16 v[48:63], v[144:147], v[140:143], v[48:63]
	v_mfma_f32_32x32x16_bf16 v[112:127], v[148:151], v[140:143], v[112:127]
	ds_read_b128 v[140:143], v241 offset:38432
	s_waitcnt lgkmcnt(9)
	v_mfma_f32_32x32x16_bf16 v[0:15], v[152:155], v[128:131], v[0:15]
	global_load_dwordx4 v[158:161], v[182:183], off offset:1152
	global_load_dwordx4 v[162:165], v[184:185], off offset:1152
	v_mfma_f32_32x32x16_bf16 v[64:79], v[248:251], v[128:131], v[64:79]
	s_waitcnt lgkmcnt(6)
	v_mfma_f32_32x32x16_bf16 v[16:31], v[152:155], v[132:135], v[16:31]
	global_load_dwordx4 v[166:169], v[186:187], off offset:1152
	global_load_dwordx4 v[170:173], v[188:189], off offset:1152
	v_mfma_f32_32x32x16_bf16 v[80:95], v[248:251], v[132:135], v[80:95]
	s_waitcnt lgkmcnt(3)
	v_mfma_f32_32x32x16_bf16 v[32:47], v[152:155], v[136:139], v[32:47]
	global_load_dwordx4 v[174:177], v[190:191], off offset:1152
	global_load_dwordx4 v[178:181], v[192:193], off offset:1152
	v_mfma_f32_32x32x16_bf16 v[96:111], v[248:251], v[136:139], v[96:111]
	s_waitcnt lgkmcnt(0)
	v_mfma_f32_32x32x16_bf16 v[48:63], v[152:155], v[140:143], v[48:63]
	v_mfma_f32_32x32x16_bf16 v[112:127], v[248:251], v[140:143], v[112:127]
	s_waitcnt lgkmcnt(0)
	s_barrier
; #define G_LOAD(S, kt_) do { G_LD1(S##a0, S##b0, 0, kt_); G_LD1(S##a1, S##b1, 1, kt_); G_LD1(S##a2, S##b2, 2, kt_); G_LD1(S##a3, S##b3, 3, kt_); } while (0)
; #define G_STORE(S, buf_) do { G_ST1(S##a0, S##b0, 0, buf_); G_ST1(S##a1, S##b1, 1, buf_); G_ST1(S##a2, S##b2, 2, buf_); G_ST1(S##a3, S##b3, 3, buf_); } while (0)
; template <class AL, class BL>
; DI void gemm_core(AL al, BL bl, int m0, int n0, int K, char* smem, f32x16 (&acc)[2][2]) {
;     ...
;   G_LOAD(x, 0);
;   G_STORE(x, 0);
;   G_LOAD(x, 1);
;   G_LOAD(y, (nk > 2) ? 2 : 1);
;   __syncthreads();
;   for (int kt = 0; kt < nk; kt += 2) {
;     G_TILE(0, x, true, (kt + 3 < nk), kt + 3);
;     __syncthreads();
;     G_TILE(1, y, (kt + 2 < nk), (kt + 4 < nk), kt + 4);
;     __syncthreads();
;   }
	ds_read_b128 v[128:131], v241 offset:0
	ds_read_b128 v[132:135], v241 offset:2560
	ds_read_b128 v[136:139], v241 offset:5120
	ds_read_b128 v[140:143], v241 offset:7680
	ds_read_b128 v[144:147], v240 offset:0
	ds_read_b128 v[148:151], v240 offset:2560
	ds_read_b128 v[152:155], v240 offset:32
	ds_read_b128 v[248:251], v240 offset:2592
	s_waitcnt lgkmcnt(2)
	v_mfma_f32_32x32x16_bf16 v[0:15], v[144:147], v[128:131], v[0:15]
	v_mfma_f32_32x32x16_bf16 v[64:79], v[148:151], v[128:131], v[64:79]
	ds_read_b128 v[128:131], v241 offset:32
	s_waitcnt vmcnt(6)
	ds_write_b128 v242, v[214:217] offset:30720
	ds_write_b128 v242, v[218:221] offset:35840
	v_mfma_f32_32x32x16_bf16 v[16:31], v[144:147], v[132:135], v[16:31]
	v_mfma_f32_32x32x16_bf16 v[80:95], v[148:151], v[132:135], v[80:95]
	ds_read_b128 v[132:135], v241 offset:2592
	ds_write_b128 v242, v[222:225] offset:40960
	ds_write_b128 v242, v[228:231] offset:46080
	v_mfma_f32_32x32x16_bf16 v[32:47], v[144:147], v[136:139], v[32:47]
	v_mfma_f32_32x32x16_bf16 v[96:111], v[148:151], v[136:139], v[96:111]
	ds_read_b128 v[136:139], v241 offset:5152
	ds_write_b128 v242, v[232:235] offset:51200
	ds_write_b128 v242, v[236:239] offset:56320
	v_mfma_f32_32x32x16_bf16 v[48:63], v[144:147], v[140:143], v[48:63]
	v_mfma_f32_32x32x16_bf16 v[112:127], v[148:151], v[140:143], v[112:127]
	ds_read_b128 v[140:143], v241 offset:7712
	s_waitcnt lgkmcnt(9)
	v_mfma_f32_32x32x16_bf16 v[0:15], v[152:155], v[128:131], v[0:15]
	global_load_dwordx4 v[214:217], v[182:183], off offset:1216
	global_load_dwordx4 v[218:221], v[184:185], off offset:1216
	v_mfma_f32_32x32x16_bf16 v[64:79], v[248:251], v[128:131], v[64:79]
	s_waitcnt lgkmcnt(6)
	v_mfma_f32_32x32x16_bf16 v[16:31], v[152:155], v[132:135], v[16:31]
	global_load_dwordx4 v[222:225], v[186:187], off offset:1216
	global_load_dwordx4 v[228:231], v[188:189], off offset:1216
	v_mfma_f32_32x32x16_bf16 v[80:95], v[248:251], v[132:135], v[80:95]
	s_waitcnt lgkmcnt(3)
	v_mfma_f32_32x32x16_bf16 v[32:47], v[152:155], v[136:139], v[32:47]
	global_load_dwordx4 v[232:235], v[190:191], off offset:1216
	global_load_dwordx4 v[236:239], v[192:193], off offset:1216
	v_mfma_f32_32x32x16_bf16 v[96:111], v[248:251], v[136:139], v[96:111]
	s_waitcnt lgkmcnt(0)
	v_mfma_f32_32x32x16_bf16 v[48:63], v[152:155], v[140:143], v[48:63]
	v_mfma_f32_32x32x16_bf16 v[112:127], v[248:251], v[140:143], v[112:127]
	s_waitcnt lgkmcnt(0)
	s_barrier
	ds_read_b128 v[128:131], v241 offset:30720
	ds_read_b128 v[132:135], v241 offset:33280
	ds_read_b128 v[136:139], v241 offset:35840
	ds_read_b128 v[140:143], v241 offset:38400
	ds_read_b128 v[144:147], v240 offset:30720
	ds_read_b128 v[148:151], v240 offset:33280
	ds_read_b128 v[152:155], v240 offset:30752
	ds_read_b128 v[248:251], v240 offset:33312
	s_waitcnt lgkmcnt(2)
	v_mfma_f32_32x32x16_bf16 v[0:15], v[144:147], v[128:131], v[0:15]
	v_mfma_f32_32x32x16_bf16 v[64:79], v[148:151], v[128:131], v[64:79]
	ds_read_b128 v[128:131], v241 offset:30752
	s_waitcnt vmcnt(6)
	ds_write_b128 v242, v[158:161] offset:0
	ds_write_b128 v242, v[162:165] offset:5120
	v_mfma_f32_32x32x16_bf16 v[16:31], v[144:147], v[132:135], v[16:31]
	v_mfma_f32_32x32x16_bf16 v[80:95], v[148:151], v[132:135], v[80:95]
	ds_read_b128 v[132:135], v241 offset:33312
	ds_write_b128 v242, v[166:169] offset:10240
	ds_write_b128 v242, v[170:173] offset:15360
	v_mfma_f32_32x32x16_bf16 v[32:47], v[144:147], v[136:139], v[32:47]
	v_mfma_f32_32x32x16_bf16 v[96:111], v[148:151], v[136:139], v[96:111]
	ds_read_b128 v[136:139], v241 offset:35872
	ds_write_b128 v242, v[174:177] offset:20480
	ds_write_b128 v242, v[178:181] offset:25600
	v_mfma_f32_32x32x16_bf16 v[48:63], v[144:147], v[140:143], v[48:63]
	v_mfma_f32_32x32x16_bf16 v[112:127], v[148:151], v[140:143], v[112:127]
	ds_read_b128 v[140:143], v241 offset:38432
	s_waitcnt lgkmcnt(9)
	v_mfma_f32_32x32x16_bf16 v[0:15], v[152:155], v[128:131], v[0:15]
	global_load_dwordx4 v[158:161], v[182:183], off offset:1280
	global_load_dwordx4 v[162:165], v[184:185], off offset:1280
	v_mfma_f32_32x32x16_bf16 v[64:79], v[248:251], v[128:131], v[64:79]
	s_waitcnt lgkmcnt(6)
	v_mfma_f32_32x32x16_bf16 v[16:31], v[152:155], v[132:135], v[16:31]
	global_load_dwordx4 v[166:169], v[186:187], off offset:1280
	global_load_dwordx4 v[170:173], v[188:189], off offset:1280
	v_mfma_f32_32x32x16_bf16 v[80:95], v[248:251], v[132:135], v[80:95]
	s_waitcnt lgkmcnt(3)
	v_mfma_f32_32x32x16_bf16 v[32:47], v[152:155], v[136:139], v[32:47]
	global_load_dwordx4 v[174:177], v[190:191], off offset:1280
	global_load_dwordx4 v[178:181], v[192:193], off offset:1280
	v_mfma_f32_32x32x16_bf16 v[96:111], v[248:251], v[136:139], v[96:111]
	s_waitcnt lgkmcnt(0)
	v_mfma_f32_32x32x16_bf16 v[48:63], v[152:155], v[140:143], v[48:63]
	v_mfma_f32_32x32x16_bf16 v[112:127], v[248:251], v[140:143], v[112:127]
	s_waitcnt lgkmcnt(0)
	s_barrier
; #define G_LOAD(S, kt_) do { G_LD1(S##a0, S##b0, 0, kt_); G_LD1(S##a1, S##b1, 1, kt_); G_LD1(S##a2, S##b2, 2, kt_); G_LD1(S##a3, S##b3, 3, kt_); } while (0)
; #define G_STORE(S, buf_) do { G_ST1(S##a0, S##b0, 0, buf_); G_ST1(S##a1, S##b1, 1, buf_); G_ST1(S##a2, S##b2, 2, buf_); G_ST1(S##a3, S##b3, 3, buf_); } while (0)
; template <class AL, class BL>
; DI void gemm_core(AL al, BL bl, int m0, int n0, int K, char* smem, f32x16 (&acc)[2][2]) {
;     ...
;   G_LOAD(x, 0);
;   G_STORE(x, 0);
;   G_LOAD(x, 1);
;   G_LOAD(y, (nk > 2) ? 2 : 1);
;   __syncthreads();
;   for (int kt = 0; kt < nk; kt += 2) {
;     G_TILE(0, x, true, (kt + 3 < nk), kt + 3);
;     __syncthreads();
;     G_TILE(1, y, (kt + 2 < nk), (kt + 4 < nk), kt + 4);
;     __syncthreads();
;   }
	ds_read_b128 v[128:131], v241 offset:0
	ds_read_b128 v[132:135], v241 offset:2560
	ds_read_b128 v[136:139], v241 offset:5120
	ds_read_b128 v[140:143], v241 offset:7680
	ds_read_b128 v[144:147], v240 offset:0
	ds_read_b128 v[148:151], v240 offset:2560
	ds_read_b128 v[152:155], v240 offset:32
	ds_read_b128 v[248:251], v240 offset:2592
	s_waitcnt lgkmcnt(2)
	v_mfma_f32_32x32x16_bf16 v[0:15], v[144:147], v[128:131], v[0:15]
	v_mfma_f32_32x32x16_bf16 v[64:79], v[148:151], v[128:131], v[64:79]
	ds_read_b128 v[128:131], v241 offset:32
	s_waitcnt vmcnt(6)
	ds_write_b128 v242, v[214:217] offset:30720
	ds_write_b128 v242, v[218:221] offset:35840
	v_mfma_f32_32x32x16_bf16 v[16:31], v[144:147], v[132:135], v[16:31]
	v_mfma_f32_32x32x16_bf16 v[80:95], v[148:151], v[132:135], v[80:95]
	ds_read_b128 v[132:135], v241 offset:2592
	ds_write_b128 v242, v[222:225] offset:40960
	ds_write_b128 v242, v[228:231] offset:46080
	v_mfma_f32_32x32x16_bf16 v[32:47], v[144:147], v[136:139], v[32:47]
	v_mfma_f32_32x32x16_bf16 v[96:111], v[148:151], v[136:139], v[96:111]
	ds_read_b128 v[136:139], v241 offset:5152
	ds_write_b128 v242, v[232:235] offset:51200
	ds_write_b128 v242, v[236:239] offset:56320
	v_mfma_f32_32x32x16_bf16 v[48:63], v[144:147], v[140:143], v[48:63]
	v_mfma_f32_32x32x16_bf16 v[112:127], v[148:151], v[140:143], v[112:127]
	ds_read_b128 v[140:143], v241 offset:7712
	s_waitcnt lgkmcnt(9)
	v_mfma_f32_32x32x16_bf16 v[0:15], v[152:155], v[128:131], v[0:15]
	global_load_dwordx4 v[214:217], v[182:183], off offset:1344
	global_load_dwordx4 v[218:221], v[184:185], off offset:1344
	v_mfma_f32_32x32x16_bf16 v[64:79], v[248:251], v[128:131], v[64:79]
	s_waitcnt lgkmcnt(6)
	v_mfma_f32_32x32x16_bf16 v[16:31], v[152:155], v[132:135], v[16:31]
	global_load_dwordx4 v[222:225], v[186:187], off offset:1344
	global_load_dwordx4 v[228:231], v[188:189], off offset:1344
	v_mfma_f32_32x32x16_bf16 v[80:95], v[248:251], v[132:135], v[80:95]
	s_waitcnt lgkmcnt(3)
	v_mfma_f32_32x32x16_bf16 v[32:47], v[152:155], v[136:139], v[32:47]
	global_load_dwordx4 v[232:235], v[190:191], off offset:1344
	global_load_dwordx4 v[236:239], v[192:193], off offset:1344
	v_mfma_f32_32x32x16_bf16 v[96:111], v[248:251], v[136:139], v[96:111]
	s_waitcnt lgkmcnt(0)
	v_mfma_f32_32x32x16_bf16 v[48:63], v[152:155], v[140:143], v[48:63]
	v_mfma_f32_32x32x16_bf16 v[112:127], v[248:251], v[140:143], v[112:127]
	s_waitcnt lgkmcnt(0)
	s_barrier
	ds_read_b128 v[128:131], v241 offset:30720
	ds_read_b128 v[132:135], v241 offset:33280
	ds_read_b128 v[136:139], v241 offset:35840
	ds_read_b128 v[140:143], v241 offset:38400
	ds_read_b128 v[144:147], v240 offset:30720
	ds_read_b128 v[148:151], v240 offset:33280
	ds_read_b128 v[152:155], v240 offset:30752
	ds_read_b128 v[248:251], v240 offset:33312
	s_waitcnt lgkmcnt(2)
	v_mfma_f32_32x32x16_bf16 v[0:15], v[144:147], v[128:131], v[0:15]
	v_mfma_f32_32x32x16_bf16 v[64:79], v[148:151], v[128:131], v[64:79]
	ds_read_b128 v[128:131], v241 offset:30752
	s_waitcnt vmcnt(6)
	ds_write_b128 v242, v[158:161] offset:0
	ds_write_b128 v242, v[162:165] offset:5120
	v_mfma_f32_32x32x16_bf16 v[16:31], v[144:147], v[132:135], v[16:31]
	v_mfma_f32_32x32x16_bf16 v[80:95], v[148:151], v[132:135], v[80:95]
	ds_read_b128 v[132:135], v241 offset:33312
	ds_write_b128 v242, v[166:169] offset:10240
	ds_write_b128 v242, v[170:173] offset:15360
	v_mfma_f32_32x32x16_bf16 v[32:47], v[144:147], v[136:139], v[32:47]
	v_mfma_f32_32x32x16_bf16 v[96:111], v[148:151], v[136:139], v[96:111]
	ds_read_b128 v[136:139], v241 offset:35872
	ds_write_b128 v242, v[174:177] offset:20480
	ds_write_b128 v242, v[178:181] offset:25600
	v_mfma_f32_32x32x16_bf16 v[48:63], v[144:147], v[140:143], v[48:63]
	v_mfma_f32_32x32x16_bf16 v[112:127], v[148:151], v[140:143], v[112:127]
	ds_read_b128 v[140:143], v241 offset:38432
	s_waitcnt lgkmcnt(9)
	v_mfma_f32_32x32x16_bf16 v[0:15], v[152:155], v[128:131], v[0:15]
	global_load_dwordx4 v[158:161], v[182:183], off offset:1408
	global_load_dwordx4 v[162:165], v[184:185], off offset:1408
	v_mfma_f32_32x32x16_bf16 v[64:79], v[248:251], v[128:131], v[64:79]
	s_waitcnt lgkmcnt(6)
	v_mfma_f32_32x32x16_bf16 v[16:31], v[152:155], v[132:135], v[16:31]
	global_load_dwordx4 v[166:169], v[186:187], off offset:1408
	global_load_dwordx4 v[170:173], v[188:189], off offset:1408
	v_mfma_f32_32x32x16_bf16 v[80:95], v[248:251], v[132:135], v[80:95]
	s_waitcnt lgkmcnt(3)
	v_mfma_f32_32x32x16_bf16 v[32:47], v[152:155], v[136:139], v[32:47]
	global_load_dwordx4 v[174:177], v[190:191], off offset:1408
	global_load_dwordx4 v[178:181], v[192:193], off offset:1408
	v_mfma_f32_32x32x16_bf16 v[96:111], v[248:251], v[136:139], v[96:111]
	s_waitcnt lgkmcnt(0)
	v_mfma_f32_32x32x16_bf16 v[48:63], v[152:155], v[140:143], v[48:63]
	v_mfma_f32_32x32x16_bf16 v[112:127], v[248:251], v[140:143], v[112:127]
	s_waitcnt lgkmcnt(0)
	s_barrier
; #define G_LOAD(S, kt_) do { G_LD1(S##a0, S##b0, 0, kt_); G_LD1(S##a1, S##b1, 1, kt_); G_LD1(S##a2, S##b2, 2, kt_); G_LD1(S##a3, S##b3, 3, kt_); } while (0)
; #define G_STORE(S, buf_) do { G_ST1(S##a0, S##b0, 0, buf_); G_ST1(S##a1, S##b1, 1, buf_); G_ST1(S##a2, S##b2, 2, buf_); G_ST1(S##a3, S##b3, 3, buf_); } while (0)
; template <class AL, class BL>
; DI void gemm_core(AL al, BL bl, int m0, int n0, int K, char* smem, f32x16 (&acc)[2][2]) {
;     ...
;   G_LOAD(x, 0);
;   G_STORE(x, 0);
;   G_LOAD(x, 1);
;   G_LOAD(y, (nk > 2) ? 2 : 1);
;   __syncthreads();
;   for (int kt = 0; kt < nk; kt += 2) {
;     G_TILE(0, x, true, (kt + 3 < nk), kt + 3);
;     __syncthreads();
;     G_TILE(1, y, (kt + 2 < nk), (kt + 4 < nk), kt + 4);
;     __syncthreads();
;   }
	ds_read_b128 v[128:131], v241 offset:0
	ds_read_b128 v[132:135], v241 offset:2560
	ds_read_b128 v[136:139], v241 offset:5120
	ds_read_b128 v[140:143], v241 offset:7680
	ds_read_b128 v[144:147], v240 offset:0
	ds_read_b128 v[148:151], v240 offset:2560
	ds_read_b128 v[152:155], v240 offset:32
	ds_read_b128 v[248:251], v240 offset:2592
	s_waitcnt lgkmcnt(2)
	v_mfma_f32_32x32x16_bf16 v[0:15], v[144:147], v[128:131], v[0:15]
	v_mfma_f32_32x32x16_bf16 v[64:79], v[148:151], v[128:131], v[64:79]
	ds_read_b128 v[128:131], v241 offset:32
	s_waitcnt vmcnt(6)
	ds_write_b128 v242, v[214:217] offset:30720
	ds_write_b128 v242, v[218:221] offset:35840
	v_mfma_f32_32x32x16_bf16 v[16:31], v[144:147], v[132:135], v[16:31]
	v_mfma_f32_32x32x16_bf16 v[80:95], v[148:151], v[132:135], v[80:95]
	ds_read_b128 v[132:135], v241 offset:2592
	ds_write_b128 v242, v[222:225] offset:40960
	ds_write_b128 v242, v[228:231] offset:46080
	v_mfma_f32_32x32x16_bf16 v[32:47], v[144:147], v[136:139], v[32:47]
	v_mfma_f32_32x32x16_bf16 v[96:111], v[148:151], v[136:139], v[96:111]
	ds_read_b128 v[136:139], v241 offset:5152
	ds_write_b128 v242, v[232:235] offset:51200
	ds_write_b128 v242, v[236:239] offset:56320
	v_mfma_f32_32x32x16_bf16 v[48:63], v[144:147], v[140:143], v[48:63]
	v_mfma_f32_32x32x16_bf16 v[112:127], v[148:151], v[140:143], v[112:127]
	ds_read_b128 v[140:143], v241 offset:7712
	s_waitcnt lgkmcnt(9)
	v_mfma_f32_32x32x16_bf16 v[0:15], v[152:155], v[128:131], v[0:15]
	global_load_dwordx4 v[214:217], v[182:183], off offset:1472
	global_load_dwordx4 v[218:221], v[184:185], off offset:1472
	v_mfma_f32_32x32x16_bf16 v[64:79], v[248:251], v[128:131], v[64:79]
	s_waitcnt lgkmcnt(6)
	v_mfma_f32_32x32x16_bf16 v[16:31], v[152:155], v[132:135], v[16:31]
	global_load_dwordx4 v[222:225], v[186:187], off offset:1472
	global_load_dwordx4 v[228:231], v[188:189], off offset:1472
	v_mfma_f32_32x32x16_bf16 v[80:95], v[248:251], v[132:135], v[80:95]
	s_waitcnt lgkmcnt(3)
	v_mfma_f32_32x32x16_bf16 v[32:47], v[152:155], v[136:139], v[32:47]
	global_load_dwordx4 v[232:235], v[190:191], off offset:1472
	global_load_dwordx4 v[236:239], v[192:193], off offset:1472
	v_mfma_f32_32x32x16_bf16 v[96:111], v[248:251], v[136:139], v[96:111]
	s_waitcnt lgkmcnt(0)
	v_mfma_f32_32x32x16_bf16 v[48:63], v[152:155], v[140:143], v[48:63]
	v_mfma_f32_32x32x16_bf16 v[112:127], v[248:251], v[140:143], v[112:127]
	s_waitcnt lgkmcnt(0)
	s_barrier
	ds_read_b128 v[128:131], v241 offset:30720
	ds_read_b128 v[132:135], v241 offset:33280
	ds_read_b128 v[136:139], v241 offset:35840
	ds_read_b128 v[140:143], v241 offset:38400
	ds_read_b128 v[144:147], v240 offset:30720
	ds_read_b128 v[148:151], v240 offset:33280
	ds_read_b128 v[152:155], v240 offset:30752
	ds_read_b128 v[248:251], v240 offset:33312
	s_waitcnt lgkmcnt(2)
	v_mfma_f32_32x32x16_bf16 v[0:15], v[144:147], v[128:131], v[0:15]
	v_mfma_f32_32x32x16_bf16 v[64:79], v[148:151], v[128:131], v[64:79]
	ds_read_b128 v[128:131], v241 offset:30752
	s_waitcnt vmcnt(6)
	ds_write_b128 v242, v[158:161] offset:0
	ds_write_b128 v242, v[162:165] offset:5120
	v_mfma_f32_32x32x16_bf16 v[16:31], v[144:147], v[132:135], v[16:31]
	v_mfma_f32_32x32x16_bf16 v[80:95], v[148:151], v[132:135], v[80:95]
	ds_read_b128 v[132:135], v241 offset:33312
	ds_write_b128 v242, v[166:169] offset:10240
	ds_write_b128 v242, v[170:173] offset:15360
	v_mfma_f32_32x32x16_bf16 v[32:47], v[144:147], v[136:139], v[32:47]
	v_mfma_f32_32x32x16_bf16 v[96:111], v[148:151], v[136:139], v[96:111]
	ds_read_b128 v[136:139], v241 offset:35872
	ds_write_b128 v242, v[174:177] offset:20480
	ds_write_b128 v242, v[178:181] offset:25600
	v_mfma_f32_32x32x16_bf16 v[48:63], v[144:147], v[140:143], v[48:63]
	v_mfma_f32_32x32x16_bf16 v[112:127], v[148:151], v[140:143], v[112:127]
	ds_read_b128 v[140:143], v241 offset:38432
	s_waitcnt lgkmcnt(9)
	v_mfma_f32_32x32x16_bf16 v[0:15], v[152:155], v[128:131], v[0:15]
	global_load_dwordx4 v[158:161], v[182:183], off offset:1536
	global_load_dwordx4 v[162:165], v[184:185], off offset:1536
	v_mfma_f32_32x32x16_bf16 v[64:79], v[248:251], v[128:131], v[64:79]
	s_waitcnt lgkmcnt(6)
	v_mfma_f32_32x32x16_bf16 v[16:31], v[152:155], v[132:135], v[16:31]
	global_load_dwordx4 v[166:169], v[186:187], off offset:1536
	global_load_dwordx4 v[170:173], v[188:189], off offset:1536
	v_mfma_f32_32x32x16_bf16 v[80:95], v[248:251], v[132:135], v[80:95]
	s_waitcnt lgkmcnt(3)
	v_mfma_f32_32x32x16_bf16 v[32:47], v[152:155], v[136:139], v[32:47]
	global_load_dwordx4 v[174:177], v[190:191], off offset:1536
	global_load_dwordx4 v[178:181], v[192:193], off offset:1536
	v_mfma_f32_32x32x16_bf16 v[96:111], v[248:251], v[136:139], v[96:111]
	s_waitcnt lgkmcnt(0)
	v_mfma_f32_32x32x16_bf16 v[48:63], v[152:155], v[140:143], v[48:63]
	v_mfma_f32_32x32x16_bf16 v[112:127], v[248:251], v[140:143], v[112:127]
	s_waitcnt lgkmcnt(0)
	s_barrier
; #define G_LOAD(S, kt_) do { G_LD1(S##a0, S##b0, 0, kt_); G_LD1(S##a1, S##b1, 1, kt_); G_LD1(S##a2, S##b2, 2, kt_); G_LD1(S##a3, S##b3, 3, kt_); } while (0)
; #define G_STORE(S, buf_) do { G_ST1(S##a0, S##b0, 0, buf_); G_ST1(S##a1, S##b1, 1, buf_); G_ST1(S##a2, S##b2, 2, buf_); G_ST1(S##a3, S##b3, 3, buf_); } while (0)
; template <class AL, class BL>
; DI void gemm_core(AL al, BL bl, int m0, int n0, int K, char* smem, f32x16 (&acc)[2][2]) {
;     ...
;   G_LOAD(x, 0);
;   G_STORE(x, 0);
;   G_LOAD(x, 1);
;   G_LOAD(y, (nk > 2) ? 2 : 1);
;   __syncthreads();
;   for (int kt = 0; kt < nk; kt += 2) {
;     G_TILE(0, x, true, (kt + 3 < nk), kt + 3);
;     __syncthreads();
;     G_TILE(1, y, (kt + 2 < nk), (kt + 4 < nk), kt + 4);
;     __syncthreads();
;   }
	ds_read_b128 v[128:131], v241 offset:0
	ds_read_b128 v[132:135], v241 offset:2560
	ds_read_b128 v[136:139], v241 offset:5120
	ds_read_b128 v[140:143], v241 offset:7680
	ds_read_b128 v[144:147], v240 offset:0
	ds_read_b128 v[148:151], v240 offset:2560
	ds_read_b128 v[152:155], v240 offset:32
	ds_read_b128 v[248:251], v240 offset:2592
	s_waitcnt lgkmcnt(2)
	v_mfma_f32_32x32x16_bf16 v[0:15], v[144:147], v[128:131], v[0:15]
	v_mfma_f32_32x32x16_bf16 v[64:79], v[148:151], v[128:131], v[64:79]
	ds_read_b128 v[128:131], v241 offset:32
	s_waitcnt vmcnt(6)
	ds_write_b128 v242, v[214:217] offset:30720
	ds_write_b128 v242, v[218:221] offset:35840
	v_mfma_f32_32x32x16_bf16 v[16:31], v[144:147], v[132:135], v[16:31]
	v_mfma_f32_32x32x16_bf16 v[80:95], v[148:151], v[132:135], v[80:95]
	ds_read_b128 v[132:135], v241 offset:2592
	ds_write_b128 v242, v[222:225] offset:40960
	ds_write_b128 v242, v[228:231] offset:46080
	v_mfma_f32_32x32x16_bf16 v[32:47], v[144:147], v[136:139], v[32:47]
	v_mfma_f32_32x32x16_bf16 v[96:111], v[148:151], v[136:139], v[96:111]
	ds_read_b128 v[136:139], v241 offset:5152
	ds_write_b128 v242, v[232:235] offset:51200
	ds_write_b128 v242, v[236:239] offset:56320
	v_mfma_f32_32x32x16_bf16 v[48:63], v[144:147], v[140:143], v[48:63]
	v_mfma_f32_32x32x16_bf16 v[112:127], v[148:151], v[140:143], v[112:127]
	ds_read_b128 v[140:143], v241 offset:7712
	s_waitcnt lgkmcnt(9)
	v_mfma_f32_32x32x16_bf16 v[0:15], v[152:155], v[128:131], v[0:15]
	global_load_dwordx4 v[214:217], v[182:183], off offset:1600
	global_load_dwordx4 v[218:221], v[184:185], off offset:1600
	v_mfma_f32_32x32x16_bf16 v[64:79], v[248:251], v[128:131], v[64:79]
	s_waitcnt lgkmcnt(6)
	v_mfma_f32_32x32x16_bf16 v[16:31], v[152:155], v[132:135], v[16:31]
	global_load_dwordx4 v[222:225], v[186:187], off offset:1600
	global_load_dwordx4 v[228:231], v[188:189], off offset:1600
	v_mfma_f32_32x32x16_bf16 v[80:95], v[248:251], v[132:135], v[80:95]
	s_waitcnt lgkmcnt(3)
	v_mfma_f32_32x32x16_bf16 v[32:47], v[152:155], v[136:139], v[32:47]
	global_load_dwordx4 v[232:235], v[190:191], off offset:1600
	global_load_dwordx4 v[236:239], v[192:193], off offset:1600
	v_mfma_f32_32x32x16_bf16 v[96:111], v[248:251], v[136:139], v[96:111]
	s_waitcnt lgkmcnt(0)
	v_mfma_f32_32x32x16_bf16 v[48:63], v[152:155], v[140:143], v[48:63]
	v_mfma_f32_32x32x16_bf16 v[112:127], v[248:251], v[140:143], v[112:127]
	s_waitcnt lgkmcnt(0)
	s_barrier
	ds_read_b128 v[128:131], v241 offset:30720
	ds_read_b128 v[132:135], v241 offset:33280
	ds_read_b128 v[136:139], v241 offset:35840
	ds_read_b128 v[140:143], v241 offset:38400
	ds_read_b128 v[144:147], v240 offset:30720
	ds_read_b128 v[148:151], v240 offset:33280
	ds_read_b128 v[152:155], v240 offset:30752
	ds_read_b128 v[248:251], v240 offset:33312
	s_waitcnt lgkmcnt(2)
	v_mfma_f32_32x32x16_bf16 v[0:15], v[144:147], v[128:131], v[0:15]
	v_mfma_f32_32x32x16_bf16 v[64:79], v[148:151], v[128:131], v[64:79]
	ds_read_b128 v[128:131], v241 offset:30752
	s_waitcnt vmcnt(6)
	ds_write_b128 v242, v[158:161] offset:0
	ds_write_b128 v242, v[162:165] offset:5120
	v_mfma_f32_32x32x16_bf16 v[16:31], v[144:147], v[132:135], v[16:31]
	v_mfma_f32_32x32x16_bf16 v[80:95], v[148:151], v[132:135], v[80:95]
	ds_read_b128 v[132:135], v241 offset:33312
	ds_write_b128 v242, v[166:169] offset:10240
	ds_write_b128 v242, v[170:173] offset:15360
	v_mfma_f32_32x32x16_bf16 v[32:47], v[144:147], v[136:139], v[32:47]
	v_mfma_f32_32x32x16_bf16 v[96:111], v[148:151], v[136:139], v[96:111]
	ds_read_b128 v[136:139], v241 offset:35872
	ds_write_b128 v242, v[174:177] offset:20480
	ds_write_b128 v242, v[178:181] offset:25600
	v_mfma_f32_32x32x16_bf16 v[48:63], v[144:147], v[140:143], v[48:63]
	v_mfma_f32_32x32x16_bf16 v[112:127], v[148:151], v[140:143], v[112:127]
	ds_read_b128 v[140:143], v241 offset:38432
	s_waitcnt lgkmcnt(9)
	v_mfma_f32_32x32x16_bf16 v[0:15], v[152:155], v[128:131], v[0:15]
	global_load_dwordx4 v[158:161], v[182:183], off offset:1664
	global_load_dwordx4 v[162:165], v[184:185], off offset:1664
	v_mfma_f32_32x32x16_bf16 v[64:79], v[248:251], v[128:131], v[64:79]
	s_waitcnt lgkmcnt(6)
	v_mfma_f32_32x32x16_bf16 v[16:31], v[152:155], v[132:135], v[16:31]
	global_load_dwordx4 v[166:169], v[186:187], off offset:1664
	global_load_dwordx4 v[170:173], v[188:189], off offset:1664
	v_mfma_f32_32x32x16_bf16 v[80:95], v[248:251], v[132:135], v[80:95]
	s_waitcnt lgkmcnt(3)
	v_mfma_f32_32x32x16_bf16 v[32:47], v[152:155], v[136:139], v[32:47]
	global_load_dwordx4 v[174:177], v[190:191], off offset:1664
	global_load_dwordx4 v[178:181], v[192:193], off offset:1664
	v_mfma_f32_32x32x16_bf16 v[96:111], v[248:251], v[136:139], v[96:111]
	s_waitcnt lgkmcnt(0)
	v_mfma_f32_32x32x16_bf16 v[48:63], v[152:155], v[140:143], v[48:63]
	v_mfma_f32_32x32x16_bf16 v[112:127], v[248:251], v[140:143], v[112:127]
	s_waitcnt lgkmcnt(0)
	s_barrier
; #define G_LOAD(S, kt_) do { G_LD1(S##a0, S##b0, 0, kt_); G_LD1(S##a1, S##b1, 1, kt_); G_LD1(S##a2, S##b2, 2, kt_); G_LD1(S##a3, S##b3, 3, kt_); } while (0)
; #define G_STORE(S, buf_) do { G_ST1(S##a0, S##b0, 0, buf_); G_ST1(S##a1, S##b1, 1, buf_); G_ST1(S##a2, S##b2, 2, buf_); G_ST1(S##a3, S##b3, 3, buf_); } while (0)
; template <class AL, class BL>
; DI void gemm_core(AL al, BL bl, int m0, int n0, int K, char* smem, f32x16 (&acc)[2][2]) {
;     ...
;   G_LOAD(x, 0);
;   G_STORE(x, 0);
;   G_LOAD(x, 1);
;   G_LOAD(y, (nk > 2) ? 2 : 1);
;   __syncthreads();
;   for (int kt = 0; kt < nk; kt += 2) {
;     G_TILE(0, x, true, (kt + 3 < nk), kt + 3);
;     __syncthreads();
;     G_TILE(1, y, (kt + 2 < nk), (kt + 4 < nk), kt + 4);
;     __syncthreads();
;   }
	ds_read_b128 v[128:131], v241 offset:0
	ds_read_b128 v[132:135], v241 offset:2560
	ds_read_b128 v[136:139], v241 offset:5120
	ds_read_b128 v[140:143], v241 offset:7680
	ds_read_b128 v[144:147], v240 offset:0
	ds_read_b128 v[148:151], v240 offset:2560
	ds_read_b128 v[152:155], v240 offset:32
	ds_read_b128 v[248:251], v240 offset:2592
	s_waitcnt lgkmcnt(2)
	v_mfma_f32_32x32x16_bf16 v[0:15], v[144:147], v[128:131], v[0:15]
	v_mfma_f32_32x32x16_bf16 v[64:79], v[148:151], v[128:131], v[64:79]
	ds_read_b128 v[128:131], v241 offset:32
	s_waitcnt vmcnt(6)
	ds_write_b128 v242, v[214:217] offset:30720
	ds_write_b128 v242, v[218:221] offset:35840
	v_mfma_f32_32x32x16_bf16 v[16:31], v[144:147], v[132:135], v[16:31]
	v_mfma_f32_32x32x16_bf16 v[80:95], v[148:151], v[132:135], v[80:95]
	ds_read_b128 v[132:135], v241 offset:2592
	ds_write_b128 v242, v[222:225] offset:40960
	ds_write_b128 v242, v[228:231] offset:46080
	v_mfma_f32_32x32x16_bf16 v[32:47], v[144:147], v[136:139], v[32:47]
	v_mfma_f32_32x32x16_bf16 v[96:111], v[148:151], v[136:139], v[96:111]
	ds_read_b128 v[136:139], v241 offset:5152
	ds_write_b128 v242, v[232:235] offset:51200
	ds_write_b128 v242, v[236:239] offset:56320
	v_mfma_f32_32x32x16_bf16 v[48:63], v[144:147], v[140:143], v[48:63]
	v_mfma_f32_32x32x16_bf16 v[112:127], v[148:151], v[140:143], v[112:127]
	ds_read_b128 v[140:143], v241 offset:7712
	s_waitcnt lgkmcnt(9)
	v_mfma_f32_32x32x16_bf16 v[0:15], v[152:155], v[128:131], v[0:15]
	global_load_dwordx4 v[214:217], v[182:183], off offset:1728
	global_load_dwordx4 v[218:221], v[184:185], off offset:1728
	v_mfma_f32_32x32x16_bf16 v[64:79], v[248:251], v[128:131], v[64:79]
	s_waitcnt lgkmcnt(6)
	v_mfma_f32_32x32x16_bf16 v[16:31], v[152:155], v[132:135], v[16:31]
	global_load_dwordx4 v[222:225], v[186:187], off offset:1728
	global_load_dwordx4 v[228:231], v[188:189], off offset:1728
	v_mfma_f32_32x32x16_bf16 v[80:95], v[248:251], v[132:135], v[80:95]
	s_waitcnt lgkmcnt(3)
	v_mfma_f32_32x32x16_bf16 v[32:47], v[152:155], v[136:139], v[32:47]
	global_load_dwordx4 v[232:235], v[190:191], off offset:1728
	global_load_dwordx4 v[236:239], v[192:193], off offset:1728
	v_mfma_f32_32x32x16_bf16 v[96:111], v[248:251], v[136:139], v[96:111]
	s_waitcnt lgkmcnt(0)
	v_mfma_f32_32x32x16_bf16 v[48:63], v[152:155], v[140:143], v[48:63]
	v_mfma_f32_32x32x16_bf16 v[112:127], v[248:251], v[140:143], v[112:127]
	s_waitcnt lgkmcnt(0)
	s_barrier
	ds_read_b128 v[128:131], v241 offset:30720
	ds_read_b128 v[132:135], v241 offset:33280
	ds_read_b128 v[136:139], v241 offset:35840
	ds_read_b128 v[140:143], v241 offset:38400
	ds_read_b128 v[144:147], v240 offset:30720
	ds_read_b128 v[148:151], v240 offset:33280
	ds_read_b128 v[152:155], v240 offset:30752
	ds_read_b128 v[248:251], v240 offset:33312
	s_waitcnt lgkmcnt(2)
	v_mfma_f32_32x32x16_bf16 v[0:15], v[144:147], v[128:131], v[0:15]
	v_mfma_f32_32x32x16_bf16 v[64:79], v[148:151], v[128:131], v[64:79]
	ds_read_b128 v[128:131], v241 offset:30752
	s_waitcnt vmcnt(6)
	ds_write_b128 v242, v[158:161] offset:0
	ds_write_b128 v242, v[162:165] offset:5120
	v_mfma_f32_32x32x16_bf16 v[16:31], v[144:147], v[132:135], v[16:31]
	v_mfma_f32_32x32x16_bf16 v[80:95], v[148:151], v[132:135], v[80:95]
	ds_read_b128 v[132:135], v241 offset:33312
	ds_write_b128 v242, v[166:169] offset:10240
	ds_write_b128 v242, v[170:173] offset:15360
	v_mfma_f32_32x32x16_bf16 v[32:47], v[144:147], v[136:139], v[32:47]
	v_mfma_f32_32x32x16_bf16 v[96:111], v[148:151], v[136:139], v[96:111]
	ds_read_b128 v[136:139], v241 offset:35872
	ds_write_b128 v242, v[174:177] offset:20480
	ds_write_b128 v242, v[178:181] offset:25600
	v_mfma_f32_32x32x16_bf16 v[48:63], v[144:147], v[140:143], v[48:63]
	v_mfma_f32_32x32x16_bf16 v[112:127], v[148:151], v[140:143], v[112:127]
	ds_read_b128 v[140:143], v241 offset:38432
	s_waitcnt lgkmcnt(9)
	v_mfma_f32_32x32x16_bf16 v[0:15], v[152:155], v[128:131], v[0:15]
	global_load_dwordx4 v[158:161], v[182:183], off offset:1792
	global_load_dwordx4 v[162:165], v[184:185], off offset:1792
	v_mfma_f32_32x32x16_bf16 v[64:79], v[248:251], v[128:131], v[64:79]
	s_waitcnt lgkmcnt(6)
	v_mfma_f32_32x32x16_bf16 v[16:31], v[152:155], v[132:135], v[16:31]
	global_load_dwordx4 v[166:169], v[186:187], off offset:1792
	global_load_dwordx4 v[170:173], v[188:189], off offset:1792
	v_mfma_f32_32x32x16_bf16 v[80:95], v[248:251], v[132:135], v[80:95]
	s_waitcnt lgkmcnt(3)
	v_mfma_f32_32x32x16_bf16 v[32:47], v[152:155], v[136:139], v[32:47]
	global_load_dwordx4 v[174:177], v[190:191], off offset:1792
	global_load_dwordx4 v[178:181], v[192:193], off offset:1792
	v_mfma_f32_32x32x16_bf16 v[96:111], v[248:251], v[136:139], v[96:111]
	s_waitcnt lgkmcnt(0)
	v_mfma_f32_32x32x16_bf16 v[48:63], v[152:155], v[140:143], v[48:63]
	v_mfma_f32_32x32x16_bf16 v[112:127], v[248:251], v[140:143], v[112:127]
	s_waitcnt lgkmcnt(0)
	s_barrier
; #define G_LOAD(S, kt_) do { G_LD1(S##a0, S##b0, 0, kt_); G_LD1(S##a1, S##b1, 1, kt_); G_LD1(S##a2, S##b2, 2, kt_); G_LD1(S##a3, S##b3, 3, kt_); } while (0)
; #define G_STORE(S, buf_) do { G_ST1(S##a0, S##b0, 0, buf_); G_ST1(S##a1, S##b1, 1, buf_); G_ST1(S##a2, S##b2, 2, buf_); G_ST1(S##a3, S##b3, 3, buf_); } while (0)
; template <class AL, class BL>
; DI void gemm_core(AL al, BL bl, int m0, int n0, int K, char* smem, f32x16 (&acc)[2][2]) {
;     ...
;   G_LOAD(x, 0);
;   G_STORE(x, 0);
;   G_LOAD(x, 1);
;   G_LOAD(y, (nk > 2) ? 2 : 1);
;   __syncthreads();
;   for (int kt = 0; kt < nk; kt += 2) {
;     G_TILE(0, x, true, (kt + 3 < nk), kt + 3);
;     __syncthreads();
;     G_TILE(1, y, (kt + 2 < nk), (kt + 4 < nk), kt + 4);
;     __syncthreads();
;   }
	ds_read_b128 v[128:131], v241 offset:0
	ds_read_b128 v[132:135], v241 offset:2560
	ds_read_b128 v[136:139], v241 offset:5120
	ds_read_b128 v[140:143], v241 offset:7680
	ds_read_b128 v[144:147], v240 offset:0
	ds_read_b128 v[148:151], v240 offset:2560
	ds_read_b128 v[152:155], v240 offset:32
	ds_read_b128 v[248:251], v240 offset:2592
	s_waitcnt lgkmcnt(2)
	v_mfma_f32_32x32x16_bf16 v[0:15], v[144:147], v[128:131], v[0:15]
	v_mfma_f32_32x32x16_bf16 v[64:79], v[148:151], v[128:131], v[64:79]
	ds_read_b128 v[128:131], v241 offset:32
	s_waitcnt vmcnt(6)
	ds_write_b128 v242, v[214:217] offset:30720
	ds_write_b128 v242, v[218:221] offset:35840
	v_mfma_f32_32x32x16_bf16 v[16:31], v[144:147], v[132:135], v[16:31]
	v_mfma_f32_32x32x16_bf16 v[80:95], v[148:151], v[132:135], v[80:95]
	ds_read_b128 v[132:135], v241 offset:2592
	ds_write_b128 v242, v[222:225] offset:40960
	ds_write_b128 v242, v[228:231] offset:46080
	v_mfma_f32_32x32x16_bf16 v[32:47], v[144:147], v[136:139], v[32:47]
	v_mfma_f32_32x32x16_bf16 v[96:111], v[148:151], v[136:139], v[96:111]
	ds_read_b128 v[136:139], v241 offset:5152
	ds_write_b128 v242, v[232:235] offset:51200
	ds_write_b128 v242, v[236:239] offset:56320
	v_mfma_f32_32x32x16_bf16 v[48:63], v[144:147], v[140:143], v[48:63]
	v_mfma_f32_32x32x16_bf16 v[112:127], v[148:151], v[140:143], v[112:127]
	ds_read_b128 v[140:143], v241 offset:7712
	s_waitcnt lgkmcnt(9)
	v_mfma_f32_32x32x16_bf16 v[0:15], v[152:155], v[128:131], v[0:15]
	global_load_dwordx4 v[214:217], v[182:183], off offset:1856
	global_load_dwordx4 v[218:221], v[184:185], off offset:1856
	v_mfma_f32_32x32x16_bf16 v[64:79], v[248:251], v[128:131], v[64:79]
	s_waitcnt lgkmcnt(6)
	v_mfma_f32_32x32x16_bf16 v[16:31], v[152:155], v[132:135], v[16:31]
	global_load_dwordx4 v[222:225], v[186:187], off offset:1856
	global_load_dwordx4 v[228:231], v[188:189], off offset:1856
	v_mfma_f32_32x32x16_bf16 v[80:95], v[248:251], v[132:135], v[80:95]
	s_waitcnt lgkmcnt(3)
	v_mfma_f32_32x32x16_bf16 v[32:47], v[152:155], v[136:139], v[32:47]
	global_load_dwordx4 v[232:235], v[190:191], off offset:1856
	global_load_dwordx4 v[236:239], v[192:193], off offset:1856
	v_mfma_f32_32x32x16_bf16 v[96:111], v[248:251], v[136:139], v[96:111]
	s_waitcnt lgkmcnt(0)
	v_mfma_f32_32x32x16_bf16 v[48:63], v[152:155], v[140:143], v[48:63]
	v_mfma_f32_32x32x16_bf16 v[112:127], v[248:251], v[140:143], v[112:127]
	s_waitcnt lgkmcnt(0)
	s_barrier
	ds_read_b128 v[128:131], v241 offset:30720
	ds_read_b128 v[132:135], v241 offset:33280
	ds_read_b128 v[136:139], v241 offset:35840
	ds_read_b128 v[140:143], v241 offset:38400
	ds_read_b128 v[144:147], v240 offset:30720
	ds_read_b128 v[148:151], v240 offset:33280
	ds_read_b128 v[152:155], v240 offset:30752
	ds_read_b128 v[248:251], v240 offset:33312
	s_waitcnt lgkmcnt(2)
	v_mfma_f32_32x32x16_bf16 v[0:15], v[144:147], v[128:131], v[0:15]
	v_mfma_f32_32x32x16_bf16 v[64:79], v[148:151], v[128:131], v[64:79]
	ds_read_b128 v[128:131], v241 offset:30752
	s_waitcnt vmcnt(6)
	ds_write_b128 v242, v[158:161] offset:0
	ds_write_b128 v242, v[162:165] offset:5120
	v_mfma_f32_32x32x16_bf16 v[16:31], v[144:147], v[132:135], v[16:31]
	v_mfma_f32_32x32x16_bf16 v[80:95], v[148:151], v[132:135], v[80:95]
	ds_read_b128 v[132:135], v241 offset:33312
	ds_write_b128 v242, v[166:169] offset:10240
	ds_write_b128 v242, v[170:173] offset:15360
	v_mfma_f32_32x32x16_bf16 v[32:47], v[144:147], v[136:139], v[32:47]
	v_mfma_f32_32x32x16_bf16 v[96:111], v[148:151], v[136:139], v[96:111]
	ds_read_b128 v[136:139], v241 offset:35872
	ds_write_b128 v242, v[174:177] offset:20480
	ds_write_b128 v242, v[178:181] offset:25600
	v_mfma_f32_32x32x16_bf16 v[48:63], v[144:147], v[140:143], v[48:63]
	v_mfma_f32_32x32x16_bf16 v[112:127], v[148:151], v[140:143], v[112:127]
	ds_read_b128 v[140:143], v241 offset:38432
	s_waitcnt lgkmcnt(9)
	v_mfma_f32_32x32x16_bf16 v[0:15], v[152:155], v[128:131], v[0:15]
	global_load_dwordx4 v[158:161], v[182:183], off offset:1920
	global_load_dwordx4 v[162:165], v[184:185], off offset:1920
	v_mfma_f32_32x32x16_bf16 v[64:79], v[248:251], v[128:131], v[64:79]
	s_waitcnt lgkmcnt(6)
	v_mfma_f32_32x32x16_bf16 v[16:31], v[152:155], v[132:135], v[16:31]
	global_load_dwordx4 v[166:169], v[186:187], off offset:1920
	global_load_dwordx4 v[170:173], v[188:189], off offset:1920
	v_mfma_f32_32x32x16_bf16 v[80:95], v[248:251], v[132:135], v[80:95]
	s_waitcnt lgkmcnt(3)
	v_mfma_f32_32x32x16_bf16 v[32:47], v[152:155], v[136:139], v[32:47]
	global_load_dwordx4 v[174:177], v[190:191], off offset:1920
	global_load_dwordx4 v[178:181], v[192:193], off offset:1920
	v_mfma_f32_32x32x16_bf16 v[96:111], v[248:251], v[136:139], v[96:111]
	s_waitcnt lgkmcnt(0)
	v_mfma_f32_32x32x16_bf16 v[48:63], v[152:155], v[140:143], v[48:63]
	v_mfma_f32_32x32x16_bf16 v[112:127], v[248:251], v[140:143], v[112:127]
	s_waitcnt lgkmcnt(0)
	s_barrier
; #define G_LOAD(S, kt_) do { G_LD1(S##a0, S##b0, 0, kt_); G_LD1(S##a1, S##b1, 1, kt_); G_LD1(S##a2, S##b2, 2, kt_); G_LD1(S##a3, S##b3, 3, kt_); } while (0)
; #define G_STORE(S, buf_) do { G_ST1(S##a0, S##b0, 0, buf_); G_ST1(S##a1, S##b1, 1, buf_); G_ST1(S##a2, S##b2, 2, buf_); G_ST1(S##a3, S##b3, 3, buf_); } while (0)
; template <class AL, class BL>
; DI void gemm_core(AL al, BL bl, int m0, int n0, int K, char* smem, f32x16 (&acc)[2][2]) {
;     ...
;   G_LOAD(x, 0);
;   G_STORE(x, 0);
;   G_LOAD(x, 1);
;   G_LOAD(y, (nk > 2) ? 2 : 1);
;   __syncthreads();
;   for (int kt = 0; kt < nk; kt += 2) {
;     G_TILE(0, x, true, (kt + 3 < nk), kt + 3);
;     __syncthreads();
;     G_TILE(1, y, (kt + 2 < nk), (kt + 4 < nk), kt + 4);
;     __syncthreads();
;   }
	ds_read_b128 v[128:131], v241 offset:0
	ds_read_b128 v[132:135], v241 offset:2560
	ds_read_b128 v[136:139], v241 offset:5120
	ds_read_b128 v[140:143], v241 offset:7680
	ds_read_b128 v[144:147], v240 offset:0
	ds_read_b128 v[148:151], v240 offset:2560
	ds_read_b128 v[152:155], v240 offset:32
	ds_read_b128 v[248:251], v240 offset:2592
	s_waitcnt lgkmcnt(2)
	v_mfma_f32_32x32x16_bf16 v[0:15], v[144:147], v[128:131], v[0:15]
	v_mfma_f32_32x32x16_bf16 v[64:79], v[148:151], v[128:131], v[64:79]
	ds_read_b128 v[128:131], v241 offset:32
	s_waitcnt vmcnt(6)
	ds_write_b128 v242, v[214:217] offset:30720
	ds_write_b128 v242, v[218:221] offset:35840
	v_mfma_f32_32x32x16_bf16 v[16:31], v[144:147], v[132:135], v[16:31]
	v_mfma_f32_32x32x16_bf16 v[80:95], v[148:151], v[132:135], v[80:95]
	ds_read_b128 v[132:135], v241 offset:2592
	ds_write_b128 v242, v[222:225] offset:40960
	ds_write_b128 v242, v[228:231] offset:46080
	v_mfma_f32_32x32x16_bf16 v[32:47], v[144:147], v[136:139], v[32:47]
	v_mfma_f32_32x32x16_bf16 v[96:111], v[148:151], v[136:139], v[96:111]
	ds_read_b128 v[136:139], v241 offset:5152
	ds_write_b128 v242, v[232:235] offset:51200
	ds_write_b128 v242, v[236:239] offset:56320
	v_mfma_f32_32x32x16_bf16 v[48:63], v[144:147], v[140:143], v[48:63]
	v_mfma_f32_32x32x16_bf16 v[112:127], v[148:151], v[140:143], v[112:127]
	ds_read_b128 v[140:143], v241 offset:7712
	s_waitcnt lgkmcnt(9)
	v_mfma_f32_32x32x16_bf16 v[0:15], v[152:155], v[128:131], v[0:15]
	global_load_dwordx4 v[214:217], v[182:183], off offset:1984
	global_load_dwordx4 v[218:221], v[184:185], off offset:1984
	v_mfma_f32_32x32x16_bf16 v[64:79], v[248:251], v[128:131], v[64:79]
	s_waitcnt lgkmcnt(6)
	v_mfma_f32_32x32x16_bf16 v[16:31], v[152:155], v[132:135], v[16:31]
	global_load_dwordx4 v[222:225], v[186:187], off offset:1984
	global_load_dwordx4 v[228:231], v[188:189], off offset:1984
	v_mfma_f32_32x32x16_bf16 v[80:95], v[248:251], v[132:135], v[80:95]
	s_waitcnt lgkmcnt(3)
	v_mfma_f32_32x32x16_bf16 v[32:47], v[152:155], v[136:139], v[32:47]
	global_load_dwordx4 v[232:235], v[190:191], off offset:1984
	global_load_dwordx4 v[236:239], v[192:193], off offset:1984
	v_mfma_f32_32x32x16_bf16 v[96:111], v[248:251], v[136:139], v[96:111]
	s_waitcnt lgkmcnt(0)
	v_mfma_f32_32x32x16_bf16 v[48:63], v[152:155], v[140:143], v[48:63]
	v_mfma_f32_32x32x16_bf16 v[112:127], v[248:251], v[140:143], v[112:127]
	s_waitcnt lgkmcnt(0)
	s_barrier
	ds_read_b128 v[128:131], v241 offset:30720
	ds_read_b128 v[132:135], v241 offset:33280
	ds_read_b128 v[136:139], v241 offset:35840
	ds_read_b128 v[140:143], v241 offset:38400
	ds_read_b128 v[144:147], v240 offset:30720
	ds_read_b128 v[148:151], v240 offset:33280
	ds_read_b128 v[152:155], v240 offset:30752
	ds_read_b128 v[248:251], v240 offset:33312
	s_waitcnt lgkmcnt(2)
	v_mfma_f32_32x32x16_bf16 v[0:15], v[144:147], v[128:131], v[0:15]
	v_mfma_f32_32x32x16_bf16 v[64:79], v[148:151], v[128:131], v[64:79]
	ds_read_b128 v[128:131], v241 offset:30752
	s_waitcnt vmcnt(6)
	ds_write_b128 v242, v[158:161] offset:0
	ds_write_b128 v242, v[162:165] offset:5120
	v_mfma_f32_32x32x16_bf16 v[16:31], v[144:147], v[132:135], v[16:31]
	v_mfma_f32_32x32x16_bf16 v[80:95], v[148:151], v[132:135], v[80:95]
	ds_read_b128 v[132:135], v241 offset:33312
	ds_write_b128 v242, v[166:169] offset:10240
	ds_write_b128 v242, v[170:173] offset:15360
	v_mfma_f32_32x32x16_bf16 v[32:47], v[144:147], v[136:139], v[32:47]
	v_mfma_f32_32x32x16_bf16 v[96:111], v[148:151], v[136:139], v[96:111]
	ds_read_b128 v[136:139], v241 offset:35872
	ds_write_b128 v242, v[174:177] offset:20480
	ds_write_b128 v242, v[178:181] offset:25600
	v_mfma_f32_32x32x16_bf16 v[48:63], v[144:147], v[140:143], v[48:63]
	v_mfma_f32_32x32x16_bf16 v[112:127], v[148:151], v[140:143], v[112:127]
	ds_read_b128 v[140:143], v241 offset:38432
	s_waitcnt lgkmcnt(9)
	v_mfma_f32_32x32x16_bf16 v[0:15], v[152:155], v[128:131], v[0:15]
	v_mfma_f32_32x32x16_bf16 v[64:79], v[248:251], v[128:131], v[64:79]
	s_waitcnt lgkmcnt(6)
	v_mfma_f32_32x32x16_bf16 v[16:31], v[152:155], v[132:135], v[16:31]
	v_mfma_f32_32x32x16_bf16 v[80:95], v[248:251], v[132:135], v[80:95]
	s_waitcnt lgkmcnt(3)
	v_mfma_f32_32x32x16_bf16 v[32:47], v[152:155], v[136:139], v[32:47]
	v_mfma_f32_32x32x16_bf16 v[96:111], v[248:251], v[136:139], v[96:111]
	s_waitcnt lgkmcnt(0)
	v_mfma_f32_32x32x16_bf16 v[48:63], v[152:155], v[140:143], v[48:63]
	v_mfma_f32_32x32x16_bf16 v[112:127], v[248:251], v[140:143], v[112:127]
	s_waitcnt lgkmcnt(0)
	s_barrier
	ds_read_b128 v[128:131], v241 offset:0
	ds_read_b128 v[132:135], v241 offset:2560
	ds_read_b128 v[136:139], v241 offset:5120
	ds_read_b128 v[140:143], v241 offset:7680
	ds_read_b128 v[144:147], v240 offset:0
	ds_read_b128 v[148:151], v240 offset:2560
	ds_read_b128 v[152:155], v240 offset:32
	ds_read_b128 v[248:251], v240 offset:2592
	s_waitcnt lgkmcnt(2)
	v_mfma_f32_32x32x16_bf16 v[0:15], v[144:147], v[128:131], v[0:15]
	v_mfma_f32_32x32x16_bf16 v[64:79], v[148:151], v[128:131], v[64:79]
	ds_read_b128 v[128:131], v241 offset:32
	s_waitcnt vmcnt(0)
	ds_write_b128 v242, v[214:217] offset:30720
	ds_write_b128 v242, v[218:221] offset:35840
	v_mfma_f32_32x32x16_bf16 v[16:31], v[144:147], v[132:135], v[16:31]
	v_mfma_f32_32x32x16_bf16 v[80:95], v[148:151], v[132:135], v[80:95]
	ds_read_b128 v[132:135], v241 offset:2592
	ds_write_b128 v242, v[222:225] offset:40960
	ds_write_b128 v242, v[228:231] offset:46080
	v_mfma_f32_32x32x16_bf16 v[32:47], v[144:147], v[136:139], v[32:47]
	v_mfma_f32_32x32x16_bf16 v[96:111], v[148:151], v[136:139], v[96:111]
	ds_read_b128 v[136:139], v241 offset:5152
	ds_write_b128 v242, v[232:235] offset:51200
	ds_write_b128 v242, v[236:239] offset:56320
	v_mfma_f32_32x32x16_bf16 v[48:63], v[144:147], v[140:143], v[48:63]
	v_mfma_f32_32x32x16_bf16 v[112:127], v[148:151], v[140:143], v[112:127]
	ds_read_b128 v[140:143], v241 offset:7712
	s_waitcnt lgkmcnt(9)
	v_mfma_f32_32x32x16_bf16 v[0:15], v[152:155], v[128:131], v[0:15]
	v_mfma_f32_32x32x16_bf16 v[64:79], v[248:251], v[128:131], v[64:79]
	s_waitcnt lgkmcnt(6)
	v_mfma_f32_32x32x16_bf16 v[16:31], v[152:155], v[132:135], v[16:31]
	v_mfma_f32_32x32x16_bf16 v[80:95], v[248:251], v[132:135], v[80:95]
	s_waitcnt lgkmcnt(3)
	v_mfma_f32_32x32x16_bf16 v[32:47], v[152:155], v[136:139], v[32:47]
	v_mfma_f32_32x32x16_bf16 v[96:111], v[248:251], v[136:139], v[96:111]
	s_waitcnt lgkmcnt(0)
	v_mfma_f32_32x32x16_bf16 v[48:63], v[152:155], v[140:143], v[48:63]
	v_mfma_f32_32x32x16_bf16 v[112:127], v[248:251], v[140:143], v[112:127]
	s_waitcnt lgkmcnt(0)
	s_barrier
; DI u16 f2bf(float x) { return (u16)(pack2(x, 0.f) & 0xffffu); }
; DI int opaque_tid() { int t = threadIdx.x; asm volatile("" : "+v"(t)); return t; }
; DI int crow(int i, int h) { return (i & 3) + 8 * (i >> 2) + 4 * h; }
; template <class AL, class BL>
; DI void gemm_core(AL al, BL bl, int m0, int n0, int K, char* smem, f32x16 (&acc)[2][2]) {
;     ...
;   for (int kt = 0; kt < nk; kt += 2) {
;     G_TILE(0, x, true, (kt + 3 < nk), kt + 3);
;     __syncthreads();
;     G_TILE(1, y, (kt + 2 < nk), (kt + 4 < nk), kt + 4);
;     __syncthreads();
;   }
; template <class F>
; DI void epi_bf16_tile(const f32x16 (&acc)[2][2], int m0, int n0, u16* dst0, long ld, char* smem, F f) {
;   const int tid = opaque_tid(), lane = tid & 63, w = tid >> 6, wm = w >> 1, wn = w & 1, h = lane >> 5;
;   u16* T = (u16*)smem;
; #pragma unroll
;   for (int mt = 0; mt < 2; mt++)
; #pragma unroll
;     for (int nt = 0; nt < 2; nt++)
; #pragma unroll
;       for (int i = 0; i < 16; i++) {
;         const int ml = wm * 64 + mt * 32 + crow(i, h), nl = wn * 64 + nt * 32 + (lane & 31);
;         T[ml * 136 + nl] = f2bf(f(m0 + ml, n0 + nl, acc[mt][nt][i]));
;       }
;   __syncthreads();
	ds_read_b128 v[128:131], v241 offset:30720
	ds_read_b128 v[132:135], v241 offset:33280
	ds_read_b128 v[136:139], v241 offset:35840
	ds_read_b128 v[140:143], v241 offset:38400
	ds_read_b128 v[144:147], v240 offset:30720
	ds_read_b128 v[148:151], v240 offset:33280
	ds_read_b128 v[152:155], v240 offset:30752
	ds_read_b128 v[248:251], v240 offset:33312
	s_waitcnt lgkmcnt(2)
	v_mfma_f32_32x32x16_bf16 v[0:15], v[144:147], v[128:131], v[0:15]
	v_mfma_f32_32x32x16_bf16 v[64:79], v[148:151], v[128:131], v[64:79]
	ds_read_b128 v[128:131], v241 offset:30752
	v_mfma_f32_32x32x16_bf16 v[16:31], v[144:147], v[132:135], v[16:31]
	v_mfma_f32_32x32x16_bf16 v[80:95], v[148:151], v[132:135], v[80:95]
	ds_read_b128 v[132:135], v241 offset:33312
	v_mfma_f32_32x32x16_bf16 v[32:47], v[144:147], v[136:139], v[32:47]
	v_mfma_f32_32x32x16_bf16 v[96:111], v[148:151], v[136:139], v[96:111]
	ds_read_b128 v[136:139], v241 offset:35872
	v_mfma_f32_32x32x16_bf16 v[48:63], v[144:147], v[140:143], v[48:63]
	v_mfma_f32_32x32x16_bf16 v[112:127], v[148:151], v[140:143], v[112:127]
	ds_read_b128 v[140:143], v241 offset:38432
	s_waitcnt lgkmcnt(3)
	v_mfma_f32_32x32x16_bf16 v[0:15], v[152:155], v[128:131], v[0:15]
	v_mfma_f32_32x32x16_bf16 v[64:79], v[248:251], v[128:131], v[64:79]
	s_waitcnt lgkmcnt(2)
	v_mfma_f32_32x32x16_bf16 v[16:31], v[152:155], v[132:135], v[16:31]
	v_mfma_f32_32x32x16_bf16 v[80:95], v[248:251], v[132:135], v[80:95]
	s_waitcnt lgkmcnt(1)
	v_mfma_f32_32x32x16_bf16 v[32:47], v[152:155], v[136:139], v[32:47]
	v_mfma_f32_32x32x16_bf16 v[96:111], v[248:251], v[136:139], v[96:111]
	s_waitcnt lgkmcnt(0)
	v_mfma_f32_32x32x16_bf16 v[48:63], v[152:155], v[140:143], v[48:63]
	v_mfma_f32_32x32x16_bf16 v[112:127], v[248:251], v[140:143], v[112:127]
	s_waitcnt lgkmcnt(0)
	s_barrier
	s_nop 7
	s_nop 3
	v_cvt_pk_bf16_f32 v252, v0, v0
	ds_write_b16 v243, v252 offset:0
	v_cvt_pk_bf16_f32 v253, v1, v1
	ds_write_b16 v243, v253 offset:528
	v_cvt_pk_bf16_f32 v156, v2, v2
	ds_write_b16 v243, v156 offset:1056
	v_cvt_pk_bf16_f32 v252, v3, v3
	ds_write_b16 v243, v252 offset:1584
	v_cvt_pk_bf16_f32 v253, v4, v4
	ds_write_b16 v243, v253 offset:4224
	v_cvt_pk_bf16_f32 v156, v5, v5
	ds_write_b16 v243, v156 offset:4752
	v_cvt_pk_bf16_f32 v252, v6, v6
	ds_write_b16 v243, v252 offset:5280
	v_cvt_pk_bf16_f32 v253, v7, v7
	ds_write_b16 v243, v253 offset:5808
	v_cvt_pk_bf16_f32 v156, v8, v8
	ds_write_b16 v243, v156 offset:8448
	v_cvt_pk_bf16_f32 v252, v9, v9
	ds_write_b16 v243, v252 offset:8976
	v_cvt_pk_bf16_f32 v253, v10, v10
	ds_write_b16 v243, v253 offset:9504
	v_cvt_pk_bf16_f32 v156, v11, v11
	ds_write_b16 v243, v156 offset:10032
	v_cvt_pk_bf16_f32 v252, v12, v12
	ds_write_b16 v243, v252 offset:12672
	v_cvt_pk_bf16_f32 v253, v13, v13
	ds_write_b16 v243, v253 offset:13200
	v_cvt_pk_bf16_f32 v156, v14, v14
	ds_write_b16 v243, v156 offset:13728
	v_cvt_pk_bf16_f32 v252, v15, v15
	ds_write_b16 v243, v252 offset:14256
	v_cvt_pk_bf16_f32 v252, v16, v16
	ds_write_b16 v243, v252 offset:64
	v_cvt_pk_bf16_f32 v253, v17, v17
	ds_write_b16 v243, v253 offset:592
	v_cvt_pk_bf16_f32 v156, v18, v18
	ds_write_b16 v243, v156 offset:1120
	v_cvt_pk_bf16_f32 v252, v19, v19
	ds_write_b16 v243, v252 offset:1648
	v_cvt_pk_bf16_f32 v253, v20, v20
	ds_write_b16 v243, v253 offset:4288
	v_cvt_pk_bf16_f32 v156, v21, v21
	ds_write_b16 v243, v156 offset:4816
	v_cvt_pk_bf16_f32 v252, v22, v22
	ds_write_b16 v243, v252 offset:5344
	v_cvt_pk_bf16_f32 v253, v23, v23
	ds_write_b16 v243, v253 offset:5872
	v_cvt_pk_bf16_f32 v156, v24, v24
	ds_write_b16 v243, v156 offset:8512
	v_cvt_pk_bf16_f32 v252, v25, v25
	ds_write_b16 v243, v252 offset:9040
	v_cvt_pk_bf16_f32 v253, v26, v26
	ds_write_b16 v243, v253 offset:9568
	v_cvt_pk_bf16_f32 v156, v27, v27
	ds_write_b16 v243, v156 offset:10096
	v_cvt_pk_bf16_f32 v252, v28, v28
	ds_write_b16 v243, v252 offset:12736
	v_cvt_pk_bf16_f32 v253, v29, v29
	ds_write_b16 v243, v253 offset:13264
	v_cvt_pk_bf16_f32 v156, v30, v30
	ds_write_b16 v243, v156 offset:13792
	v_cvt_pk_bf16_f32 v252, v31, v31
	ds_write_b16 v243, v252 offset:14320
	v_cvt_pk_bf16_f32 v252, v32, v32
	ds_write_b16 v243, v252 offset:128
	v_cvt_pk_bf16_f32 v253, v33, v33
	ds_write_b16 v243, v253 offset:656
	v_cvt_pk_bf16_f32 v156, v34, v34
	ds_write_b16 v243, v156 offset:1184
	v_cvt_pk_bf16_f32 v252, v35, v35
	ds_write_b16 v243, v252 offset:1712
	v_cvt_pk_bf16_f32 v253, v36, v36
	ds_write_b16 v243, v253 offset:4352
	v_cvt_pk_bf16_f32 v156, v37, v37
	ds_write_b16 v243, v156 offset:4880
	v_cvt_pk_bf16_f32 v252, v38, v38
	ds_write_b16 v243, v252 offset:5408
	v_cvt_pk_bf16_f32 v253, v39, v39
	ds_write_b16 v243, v253 offset:5936
	v_cvt_pk_bf16_f32 v156, v40, v40
	ds_write_b16 v243, v156 offset:8576
	v_cvt_pk_bf16_f32 v252, v41, v41
	ds_write_b16 v243, v252 offset:9104
	v_cvt_pk_bf16_f32 v253, v42, v42
	ds_write_b16 v243, v253 offset:9632
	v_cvt_pk_bf16_f32 v156, v43, v43
	ds_write_b16 v243, v156 offset:10160
	v_cvt_pk_bf16_f32 v252, v44, v44
	ds_write_b16 v243, v252 offset:12800
	v_cvt_pk_bf16_f32 v253, v45, v45
	ds_write_b16 v243, v253 offset:13328
	v_cvt_pk_bf16_f32 v156, v46, v46
	ds_write_b16 v243, v156 offset:13856
	v_cvt_pk_bf16_f32 v252, v47, v47
	ds_write_b16 v243, v252 offset:14384
	v_cvt_pk_bf16_f32 v252, v48, v48
	ds_write_b16 v243, v252 offset:192
	v_cvt_pk_bf16_f32 v253, v49, v49
	ds_write_b16 v243, v253 offset:720
	v_cvt_pk_bf16_f32 v156, v50, v50
	ds_write_b16 v243, v156 offset:1248
	v_cvt_pk_bf16_f32 v252, v51, v51
	ds_write_b16 v243, v252 offset:1776
	v_cvt_pk_bf16_f32 v253, v52, v52
	ds_write_b16 v243, v253 offset:4416
	v_cvt_pk_bf16_f32 v156, v53, v53
	ds_write_b16 v243, v156 offset:4944
	v_cvt_pk_bf16_f32 v252, v54, v54
; DI u16 f2bf(float x) { return (u16)(pack2(x, 0.f) & 0xffffu); }
; DI int crow(int i, int h) { return (i & 3) + 8 * (i >> 2) + 4 * h; }
; template <class F>
; DI void epi_bf16_tile(const f32x16 (&acc)[2][2], int m0, int n0, u16* dst0, long ld, char* smem, F f) {
;     ...
; #pragma unroll
;   for (int mt = 0; mt < 2; mt++)
; #pragma unroll
;     for (int nt = 0; nt < 2; nt++)
; #pragma unroll
;       for (int i = 0; i < 16; i++) {
;         const int ml = wm * 64 + mt * 32 + crow(i, h), nl = wn * 64 + nt * 32 + (lane & 31);
;         T[ml * 136 + nl] = f2bf(f(m0 + ml, n0 + nl, acc[mt][nt][i]));
;       }
;   __syncthreads();
	ds_write_b16 v243, v252 offset:5472
	v_cvt_pk_bf16_f32 v253, v55, v55
	ds_write_b16 v243, v253 offset:6000
	v_cvt_pk_bf16_f32 v156, v56, v56
	ds_write_b16 v243, v156 offset:8640
	v_cvt_pk_bf16_f32 v252, v57, v57
	ds_write_b16 v243, v252 offset:9168
	v_cvt_pk_bf16_f32 v253, v58, v58
	ds_write_b16 v243, v253 offset:9696
	v_cvt_pk_bf16_f32 v156, v59, v59
	ds_write_b16 v243, v156 offset:10224
	v_cvt_pk_bf16_f32 v252, v60, v60
	ds_write_b16 v243, v252 offset:12864
	v_cvt_pk_bf16_f32 v253, v61, v61
	ds_write_b16 v243, v253 offset:13392
	v_cvt_pk_bf16_f32 v156, v62, v62
	ds_write_b16 v243, v156 offset:13920
	v_cvt_pk_bf16_f32 v252, v63, v63
	ds_write_b16 v243, v252 offset:14448
	v_cvt_pk_bf16_f32 v252, v64, v64
	ds_write_b16 v243, v252 offset:16896
	v_cvt_pk_bf16_f32 v253, v65, v65
	ds_write_b16 v243, v253 offset:17424
	v_cvt_pk_bf16_f32 v156, v66, v66
	ds_write_b16 v243, v156 offset:17952
	v_cvt_pk_bf16_f32 v252, v67, v67
	ds_write_b16 v243, v252 offset:18480
	v_cvt_pk_bf16_f32 v253, v68, v68
	ds_write_b16 v243, v253 offset:21120
	v_cvt_pk_bf16_f32 v156, v69, v69
	ds_write_b16 v243, v156 offset:21648
	v_cvt_pk_bf16_f32 v252, v70, v70
	ds_write_b16 v243, v252 offset:22176
	v_cvt_pk_bf16_f32 v253, v71, v71
	ds_write_b16 v243, v253 offset:22704
	v_cvt_pk_bf16_f32 v156, v72, v72
	ds_write_b16 v243, v156 offset:25344
	v_cvt_pk_bf16_f32 v252, v73, v73
	ds_write_b16 v243, v252 offset:25872
	v_cvt_pk_bf16_f32 v253, v74, v74
	ds_write_b16 v243, v253 offset:26400
	v_cvt_pk_bf16_f32 v156, v75, v75
	ds_write_b16 v243, v156 offset:26928
	v_cvt_pk_bf16_f32 v252, v76, v76
	ds_write_b16 v243, v252 offset:29568
	v_cvt_pk_bf16_f32 v253, v77, v77
	ds_write_b16 v243, v253 offset:30096
	v_cvt_pk_bf16_f32 v156, v78, v78
	ds_write_b16 v243, v156 offset:30624
	v_cvt_pk_bf16_f32 v252, v79, v79
	ds_write_b16 v243, v252 offset:31152
	v_cvt_pk_bf16_f32 v252, v80, v80
	ds_write_b16 v243, v252 offset:16960
	v_cvt_pk_bf16_f32 v253, v81, v81
	ds_write_b16 v243, v253 offset:17488
	v_cvt_pk_bf16_f32 v156, v82, v82
	ds_write_b16 v243, v156 offset:18016
	v_cvt_pk_bf16_f32 v252, v83, v83
	ds_write_b16 v243, v252 offset:18544
	v_cvt_pk_bf16_f32 v253, v84, v84
	ds_write_b16 v243, v253 offset:21184
	v_cvt_pk_bf16_f32 v156, v85, v85
	ds_write_b16 v243, v156 offset:21712
	v_cvt_pk_bf16_f32 v252, v86, v86
	ds_write_b16 v243, v252 offset:22240
	v_cvt_pk_bf16_f32 v253, v87, v87
	ds_write_b16 v243, v253 offset:22768
	v_cvt_pk_bf16_f32 v156, v88, v88
	ds_write_b16 v243, v156 offset:25408
	v_cvt_pk_bf16_f32 v252, v89, v89
	ds_write_b16 v243, v252 offset:25936
	v_cvt_pk_bf16_f32 v253, v90, v90
	ds_write_b16 v243, v253 offset:26464
	v_cvt_pk_bf16_f32 v156, v91, v91
	ds_write_b16 v243, v156 offset:26992
	v_cvt_pk_bf16_f32 v252, v92, v92
	ds_write_b16 v243, v252 offset:29632
	v_cvt_pk_bf16_f32 v253, v93, v93
	ds_write_b16 v243, v253 offset:30160
	v_cvt_pk_bf16_f32 v156, v94, v94
	ds_write_b16 v243, v156 offset:30688
	v_cvt_pk_bf16_f32 v252, v95, v95
	ds_write_b16 v243, v252 offset:31216
	v_cvt_pk_bf16_f32 v252, v96, v96
	ds_write_b16 v243, v252 offset:17024
	v_cvt_pk_bf16_f32 v253, v97, v97
	ds_write_b16 v243, v253 offset:17552
	v_cvt_pk_bf16_f32 v156, v98, v98
	ds_write_b16 v243, v156 offset:18080
	v_cvt_pk_bf16_f32 v252, v99, v99
	ds_write_b16 v243, v252 offset:18608
	v_cvt_pk_bf16_f32 v253, v100, v100
	ds_write_b16 v243, v253 offset:21248
	v_cvt_pk_bf16_f32 v156, v101, v101
	ds_write_b16 v243, v156 offset:21776
	v_cvt_pk_bf16_f32 v252, v102, v102
	ds_write_b16 v243, v252 offset:22304
	v_cvt_pk_bf16_f32 v253, v103, v103
	ds_write_b16 v243, v253 offset:22832
	v_cvt_pk_bf16_f32 v156, v104, v104
	ds_write_b16 v243, v156 offset:25472
	v_cvt_pk_bf16_f32 v252, v105, v105
	ds_write_b16 v243, v252 offset:26000
	v_cvt_pk_bf16_f32 v253, v106, v106
	ds_write_b16 v243, v253 offset:26528
	v_cvt_pk_bf16_f32 v156, v107, v107
	ds_write_b16 v243, v156 offset:27056
	v_cvt_pk_bf16_f32 v252, v108, v108
	ds_write_b16 v243, v252 offset:29696
	v_cvt_pk_bf16_f32 v253, v109, v109
	ds_write_b16 v243, v253 offset:30224
	v_cvt_pk_bf16_f32 v156, v110, v110
	ds_write_b16 v243, v156 offset:30752
	v_cvt_pk_bf16_f32 v252, v111, v111
	ds_write_b16 v243, v252 offset:31280
	v_cvt_pk_bf16_f32 v252, v112, v112
	ds_write_b16 v243, v252 offset:17088
	v_cvt_pk_bf16_f32 v253, v113, v113
	ds_write_b16 v243, v253 offset:17616
	v_cvt_pk_bf16_f32 v156, v114, v114
	ds_write_b16 v243, v156 offset:18144
	v_cvt_pk_bf16_f32 v252, v115, v115
	ds_write_b16 v243, v252 offset:18672
	v_cvt_pk_bf16_f32 v253, v116, v116
	ds_write_b16 v243, v253 offset:21312
	v_cvt_pk_bf16_f32 v156, v117, v117
	ds_write_b16 v243, v156 offset:21840
	v_cvt_pk_bf16_f32 v252, v118, v118
	ds_write_b16 v243, v252 offset:22368
	v_cvt_pk_bf16_f32 v253, v119, v119
	ds_write_b16 v243, v253 offset:22896
	v_cvt_pk_bf16_f32 v156, v120, v120
	ds_write_b16 v243, v156 offset:25536
	v_cvt_pk_bf16_f32 v252, v121, v121
	ds_write_b16 v243, v252 offset:26064
	v_cvt_pk_bf16_f32 v253, v122, v122
	ds_write_b16 v243, v253 offset:26592
	v_cvt_pk_bf16_f32 v156, v123, v123
	ds_write_b16 v243, v156 offset:27120
	v_cvt_pk_bf16_f32 v252, v124, v124
	ds_write_b16 v243, v252 offset:29760
	v_cvt_pk_bf16_f32 v253, v125, v125
	ds_write_b16 v243, v253 offset:30288
	v_cvt_pk_bf16_f32 v156, v126, v126
	ds_write_b16 v243, v156 offset:30816
	v_cvt_pk_bf16_f32 v252, v127, v127
	ds_write_b16 v243, v252 offset:31344
	s_waitcnt lgkmcnt(0)
	s_barrier
; DI u16 f2bf(float x) { return (u16)(pack2(x, 0.f) & 0xffffu); }
; DI int opaque_tid() { int t = threadIdx.x; asm volatile("" : "+v"(t)); return t; }
; DI int crow(int i, int h) { return (i & 3) + 8 * (i >> 2) + 4 * h; }
; template <class F>
; DI void epi_bf16_tile(const f32x16 (&acc)[2][2], int m0, int n0, u16* dst0, long ld, char* smem, F f) {
;   const int tid = opaque_tid(), lane = tid & 63, w = tid >> 6, wm = w >> 1, wn = w & 1, h = lane >> 5;
;   u16* T = (u16*)smem;
; #pragma unroll
;   for (int mt = 0; mt < 2; mt++)
; #pragma unroll
;     for (int nt = 0; nt < 2; nt++)
; #pragma unroll
;       for (int i = 0; i < 16; i++) {
;         const int ml = wm * 64 + mt * 32 + crow(i, h), nl = wn * 64 + nt * 32 + (lane & 31);
;         T[ml * 136 + nl] = f2bf(f(m0 + ml, n0 + nl, acc[mt][nt][i]));
;       }
;   __syncthreads();
; #pragma unroll
;   for (int j = 0; j < 8; j++) {
;     const int idx = tid + 256 * j, row = idx >> 4, ch = idx & 15;
;     *(uint4*)(dst0 + (long)row * ld + ch * 8) = *(const uint4*)(T + row * 136 + ch * 8);
;   }
;   __syncthreads();
; }
	ds_read_b128 v[128:131], v244 offset:0
	ds_read_b128 v[132:135], v244 offset:4224
	ds_read_b128 v[136:139], v244 offset:8448
	ds_read_b128 v[140:143], v244 offset:12672
	ds_read_b128 v[144:147], v244 offset:16896
	ds_read_b128 v[148:151], v244 offset:21120
	ds_read_b128 v[152:155], v244 offset:25344
	ds_read_b128 v[248:251], v244 offset:29568
	s_waitcnt lgkmcnt(7)
	global_store_dwordx4 v227, v[128:131], s[14:15]
	s_add_u32 s14, s14, 16384
	s_addc_u32 s15, s15, 0
	ds_read_b128 v[128:131], v244 offset:33792
	s_waitcnt lgkmcnt(7)
	global_store_dwordx4 v227, v[132:135], s[14:15]
	s_add_u32 s14, s14, 16384
	s_addc_u32 s15, s15, 0
	ds_read_b128 v[132:135], v244 offset:38016
	s_waitcnt lgkmcnt(7)
	global_store_dwordx4 v227, v[136:139], s[14:15]
	s_add_u32 s14, s14, 16384
	s_addc_u32 s15, s15, 0
	ds_read_b128 v[136:139], v244 offset:42240
	s_waitcnt lgkmcnt(7)
	global_store_dwordx4 v227, v[140:143], s[14:15]
	s_add_u32 s14, s14, 16384
	s_addc_u32 s15, s15, 0
	ds_read_b128 v[140:143], v244 offset:46464
	s_waitcnt lgkmcnt(7)
	global_store_dwordx4 v227, v[144:147], s[14:15]
	s_add_u32 s14, s14, 16384
	s_addc_u32 s15, s15, 0
	ds_read_b128 v[144:147], v244 offset:50688
	s_waitcnt lgkmcnt(7)
	global_store_dwordx4 v227, v[148:151], s[14:15]
	s_add_u32 s14, s14, 16384
	s_addc_u32 s15, s15, 0
	ds_read_b128 v[148:151], v244 offset:54912
	s_waitcnt lgkmcnt(7)
	global_store_dwordx4 v227, v[152:155], s[14:15]
	s_add_u32 s14, s14, 16384
	s_addc_u32 s15, s15, 0
	ds_read_b128 v[152:155], v244 offset:59136
	s_waitcnt lgkmcnt(7)
	global_store_dwordx4 v227, v[248:251], s[14:15]
	s_add_u32 s14, s14, 16384
	s_addc_u32 s15, s15, 0
	ds_read_b128 v[248:251], v244 offset:63360
	s_waitcnt lgkmcnt(7)
	global_store_dwordx4 v227, v[128:131], s[14:15]
	s_add_u32 s14, s14, 16384
	s_addc_u32 s15, s15, 0
	s_waitcnt lgkmcnt(6)
	global_store_dwordx4 v227, v[132:135], s[14:15]
	s_add_u32 s14, s14, 16384
	s_addc_u32 s15, s15, 0
	s_waitcnt lgkmcnt(5)
	global_store_dwordx4 v227, v[136:139], s[14:15]
	s_add_u32 s14, s14, 16384
	s_addc_u32 s15, s15, 0
	s_waitcnt lgkmcnt(4)
	global_store_dwordx4 v227, v[140:143], s[14:15]
	s_add_u32 s14, s14, 16384
	s_addc_u32 s15, s15, 0
	s_waitcnt lgkmcnt(3)
	global_store_dwordx4 v227, v[144:147], s[14:15]
	s_add_u32 s14, s14, 16384
	s_addc_u32 s15, s15, 0
	s_waitcnt lgkmcnt(2)
	global_store_dwordx4 v227, v[148:151], s[14:15]
	s_add_u32 s14, s14, 16384
	s_addc_u32 s15, s15, 0
	s_waitcnt lgkmcnt(1)
	global_store_dwordx4 v227, v[152:155], s[14:15]
	s_add_u32 s14, s14, 16384
	s_addc_u32 s15, s15, 0
	s_waitcnt lgkmcnt(0)
	global_store_dwordx4 v227, v[248:251], s[14:15]
	s_barrier
	s_add_u32 s60, s78, 0x400
	s_branch .Lfd0_go
.Lfd0_skip:
	s_mov_b32 s60, s78
.Lfd0_go:
	s_branch .LBB0_1036
.LBB0_1034:
	s_ashr_i32 s39, s38, 31
	s_lshl_b64 s[2:3], s[38:39], 18
	s_waitcnt vmcnt(1)
	v_mov_b32_e32 v64, v202
	s_add_u32 s2, s33, s2
	s_addc_u32 s3, s42, s3
	v_lshrrev_b32_e32 v65, 1, v64
	s_ashr_i32 s1, s0, 31
	v_and_b32_e32 v65, 0xfffffc0, v65
	v_lshrrev_b32_e32 v66, 3, v64
	s_lshl_b64 s[0:1], s[0:1], 1
	v_and_or_b32 v65, v66, 4, v65
	s_add_u32 s0, s2, s0
	v_and_b32_e32 v66, 0x5f, v64
	v_mul_lo_u32 v65, v65, s57
	v_lshl_add_u32 v65, v66, 1, v65
	v_cvt_pk_bf16_f32 v0, v0, s0
	ds_write_b16 v65, v0 offset:8768
	v_cvt_pk_bf16_f32 v0, v1, s0
	ds_write_b16 v65, v0 offset:9040
	v_cvt_pk_bf16_f32 v0, v2, s0
	ds_write_b16 v65, v0 offset:9312
	v_cvt_pk_bf16_f32 v0, v3, s0
	v_cvt_pk_bf16_f32 v48, v48, s0
	v_cvt_pk_bf16_f32 v32, v32, s0
	v_cvt_pk_bf16_f32 v16, v16, s0
	ds_write_b16 v65, v0 offset:9584
	v_cvt_pk_bf16_f32 v0, v4, s0
	ds_write_b16 v65, v48
	v_cvt_pk_bf16_f32 v48, v49, s0
	ds_write_b16 v65, v32 offset:64
	v_cvt_pk_bf16_f32 v32, v33, s0
	ds_write_b16 v65, v16 offset:8704
	v_cvt_pk_bf16_f32 v16, v17, s0
	ds_write_b16 v65, v0 offset:10944
	v_cvt_pk_bf16_f32 v0, v5, s0
	ds_write_b16 v65, v48 offset:272
	v_cvt_pk_bf16_f32 v48, v50, s0
	ds_write_b16 v65, v32 offset:336
	v_cvt_pk_bf16_f32 v32, v34, s0
	ds_write_b16 v65, v16 offset:8976
	v_cvt_pk_bf16_f32 v16, v18, s0
	ds_write_b16 v65, v0 offset:11216
	v_cvt_pk_bf16_f32 v0, v6, s0
	ds_write_b16 v65, v48 offset:544
	v_cvt_pk_bf16_f32 v48, v51, s0
	ds_write_b16 v65, v32 offset:608
	v_cvt_pk_bf16_f32 v32, v35, s0
	ds_write_b16 v65, v16 offset:9248
	v_cvt_pk_bf16_f32 v16, v19, s0
	ds_write_b16 v65, v0 offset:11488
	v_cvt_pk_bf16_f32 v0, v7, s0
	ds_write_b16 v65, v48 offset:816
	v_cvt_pk_bf16_f32 v48, v52, s0
	ds_write_b16 v65, v32 offset:880
	v_cvt_pk_bf16_f32 v32, v36, s0
	ds_write_b16 v65, v16 offset:9520
	v_cvt_pk_bf16_f32 v16, v20, s0
	ds_write_b16 v65, v0 offset:11760
	v_cvt_pk_bf16_f32 v0, v8, s0
	ds_write_b16 v65, v48 offset:2176
	v_cvt_pk_bf16_f32 v48, v53, s0
	ds_write_b16 v65, v32 offset:2240
	v_cvt_pk_bf16_f32 v32, v37, s0
	ds_write_b16 v65, v16 offset:10880
	v_cvt_pk_bf16_f32 v16, v21, s0
	ds_write_b16 v65, v0 offset:13120
	v_cvt_pk_bf16_f32 v0, v9, s0
	ds_write_b16 v65, v48 offset:2448
	v_cvt_pk_bf16_f32 v48, v54, s0
	ds_write_b16 v65, v32 offset:2512
	v_cvt_pk_bf16_f32 v32, v38, s0
	ds_write_b16 v65, v16 offset:11152
; DI u16 f2bf(float x) { return (u16)(pack2(x, 0.f) & 0xffffu); }
; DI int opaque_tid() { int t = threadIdx.x; asm volatile("" : "+v"(t)); return t; }
; DI int crow(int i, int h) { return (i & 3) + 8 * (i >> 2) + 4 * h; }
; template <class F>
; DI void epi_bf16_tile(const f32x16 (&acc)[2][2], int m0, int n0, u16* dst0, long ld, char* smem, F f) {
;   const int tid = opaque_tid(), lane = tid & 63, w = tid >> 6, wm = w >> 1, wn = w & 1, h = lane >> 5;
;   u16* T = (u16*)smem;
; #pragma unroll
;   for (int mt = 0; mt < 2; mt++)
; #pragma unroll
;     for (int nt = 0; nt < 2; nt++)
; #pragma unroll
;       for (int i = 0; i < 16; i++) {
;         const int ml = wm * 64 + mt * 32 + crow(i, h), nl = wn * 64 + nt * 32 + (lane & 31);
;         T[ml * 136 + nl] = f2bf(f(m0 + ml, n0 + nl, acc[mt][nt][i]));
;       }
;   __syncthreads();
; #pragma unroll
;   for (int j = 0; j < 8; j++) {
;     const int idx = tid + 256 * j, row = idx >> 4, ch = idx & 15;
;     *(uint4*)(dst0 + (long)row * ld + ch * 8) = *(const uint4*)(T + row * 136 + ch * 8);
;   }
;   __syncthreads();
; }
	v_cvt_pk_bf16_f32 v16, v22, s0
	ds_write_b16 v65, v0 offset:13392
	v_cvt_pk_bf16_f32 v0, v10, s0
	ds_write_b16 v65, v48 offset:2720
	v_cvt_pk_bf16_f32 v48, v55, s0
	ds_write_b16 v65, v32 offset:2784
	v_cvt_pk_bf16_f32 v32, v39, s0
	ds_write_b16 v65, v16 offset:11424
	v_cvt_pk_bf16_f32 v16, v23, s0
	ds_write_b16 v65, v0 offset:13664
	v_cvt_pk_bf16_f32 v0, v11, s0
	ds_write_b16 v65, v48 offset:2992
	v_cvt_pk_bf16_f32 v48, v56, s0
	ds_write_b16 v65, v32 offset:3056
	v_cvt_pk_bf16_f32 v32, v40, s0
	ds_write_b16 v65, v16 offset:11696
	v_cvt_pk_bf16_f32 v16, v24, s0
	ds_write_b16 v65, v0 offset:13936
	v_cvt_pk_bf16_f32 v0, v12, s0
	ds_write_b16 v65, v48 offset:4352
	v_cvt_pk_bf16_f32 v48, v57, s0
	ds_write_b16 v65, v32 offset:4416
	v_cvt_pk_bf16_f32 v32, v41, s0
	ds_write_b16 v65, v16 offset:13056
	v_cvt_pk_bf16_f32 v16, v25, s0
	ds_write_b16 v65, v0 offset:15296
	v_cvt_pk_bf16_f32 v0, v13, s0
	ds_write_b16 v65, v48 offset:4624
	v_cvt_pk_bf16_f32 v48, v58, s0
	ds_write_b16 v65, v32 offset:4688
	v_cvt_pk_bf16_f32 v32, v42, s0
	ds_write_b16 v65, v16 offset:13328
	v_cvt_pk_bf16_f32 v16, v26, s0
	ds_write_b16 v65, v0 offset:15568
	v_cvt_pk_bf16_f32 v0, v14, s0
	ds_write_b16 v65, v48 offset:4896
	v_cvt_pk_bf16_f32 v48, v59, s0
	ds_write_b16 v65, v32 offset:4960
	v_cvt_pk_bf16_f32 v32, v43, s0
	ds_write_b16 v65, v16 offset:13600
	v_cvt_pk_bf16_f32 v16, v27, s0
	ds_write_b16 v65, v0 offset:15840
	v_cvt_pk_bf16_f32 v0, v15, s0
	ds_write_b16 v65, v48 offset:5168
	v_cvt_pk_bf16_f32 v48, v60, s0
	ds_write_b16 v65, v32 offset:5232
	v_cvt_pk_bf16_f32 v32, v44, s0
	ds_write_b16 v65, v16 offset:13872
	v_cvt_pk_bf16_f32 v16, v28, s0
	ds_write_b16 v65, v0 offset:16112
	v_lshlrev_b32_e32 v0, 4, v64
	ds_write_b16 v65, v48 offset:6528
	v_cvt_pk_bf16_f32 v48, v61, s0
	ds_write_b16 v65, v32 offset:6592
	v_cvt_pk_bf16_f32 v32, v45, s0
	ds_write_b16 v65, v16 offset:15232
	v_cvt_pk_bf16_f32 v16, v29, s0
	v_and_b32_e32 v156, 0xf0, v0
	v_ashrrev_i32_e32 v0, 4, v64
	s_addc_u32 s1, s3, s1
	ds_write_b16 v65, v48 offset:6800
	v_cvt_pk_bf16_f32 v48, v62, s0
	ds_write_b16 v65, v32 offset:6864
	v_cvt_pk_bf16_f32 v32, v46, s0
	ds_write_b16 v65, v16 offset:15504
	v_cvt_pk_bf16_f32 v16, v30, s0
	v_ashrrev_i32_e32 v1, 31, v0
	ds_write_b16 v65, v48 offset:7072
	v_cvt_pk_bf16_f32 v48, v63, s0
	ds_write_b16 v65, v32 offset:7136
	v_cvt_pk_bf16_f32 v32, v47, s0
	ds_write_b16 v65, v16 offset:15776
	v_cvt_pk_bf16_f32 v16, v31, s0
	v_lshl_add_u64 v[8:9], s[0:1], 0, v[156:157]
	v_mad_u64_u32 v[2:3], s[0:1], v0, s57, v[156:157]
	v_lshlrev_b64 v[0:1], 11, v[0:1]
	v_add_u32_e32 v4, 0x100, v64
	ds_write_b16 v65, v48 offset:7344
	ds_write_b16 v65, v32 offset:7408
	ds_write_b16 v65, v16 offset:16048
	s_waitcnt lgkmcnt(0)
	s_barrier
	v_lshl_add_u64 v[10:11], v[8:9], 0, v[0:1]
	ds_read_b128 v[0:3], v2
	v_ashrrev_i32_e32 v12, 4, v4
	v_mad_u64_u32 v[4:5], s[0:1], v12, s57, v[156:157]
	ds_read_b128 v[4:7], v4
	v_ashrrev_i32_e32 v13, 31, v12
	s_waitcnt lgkmcnt(1)
	global_store_dwordx4 v[10:11], v[0:3], off
	s_nop 1
	v_lshlrev_b64 v[0:1], 11, v[12:13]
	v_lshl_add_u64 v[0:1], v[8:9], 0, v[0:1]
	s_waitcnt lgkmcnt(0)
	global_store_dwordx4 v[0:1], v[4:7], off
	v_add_u32_e32 v0, 0x200, v64
	v_ashrrev_i32_e32 v0, 4, v0
	v_ashrrev_i32_e32 v1, 31, v0
	v_mad_u64_u32 v[2:3], s[0:1], v0, s57, v[156:157]
	v_lshlrev_b64 v[0:1], 11, v[0:1]
	v_add_u32_e32 v4, 0x300, v64
	v_lshl_add_u64 v[10:11], v[8:9], 0, v[0:1]
	ds_read_b128 v[0:3], v2
	v_ashrrev_i32_e32 v12, 4, v4
	v_mad_u64_u32 v[4:5], s[0:1], v12, s57, v[156:157]
	ds_read_b128 v[4:7], v4
	v_ashrrev_i32_e32 v13, 31, v12
	s_waitcnt lgkmcnt(1)
	global_store_dwordx4 v[10:11], v[0:3], off
	s_nop 1
	v_lshlrev_b64 v[0:1], 11, v[12:13]
	v_lshl_add_u64 v[0:1], v[8:9], 0, v[0:1]
	s_waitcnt lgkmcnt(0)
	global_store_dwordx4 v[0:1], v[4:7], off
	v_add_u32_e32 v0, 0x400, v64
	v_ashrrev_i32_e32 v0, 4, v0
	v_ashrrev_i32_e32 v1, 31, v0
	v_mad_u64_u32 v[2:3], s[0:1], v0, s57, v[156:157]
	v_lshlrev_b64 v[0:1], 11, v[0:1]
	v_add_u32_e32 v4, 0x500, v64
	v_lshl_add_u64 v[10:11], v[8:9], 0, v[0:1]
	ds_read_b128 v[0:3], v2
	v_ashrrev_i32_e32 v12, 4, v4
	v_mad_u64_u32 v[4:5], s[0:1], v12, s57, v[156:157]
	ds_read_b128 v[4:7], v4
	v_ashrrev_i32_e32 v13, 31, v12
	s_waitcnt lgkmcnt(1)
	global_store_dwordx4 v[10:11], v[0:3], off
	s_nop 1
	v_lshlrev_b64 v[0:1], 11, v[12:13]
	v_lshl_add_u64 v[0:1], v[8:9], 0, v[0:1]
	s_waitcnt lgkmcnt(0)
	global_store_dwordx4 v[0:1], v[4:7], off
	v_add_u32_e32 v0, 0x600, v64
	v_ashrrev_i32_e32 v0, 4, v0
	v_ashrrev_i32_e32 v1, 31, v0
	v_mad_u64_u32 v[2:3], s[0:1], v0, s57, v[156:157]
	v_lshlrev_b64 v[0:1], 11, v[0:1]
	v_add_u32_e32 v4, 0x700, v64
	v_lshl_add_u64 v[10:11], v[8:9], 0, v[0:1]
	ds_read_b128 v[0:3], v2
	v_ashrrev_i32_e32 v12, 4, v4
	v_mad_u64_u32 v[4:5], s[0:1], v12, s57, v[156:157]
	ds_read_b128 v[4:7], v4
	v_ashrrev_i32_e32 v13, 31, v12
	s_waitcnt lgkmcnt(1)
	global_store_dwordx4 v[10:11], v[0:3], off
	s_nop 1
	v_lshlrev_b64 v[0:1], 11, v[12:13]
	v_lshl_add_u64 v[0:1], v[8:9], 0, v[0:1]
	s_waitcnt lgkmcnt(0)
	global_store_dwordx4 v[0:1], v[4:7], off
	s_barrier
